# E4 + every v_pk_mul/add/fma_f32 in the kernel split into scalar f32 pairs (bit-identical)
# baseline (speedup 1.0000x reference)
; __device__ __forceinline__ unsigned cvt_pk_bf16(float lo, float hi) { f32x2_t v = {lo, hi}; bf16x2_t b = __builtin_convertvector(v, bf16x2_t); return __builtin_bit_cast(unsigned, b); }
; __device__ __forceinline__ float rstd_of(const float* ss, int row) { return __builtin_amdgcn_rsqf(ss[row] * (1.0f / 1024.0f) + RMS_EPS); }
; __device__ __forceinline__ float sigmoidf_(float v) { return __builtin_amdgcn_rcpf(1.0f + __builtin_amdgcn_exp2f(-v * LOG2E)); }
;     __device__ __forceinline__ void operator()(const Acc& acc, const Unit& u, int wr, int wc, int fr, int fq) const {
;         const int row0 = u.pm * BM + wr * 64 + fr, col0 = u.pn * 128 + wc * 32 + 8 * fq;
; #pragma unroll
;         for (int ai = 0; ai < 2; ++ai)
; #pragma unroll
;             for (int m = 0; m < 4; ++m) {
;                 const int row = row0 + ai * HALF + m * 16; const float rs = rstd_of(ss, row);
;                 float o[8];
; #pragma unroll
;                 for (int n = 0; n < 2; ++n)
; #pragma unroll
;                     for (int e = 0; e < 4; ++e) { const float gv = acc[ai][0][m][n][e] * rs, uv = acc[ai][1][m][n][e] * rs; o[4 * n + e] = gv * sigmoidf_(gv) * uv; }
;                 u32x4 w; w.x = cvt_pk_bf16(o[0], o[1]); w.y = cvt_pk_bf16(o[2], o[3]); w.z = cvt_pk_bf16(o[4], o[5]); w.w = cvt_pk_bf16(o[6], o[7]);
;                 *(u32x4*)(H + (size_t)row * FF + col0) = w;
;             }
.LBB0_217:
	v_lshl_add_u32 v144, s46, 8, v152
	v_ashrrev_i32_e32 v145, 31, v144
	v_lshl_add_u64 v[150:151], v[144:145], 2, s[48:49]
	global_load_dword v145, v[150:151], off
	v_lshl_or_b32 v148, s34, 7, v154
	v_mov_b64_e32 v[146:147], s[20:21]
	v_ashrrev_i32_e32 v149, 31, v148
	v_mad_i64_i32 v[164:165], s[6:7], v144, s33, v[146:147]
	v_lshlrev_b64 v[148:149], 1, v[148:149]
	v_lshl_add_u64 v[164:165], v[164:165], 0, v[148:149]
	s_andn2_b64 vcc, exec, s[4:5]
	s_mov_b64 s[4:5], -1
	s_waitcnt vmcnt(0)
	v_fmamk_f32 v145, v145, 0x3a800000, v158
	v_rsq_f32_e32 v162, v145
	s_nop 0
	v_mul_f32_e32 v124, v124, v162
	v_mul_f32_e32 v125, v125, v162
	v_mul_f32_e32 v126, v126, v162
	v_mul_f32_e32 v127, v127, v162
	v_mul_f32_e32 v120, v120, v162
	v_mul_f32_e32 v121, v121, v162
	v_mul_f32_e32 v122, v122, v162
	v_mul_f32_e32 v123, v123, v162
	v_mul_f32_e32 v116, v116, v162
	v_mul_f32_e32 v117, v117, v162
	v_mul_f32_e32 v118, v118, v162
	v_mul_f32_e32 v119, v119, v162
	v_mul_f32_e32 v112, v112, v162
	v_mul_f32_e32 v113, v113, v162
	v_mul_f32_e32 v114, v114, v162
	v_mul_f32_e32 v115, v115, v162
	v_mul_f32_e32 v145, 0xbfb8aa3b, v124
	v_mul_f32_e32 v159, 0xbfb8aa3b, v125
	v_mul_f32_e32 v162, 0xbfb8aa3b, v126
	v_mul_f32_e32 v163, 0xbfb8aa3b, v127
	v_mul_f32_e32 v166, 0xbfb8aa3b, v120
	v_mul_f32_e32 v167, 0xbfb8aa3b, v121
	v_mul_f32_e32 v168, 0xbfb8aa3b, v122
	v_mul_f32_e32 v169, 0xbfb8aa3b, v123
	v_exp_f32_e32 v145, v145
	v_exp_f32_e32 v159, v159
	v_exp_f32_e32 v162, v162
	v_exp_f32_e32 v163, v163
	v_exp_f32_e32 v166, v166
	v_exp_f32_e32 v167, v167
	v_exp_f32_e32 v168, v168
	v_exp_f32_e32 v169, v169
	v_add_f32_e32 v145, 1.0, v145
	v_add_f32_e32 v159, 1.0, v159
	v_add_f32_e32 v170, 1.0, v162
	v_add_f32_e32 v171, 1.0, v163
	v_add_f32_e32 v173, 1.0, v166
	v_add_f32_e32 v174, 1.0, v167
	v_add_f32_e32 v178, 1.0, v168
	v_add_f32_e32 v179, 1.0, v169
	v_rcp_f32_e32 v162, v145
	v_rcp_f32_e32 v163, v159
	v_rcp_f32_e32 v166, v170
	v_rcp_f32_e32 v167, v171
	v_rcp_f32_e32 v168, v173
	v_rcp_f32_e32 v169, v174
	v_rcp_f32_e32 v170, v178
	v_rcp_f32_e32 v171, v179
	v_mul_f32_e32 v124, v124, v162
	v_mul_f32_e32 v125, v125, v163
	v_mul_f32_e32 v126, v126, v166
	v_mul_f32_e32 v127, v127, v167
	v_mul_f32_e32 v120, v120, v168
	v_mul_f32_e32 v121, v121, v169
	v_mul_f32_e32 v122, v122, v170
	v_mul_f32_e32 v123, v123, v171
	v_mul_f32_e32 v116, v116, v124
	v_mul_f32_e32 v117, v117, v125
	v_mul_f32_e32 v118, v118, v126
	v_mul_f32_e32 v119, v119, v127
	v_mul_f32_e32 v120, v112, v120
	v_mul_f32_e32 v121, v113, v121
	v_mul_f32_e32 v122, v114, v122
	v_mul_f32_e32 v123, v115, v123
	v_cvt_pk_bf16_f32 v112, v116, v117
	v_cvt_pk_bf16_f32 v113, v118, v119
	v_cvt_pk_bf16_f32 v114, v120, v121
	v_cvt_pk_bf16_f32 v115, v122, v123
	global_store_dwordx4 v[164:165], v[112:115], off
	global_load_dword v112, v[150:151], off offset:64
	s_nop 0
	v_or_b32_e32 v113, 16, v144
	v_mad_i64_i32 v[114:115], s[6:7], v113, s33, v[146:147]
	v_lshl_add_u64 v[114:115], v[114:115], 0, v[148:149]
	s_waitcnt vmcnt(0)
	v_fmamk_f32 v112, v112, 0x3a800000, v158
	v_rsq_f32_e32 v112, v112
	s_nop 0
	v_mul_f32_e32 v108, v108, v112
	v_mul_f32_e32 v109, v109, v112
	v_mul_f32_e32 v110, v110, v112
	v_mul_f32_e32 v111, v111, v112
	v_mul_f32_e32 v104, v104, v112
	v_mul_f32_e32 v105, v105, v112
	v_mul_f32_e32 v106, v106, v112
	v_mul_f32_e32 v107, v107, v112
	v_mul_f32_e32 v100, v100, v112
	v_mul_f32_e32 v101, v101, v112
	v_mul_f32_e32 v102, v102, v112
	v_mul_f32_e32 v103, v103, v112
	v_mul_f32_e32 v96, v96, v112
	v_mul_f32_e32 v97, v97, v112
	v_mul_f32_e32 v98, v98, v112
	v_mul_f32_e32 v99, v99, v112
	v_mul_f32_e32 v112, 0xbfb8aa3b, v108
	v_mul_f32_e32 v113, 0xbfb8aa3b, v109
	v_mul_f32_e32 v116, 0xbfb8aa3b, v110
	v_mul_f32_e32 v117, 0xbfb8aa3b, v111
	v_mul_f32_e32 v118, 0xbfb8aa3b, v104
	v_mul_f32_e32 v119, 0xbfb8aa3b, v105
	v_mul_f32_e32 v120, 0xbfb8aa3b, v106
	v_mul_f32_e32 v121, 0xbfb8aa3b, v107
	v_exp_f32_e32 v112, v112
	v_exp_f32_e32 v113, v113
	v_exp_f32_e32 v116, v116
	v_exp_f32_e32 v117, v117
	v_exp_f32_e32 v118, v118
	v_exp_f32_e32 v119, v119
	v_exp_f32_e32 v120, v120
	v_exp_f32_e32 v121, v121
	v_add_f32_e32 v112, 1.0, v112
	v_add_f32_e32 v113, 1.0, v113
	v_add_f32_e32 v116, 1.0, v116
	v_add_f32_e32 v117, 1.0, v117
	v_add_f32_e32 v118, 1.0, v118
	v_add_f32_e32 v119, 1.0, v119
	v_add_f32_e32 v120, 1.0, v120
	v_add_f32_e32 v121, 1.0, v121
	v_rcp_f32_e32 v112, v112
	v_rcp_f32_e32 v113, v113
	v_rcp_f32_e32 v116, v116
	v_rcp_f32_e32 v117, v117
	v_rcp_f32_e32 v118, v118
	v_rcp_f32_e32 v119, v119
	v_rcp_f32_e32 v120, v120
	v_rcp_f32_e32 v121, v121
	v_mul_f32_e32 v108, v108, v112
	v_mul_f32_e32 v109, v109, v113
	v_mul_f32_e32 v110, v110, v116
	v_mul_f32_e32 v111, v111, v117
	v_mul_f32_e32 v104, v104, v118
	v_mul_f32_e32 v105, v105, v119
	v_mul_f32_e32 v106, v106, v120
	v_mul_f32_e32 v107, v107, v121
	v_mul_f32_e32 v100, v100, v108
	v_mul_f32_e32 v101, v101, v109
	v_mul_f32_e32 v102, v102, v110
	v_mul_f32_e32 v103, v103, v111
	v_mul_f32_e32 v104, v96, v104
	v_mul_f32_e32 v105, v97, v105
	v_mul_f32_e32 v106, v98, v106
	v_mul_f32_e32 v107, v99, v107
	v_cvt_pk_bf16_f32 v96, v100, v101
	v_cvt_pk_bf16_f32 v97, v102, v103
	v_cvt_pk_bf16_f32 v98, v104, v105
	v_cvt_pk_bf16_f32 v99, v106, v107
	global_store_dwordx4 v[114:115], v[96:99], off
	global_load_dword v96, v[150:151], off offset:128
	s_nop 0
	v_or_b32_e32 v97, 32, v144
	v_mad_i64_i32 v[98:99], s[6:7], v97, s33, v[146:147]
	v_lshl_add_u64 v[98:99], v[98:99], 0, v[148:149]
	s_waitcnt vmcnt(0)
; __device__ __forceinline__ unsigned cvt_pk_bf16(float lo, float hi) { f32x2_t v = {lo, hi}; bf16x2_t b = __builtin_convertvector(v, bf16x2_t); return __builtin_bit_cast(unsigned, b); }
; __device__ __forceinline__ float rstd_of(const float* ss, int row) { return __builtin_amdgcn_rsqf(ss[row] * (1.0f / 1024.0f) + RMS_EPS); }
; __device__ __forceinline__ float sigmoidf_(float v) { return __builtin_amdgcn_rcpf(1.0f + __builtin_amdgcn_exp2f(-v * LOG2E)); }
;     __device__ __forceinline__ void operator()(const Acc& acc, const Unit& u, int wr, int wc, int fr, int fq) const {
;         const int row0 = u.pm * BM + wr * 64 + fr, col0 = u.pn * 128 + wc * 32 + 8 * fq;
; #pragma unroll
;         for (int ai = 0; ai < 2; ++ai)
; #pragma unroll
;             for (int m = 0; m < 4; ++m) {
;                 const int row = row0 + ai * HALF + m * 16; const float rs = rstd_of(ss, row);
;                 float o[8];
; #pragma unroll
;                 for (int n = 0; n < 2; ++n)
; #pragma unroll
;                     for (int e = 0; e < 4; ++e) { const float gv = acc[ai][0][m][n][e] * rs, uv = acc[ai][1][m][n][e] * rs; o[4 * n + e] = gv * sigmoidf_(gv) * uv; }
;                 u32x4 w; w.x = cvt_pk_bf16(o[0], o[1]); w.y = cvt_pk_bf16(o[2], o[3]); w.z = cvt_pk_bf16(o[4], o[5]); w.w = cvt_pk_bf16(o[6], o[7]);
;                 *(u32x4*)(H + (size_t)row * FF + col0) = w;
;             }
	v_fmamk_f32 v96, v96, 0x3a800000, v158
	v_rsq_f32_e32 v96, v96
	s_nop 0
	v_mul_f32_e32 v92, v92, v96
	v_mul_f32_e32 v93, v93, v96
	v_mul_f32_e32 v94, v94, v96
	v_mul_f32_e32 v95, v95, v96
	v_mul_f32_e32 v88, v88, v96
	v_mul_f32_e32 v89, v89, v96
	v_mul_f32_e32 v90, v90, v96
	v_mul_f32_e32 v91, v91, v96
	v_mul_f32_e32 v84, v84, v96
	v_mul_f32_e32 v85, v85, v96
	v_mul_f32_e32 v86, v86, v96
	v_mul_f32_e32 v87, v87, v96
	v_mul_f32_e32 v80, v80, v96
	v_mul_f32_e32 v81, v81, v96
	v_mul_f32_e32 v82, v82, v96
	v_mul_f32_e32 v83, v83, v96
	v_mul_f32_e32 v96, 0xbfb8aa3b, v92
	v_mul_f32_e32 v97, 0xbfb8aa3b, v93
	v_mul_f32_e32 v100, 0xbfb8aa3b, v94
	v_mul_f32_e32 v101, 0xbfb8aa3b, v95
	v_mul_f32_e32 v102, 0xbfb8aa3b, v88
	v_mul_f32_e32 v103, 0xbfb8aa3b, v89
	v_mul_f32_e32 v104, 0xbfb8aa3b, v90
	v_mul_f32_e32 v105, 0xbfb8aa3b, v91
	v_exp_f32_e32 v96, v96
	v_exp_f32_e32 v97, v97
	v_exp_f32_e32 v100, v100
	v_exp_f32_e32 v101, v101
	v_exp_f32_e32 v102, v102
	v_exp_f32_e32 v103, v103
	v_exp_f32_e32 v104, v104
	v_exp_f32_e32 v105, v105
	v_add_f32_e32 v96, 1.0, v96
	v_add_f32_e32 v97, 1.0, v97
	v_add_f32_e32 v100, 1.0, v100
	v_add_f32_e32 v101, 1.0, v101
	v_add_f32_e32 v102, 1.0, v102
	v_add_f32_e32 v103, 1.0, v103
	v_add_f32_e32 v104, 1.0, v104
	v_add_f32_e32 v105, 1.0, v105
	v_rcp_f32_e32 v96, v96
	v_rcp_f32_e32 v97, v97
	v_rcp_f32_e32 v100, v100
	v_rcp_f32_e32 v101, v101
	v_rcp_f32_e32 v102, v102
	v_rcp_f32_e32 v103, v103
	v_rcp_f32_e32 v104, v104
	v_rcp_f32_e32 v105, v105
	v_mul_f32_e32 v92, v92, v96
	v_mul_f32_e32 v93, v93, v97
	v_mul_f32_e32 v94, v94, v100
	v_mul_f32_e32 v95, v95, v101
	v_mul_f32_e32 v88, v88, v102
	v_mul_f32_e32 v89, v89, v103
	v_mul_f32_e32 v90, v90, v104
	v_mul_f32_e32 v91, v91, v105
	v_mul_f32_e32 v84, v84, v92
	v_mul_f32_e32 v85, v85, v93
	v_mul_f32_e32 v86, v86, v94
	v_mul_f32_e32 v87, v87, v95
	v_mul_f32_e32 v88, v80, v88
	v_mul_f32_e32 v89, v81, v89
	v_mul_f32_e32 v90, v82, v90
	v_mul_f32_e32 v91, v83, v91
	v_cvt_pk_bf16_f32 v80, v84, v85
	v_cvt_pk_bf16_f32 v81, v86, v87
	v_cvt_pk_bf16_f32 v82, v88, v89
	v_cvt_pk_bf16_f32 v83, v90, v91
	global_store_dwordx4 v[98:99], v[80:83], off
	global_load_dword v80, v[150:151], off offset:192
	s_nop 0
	v_or_b32_e32 v81, 48, v144
	v_mad_i64_i32 v[82:83], s[6:7], v81, s33, v[146:147]
	v_lshl_add_u64 v[82:83], v[82:83], 0, v[148:149]
	s_waitcnt vmcnt(0)
	v_fmamk_f32 v80, v80, 0x3a800000, v158
	v_rsq_f32_e32 v80, v80
	s_nop 0
	v_mul_f32_e32 v76, v76, v80
	v_mul_f32_e32 v77, v77, v80
	v_mul_f32_e32 v78, v78, v80
	v_mul_f32_e32 v79, v79, v80
	v_mul_f32_e32 v72, v72, v80
	v_mul_f32_e32 v73, v73, v80
	v_mul_f32_e32 v74, v74, v80
	v_mul_f32_e32 v75, v75, v80
	v_mul_f32_e32 v68, v68, v80
	v_mul_f32_e32 v69, v69, v80
	v_mul_f32_e32 v70, v70, v80
	v_mul_f32_e32 v71, v71, v80
	v_mul_f32_e32 v64, v64, v80
	v_mul_f32_e32 v65, v65, v80
	v_mul_f32_e32 v66, v66, v80
	v_mul_f32_e32 v67, v67, v80
	v_mul_f32_e32 v80, 0xbfb8aa3b, v76
	v_mul_f32_e32 v81, 0xbfb8aa3b, v77
	v_mul_f32_e32 v84, 0xbfb8aa3b, v78
	v_mul_f32_e32 v85, 0xbfb8aa3b, v79
	v_mul_f32_e32 v86, 0xbfb8aa3b, v72
	v_mul_f32_e32 v87, 0xbfb8aa3b, v73
	v_mul_f32_e32 v88, 0xbfb8aa3b, v74
	v_mul_f32_e32 v89, 0xbfb8aa3b, v75
	v_exp_f32_e32 v80, v80
	v_exp_f32_e32 v81, v81
	v_exp_f32_e32 v84, v84
	v_exp_f32_e32 v85, v85
	v_exp_f32_e32 v86, v86
	v_exp_f32_e32 v87, v87
	v_exp_f32_e32 v88, v88
	v_exp_f32_e32 v89, v89
	v_add_f32_e32 v80, 1.0, v80
	v_add_f32_e32 v81, 1.0, v81
	v_add_f32_e32 v84, 1.0, v84
	v_add_f32_e32 v85, 1.0, v85
	v_add_f32_e32 v86, 1.0, v86
	v_add_f32_e32 v87, 1.0, v87
	v_add_f32_e32 v88, 1.0, v88
	v_add_f32_e32 v89, 1.0, v89
	v_rcp_f32_e32 v80, v80
	v_rcp_f32_e32 v81, v81
	v_rcp_f32_e32 v84, v84
	v_rcp_f32_e32 v85, v85
	v_rcp_f32_e32 v86, v86
	v_rcp_f32_e32 v87, v87
	v_rcp_f32_e32 v88, v88
	v_rcp_f32_e32 v89, v89
	v_mul_f32_e32 v76, v76, v80
	v_mul_f32_e32 v77, v77, v81
	v_mul_f32_e32 v78, v78, v84
	v_mul_f32_e32 v79, v79, v85
	v_mul_f32_e32 v72, v72, v86
	v_mul_f32_e32 v73, v73, v87
	v_mul_f32_e32 v74, v74, v88
	v_mul_f32_e32 v75, v75, v89
	v_mul_f32_e32 v68, v68, v76
	v_mul_f32_e32 v69, v69, v77
	v_mul_f32_e32 v70, v70, v78
	v_mul_f32_e32 v71, v71, v79
	v_mul_f32_e32 v72, v64, v72
	v_mul_f32_e32 v73, v65, v73
	v_mul_f32_e32 v74, v66, v74
	v_mul_f32_e32 v75, v67, v75
	v_cvt_pk_bf16_f32 v64, v68, v69
	v_cvt_pk_bf16_f32 v65, v70, v71
	v_cvt_pk_bf16_f32 v66, v72, v73
	v_cvt_pk_bf16_f32 v67, v74, v75
	global_store_dwordx4 v[82:83], v[64:67], off
	global_load_dword v64, v[150:151], off offset:512
	s_nop 0
	v_add_u32_e32 v65, 0x80, v144
	v_mad_i64_i32 v[66:67], s[6:7], v65, s33, v[146:147]
	v_lshl_add_u64 v[66:67], v[66:67], 0, v[148:149]
	s_waitcnt vmcnt(0)
; __device__ __forceinline__ unsigned cvt_pk_bf16(float lo, float hi) { f32x2_t v = {lo, hi}; bf16x2_t b = __builtin_convertvector(v, bf16x2_t); return __builtin_bit_cast(unsigned, b); }
; __device__ __forceinline__ float rstd_of(const float* ss, int row) { return __builtin_amdgcn_rsqf(ss[row] * (1.0f / 1024.0f) + RMS_EPS); }
; __device__ __forceinline__ float sigmoidf_(float v) { return __builtin_amdgcn_rcpf(1.0f + __builtin_amdgcn_exp2f(-v * LOG2E)); }
;     __device__ __forceinline__ void operator()(const Acc& acc, const Unit& u, int wr, int wc, int fr, int fq) const {
;         const int row0 = u.pm * BM + wr * 64 + fr, col0 = u.pn * 128 + wc * 32 + 8 * fq;
; #pragma unroll
;         for (int ai = 0; ai < 2; ++ai)
; #pragma unroll
;             for (int m = 0; m < 4; ++m) {
;                 const int row = row0 + ai * HALF + m * 16; const float rs = rstd_of(ss, row);
;                 float o[8];
; #pragma unroll
;                 for (int n = 0; n < 2; ++n)
; #pragma unroll
;                     for (int e = 0; e < 4; ++e) { const float gv = acc[ai][0][m][n][e] * rs, uv = acc[ai][1][m][n][e] * rs; o[4 * n + e] = gv * sigmoidf_(gv) * uv; }
;                 u32x4 w; w.x = cvt_pk_bf16(o[0], o[1]); w.y = cvt_pk_bf16(o[2], o[3]); w.z = cvt_pk_bf16(o[4], o[5]); w.w = cvt_pk_bf16(o[6], o[7]);
;                 *(u32x4*)(H + (size_t)row * FF + col0) = w;
;             }
	v_fmamk_f32 v64, v64, 0x3a800000, v158
	v_rsq_f32_e32 v64, v64
	s_nop 0
	v_mul_f32_e32 v60, v60, v64
	v_mul_f32_e32 v61, v61, v64
	v_mul_f32_e32 v62, v62, v64
	v_mul_f32_e32 v63, v63, v64
	v_mul_f32_e32 v56, v56, v64
	v_mul_f32_e32 v57, v57, v64
	v_mul_f32_e32 v58, v58, v64
	v_mul_f32_e32 v59, v59, v64
	v_mul_f32_e32 v52, v52, v64
	v_mul_f32_e32 v53, v53, v64
	v_mul_f32_e32 v54, v54, v64
	v_mul_f32_e32 v55, v55, v64
	v_mul_f32_e32 v48, v48, v64
	v_mul_f32_e32 v49, v49, v64
	v_mul_f32_e32 v50, v50, v64
	v_mul_f32_e32 v51, v51, v64
	v_mul_f32_e32 v64, 0xbfb8aa3b, v60
	v_mul_f32_e32 v65, 0xbfb8aa3b, v61
	v_mul_f32_e32 v68, 0xbfb8aa3b, v62
	v_mul_f32_e32 v69, 0xbfb8aa3b, v63
	v_mul_f32_e32 v70, 0xbfb8aa3b, v56
	v_mul_f32_e32 v71, 0xbfb8aa3b, v57
	v_mul_f32_e32 v72, 0xbfb8aa3b, v58
	v_mul_f32_e32 v73, 0xbfb8aa3b, v59
	v_exp_f32_e32 v64, v64
	v_exp_f32_e32 v65, v65
	v_exp_f32_e32 v68, v68
	v_exp_f32_e32 v69, v69
	v_exp_f32_e32 v70, v70
	v_exp_f32_e32 v71, v71
	v_exp_f32_e32 v72, v72
	v_exp_f32_e32 v73, v73
	v_add_f32_e32 v64, 1.0, v64
	v_add_f32_e32 v65, 1.0, v65
	v_add_f32_e32 v68, 1.0, v68
	v_add_f32_e32 v69, 1.0, v69
	v_add_f32_e32 v70, 1.0, v70
	v_add_f32_e32 v71, 1.0, v71
	v_add_f32_e32 v72, 1.0, v72
	v_add_f32_e32 v73, 1.0, v73
	v_rcp_f32_e32 v64, v64
	v_rcp_f32_e32 v65, v65
	v_rcp_f32_e32 v68, v68
	v_rcp_f32_e32 v69, v69
	v_rcp_f32_e32 v70, v70
	v_rcp_f32_e32 v71, v71
	v_rcp_f32_e32 v72, v72
	v_rcp_f32_e32 v73, v73
	v_mul_f32_e32 v60, v60, v64
	v_mul_f32_e32 v61, v61, v65
	v_mul_f32_e32 v62, v62, v68
	v_mul_f32_e32 v63, v63, v69
	v_mul_f32_e32 v56, v56, v70
	v_mul_f32_e32 v57, v57, v71
	v_mul_f32_e32 v58, v58, v72
	v_mul_f32_e32 v59, v59, v73
	v_mul_f32_e32 v52, v52, v60
	v_mul_f32_e32 v53, v53, v61
	v_mul_f32_e32 v54, v54, v62
	v_mul_f32_e32 v55, v55, v63
	v_mul_f32_e32 v56, v48, v56
	v_mul_f32_e32 v57, v49, v57
	v_mul_f32_e32 v58, v50, v58
	v_mul_f32_e32 v59, v51, v59
	v_cvt_pk_bf16_f32 v48, v52, v53
	v_cvt_pk_bf16_f32 v49, v54, v55
	v_cvt_pk_bf16_f32 v50, v56, v57
	v_cvt_pk_bf16_f32 v51, v58, v59
	global_store_dwordx4 v[66:67], v[48:51], off
	global_load_dword v48, v[150:151], off offset:576
	s_nop 0
	v_add_u32_e32 v49, 0x90, v144
	v_mad_i64_i32 v[50:51], s[6:7], v49, s33, v[146:147]
	v_lshl_add_u64 v[50:51], v[50:51], 0, v[148:149]
	s_waitcnt vmcnt(0)
	v_fmamk_f32 v48, v48, 0x3a800000, v158
	v_rsq_f32_e32 v48, v48
	s_nop 0
	v_mul_f32_e32 v44, v44, v48
	v_mul_f32_e32 v45, v45, v48
	v_mul_f32_e32 v46, v46, v48
	v_mul_f32_e32 v47, v47, v48
	v_mul_f32_e32 v40, v40, v48
	v_mul_f32_e32 v41, v41, v48
	v_mul_f32_e32 v42, v42, v48
	v_mul_f32_e32 v43, v43, v48
	v_mul_f32_e32 v36, v36, v48
	v_mul_f32_e32 v37, v37, v48
	v_mul_f32_e32 v38, v38, v48
	v_mul_f32_e32 v39, v39, v48
	v_mul_f32_e32 v32, v32, v48
	v_mul_f32_e32 v33, v33, v48
	v_mul_f32_e32 v34, v34, v48
	v_mul_f32_e32 v35, v35, v48
	v_mul_f32_e32 v48, 0xbfb8aa3b, v44
	v_mul_f32_e32 v49, 0xbfb8aa3b, v45
	v_mul_f32_e32 v52, 0xbfb8aa3b, v46
	v_mul_f32_e32 v53, 0xbfb8aa3b, v47
	v_mul_f32_e32 v54, 0xbfb8aa3b, v40
	v_mul_f32_e32 v55, 0xbfb8aa3b, v41
	v_mul_f32_e32 v56, 0xbfb8aa3b, v42
	v_mul_f32_e32 v57, 0xbfb8aa3b, v43
	v_exp_f32_e32 v48, v48
	v_exp_f32_e32 v49, v49
	v_exp_f32_e32 v52, v52
	v_exp_f32_e32 v53, v53
	v_exp_f32_e32 v54, v54
	v_exp_f32_e32 v55, v55
	v_exp_f32_e32 v56, v56
	v_exp_f32_e32 v57, v57
	v_add_f32_e32 v48, 1.0, v48
	v_add_f32_e32 v49, 1.0, v49
	v_add_f32_e32 v52, 1.0, v52
	v_add_f32_e32 v53, 1.0, v53
	v_add_f32_e32 v54, 1.0, v54
	v_add_f32_e32 v55, 1.0, v55
	v_add_f32_e32 v56, 1.0, v56
	v_add_f32_e32 v57, 1.0, v57
	v_rcp_f32_e32 v48, v48
	v_rcp_f32_e32 v49, v49
	v_rcp_f32_e32 v52, v52
	v_rcp_f32_e32 v53, v53
	v_rcp_f32_e32 v54, v54
	v_rcp_f32_e32 v55, v55
	v_rcp_f32_e32 v56, v56
	v_rcp_f32_e32 v57, v57
	v_mul_f32_e32 v44, v44, v48
	v_mul_f32_e32 v45, v45, v49
	v_mul_f32_e32 v46, v46, v52
	v_mul_f32_e32 v47, v47, v53
	v_mul_f32_e32 v40, v40, v54
	v_mul_f32_e32 v41, v41, v55
	v_mul_f32_e32 v42, v42, v56
	v_mul_f32_e32 v43, v43, v57
	v_mul_f32_e32 v36, v36, v44
	v_mul_f32_e32 v37, v37, v45
	v_mul_f32_e32 v38, v38, v46
	v_mul_f32_e32 v39, v39, v47
	v_mul_f32_e32 v40, v32, v40
	v_mul_f32_e32 v41, v33, v41
	v_mul_f32_e32 v42, v34, v42
	v_mul_f32_e32 v43, v35, v43
	v_cvt_pk_bf16_f32 v32, v36, v37
	v_cvt_pk_bf16_f32 v33, v38, v39
	v_cvt_pk_bf16_f32 v34, v40, v41
	v_cvt_pk_bf16_f32 v35, v42, v43
	global_store_dwordx4 v[50:51], v[32:35], off
	global_load_dword v32, v[150:151], off offset:640
	s_nop 0
	v_add_u32_e32 v33, 0xa0, v144
	v_mad_i64_i32 v[34:35], s[6:7], v33, s33, v[146:147]
	v_lshl_add_u64 v[34:35], v[34:35], 0, v[148:149]
	s_waitcnt vmcnt(0)
; __device__ __forceinline__ unsigned cvt_pk_bf16(float lo, float hi) { f32x2_t v = {lo, hi}; bf16x2_t b = __builtin_convertvector(v, bf16x2_t); return __builtin_bit_cast(unsigned, b); }
; __device__ __forceinline__ float rstd_of(const float* ss, int row) { return __builtin_amdgcn_rsqf(ss[row] * (1.0f / 1024.0f) + RMS_EPS); }
; __device__ __forceinline__ float sigmoidf_(float v) { return __builtin_amdgcn_rcpf(1.0f + __builtin_amdgcn_exp2f(-v * LOG2E)); }
;     __device__ __forceinline__ void operator()(const Acc& acc, const Unit& u, int wr, int wc, int fr, int fq) const {
;         const int row0 = u.pm * BM + wr * 64 + fr, col0 = u.pn * 128 + wc * 32 + 8 * fq;
; #pragma unroll
;         for (int ai = 0; ai < 2; ++ai)
; #pragma unroll
;             for (int m = 0; m < 4; ++m) {
;                 const int row = row0 + ai * HALF + m * 16; const float rs = rstd_of(ss, row);
;                 float o[8];
; #pragma unroll
;                 for (int n = 0; n < 2; ++n)
; #pragma unroll
;                     for (int e = 0; e < 4; ++e) { const float gv = acc[ai][0][m][n][e] * rs, uv = acc[ai][1][m][n][e] * rs; o[4 * n + e] = gv * sigmoidf_(gv) * uv; }
;                 u32x4 w; w.x = cvt_pk_bf16(o[0], o[1]); w.y = cvt_pk_bf16(o[2], o[3]); w.z = cvt_pk_bf16(o[4], o[5]); w.w = cvt_pk_bf16(o[6], o[7]);
;                 *(u32x4*)(H + (size_t)row * FF + col0) = w;
;             }
	v_fmamk_f32 v32, v32, 0x3a800000, v158
	v_rsq_f32_e32 v32, v32
	s_nop 0
	v_mul_f32_e32 v28, v28, v32
	v_mul_f32_e32 v29, v29, v32
	v_mul_f32_e32 v30, v30, v32
	v_mul_f32_e32 v31, v31, v32
	v_mul_f32_e32 v24, v24, v32
	v_mul_f32_e32 v25, v25, v32
	v_mul_f32_e32 v26, v26, v32
	v_mul_f32_e32 v27, v27, v32
	v_mul_f32_e32 v20, v20, v32
	v_mul_f32_e32 v21, v21, v32
	v_mul_f32_e32 v22, v22, v32
	v_mul_f32_e32 v23, v23, v32
	v_mul_f32_e32 v16, v16, v32
	v_mul_f32_e32 v17, v17, v32
	v_mul_f32_e32 v18, v18, v32
	v_mul_f32_e32 v19, v19, v32
	v_mul_f32_e32 v32, 0xbfb8aa3b, v28
	v_mul_f32_e32 v33, 0xbfb8aa3b, v29
	v_mul_f32_e32 v36, 0xbfb8aa3b, v30
	v_mul_f32_e32 v37, 0xbfb8aa3b, v31
	v_mul_f32_e32 v38, 0xbfb8aa3b, v24
	v_mul_f32_e32 v39, 0xbfb8aa3b, v25
	v_mul_f32_e32 v40, 0xbfb8aa3b, v26
	v_mul_f32_e32 v41, 0xbfb8aa3b, v27
	v_exp_f32_e32 v32, v32
	v_exp_f32_e32 v33, v33
	v_exp_f32_e32 v36, v36
	v_exp_f32_e32 v37, v37
	v_exp_f32_e32 v38, v38
	v_exp_f32_e32 v39, v39
	v_exp_f32_e32 v40, v40
	v_exp_f32_e32 v41, v41
	v_add_f32_e32 v32, 1.0, v32
	v_add_f32_e32 v33, 1.0, v33
	v_add_f32_e32 v36, 1.0, v36
	v_add_f32_e32 v37, 1.0, v37
	v_add_f32_e32 v38, 1.0, v38
	v_add_f32_e32 v39, 1.0, v39
	v_add_f32_e32 v40, 1.0, v40
	v_add_f32_e32 v41, 1.0, v41
	v_rcp_f32_e32 v32, v32
	v_rcp_f32_e32 v33, v33
	v_rcp_f32_e32 v36, v36
	v_rcp_f32_e32 v37, v37
	v_rcp_f32_e32 v38, v38
	v_rcp_f32_e32 v39, v39
	v_rcp_f32_e32 v40, v40
	v_rcp_f32_e32 v41, v41
	v_mul_f32_e32 v28, v28, v32
	v_mul_f32_e32 v29, v29, v33
	v_mul_f32_e32 v30, v30, v36
	v_mul_f32_e32 v31, v31, v37
	v_mul_f32_e32 v24, v24, v38
	v_mul_f32_e32 v25, v25, v39
	v_mul_f32_e32 v26, v26, v40
	v_mul_f32_e32 v27, v27, v41
	v_mul_f32_e32 v20, v20, v28
	v_mul_f32_e32 v21, v21, v29
	v_mul_f32_e32 v22, v22, v30
	v_mul_f32_e32 v23, v23, v31
	v_mul_f32_e32 v24, v16, v24
	v_mul_f32_e32 v25, v17, v25
	v_mul_f32_e32 v26, v18, v26
	v_mul_f32_e32 v27, v19, v27
	v_cvt_pk_bf16_f32 v16, v20, v21
	v_cvt_pk_bf16_f32 v17, v22, v23
	v_cvt_pk_bf16_f32 v18, v24, v25
	v_cvt_pk_bf16_f32 v19, v26, v27
	global_store_dwordx4 v[34:35], v[16:19], off
	global_load_dword v16, v[150:151], off offset:704
	s_nop 0
	v_add_u32_e32 v17, 0xb0, v144
	v_mad_i64_i32 v[18:19], s[6:7], v17, s33, v[146:147]
	v_lshl_add_u64 v[18:19], v[18:19], 0, v[148:149]
	s_waitcnt vmcnt(0)
	v_fmamk_f32 v16, v16, 0x3a800000, v158
	v_rsq_f32_e32 v16, v16
	s_nop 0
	v_mul_f32_e32 v12, v12, v16
	v_mul_f32_e32 v13, v13, v16
	v_mul_f32_e32 v14, v14, v16
	v_mul_f32_e32 v15, v15, v16
	v_mul_f32_e32 v8, v8, v16
	v_mul_f32_e32 v9, v9, v16
	v_mul_f32_e32 v10, v10, v16
	v_mul_f32_e32 v11, v11, v16
	v_mul_f32_e32 v4, v4, v16
	v_mul_f32_e32 v5, v5, v16
	v_mul_f32_e32 v6, v6, v16
	v_mul_f32_e32 v7, v7, v16
	v_mul_f32_e32 v0, v0, v16
	v_mul_f32_e32 v1, v1, v16
	v_mul_f32_e32 v2, v2, v16
	v_mul_f32_e32 v3, v3, v16
	v_mul_f32_e32 v16, 0xbfb8aa3b, v12
	v_mul_f32_e32 v17, 0xbfb8aa3b, v13
	v_mul_f32_e32 v20, 0xbfb8aa3b, v14
	v_mul_f32_e32 v21, 0xbfb8aa3b, v15
	v_mul_f32_e32 v22, 0xbfb8aa3b, v8
	v_mul_f32_e32 v23, 0xbfb8aa3b, v9
	v_mul_f32_e32 v24, 0xbfb8aa3b, v10
	v_mul_f32_e32 v25, 0xbfb8aa3b, v11
	v_exp_f32_e32 v16, v16
	v_exp_f32_e32 v17, v17
	v_exp_f32_e32 v20, v20
	v_exp_f32_e32 v21, v21
	v_exp_f32_e32 v22, v22
	v_exp_f32_e32 v23, v23
	v_exp_f32_e32 v24, v24
	v_exp_f32_e32 v25, v25
	v_add_f32_e32 v16, 1.0, v16
	v_add_f32_e32 v17, 1.0, v17
	v_add_f32_e32 v20, 1.0, v20
	v_add_f32_e32 v21, 1.0, v21
	v_add_f32_e32 v22, 1.0, v22
	v_add_f32_e32 v23, 1.0, v23
	v_add_f32_e32 v24, 1.0, v24
	v_add_f32_e32 v25, 1.0, v25
	v_rcp_f32_e32 v16, v16
	v_rcp_f32_e32 v17, v17
	v_rcp_f32_e32 v20, v20
	v_rcp_f32_e32 v21, v21
	v_rcp_f32_e32 v22, v22
	v_rcp_f32_e32 v23, v23
	v_rcp_f32_e32 v24, v24
	v_rcp_f32_e32 v25, v25
	v_mul_f32_e32 v12, v12, v16
	v_mul_f32_e32 v13, v13, v17
	v_mul_f32_e32 v14, v14, v20
	v_mul_f32_e32 v15, v15, v21
	v_mul_f32_e32 v8, v8, v22
	v_mul_f32_e32 v9, v9, v23
	v_mul_f32_e32 v10, v10, v24
	v_mul_f32_e32 v11, v11, v25
	v_mul_f32_e32 v4, v4, v12
	v_mul_f32_e32 v5, v5, v13
	v_mul_f32_e32 v6, v6, v14
	v_mul_f32_e32 v7, v7, v15
	v_mul_f32_e32 v8, v0, v8
	v_mul_f32_e32 v9, v1, v9
	v_mul_f32_e32 v10, v2, v10
	v_mul_f32_e32 v11, v3, v11
	v_cvt_pk_bf16_f32 v0, v4, v5
	v_cvt_pk_bf16_f32 v1, v6, v7
	v_cvt_pk_bf16_f32 v2, v8, v9
	v_cvt_pk_bf16_f32 v3, v10, v11
	global_store_dwordx4 v[18:19], v[0:3], off
	s_cbranch_vccnz .LBB0_210
	s_andn2_b64 vcc, exec, s[0:1]
	s_cbranch_vccnz .LBB0_209
	s_barrier
	s_branch .LBB0_209

; __device__ __forceinline__ unsigned cvt_pk_bf16(float lo, float hi) { f32x2_t v = {lo, hi}; bf16x2_t b = __builtin_convertvector(v, bf16x2_t); return __builtin_bit_cast(unsigned, b); }
;     __device__ __forceinline__ void operator()(const Acc& acc, const Unit& u, int wr, int wc, int fr, int fq) const {
;         const int row0 = u.pm * BM + wr * 64 + fr, col0 = u.pn * BM + wc * 32 + 8 * fq;
; #pragma unroll
;         for (int ai = 0; ai < 2; ++ai)
; #pragma unroll
;             for (int m = 0; m < 4; ++m) {
;                 const int row = row0 + ai * HALF + m * 16; float sq = 0.f;
; #pragma unroll
;                 for (int bj = 0; bj < 2; ++bj) {
;                     const size_t off = (size_t)row * DM + col0 + bj * HALF;
;                     const f32x4 b0 = *(const f32x4*)(base + off), b1 = *(const f32x4*)(base + off + 4);
;                     const f32x4 x0 = b0 + acc[ai][bj][m][0] * alpha, x1 = b1 + acc[ai][bj][m][1] * alpha;
;                     __builtin_nontemporal_store(x0, (f32x4*)(out + off)); __builtin_nontemporal_store(x1, (f32x4*)(out + off + 4));
;                     sq += (x0[0] * x0[0] + x0[1] * x0[1]) + (x0[2] * x0[2] + x0[3] * x0[3]) + (x1[0] * x1[0] + x1[1] * x1[1]) + (x1[2] * x1[2] + x1[3] * x1[3]);
;                     if (xb) { u32x4 w; w.x = cvt_pk_bf16(x0[0], x0[1]); w.y = cvt_pk_bf16(x0[2], x0[3]); w.z = cvt_pk_bf16(x1[0], x1[1]); w.w = cvt_pk_bf16(x1[2], x1[3]); *(u32x4*)(xb + off) = w; }
;                 }
.LBB0_299:
	v_lshl_add_u32 v146, s31, 8, v154
	v_lshl_or_b32 v144, s33, 8, v156
	v_ashrrev_i32_e32 v147, 31, v146
	v_ashrrev_i32_e32 v145, 31, v144
	v_lshlrev_b64 v[148:149], 10, v[146:147]
	v_lshl_add_u64 v[148:149], v[148:149], 0, v[144:145]
	v_lshlrev_b64 v[152:153], 2, v[148:149]
	v_lshl_add_u64 v[150:151], s[52:53], 0, v[152:153]
	global_load_dwordx4 v[164:167], v[150:151], off
	global_load_dwordx4 v[168:171], v[150:151], off offset:16
	v_cndmask_b32_e64 v163, 0, 1, s[46:47]
	v_cmp_ne_u32_e64 s[12:13], 1, v163
	s_andn2_b64 vcc, exec, s[46:47]
	v_lshl_add_u64 v[152:153], s[90:91], 0, v[152:153]
	s_waitcnt vmcnt(0)
	v_fma_f32 v126, v126, 0.5, v166
	v_fma_f32 v127, v127, 0.5, v167
	v_fma_f32 v124, v124, 0.5, v164
	v_fma_f32 v125, v125, 0.5, v165
	v_fma_f32 v122, v122, 0.5, v170
	v_fma_f32 v123, v123, 0.5, v171
	v_fma_f32 v120, v120, 0.5, v168
	v_fma_f32 v121, v121, 0.5, v169
	global_store_dwordx4 v[152:153], v[124:127], off nt
	global_store_dwordx4 v[152:153], v[120:123], off offset:16 nt
	s_cbranch_vccnz .LBB0_301
	v_cvt_pk_bf16_f32 v164, v124, v125
	v_cvt_pk_bf16_f32 v165, v126, v127
	v_cvt_pk_bf16_f32 v166, v120, v121
	v_cvt_pk_bf16_f32 v167, v122, v123
	v_lshl_add_u64 v[168:169], v[148:149], 1, s[70:71]
	global_store_dwordx4 v[168:169], v[164:167], off
.LBB0_301:
	global_load_dwordx4 v[164:167], v[150:151], off offset:512
	s_nop 0
	global_load_dwordx4 v[168:171], v[150:151], off offset:528
	s_and_b64 vcc, exec, s[12:13]
	s_waitcnt vmcnt(1)
	v_fma_f32 v118, v118, 0.5, v166
	v_fma_f32 v119, v119, 0.5, v167
	v_fma_f32 v116, v116, 0.5, v164
	v_fma_f32 v117, v117, 0.5, v165
	s_waitcnt vmcnt(0)
	v_fma_f32 v114, v114, 0.5, v170
	v_fma_f32 v115, v115, 0.5, v171
	v_fma_f32 v112, v112, 0.5, v168
	v_fma_f32 v113, v113, 0.5, v169
	global_store_dwordx4 v[152:153], v[116:119], off offset:512 nt
	global_store_dwordx4 v[152:153], v[112:115], off offset:528 nt
	s_cbranch_vccnz .LBB0_303
	v_lshlrev_b64 v[152:153], 1, v[148:149]
	v_or_b32_e32 v152, 0x100, v152
	v_cvt_pk_bf16_f32 v148, v116, v117
	v_cvt_pk_bf16_f32 v149, v118, v119
	v_cvt_pk_bf16_f32 v150, v112, v113
	v_cvt_pk_bf16_f32 v151, v114, v115
	v_lshl_add_u64 v[152:153], s[70:71], 0, v[152:153]
	global_store_dwordx4 v[152:153], v[148:151], off

; __device__ __forceinline__ unsigned cvt_pk_bf16(float lo, float hi) { f32x2_t v = {lo, hi}; bf16x2_t b = __builtin_convertvector(v, bf16x2_t); return __builtin_bit_cast(unsigned, b); }
;     __device__ __forceinline__ void operator()(const Acc& acc, const Unit& u, int wr, int wc, int fr, int fq) const {
;         const int row0 = u.pm * BM + wr * 64 + fr, col0 = u.pn * BM + wc * 32 + 8 * fq;
; #pragma unroll
;         for (int ai = 0; ai < 2; ++ai)
; #pragma unroll
;             for (int m = 0; m < 4; ++m) {
;                 const int row = row0 + ai * HALF + m * 16; float sq = 0.f;
; #pragma unroll
;                 for (int bj = 0; bj < 2; ++bj) {
;                     const size_t off = (size_t)row * DM + col0 + bj * HALF;
;                     const f32x4 b0 = *(const f32x4*)(base + off), b1 = *(const f32x4*)(base + off + 4);
;                     const f32x4 x0 = b0 + acc[ai][bj][m][0] * alpha, x1 = b1 + acc[ai][bj][m][1] * alpha;
;                     __builtin_nontemporal_store(x0, (f32x4*)(out + off)); __builtin_nontemporal_store(x1, (f32x4*)(out + off + 4));
;                     sq += (x0[0] * x0[0] + x0[1] * x0[1]) + (x0[2] * x0[2] + x0[3] * x0[3]) + (x1[0] * x1[0] + x1[1] * x1[1]) + (x1[2] * x1[2] + x1[3] * x1[3]);
;                     if (xb) { u32x4 w; w.x = cvt_pk_bf16(x0[0], x0[1]); w.y = cvt_pk_bf16(x0[2], x0[3]); w.z = cvt_pk_bf16(x1[0], x1[1]); w.w = cvt_pk_bf16(x1[2], x1[3]); *(u32x4*)(xb + off) = w; }
;                 }
.LBB0_305:
	s_or_b64 exec, exec, s[6:7]
	v_or_b32_e32 v112, 16, v146
	s_waitcnt lgkmcnt(0)
	v_ashrrev_i32_e32 v113, 31, v112
	v_lshlrev_b64 v[114:115], 10, v[112:113]
	v_lshl_add_u64 v[114:115], v[114:115], 0, v[144:145]
	v_lshlrev_b64 v[116:117], 2, v[114:115]
	v_lshl_add_u64 v[118:119], s[52:53], 0, v[116:117]
	global_load_dwordx4 v[122:125], v[118:119], off
	global_load_dwordx4 v[148:151], v[118:119], off offset:16
	s_and_b64 vcc, exec, s[12:13]
	v_lshl_add_u64 v[116:117], s[90:91], 0, v[116:117]
	s_waitcnt vmcnt(1)
	v_fma_f32 v110, v110, 0.5, v124
	v_fma_f32 v111, v111, 0.5, v125
	v_fma_f32 v108, v108, 0.5, v122
	v_fma_f32 v109, v109, 0.5, v123
	s_waitcnt vmcnt(0)
	v_fma_f32 v106, v106, 0.5, v150
	v_fma_f32 v107, v107, 0.5, v151
	v_fma_f32 v104, v104, 0.5, v148
	v_fma_f32 v105, v105, 0.5, v149
	global_store_dwordx4 v[116:117], v[108:111], off nt
	global_store_dwordx4 v[116:117], v[104:107], off offset:16 nt
	s_cbranch_vccnz .LBB0_307
	v_cvt_pk_bf16_f32 v122, v108, v109
	v_cvt_pk_bf16_f32 v123, v110, v111
	v_cvt_pk_bf16_f32 v124, v104, v105
	v_cvt_pk_bf16_f32 v125, v106, v107
	v_lshl_add_u64 v[126:127], v[114:115], 1, s[70:71]
	global_store_dwordx4 v[126:127], v[122:125], off
.LBB0_307:
	global_load_dwordx4 v[122:125], v[118:119], off offset:512
	s_nop 0
	global_load_dwordx4 v[148:151], v[118:119], off offset:528
	s_and_b64 vcc, exec, s[12:13]
	s_waitcnt vmcnt(1)
	v_fma_f32 v102, v102, 0.5, v124
	v_fma_f32 v103, v103, 0.5, v125
	v_fma_f32 v100, v100, 0.5, v122
	v_fma_f32 v101, v101, 0.5, v123
	s_waitcnt vmcnt(0)
	v_fma_f32 v98, v98, 0.5, v150
	v_fma_f32 v99, v99, 0.5, v151
	v_fma_f32 v96, v96, 0.5, v148
	v_fma_f32 v97, v97, 0.5, v149
	global_store_dwordx4 v[116:117], v[100:103], off offset:512 nt
	global_store_dwordx4 v[116:117], v[96:99], off offset:528 nt
	s_cbranch_vccnz .LBB0_309
	v_lshlrev_b64 v[118:119], 1, v[114:115]
	v_or_b32_e32 v118, 0x100, v118
	v_cvt_pk_bf16_f32 v114, v100, v101
	v_cvt_pk_bf16_f32 v115, v102, v103
	v_cvt_pk_bf16_f32 v116, v96, v97
	v_cvt_pk_bf16_f32 v117, v98, v99
	v_lshl_add_u64 v[118:119], s[70:71], 0, v[118:119]
	global_store_dwordx4 v[118:119], v[114:117], off

; __device__ __forceinline__ unsigned cvt_pk_bf16(float lo, float hi) { f32x2_t v = {lo, hi}; bf16x2_t b = __builtin_convertvector(v, bf16x2_t); return __builtin_bit_cast(unsigned, b); }
;     __device__ __forceinline__ void operator()(const Acc& acc, const Unit& u, int wr, int wc, int fr, int fq) const {
;         const int row0 = u.pm * BM + wr * 64 + fr, col0 = u.pn * BM + wc * 32 + 8 * fq;
; #pragma unroll
;         for (int ai = 0; ai < 2; ++ai)
; #pragma unroll
;             for (int m = 0; m < 4; ++m) {
;                 const int row = row0 + ai * HALF + m * 16; float sq = 0.f;
; #pragma unroll
;                 for (int bj = 0; bj < 2; ++bj) {
;                     const size_t off = (size_t)row * DM + col0 + bj * HALF;
;                     const f32x4 b0 = *(const f32x4*)(base + off), b1 = *(const f32x4*)(base + off + 4);
;                     const f32x4 x0 = b0 + acc[ai][bj][m][0] * alpha, x1 = b1 + acc[ai][bj][m][1] * alpha;
;                     __builtin_nontemporal_store(x0, (f32x4*)(out + off)); __builtin_nontemporal_store(x1, (f32x4*)(out + off + 4));
;                     sq += (x0[0] * x0[0] + x0[1] * x0[1]) + (x0[2] * x0[2] + x0[3] * x0[3]) + (x1[0] * x1[0] + x1[1] * x1[1]) + (x1[2] * x1[2] + x1[3] * x1[3]);
;                     if (xb) { u32x4 w; w.x = cvt_pk_bf16(x0[0], x0[1]); w.y = cvt_pk_bf16(x0[2], x0[3]); w.z = cvt_pk_bf16(x1[0], x1[1]); w.w = cvt_pk_bf16(x1[2], x1[3]); *(u32x4*)(xb + off) = w; }
;                 }
.LBB0_311:
	s_or_b64 exec, exec, s[6:7]
	v_or_b32_e32 v96, 32, v146
	s_waitcnt lgkmcnt(0)
	v_ashrrev_i32_e32 v97, 31, v96
	v_lshlrev_b64 v[98:99], 10, v[96:97]
	v_lshl_add_u64 v[98:99], v[98:99], 0, v[144:145]
	v_lshlrev_b64 v[100:101], 2, v[98:99]
	v_lshl_add_u64 v[102:103], s[52:53], 0, v[100:101]
	global_load_dwordx4 v[104:107], v[102:103], off
	global_load_dwordx4 v[108:111], v[102:103], off offset:16
	s_and_b64 vcc, exec, s[12:13]
	v_lshl_add_u64 v[100:101], s[90:91], 0, v[100:101]
	s_waitcnt vmcnt(1)
	v_fma_f32 v94, v94, 0.5, v106
	v_fma_f32 v95, v95, 0.5, v107
	v_fma_f32 v92, v92, 0.5, v104
	v_fma_f32 v93, v93, 0.5, v105
	s_waitcnt vmcnt(0)
	v_fma_f32 v90, v90, 0.5, v110
	v_fma_f32 v91, v91, 0.5, v111
	v_fma_f32 v88, v88, 0.5, v108
	v_fma_f32 v89, v89, 0.5, v109
	global_store_dwordx4 v[100:101], v[92:95], off nt
	global_store_dwordx4 v[100:101], v[88:91], off offset:16 nt
	s_cbranch_vccnz .LBB0_313
	v_cvt_pk_bf16_f32 v104, v92, v93
	v_cvt_pk_bf16_f32 v105, v94, v95
	v_cvt_pk_bf16_f32 v106, v88, v89
	v_cvt_pk_bf16_f32 v107, v90, v91
	v_lshl_add_u64 v[108:109], v[98:99], 1, s[70:71]
	global_store_dwordx4 v[108:109], v[104:107], off
.LBB0_313:
	global_load_dwordx4 v[104:107], v[102:103], off offset:512
	s_nop 0
	global_load_dwordx4 v[108:111], v[102:103], off offset:528
	s_and_b64 vcc, exec, s[12:13]
	s_waitcnt vmcnt(1)
	v_fma_f32 v86, v86, 0.5, v106
	v_fma_f32 v87, v87, 0.5, v107
	v_fma_f32 v84, v84, 0.5, v104
	v_fma_f32 v85, v85, 0.5, v105
	s_waitcnt vmcnt(0)
	v_fma_f32 v82, v82, 0.5, v110
	v_fma_f32 v83, v83, 0.5, v111
	v_fma_f32 v80, v80, 0.5, v108
	v_fma_f32 v81, v81, 0.5, v109
	global_store_dwordx4 v[100:101], v[84:87], off offset:512 nt
	global_store_dwordx4 v[100:101], v[80:83], off offset:528 nt
	s_cbranch_vccnz .LBB0_315
	v_lshlrev_b64 v[102:103], 1, v[98:99]
	v_or_b32_e32 v102, 0x100, v102
	v_cvt_pk_bf16_f32 v98, v84, v85
	v_cvt_pk_bf16_f32 v99, v86, v87
	v_cvt_pk_bf16_f32 v100, v80, v81
	v_cvt_pk_bf16_f32 v101, v82, v83
	v_lshl_add_u64 v[102:103], s[70:71], 0, v[102:103]
	global_store_dwordx4 v[102:103], v[98:101], off

; __device__ __forceinline__ unsigned cvt_pk_bf16(float lo, float hi) { f32x2_t v = {lo, hi}; bf16x2_t b = __builtin_convertvector(v, bf16x2_t); return __builtin_bit_cast(unsigned, b); }
;     __device__ __forceinline__ void operator()(const Acc& acc, const Unit& u, int wr, int wc, int fr, int fq) const {
;         const int row0 = u.pm * BM + wr * 64 + fr, col0 = u.pn * BM + wc * 32 + 8 * fq;
; #pragma unroll
;         for (int ai = 0; ai < 2; ++ai)
; #pragma unroll
;             for (int m = 0; m < 4; ++m) {
;                 const int row = row0 + ai * HALF + m * 16; float sq = 0.f;
; #pragma unroll
;                 for (int bj = 0; bj < 2; ++bj) {
;                     const size_t off = (size_t)row * DM + col0 + bj * HALF;
;                     const f32x4 b0 = *(const f32x4*)(base + off), b1 = *(const f32x4*)(base + off + 4);
;                     const f32x4 x0 = b0 + acc[ai][bj][m][0] * alpha, x1 = b1 + acc[ai][bj][m][1] * alpha;
;                     __builtin_nontemporal_store(x0, (f32x4*)(out + off)); __builtin_nontemporal_store(x1, (f32x4*)(out + off + 4));
;                     sq += (x0[0] * x0[0] + x0[1] * x0[1]) + (x0[2] * x0[2] + x0[3] * x0[3]) + (x1[0] * x1[0] + x1[1] * x1[1]) + (x1[2] * x1[2] + x1[3] * x1[3]);
;                     if (xb) { u32x4 w; w.x = cvt_pk_bf16(x0[0], x0[1]); w.y = cvt_pk_bf16(x0[2], x0[3]); w.z = cvt_pk_bf16(x1[0], x1[1]); w.w = cvt_pk_bf16(x1[2], x1[3]); *(u32x4*)(xb + off) = w; }
;                 }
.LBB0_317:
	s_or_b64 exec, exec, s[6:7]
	v_or_b32_e32 v80, 48, v146
	s_waitcnt lgkmcnt(0)
	v_ashrrev_i32_e32 v81, 31, v80
	v_lshlrev_b64 v[82:83], 10, v[80:81]
	v_lshl_add_u64 v[82:83], v[82:83], 0, v[144:145]
	v_lshlrev_b64 v[84:85], 2, v[82:83]
	v_lshl_add_u64 v[86:87], s[52:53], 0, v[84:85]
	global_load_dwordx4 v[88:91], v[86:87], off
	global_load_dwordx4 v[92:95], v[86:87], off offset:16
	s_and_b64 vcc, exec, s[12:13]
	v_lshl_add_u64 v[84:85], s[90:91], 0, v[84:85]
	s_waitcnt vmcnt(1)
	v_fma_f32 v78, v78, 0.5, v90
	v_fma_f32 v79, v79, 0.5, v91
	v_fma_f32 v76, v76, 0.5, v88
	v_fma_f32 v77, v77, 0.5, v89
	s_waitcnt vmcnt(0)
	v_fma_f32 v74, v74, 0.5, v94
	v_fma_f32 v75, v75, 0.5, v95
	v_fma_f32 v72, v72, 0.5, v92
	v_fma_f32 v73, v73, 0.5, v93
	global_store_dwordx4 v[84:85], v[76:79], off nt
	global_store_dwordx4 v[84:85], v[72:75], off offset:16 nt
	s_cbranch_vccnz .LBB0_319
	v_cvt_pk_bf16_f32 v88, v76, v77
	v_cvt_pk_bf16_f32 v89, v78, v79
	v_cvt_pk_bf16_f32 v90, v72, v73
	v_cvt_pk_bf16_f32 v91, v74, v75
	v_lshl_add_u64 v[92:93], v[82:83], 1, s[70:71]
	global_store_dwordx4 v[92:93], v[88:91], off
.LBB0_319:
	global_load_dwordx4 v[88:91], v[86:87], off offset:512
	s_nop 0
	global_load_dwordx4 v[92:95], v[86:87], off offset:528
	s_and_b64 vcc, exec, s[12:13]
	s_waitcnt vmcnt(1)
	v_fma_f32 v70, v70, 0.5, v90
	v_fma_f32 v71, v71, 0.5, v91
	v_fma_f32 v68, v68, 0.5, v88
	v_fma_f32 v69, v69, 0.5, v89
	s_waitcnt vmcnt(0)
	v_fma_f32 v66, v66, 0.5, v94
	v_fma_f32 v67, v67, 0.5, v95
	v_fma_f32 v64, v64, 0.5, v92
	v_fma_f32 v65, v65, 0.5, v93
	global_store_dwordx4 v[84:85], v[68:71], off offset:512 nt
	global_store_dwordx4 v[84:85], v[64:67], off offset:528 nt
	s_cbranch_vccnz .LBB0_321
	v_lshlrev_b64 v[86:87], 1, v[82:83]
	v_or_b32_e32 v86, 0x100, v86
	v_cvt_pk_bf16_f32 v82, v68, v69
	v_cvt_pk_bf16_f32 v83, v70, v71
	v_cvt_pk_bf16_f32 v84, v64, v65
	v_cvt_pk_bf16_f32 v85, v66, v67
	v_lshl_add_u64 v[86:87], s[70:71], 0, v[86:87]
	global_store_dwordx4 v[86:87], v[82:85], off

; __device__ __forceinline__ unsigned cvt_pk_bf16(float lo, float hi) { f32x2_t v = {lo, hi}; bf16x2_t b = __builtin_convertvector(v, bf16x2_t); return __builtin_bit_cast(unsigned, b); }
;     __device__ __forceinline__ void operator()(const Acc& acc, const Unit& u, int wr, int wc, int fr, int fq) const {
;         const int row0 = u.pm * BM + wr * 64 + fr, col0 = u.pn * BM + wc * 32 + 8 * fq;
; #pragma unroll
;         for (int ai = 0; ai < 2; ++ai)
; #pragma unroll
;             for (int m = 0; m < 4; ++m) {
;                 const int row = row0 + ai * HALF + m * 16; float sq = 0.f;
; #pragma unroll
;                 for (int bj = 0; bj < 2; ++bj) {
;                     const size_t off = (size_t)row * DM + col0 + bj * HALF;
;                     const f32x4 b0 = *(const f32x4*)(base + off), b1 = *(const f32x4*)(base + off + 4);
;                     const f32x4 x0 = b0 + acc[ai][bj][m][0] * alpha, x1 = b1 + acc[ai][bj][m][1] * alpha;
;                     __builtin_nontemporal_store(x0, (f32x4*)(out + off)); __builtin_nontemporal_store(x1, (f32x4*)(out + off + 4));
;                     sq += (x0[0] * x0[0] + x0[1] * x0[1]) + (x0[2] * x0[2] + x0[3] * x0[3]) + (x1[0] * x1[0] + x1[1] * x1[1]) + (x1[2] * x1[2] + x1[3] * x1[3]);
;                     if (xb) { u32x4 w; w.x = cvt_pk_bf16(x0[0], x0[1]); w.y = cvt_pk_bf16(x0[2], x0[3]); w.z = cvt_pk_bf16(x1[0], x1[1]); w.w = cvt_pk_bf16(x1[2], x1[3]); *(u32x4*)(xb + off) = w; }
;                 }
.LBB0_323:
	s_or_b64 exec, exec, s[6:7]
	v_add_u32_e32 v64, 0x80, v146
	s_waitcnt lgkmcnt(0)
	v_ashrrev_i32_e32 v65, 31, v64
	v_lshlrev_b64 v[66:67], 10, v[64:65]
	v_lshl_add_u64 v[66:67], v[66:67], 0, v[144:145]
	v_lshlrev_b64 v[68:69], 2, v[66:67]
	v_lshl_add_u64 v[70:71], s[52:53], 0, v[68:69]
	global_load_dwordx4 v[72:75], v[70:71], off
	global_load_dwordx4 v[76:79], v[70:71], off offset:16
	s_and_b64 vcc, exec, s[12:13]
	v_lshl_add_u64 v[68:69], s[90:91], 0, v[68:69]
	s_waitcnt vmcnt(1)
	v_fma_f32 v62, v62, 0.5, v74
	v_fma_f32 v63, v63, 0.5, v75
	v_fma_f32 v60, v60, 0.5, v72
	v_fma_f32 v61, v61, 0.5, v73
	s_waitcnt vmcnt(0)
	v_fma_f32 v58, v58, 0.5, v78
	v_fma_f32 v59, v59, 0.5, v79
	v_fma_f32 v56, v56, 0.5, v76
	v_fma_f32 v57, v57, 0.5, v77
	global_store_dwordx4 v[68:69], v[60:63], off nt
	global_store_dwordx4 v[68:69], v[56:59], off offset:16 nt
	s_cbranch_vccnz .LBB0_325
	v_cvt_pk_bf16_f32 v72, v60, v61
	v_cvt_pk_bf16_f32 v73, v62, v63
	v_cvt_pk_bf16_f32 v74, v56, v57
	v_cvt_pk_bf16_f32 v75, v58, v59
	v_lshl_add_u64 v[76:77], v[66:67], 1, s[70:71]
	global_store_dwordx4 v[76:77], v[72:75], off
.LBB0_325:
	global_load_dwordx4 v[72:75], v[70:71], off offset:512
	s_nop 0
	global_load_dwordx4 v[76:79], v[70:71], off offset:528
	s_and_b64 vcc, exec, s[12:13]
	s_waitcnt vmcnt(1)
	v_fma_f32 v54, v54, 0.5, v74
	v_fma_f32 v55, v55, 0.5, v75
	v_fma_f32 v52, v52, 0.5, v72
	v_fma_f32 v53, v53, 0.5, v73
	s_waitcnt vmcnt(0)
	v_fma_f32 v50, v50, 0.5, v78
	v_fma_f32 v51, v51, 0.5, v79
	v_fma_f32 v48, v48, 0.5, v76
	v_fma_f32 v49, v49, 0.5, v77
	global_store_dwordx4 v[68:69], v[52:55], off offset:512 nt
	global_store_dwordx4 v[68:69], v[48:51], off offset:528 nt
	s_cbranch_vccnz .LBB0_327
	v_lshlrev_b64 v[70:71], 1, v[66:67]
	v_or_b32_e32 v70, 0x100, v70
	v_cvt_pk_bf16_f32 v66, v52, v53
	v_cvt_pk_bf16_f32 v67, v54, v55
	v_cvt_pk_bf16_f32 v68, v48, v49
	v_cvt_pk_bf16_f32 v69, v50, v51
	v_lshl_add_u64 v[70:71], s[70:71], 0, v[70:71]
	global_store_dwordx4 v[70:71], v[66:69], off

; __device__ __forceinline__ unsigned cvt_pk_bf16(float lo, float hi) { f32x2_t v = {lo, hi}; bf16x2_t b = __builtin_convertvector(v, bf16x2_t); return __builtin_bit_cast(unsigned, b); }
;     __device__ __forceinline__ void operator()(const Acc& acc, const Unit& u, int wr, int wc, int fr, int fq) const {
;         const int row0 = u.pm * BM + wr * 64 + fr, col0 = u.pn * BM + wc * 32 + 8 * fq;
; #pragma unroll
;         for (int ai = 0; ai < 2; ++ai)
; #pragma unroll
;             for (int m = 0; m < 4; ++m) {
;                 const int row = row0 + ai * HALF + m * 16; float sq = 0.f;
; #pragma unroll
;                 for (int bj = 0; bj < 2; ++bj) {
;                     const size_t off = (size_t)row * DM + col0 + bj * HALF;
;                     const f32x4 b0 = *(const f32x4*)(base + off), b1 = *(const f32x4*)(base + off + 4);
;                     const f32x4 x0 = b0 + acc[ai][bj][m][0] * alpha, x1 = b1 + acc[ai][bj][m][1] * alpha;
;                     __builtin_nontemporal_store(x0, (f32x4*)(out + off)); __builtin_nontemporal_store(x1, (f32x4*)(out + off + 4));
;                     sq += (x0[0] * x0[0] + x0[1] * x0[1]) + (x0[2] * x0[2] + x0[3] * x0[3]) + (x1[0] * x1[0] + x1[1] * x1[1]) + (x1[2] * x1[2] + x1[3] * x1[3]);
;                     if (xb) { u32x4 w; w.x = cvt_pk_bf16(x0[0], x0[1]); w.y = cvt_pk_bf16(x0[2], x0[3]); w.z = cvt_pk_bf16(x1[0], x1[1]); w.w = cvt_pk_bf16(x1[2], x1[3]); *(u32x4*)(xb + off) = w; }
;                 }
.LBB0_329:
	s_or_b64 exec, exec, s[6:7]
	v_add_u32_e32 v48, 0x90, v146
	s_waitcnt lgkmcnt(0)
	v_ashrrev_i32_e32 v49, 31, v48
	v_lshlrev_b64 v[50:51], 10, v[48:49]
	v_lshl_add_u64 v[50:51], v[50:51], 0, v[144:145]
	v_lshlrev_b64 v[52:53], 2, v[50:51]
	v_lshl_add_u64 v[54:55], s[52:53], 0, v[52:53]
	global_load_dwordx4 v[56:59], v[54:55], off
	global_load_dwordx4 v[60:63], v[54:55], off offset:16
	s_and_b64 vcc, exec, s[12:13]
	v_lshl_add_u64 v[52:53], s[90:91], 0, v[52:53]
	s_waitcnt vmcnt(1)
	v_fma_f32 v46, v46, 0.5, v58
	v_fma_f32 v47, v47, 0.5, v59
	v_fma_f32 v44, v44, 0.5, v56
	v_fma_f32 v45, v45, 0.5, v57
	s_waitcnt vmcnt(0)
	v_fma_f32 v42, v42, 0.5, v62
	v_fma_f32 v43, v43, 0.5, v63
	v_fma_f32 v40, v40, 0.5, v60
	v_fma_f32 v41, v41, 0.5, v61
	global_store_dwordx4 v[52:53], v[44:47], off nt
	global_store_dwordx4 v[52:53], v[40:43], off offset:16 nt
	s_cbranch_vccnz .LBB0_331
	v_cvt_pk_bf16_f32 v56, v44, v45
	v_cvt_pk_bf16_f32 v57, v46, v47
	v_cvt_pk_bf16_f32 v58, v40, v41
	v_cvt_pk_bf16_f32 v59, v42, v43
	v_lshl_add_u64 v[60:61], v[50:51], 1, s[70:71]
	global_store_dwordx4 v[60:61], v[56:59], off
.LBB0_331:
	global_load_dwordx4 v[56:59], v[54:55], off offset:512
	s_nop 0
	global_load_dwordx4 v[60:63], v[54:55], off offset:528
	s_and_b64 vcc, exec, s[12:13]
	s_waitcnt vmcnt(1)
	v_fma_f32 v38, v38, 0.5, v58
	v_fma_f32 v39, v39, 0.5, v59
	v_fma_f32 v36, v36, 0.5, v56
	v_fma_f32 v37, v37, 0.5, v57
	s_waitcnt vmcnt(0)
	v_fma_f32 v34, v34, 0.5, v62
	v_fma_f32 v35, v35, 0.5, v63
	v_fma_f32 v32, v32, 0.5, v60
	v_fma_f32 v33, v33, 0.5, v61
	global_store_dwordx4 v[52:53], v[36:39], off offset:512 nt
	global_store_dwordx4 v[52:53], v[32:35], off offset:528 nt
	s_cbranch_vccnz .LBB0_333
	v_lshlrev_b64 v[54:55], 1, v[50:51]
	v_or_b32_e32 v54, 0x100, v54
	v_cvt_pk_bf16_f32 v50, v36, v37
	v_cvt_pk_bf16_f32 v51, v38, v39
	v_cvt_pk_bf16_f32 v52, v32, v33
	v_cvt_pk_bf16_f32 v53, v34, v35
	v_lshl_add_u64 v[54:55], s[70:71], 0, v[54:55]
	global_store_dwordx4 v[54:55], v[50:53], off

; __device__ __forceinline__ unsigned cvt_pk_bf16(float lo, float hi) { f32x2_t v = {lo, hi}; bf16x2_t b = __builtin_convertvector(v, bf16x2_t); return __builtin_bit_cast(unsigned, b); }
;     __device__ __forceinline__ void operator()(const Acc& acc, const Unit& u, int wr, int wc, int fr, int fq) const {
;     ...
;                 const int row = row0 + ai * HALF + m * 16; float sq = 0.f;
; #pragma unroll
;                 for (int bj = 0; bj < 2; ++bj) {
;                     const size_t off = (size_t)row * DM + col0 + bj * HALF;
;                     const f32x4 b0 = *(const f32x4*)(base + off), b1 = *(const f32x4*)(base + off + 4);
;                     const f32x4 x0 = b0 + acc[ai][bj][m][0] * alpha, x1 = b1 + acc[ai][bj][m][1] * alpha;
;                     __builtin_nontemporal_store(x0, (f32x4*)(out + off)); __builtin_nontemporal_store(x1, (f32x4*)(out + off + 4));
;                     sq += (x0[0] * x0[0] + x0[1] * x0[1]) + (x0[2] * x0[2] + x0[3] * x0[3]) + (x1[0] * x1[0] + x1[1] * x1[1]) + (x1[2] * x1[2] + x1[3] * x1[3]);
;                     if (xb) { u32x4 w; w.x = cvt_pk_bf16(x0[0], x0[1]); w.y = cvt_pk_bf16(x0[2], x0[3]); w.z = cvt_pk_bf16(x1[0], x1[1]); w.w = cvt_pk_bf16(x1[2], x1[3]); *(u32x4*)(xb + off) = w; }
;                 }
.LBB0_335:
	s_or_b64 exec, exec, s[6:7]
	v_add_u32_e32 v32, 0xa0, v146
	s_waitcnt lgkmcnt(0)
	v_ashrrev_i32_e32 v33, 31, v32
	v_lshlrev_b64 v[34:35], 10, v[32:33]
	v_lshl_add_u64 v[34:35], v[34:35], 0, v[144:145]
	v_lshlrev_b64 v[36:37], 2, v[34:35]
	v_lshl_add_u64 v[38:39], s[52:53], 0, v[36:37]
	global_load_dwordx4 v[40:43], v[38:39], off
	global_load_dwordx4 v[44:47], v[38:39], off offset:16
	s_and_b64 vcc, exec, s[12:13]
	v_lshl_add_u64 v[36:37], s[90:91], 0, v[36:37]
	s_waitcnt vmcnt(1)
	v_fma_f32 v30, v30, 0.5, v42
	v_fma_f32 v31, v31, 0.5, v43
	v_fma_f32 v28, v28, 0.5, v40
	v_fma_f32 v29, v29, 0.5, v41
	s_waitcnt vmcnt(0)
	v_fma_f32 v26, v26, 0.5, v46
	v_fma_f32 v27, v27, 0.5, v47
	v_fma_f32 v24, v24, 0.5, v44
	v_fma_f32 v25, v25, 0.5, v45
	global_store_dwordx4 v[36:37], v[28:31], off nt
	global_store_dwordx4 v[36:37], v[24:27], off offset:16 nt
	s_cbranch_vccnz .LBB0_337
	v_cvt_pk_bf16_f32 v40, v28, v29
	v_cvt_pk_bf16_f32 v41, v30, v31
	v_cvt_pk_bf16_f32 v42, v24, v25
	v_cvt_pk_bf16_f32 v43, v26, v27
	v_lshl_add_u64 v[44:45], v[34:35], 1, s[70:71]
	global_store_dwordx4 v[44:45], v[40:43], off
.LBB0_337:
	global_load_dwordx4 v[40:43], v[38:39], off offset:512
	s_nop 0
	global_load_dwordx4 v[44:47], v[38:39], off offset:528
	s_and_b64 vcc, exec, s[12:13]
	s_waitcnt vmcnt(1)
	v_fma_f32 v22, v22, 0.5, v42
	v_fma_f32 v23, v23, 0.5, v43
	v_fma_f32 v20, v20, 0.5, v40
	v_fma_f32 v21, v21, 0.5, v41
	s_waitcnt vmcnt(0)
	v_fma_f32 v18, v18, 0.5, v46
	v_fma_f32 v19, v19, 0.5, v47
	v_fma_f32 v16, v16, 0.5, v44
	v_fma_f32 v17, v17, 0.5, v45
	global_store_dwordx4 v[36:37], v[20:23], off offset:512 nt
	global_store_dwordx4 v[36:37], v[16:19], off offset:528 nt
	s_cbranch_vccnz .LBB0_339
	v_lshlrev_b64 v[38:39], 1, v[34:35]
	v_or_b32_e32 v38, 0x100, v38
	v_cvt_pk_bf16_f32 v34, v20, v21
	v_cvt_pk_bf16_f32 v35, v22, v23
	v_cvt_pk_bf16_f32 v36, v16, v17
	v_cvt_pk_bf16_f32 v37, v18, v19
	v_lshl_add_u64 v[38:39], s[70:71], 0, v[38:39]
	global_store_dwordx4 v[38:39], v[34:37], off

; __device__ __forceinline__ unsigned cvt_pk_bf16(float lo, float hi) { f32x2_t v = {lo, hi}; bf16x2_t b = __builtin_convertvector(v, bf16x2_t); return __builtin_bit_cast(unsigned, b); }
;     __device__ __forceinline__ void operator()(const Acc& acc, const Unit& u, int wr, int wc, int fr, int fq) const {
;     ...
;                 const int row = row0 + ai * HALF + m * 16; float sq = 0.f;
; #pragma unroll
;                 for (int bj = 0; bj < 2; ++bj) {
;                     const size_t off = (size_t)row * DM + col0 + bj * HALF;
;                     const f32x4 b0 = *(const f32x4*)(base + off), b1 = *(const f32x4*)(base + off + 4);
;                     const f32x4 x0 = b0 + acc[ai][bj][m][0] * alpha, x1 = b1 + acc[ai][bj][m][1] * alpha;
;                     __builtin_nontemporal_store(x0, (f32x4*)(out + off)); __builtin_nontemporal_store(x1, (f32x4*)(out + off + 4));
;                     sq += (x0[0] * x0[0] + x0[1] * x0[1]) + (x0[2] * x0[2] + x0[3] * x0[3]) + (x1[0] * x1[0] + x1[1] * x1[1]) + (x1[2] * x1[2] + x1[3] * x1[3]);
;                     if (xb) { u32x4 w; w.x = cvt_pk_bf16(x0[0], x0[1]); w.y = cvt_pk_bf16(x0[2], x0[3]); w.z = cvt_pk_bf16(x1[0], x1[1]); w.w = cvt_pk_bf16(x1[2], x1[3]); *(u32x4*)(xb + off) = w; }
;                 }
.LBB0_341:
	s_or_b64 exec, exec, s[6:7]
	v_add_u32_e32 v16, 0xb0, v146
	s_waitcnt lgkmcnt(0)
	v_ashrrev_i32_e32 v17, 31, v16
	v_lshlrev_b64 v[18:19], 10, v[16:17]
	v_lshl_add_u64 v[18:19], v[18:19], 0, v[144:145]
	v_lshlrev_b64 v[20:21], 2, v[18:19]
	v_lshl_add_u64 v[22:23], s[52:53], 0, v[20:21]
	global_load_dwordx4 v[24:27], v[22:23], off
	global_load_dwordx4 v[28:31], v[22:23], off offset:16
	s_and_b64 vcc, exec, s[12:13]
	v_lshl_add_u64 v[20:21], s[90:91], 0, v[20:21]
	s_waitcnt vmcnt(1)
	v_fma_f32 v14, v14, 0.5, v26
	v_fma_f32 v15, v15, 0.5, v27
	v_fma_f32 v12, v12, 0.5, v24
	v_fma_f32 v13, v13, 0.5, v25
	s_waitcnt vmcnt(0)
	v_fma_f32 v10, v10, 0.5, v30
	v_fma_f32 v11, v11, 0.5, v31
	v_fma_f32 v8, v8, 0.5, v28
	v_fma_f32 v9, v9, 0.5, v29
	global_store_dwordx4 v[20:21], v[12:15], off nt
	global_store_dwordx4 v[20:21], v[8:11], off offset:16 nt
	s_cbranch_vccnz .LBB0_343
	v_cvt_pk_bf16_f32 v24, v12, v13
	v_cvt_pk_bf16_f32 v25, v14, v15
	v_cvt_pk_bf16_f32 v26, v8, v9
	v_cvt_pk_bf16_f32 v27, v10, v11
	v_lshl_add_u64 v[28:29], v[18:19], 1, s[70:71]
	global_store_dwordx4 v[28:29], v[24:27], off
.LBB0_343:
	global_load_dwordx4 v[24:27], v[22:23], off offset:512
	s_nop 0
	global_load_dwordx4 v[28:31], v[22:23], off offset:528
	s_and_b64 vcc, exec, s[12:13]
	s_waitcnt vmcnt(1)
	v_fma_f32 v6, v6, 0.5, v26
	v_fma_f32 v7, v7, 0.5, v27
	v_fma_f32 v4, v4, 0.5, v24
	v_fma_f32 v5, v5, 0.5, v25
	s_waitcnt vmcnt(0)
	v_fma_f32 v2, v2, 0.5, v30
	v_fma_f32 v3, v3, 0.5, v31
	v_fma_f32 v0, v0, 0.5, v28
	v_fma_f32 v1, v1, 0.5, v29
	global_store_dwordx4 v[20:21], v[4:7], off offset:512 nt
	global_store_dwordx4 v[20:21], v[0:3], off offset:528 nt
	s_cbranch_vccnz .LBB0_345
	v_lshlrev_b64 v[22:23], 1, v[18:19]
	v_or_b32_e32 v22, 0x100, v22
	v_cvt_pk_bf16_f32 v18, v4, v5
	v_cvt_pk_bf16_f32 v19, v6, v7
	v_cvt_pk_bf16_f32 v20, v0, v1
	v_cvt_pk_bf16_f32 v21, v2, v3
	v_lshl_add_u64 v[22:23], s[70:71], 0, v[22:23]
	global_store_dwordx4 v[22:23], v[18:21], off

; __device__ __forceinline__ unsigned cvt_pk_bf16(float lo, float hi) { f32x2_t v = {lo, hi}; bf16x2_t b = __builtin_convertvector(v, bf16x2_t); return __builtin_bit_cast(unsigned, b); }
; __device__ __forceinline__ float rstd_of(const float* ss, int row) { return __builtin_amdgcn_rsqf(ss[row] * (1.0f / 1024.0f) + RMS_EPS); }
;     __device__ __forceinline__ void operator()(const Acc& acc, const Unit& u, int wr, int wc, int fr, int fq) const {
;         const int row0 = u.pm * BM + wr * 64 + fr, col0 = u.pn * BM + wc * 32 + 8 * fq;
;         float rs[2][8];
; #pragma unroll
;         for (int bj = 0; bj < 2; ++bj)
; #pragma unroll
;             for (int e = 0; e < 8; ++e) rs[bj][e] = rstd_of(ss, col0 + bj * HALF + e);
; #pragma unroll
;         for (int ai = 0; ai < 2; ++ai)
; #pragma unroll
;             for (int m = 0; m < 4; ++m) {
;                 const int row = row0 + ai * HALF + m * 16;
; #pragma unroll
;                 for (int bj = 0; bj < 2; ++bj) {
;                     float o[8];
; #pragma unroll
;                     for (int n = 0; n < 2; ++n)
; #pragma unroll
;                         for (int e = 0; e < 4; ++e) o[4 * n + e] = acc[ai][bj][m][n][e] * rs[bj][4 * n + e];
;                     u32x4 w; w.x = cvt_pk_bf16(o[0], o[1]); w.y = cvt_pk_bf16(o[2], o[3]); w.z = cvt_pk_bf16(o[4], o[5]); w.w = cvt_pk_bf16(o[6], o[7]);
;                     const int tok = col0 + bj * HALF, b = tok >> 11, t = tok & (SEQ - 1);
;                     bf16_t* dst;
;                     if (row < 1024) dst = VT + ((size_t)(((b * 8 + (row >> 7)) * 32 + (t >> 6)) * 128 + (row & 127))) * 64 + (t & 63);
;                     else { const int f = row - 1024; dst = VTS + ((size_t)(((b * 4 + (f >> 6)) * 32 + (t >> 6)) * 64 + (f & 63))) * 64 + (t & 63); }
;                     *(u32x4*)dst = w;
.LBB0_723:
	s_lshl_b32 s35, s58, 8
	v_or_b32_e32 v166, s35, v174
	v_ashrrev_i32_e32 v167, 31, v166
	v_lshl_add_u64 v[132:133], v[166:167], 2, s[44:45]
	global_load_dwordx4 v[136:139], v[132:133], off offset:16
	global_load_dwordx4 v[140:143], v[132:133], off
	global_load_dwordx4 v[128:131], v[132:133], off offset:528
	s_nop 0
	global_load_dwordx4 v[132:135], v[132:133], off offset:512
	s_lshl_b32 s38, s60, 8
	s_lshl_b32 s6, s58, 10
	s_add_i32 s38, s38, s19
	s_and_b32 s15, s6, 0xffffe000
	s_addk_i32 s15, 0x8000
	s_lshl_b32 s36, s38, 5
	v_or_b32_e32 v167, s38, v155
	s_add_i32 s36, s36, s15
	v_cmp_lt_i32_e32 vcc, s29, v167
	v_or_b32_e32 v190, s36, v155
	s_and_saveexec_b64 s[6:7], vcc
	s_xor_b64 s[6:7], exec, s[6:7]
	v_and_or_b32 v168, v166, s30, v190
	s_or_saveexec_b64 s[60:61], s[6:7]
	v_bitop3_b32 v189, s35, v186, v174 bitop3:0xc8
	s_and_b32 s35, s58, 0xffff8
	s_lshr_b32 s6, s38, 7
	s_add_i32 s6, s6, s35
	s_lshl_b32 s37, s6, 12
	v_bitop3_b32 v191, s38, v187, v155 bitop3:0xc8
	v_or_b32_e32 v192, s37, v191
	v_mov_b64_e32 v[170:171], 0x9600000
	v_lshlrev_b32_e32 v188, 1, v189
	s_xor_b64 exec, exec, s[60:61]
	v_and_or_b32 v168, v188, s31, v192
	v_mov_b64_e32 v[170:171], 0x5600000
	s_or_b64 exec, exec, s[60:61]
	s_waitcnt vmcnt(0)
	v_fmamk_f32 v140, v140, 0x3a800000, v185
	v_fmamk_f32 v141, v141, 0x3a800000, v185
	v_fmamk_f32 v142, v142, 0x3a800000, v185
	v_fmamk_f32 v143, v143, 0x3a800000, v185
	v_rsq_f32_e32 v140, v140
	v_rsq_f32_e32 v141, v141
	v_rsq_f32_e32 v142, v142
	v_rsq_f32_e32 v143, v143
	v_fmamk_f32 v136, v136, 0x3a800000, v185
	v_fmamk_f32 v137, v137, 0x3a800000, v185
	v_rsq_f32_e32 v136, v136
	v_rsq_f32_e32 v137, v137
	v_fmamk_f32 v138, v138, 0x3a800000, v185
	v_fmamk_f32 v139, v139, 0x3a800000, v185
	v_rsq_f32_e32 v138, v138
	v_rsq_f32_e32 v139, v139
	v_mul_f32_e32 v124, v124, v140
	v_mul_f32_e32 v125, v125, v141
	v_mul_f32_e32 v126, v126, v142
	v_mul_f32_e32 v127, v127, v143
	v_ashrrev_i32_e32 v169, 31, v168
	v_mul_f32_e32 v194, v120, v136
	v_mul_f32_e32 v195, v121, v137
	v_cvt_pk_bf16_f32 v120, v124, v125
	v_cvt_pk_bf16_f32 v121, v126, v127
	v_lshl_add_u64 v[124:125], s[48:49], 0, v[170:171]
	v_lshlrev_b64 v[126:127], 7, v[168:169]
	v_mul_f32_e32 v196, v122, v138
	v_mul_f32_e32 v197, v123, v139
	v_lshl_add_u64 v[124:125], v[124:125], 0, v[126:127]
	v_lshlrev_b32_e32 v152, 1, v154
	v_cvt_pk_bf16_f32 v122, v194, v195
	v_cvt_pk_bf16_f32 v123, v196, v197
	v_lshl_add_u64 v[124:125], v[124:125], 0, v[152:153]
	v_or_b32_e32 v189, 0x80, v189
	global_store_dwordx4 v[124:125], v[120:123], off
	s_and_saveexec_b64 s[6:7], vcc
	s_xor_b64 s[6:7], exec, s[6:7]
	v_and_or_b32 v168, v189, s33, v190
	s_or_saveexec_b64 s[6:7], s[6:7]
	v_mov_b64_e32 v[170:171], 0x9600000
	v_lshlrev_b32_e32 v190, 1, v189
	s_xor_b64 exec, exec, s[6:7]
	v_and_or_b32 v168, v190, s34, v192
	v_mov_b64_e32 v[170:171], 0x5600000
	s_or_b64 exec, exec, s[6:7]
	v_fmamk_f32 v120, v132, 0x3a800000, v185
	v_rsq_f32_e32 v122, v120
	v_fmamk_f32 v120, v133, 0x3a800000, v185
	v_rsq_f32_e32 v123, v120
	v_fmamk_f32 v120, v134, 0x3a800000, v185
	v_fmamk_f32 v121, v135, 0x3a800000, v185
	v_fmamk_f32 v124, v128, 0x3a800000, v185
	v_rsq_f32_e32 v120, v120
	v_rsq_f32_e32 v121, v121
	v_rsq_f32_e32 v126, v124
	v_fmamk_f32 v124, v129, 0x3a800000, v185
	v_rsq_f32_e32 v127, v124
	v_fmamk_f32 v124, v130, 0x3a800000, v185
	v_fmamk_f32 v125, v131, 0x3a800000, v185
	v_rsq_f32_e32 v124, v124
	v_rsq_f32_e32 v125, v125
	v_mul_f32_e32 v116, v116, v122
	v_mul_f32_e32 v117, v117, v123
	v_mul_f32_e32 v118, v118, v120
	v_mul_f32_e32 v119, v119, v121
	v_ashrrev_i32_e32 v169, 31, v168
	v_mul_f32_e32 v128, v112, v126
	v_mul_f32_e32 v129, v113, v127
	v_cvt_pk_bf16_f32 v112, v116, v117
	v_cvt_pk_bf16_f32 v113, v118, v119
	v_lshl_add_u64 v[116:117], s[48:49], 0, v[170:171]
	v_lshlrev_b64 v[118:119], 7, v[168:169]
	v_mul_f32_e32 v130, v114, v124
	v_mul_f32_e32 v131, v115, v125
	v_lshl_add_u64 v[116:117], v[116:117], 0, v[118:119]
	v_cvt_pk_bf16_f32 v114, v128, v129
	v_cvt_pk_bf16_f32 v115, v130, v131
	v_lshl_add_u64 v[116:117], v[116:117], 0, v[152:153]
	global_store_dwordx4 v[116:117], v[112:115], off
	v_or_b32_e32 v116, s36, v178
	s_nop 0
	v_or_b32_e32 v112, 16, v167
	v_cmp_lt_i32_e32 vcc, s29, v112
	s_and_saveexec_b64 s[6:7], vcc
	s_xor_b64 s[6:7], exec, s[6:7]
	v_and_or_b32 v112, v166, s30, v116
	s_or_saveexec_b64 s[6:7], s[6:7]
	s_movk_i32 s38, 0x5f
	v_bitop3_b32 v113, v167, s38, 16 bitop3:0xc8
	v_or_b32_e32 v117, s37, v113
	v_mov_b64_e32 v[114:115], 0x9600000
	s_xor_b64 exec, exec, s[6:7]
	v_and_or_b32 v112, v188, s31, v117
	v_mov_b64_e32 v[114:115], 0x5600000
	s_or_b64 exec, exec, s[6:7]
	v_mul_f32_e32 v108, v108, v140
	v_mul_f32_e32 v109, v109, v141
	v_mul_f32_e32 v110, v110, v142
	v_mul_f32_e32 v111, v111, v143
	v_ashrrev_i32_e32 v113, 31, v112
	v_mul_f32_e32 v118, v104, v136
	v_mul_f32_e32 v119, v105, v137
	v_cvt_pk_bf16_f32 v104, v108, v109
	v_cvt_pk_bf16_f32 v105, v110, v111
	v_lshl_add_u64 v[108:109], s[48:49], 0, v[114:115]
	v_lshlrev_b64 v[110:111], 7, v[112:113]
	v_mul_f32_e32 v128, v106, v138
	v_mul_f32_e32 v129, v107, v139
	v_lshl_add_u64 v[108:109], v[108:109], 0, v[110:111]
	v_cvt_pk_bf16_f32 v106, v118, v119
	v_cvt_pk_bf16_f32 v107, v128, v129
	v_lshl_add_u64 v[108:109], v[108:109], 0, v[152:153]
	global_store_dwordx4 v[108:109], v[104:107], off
	s_and_saveexec_b64 s[6:7], vcc
	s_xor_b64 s[6:7], exec, s[6:7]
	v_and_or_b32 v104, v189, s33, v116
	s_or_saveexec_b64 s[6:7], s[6:7]
	v_mov_b64_e32 v[106:107], 0x9600000
	s_xor_b64 exec, exec, s[6:7]
	v_and_or_b32 v104, v190, s34, v117
	v_mov_b64_e32 v[106:107], 0x5600000
	s_or_b64 exec, exec, s[6:7]
	v_mul_f32_e32 v100, v100, v122
; __device__ __forceinline__ unsigned cvt_pk_bf16(float lo, float hi) { f32x2_t v = {lo, hi}; bf16x2_t b = __builtin_convertvector(v, bf16x2_t); return __builtin_bit_cast(unsigned, b); }
;     __device__ __forceinline__ void operator()(const Acc& acc, const Unit& u, int wr, int wc, int fr, int fq) const {
;     ...
;                 const int row = row0 + ai * HALF + m * 16;
; #pragma unroll
;                 for (int bj = 0; bj < 2; ++bj) {
;                     float o[8];
; #pragma unroll
;                     for (int n = 0; n < 2; ++n)
; #pragma unroll
;                         for (int e = 0; e < 4; ++e) o[4 * n + e] = acc[ai][bj][m][n][e] * rs[bj][4 * n + e];
;                     u32x4 w; w.x = cvt_pk_bf16(o[0], o[1]); w.y = cvt_pk_bf16(o[2], o[3]); w.z = cvt_pk_bf16(o[4], o[5]); w.w = cvt_pk_bf16(o[6], o[7]);
;                     const int tok = col0 + bj * HALF, b = tok >> 11, t = tok & (SEQ - 1);
;                     bf16_t* dst;
;                     if (row < 1024) dst = VT + ((size_t)(((b * 8 + (row >> 7)) * 32 + (t >> 6)) * 128 + (row & 127))) * 64 + (t & 63);
;                     else { const int f = row - 1024; dst = VTS + ((size_t)(((b * 4 + (f >> 6)) * 32 + (t >> 6)) * 64 + (f & 63))) * 64 + (t & 63); }
;                     *(u32x4*)dst = w;
	v_mul_f32_e32 v101, v101, v123
	v_mul_f32_e32 v102, v102, v120
	v_mul_f32_e32 v103, v103, v121
	v_ashrrev_i32_e32 v105, 31, v104
	v_mul_f32_e32 v108, v96, v126
	v_mul_f32_e32 v109, v97, v127
	v_cvt_pk_bf16_f32 v96, v100, v101
	v_cvt_pk_bf16_f32 v97, v102, v103
	v_lshl_add_u64 v[100:101], s[48:49], 0, v[106:107]
	v_lshlrev_b64 v[102:103], 7, v[104:105]
	v_mul_f32_e32 v110, v98, v124
	v_mul_f32_e32 v111, v99, v125
	v_lshl_add_u64 v[100:101], v[100:101], 0, v[102:103]
	v_cvt_pk_bf16_f32 v98, v108, v109
	v_cvt_pk_bf16_f32 v99, v110, v111
	v_lshl_add_u64 v[100:101], v[100:101], 0, v[152:153]
	global_store_dwordx4 v[100:101], v[96:99], off
	v_or_b32_e32 v100, s36, v180
	s_nop 0
	v_or_b32_e32 v96, 32, v167
	v_cmp_lt_i32_e32 vcc, s29, v96
	s_and_saveexec_b64 s[6:7], vcc
	s_xor_b64 s[6:7], exec, s[6:7]
	v_and_or_b32 v96, v166, s30, v100
	s_or_saveexec_b64 s[6:7], s[6:7]
	s_movk_i32 s38, 0x6f
	v_bitop3_b32 v97, v167, s38, 32 bitop3:0xc8
	v_or_b32_e32 v101, s37, v97
	v_mov_b64_e32 v[98:99], 0x9600000
	s_xor_b64 exec, exec, s[6:7]
	v_and_or_b32 v96, v188, s31, v101
	v_mov_b64_e32 v[98:99], 0x5600000
	s_or_b64 exec, exec, s[6:7]
	v_mul_f32_e32 v92, v92, v140
	v_mul_f32_e32 v93, v93, v141
	v_mul_f32_e32 v94, v94, v142
	v_mul_f32_e32 v95, v95, v143
	v_ashrrev_i32_e32 v97, 31, v96
	v_mul_f32_e32 v102, v88, v136
	v_mul_f32_e32 v103, v89, v137
	v_cvt_pk_bf16_f32 v88, v92, v93
	v_cvt_pk_bf16_f32 v89, v94, v95
	v_lshl_add_u64 v[92:93], s[48:49], 0, v[98:99]
	v_lshlrev_b64 v[94:95], 7, v[96:97]
	v_mul_f32_e32 v104, v90, v138
	v_mul_f32_e32 v105, v91, v139
	v_lshl_add_u64 v[92:93], v[92:93], 0, v[94:95]
	v_cvt_pk_bf16_f32 v90, v102, v103
	v_cvt_pk_bf16_f32 v91, v104, v105
	v_lshl_add_u64 v[92:93], v[92:93], 0, v[152:153]
	global_store_dwordx4 v[92:93], v[88:91], off
	s_and_saveexec_b64 s[6:7], vcc
	s_xor_b64 s[6:7], exec, s[6:7]
	v_and_or_b32 v88, v189, s33, v100
	s_or_saveexec_b64 s[6:7], s[6:7]
	v_mov_b64_e32 v[90:91], 0x9600000
	s_xor_b64 exec, exec, s[6:7]
	v_and_or_b32 v88, v190, s34, v101
	v_mov_b64_e32 v[90:91], 0x5600000
	s_or_b64 exec, exec, s[6:7]
	v_mul_f32_e32 v84, v84, v122
	v_mul_f32_e32 v85, v85, v123
	v_mul_f32_e32 v86, v86, v120
	v_mul_f32_e32 v87, v87, v121
	v_ashrrev_i32_e32 v89, 31, v88
	v_mul_f32_e32 v92, v80, v126
	v_mul_f32_e32 v93, v81, v127
	v_cvt_pk_bf16_f32 v80, v84, v85
	v_cvt_pk_bf16_f32 v81, v86, v87
	v_lshl_add_u64 v[84:85], s[48:49], 0, v[90:91]
	v_lshlrev_b64 v[86:87], 7, v[88:89]
	v_mul_f32_e32 v94, v82, v124
	v_mul_f32_e32 v95, v83, v125
	v_lshl_add_u64 v[84:85], v[84:85], 0, v[86:87]
	v_cvt_pk_bf16_f32 v82, v92, v93
	v_cvt_pk_bf16_f32 v83, v94, v95
	v_lshl_add_u64 v[84:85], v[84:85], 0, v[152:153]
	global_store_dwordx4 v[84:85], v[80:83], off
	v_or_b32_e32 v84, s36, v181
	s_nop 0
	v_or_b32_e32 v80, 48, v167
	v_cmp_lt_i32_e32 vcc, s29, v80
	s_and_saveexec_b64 s[6:7], vcc
	s_xor_b64 s[6:7], exec, s[6:7]
	v_and_or_b32 v80, v166, s30, v84
	s_or_saveexec_b64 s[6:7], s[6:7]
	s_movk_i32 s36, 0x7f
	v_bitop3_b32 v81, v167, s36, 48 bitop3:0xc8
	v_or_b32_e32 v85, s37, v81
	v_mov_b64_e32 v[82:83], 0x9600000
	s_xor_b64 exec, exec, s[6:7]
	v_and_or_b32 v80, v188, s31, v85
	v_mov_b64_e32 v[82:83], 0x5600000
	s_or_b64 exec, exec, s[6:7]
	v_mul_f32_e32 v76, v76, v140
	v_mul_f32_e32 v77, v77, v141
	v_mul_f32_e32 v78, v78, v142
	v_mul_f32_e32 v79, v79, v143
	v_ashrrev_i32_e32 v81, 31, v80
	v_mul_f32_e32 v86, v72, v136
	v_mul_f32_e32 v87, v73, v137
	v_cvt_pk_bf16_f32 v72, v76, v77
	v_cvt_pk_bf16_f32 v73, v78, v79
	v_lshl_add_u64 v[76:77], s[48:49], 0, v[82:83]
	v_lshlrev_b64 v[78:79], 7, v[80:81]
	v_mul_f32_e32 v88, v74, v138
	v_mul_f32_e32 v89, v75, v139
	v_lshl_add_u64 v[76:77], v[76:77], 0, v[78:79]
	v_cvt_pk_bf16_f32 v74, v86, v87
	v_cvt_pk_bf16_f32 v75, v88, v89
	v_lshl_add_u64 v[76:77], v[76:77], 0, v[152:153]
	global_store_dwordx4 v[76:77], v[72:75], off
	s_and_saveexec_b64 s[6:7], vcc
	s_xor_b64 s[6:7], exec, s[6:7]
	v_and_or_b32 v72, v189, s33, v84
	s_or_saveexec_b64 s[6:7], s[6:7]
	v_mov_b64_e32 v[74:75], 0x9600000
	s_xor_b64 exec, exec, s[6:7]
	v_and_or_b32 v72, v190, s34, v85
	v_mov_b64_e32 v[74:75], 0x5600000
	s_or_b64 exec, exec, s[6:7]
	v_mul_f32_e32 v68, v68, v122
	v_mul_f32_e32 v69, v69, v123
	v_mul_f32_e32 v70, v70, v120
	v_mul_f32_e32 v71, v71, v121
	v_ashrrev_i32_e32 v73, 31, v72
	v_mul_f32_e32 v76, v64, v126
	v_mul_f32_e32 v77, v65, v127
	v_cvt_pk_bf16_f32 v64, v68, v69
	v_cvt_pk_bf16_f32 v65, v70, v71
	v_lshl_add_u64 v[68:69], s[48:49], 0, v[74:75]
	v_lshlrev_b64 v[70:71], 7, v[72:73]
	v_mul_f32_e32 v78, v66, v124
	v_mul_f32_e32 v79, v67, v125
	v_lshl_add_u64 v[68:69], v[68:69], 0, v[70:71]
	v_cvt_pk_bf16_f32 v66, v76, v77
	v_cvt_pk_bf16_f32 v67, v78, v79
	v_lshl_add_u64 v[68:69], v[68:69], 0, v[152:153]
	global_store_dwordx4 v[68:69], v[64:67], off
	s_movk_i32 s6, 0x37f
	v_cmp_lt_i32_e32 vcc, s6, v167
	v_add_u32_e32 v65, 0x80, v167
	v_lshlrev_b32_e32 v64, 5, v65
	v_and_b32_e32 v64, 0xfffff800, v64
	v_add_u32_e32 v68, s15, v64
	v_or_b32_e32 v70, v68, v155
	s_and_saveexec_b64 s[6:7], vcc
	s_xor_b64 s[6:7], exec, s[6:7]
	v_and_or_b32 v64, v166, s30, v70
	s_or_saveexec_b64 s[6:7], s[6:7]
	v_lshrrev_b32_e32 v65, 7, v65
	v_add_u32_e32 v65, s35, v65
	v_lshl_or_b32 v69, v65, 12, v191
	v_mov_b64_e32 v[66:67], 0x9600000
	s_xor_b64 exec, exec, s[6:7]
	v_and_or_b32 v64, v188, s31, v69
	v_mov_b64_e32 v[66:67], 0x5600000
	s_or_b64 exec, exec, s[6:7]
	v_mul_f32_e32 v60, v60, v140
	v_mul_f32_e32 v61, v61, v141
	v_mul_f32_e32 v62, v62, v142
	v_mul_f32_e32 v63, v63, v143
	v_ashrrev_i32_e32 v65, 31, v64
	v_mul_f32_e32 v72, v56, v136
	v_mul_f32_e32 v73, v57, v137
	v_cvt_pk_bf16_f32 v56, v60, v61
	v_cvt_pk_bf16_f32 v57, v62, v63
; __device__ __forceinline__ unsigned cvt_pk_bf16(float lo, float hi) { f32x2_t v = {lo, hi}; bf16x2_t b = __builtin_convertvector(v, bf16x2_t); return __builtin_bit_cast(unsigned, b); }
;     __device__ __forceinline__ void operator()(const Acc& acc, const Unit& u, int wr, int wc, int fr, int fq) const {
;     ...
;                 const int row = row0 + ai * HALF + m * 16;
; #pragma unroll
;                 for (int bj = 0; bj < 2; ++bj) {
;                     float o[8];
; #pragma unroll
;                     for (int n = 0; n < 2; ++n)
; #pragma unroll
;                         for (int e = 0; e < 4; ++e) o[4 * n + e] = acc[ai][bj][m][n][e] * rs[bj][4 * n + e];
;                     u32x4 w; w.x = cvt_pk_bf16(o[0], o[1]); w.y = cvt_pk_bf16(o[2], o[3]); w.z = cvt_pk_bf16(o[4], o[5]); w.w = cvt_pk_bf16(o[6], o[7]);
;                     const int tok = col0 + bj * HALF, b = tok >> 11, t = tok & (SEQ - 1);
;                     bf16_t* dst;
;                     if (row < 1024) dst = VT + ((size_t)(((b * 8 + (row >> 7)) * 32 + (t >> 6)) * 128 + (row & 127))) * 64 + (t & 63);
;                     else { const int f = row - 1024; dst = VTS + ((size_t)(((b * 4 + (f >> 6)) * 32 + (t >> 6)) * 64 + (f & 63))) * 64 + (t & 63); }
;                     *(u32x4*)dst = w;
	v_lshl_add_u64 v[60:61], s[48:49], 0, v[66:67]
	v_lshlrev_b64 v[62:63], 7, v[64:65]
	v_mul_f32_e32 v74, v58, v138
	v_mul_f32_e32 v75, v59, v139
	v_lshl_add_u64 v[60:61], v[60:61], 0, v[62:63]
	v_cvt_pk_bf16_f32 v58, v72, v73
	v_cvt_pk_bf16_f32 v59, v74, v75
	v_lshl_add_u64 v[60:61], v[60:61], 0, v[152:153]
	global_store_dwordx4 v[60:61], v[56:59], off
	s_and_saveexec_b64 s[6:7], vcc
	s_xor_b64 s[6:7], exec, s[6:7]
	v_and_or_b32 v56, v189, s33, v70
	s_or_saveexec_b64 s[6:7], s[6:7]
	v_mov_b64_e32 v[58:59], 0x9600000
	s_xor_b64 exec, exec, s[6:7]
	v_and_or_b32 v56, v190, s34, v69
	v_mov_b64_e32 v[58:59], 0x5600000
	s_or_b64 exec, exec, s[6:7]
	v_mul_f32_e32 v52, v52, v122
	v_mul_f32_e32 v53, v53, v123
	v_mul_f32_e32 v54, v54, v120
	v_mul_f32_e32 v55, v55, v121
	v_ashrrev_i32_e32 v57, 31, v56
	v_mul_f32_e32 v60, v48, v126
	v_mul_f32_e32 v61, v49, v127
	v_cvt_pk_bf16_f32 v48, v52, v53
	v_cvt_pk_bf16_f32 v49, v54, v55
	v_lshl_add_u64 v[52:53], s[48:49], 0, v[58:59]
	v_lshlrev_b64 v[54:55], 7, v[56:57]
	v_mul_f32_e32 v62, v50, v124
	v_mul_f32_e32 v63, v51, v125
	v_lshl_add_u64 v[52:53], v[52:53], 0, v[54:55]
	v_cvt_pk_bf16_f32 v50, v60, v61
	v_cvt_pk_bf16_f32 v51, v62, v63
	v_lshl_add_u64 v[52:53], v[52:53], 0, v[152:153]
	s_movk_i32 s6, 0x36f
	global_store_dwordx4 v[52:53], v[48:51], off
	v_cmp_lt_i32_e32 vcc, s6, v167
	v_or_b32_e32 v52, v68, v178
	s_and_saveexec_b64 s[6:7], vcc
	s_xor_b64 s[6:7], exec, s[6:7]
	v_and_or_b32 v48, v166, s30, v52
	s_or_saveexec_b64 s[6:7], s[6:7]
	v_or_b32_e32 v53, 16, v69
	v_mov_b64_e32 v[50:51], 0x9600000
	s_xor_b64 exec, exec, s[6:7]
	v_and_or_b32 v48, v188, s31, v53
	v_mov_b64_e32 v[50:51], 0x5600000
	s_or_b64 exec, exec, s[6:7]
	v_mul_f32_e32 v44, v44, v140
	v_mul_f32_e32 v45, v45, v141
	v_mul_f32_e32 v46, v46, v142
	v_mul_f32_e32 v47, v47, v143
	v_ashrrev_i32_e32 v49, 31, v48
	v_mul_f32_e32 v54, v40, v136
	v_mul_f32_e32 v55, v41, v137
	v_cvt_pk_bf16_f32 v40, v44, v45
	v_cvt_pk_bf16_f32 v41, v46, v47
	v_lshl_add_u64 v[44:45], s[48:49], 0, v[50:51]
	v_lshlrev_b64 v[46:47], 7, v[48:49]
	v_mul_f32_e32 v56, v42, v138
	v_mul_f32_e32 v57, v43, v139
	v_lshl_add_u64 v[44:45], v[44:45], 0, v[46:47]
	v_cvt_pk_bf16_f32 v42, v54, v55
	v_cvt_pk_bf16_f32 v43, v56, v57
	v_lshl_add_u64 v[44:45], v[44:45], 0, v[152:153]
	global_store_dwordx4 v[44:45], v[40:43], off
	s_and_saveexec_b64 s[6:7], vcc
	s_xor_b64 s[6:7], exec, s[6:7]
	v_and_or_b32 v40, v189, s33, v52
	s_or_saveexec_b64 s[6:7], s[6:7]
	v_mov_b64_e32 v[42:43], 0x9600000
	s_xor_b64 exec, exec, s[6:7]
	v_and_or_b32 v40, v190, s34, v53
	v_mov_b64_e32 v[42:43], 0x5600000
	s_or_b64 exec, exec, s[6:7]
	v_mul_f32_e32 v36, v36, v122
	v_mul_f32_e32 v37, v37, v123
	v_mul_f32_e32 v38, v38, v120
	v_mul_f32_e32 v39, v39, v121
	v_ashrrev_i32_e32 v41, 31, v40
	v_mul_f32_e32 v44, v32, v126
	v_mul_f32_e32 v45, v33, v127
	v_cvt_pk_bf16_f32 v32, v36, v37
	v_cvt_pk_bf16_f32 v33, v38, v39
	v_lshl_add_u64 v[36:37], s[48:49], 0, v[42:43]
	v_lshlrev_b64 v[38:39], 7, v[40:41]
	v_mul_f32_e32 v46, v34, v124
	v_mul_f32_e32 v47, v35, v125
	v_lshl_add_u64 v[36:37], v[36:37], 0, v[38:39]
	v_cvt_pk_bf16_f32 v34, v44, v45
	v_cvt_pk_bf16_f32 v35, v46, v47
	v_lshl_add_u64 v[36:37], v[36:37], 0, v[152:153]
	s_movk_i32 s6, 0x35f
	global_store_dwordx4 v[36:37], v[32:35], off
	v_cmp_lt_i32_e32 vcc, s6, v167
	v_or_b32_e32 v36, v68, v180
	s_and_saveexec_b64 s[6:7], vcc
	s_xor_b64 s[6:7], exec, s[6:7]
	v_and_or_b32 v32, v166, s30, v36
	s_or_saveexec_b64 s[6:7], s[6:7]
	v_or_b32_e32 v37, 32, v69
	v_mov_b64_e32 v[34:35], 0x9600000
	s_xor_b64 exec, exec, s[6:7]
	v_and_or_b32 v32, v188, s31, v37
	v_mov_b64_e32 v[34:35], 0x5600000
	s_or_b64 exec, exec, s[6:7]
; __device__ __forceinline__ unsigned cvt_pk_bf16(float lo, float hi) { f32x2_t v = {lo, hi}; bf16x2_t b = __builtin_convertvector(v, bf16x2_t); return __builtin_bit_cast(unsigned, b); }
; #define PG8_BAR __builtin_amdgcn_s_barrier()
; template <class Epi>
; __device__ __forceinline__ void gemm_phase(LAS unsigned char* lds, const Gemm g, const StaticOrder& S, const Epi& E) {
;     ...
;         if (wr == 0) PG8_BAR;
;         E(acc, cur, wr, wc, fr, fq);
;         if (!has_next) break;
; #pragma unroll
;         for (int a = 0; a < 2; ++a)
; #pragma unroll
;             for (int b = 0; b < 2; ++b)
; #pragma unroll
;                 for (int m = 0; m < 4; ++m)
; #pragma unroll
;                     for (int n = 0; n < 2; ++n) acc[a][b][m][n] = (f32x4){0.f, 0.f, 0.f, 0.f};
;         cur = nxt; cA = nA; cB = nB; ++ui;
;         if (wr == 1) PG8_BAR;
;     __device__ __forceinline__ void operator()(const Acc& acc, const Unit& u, int wr, int wc, int fr, int fq) const {
;     ...
;                 const int row = row0 + ai * HALF + m * 16;
; #pragma unroll
;                 for (int bj = 0; bj < 2; ++bj) {
;                     float o[8];
; #pragma unroll
;                     for (int n = 0; n < 2; ++n)
; #pragma unroll
;                         for (int e = 0; e < 4; ++e) o[4 * n + e] = acc[ai][bj][m][n][e] * rs[bj][4 * n + e];
;                     u32x4 w; w.x = cvt_pk_bf16(o[0], o[1]); w.y = cvt_pk_bf16(o[2], o[3]); w.z = cvt_pk_bf16(o[4], o[5]); w.w = cvt_pk_bf16(o[6], o[7]);
;                     const int tok = col0 + bj * HALF, b = tok >> 11, t = tok & (SEQ - 1);
;                     bf16_t* dst;
;                     if (row < 1024) dst = VT + ((size_t)(((b * 8 + (row >> 7)) * 32 + (t >> 6)) * 128 + (row & 127))) * 64 + (t & 63);
;                     else { const int f = row - 1024; dst = VTS + ((size_t)(((b * 4 + (f >> 6)) * 32 + (t >> 6)) * 64 + (f & 63))) * 64 + (t & 63); }
;                     *(u32x4*)dst = w;
	v_mul_f32_e32 v28, v28, v140
	v_mul_f32_e32 v29, v29, v141
	v_mul_f32_e32 v30, v30, v142
	v_mul_f32_e32 v31, v31, v143
	v_ashrrev_i32_e32 v33, 31, v32
	v_mul_f32_e32 v38, v24, v136
	v_mul_f32_e32 v39, v25, v137
	v_cvt_pk_bf16_f32 v24, v28, v29
	v_cvt_pk_bf16_f32 v25, v30, v31
	v_lshl_add_u64 v[28:29], s[48:49], 0, v[34:35]
	v_lshlrev_b64 v[30:31], 7, v[32:33]
	v_mul_f32_e32 v40, v26, v138
	v_mul_f32_e32 v41, v27, v139
	v_lshl_add_u64 v[28:29], v[28:29], 0, v[30:31]
	v_cvt_pk_bf16_f32 v26, v38, v39
	v_cvt_pk_bf16_f32 v27, v40, v41
	v_lshl_add_u64 v[28:29], v[28:29], 0, v[152:153]
	global_store_dwordx4 v[28:29], v[24:27], off
	s_and_saveexec_b64 s[6:7], vcc
	s_xor_b64 s[6:7], exec, s[6:7]
	v_and_or_b32 v24, v189, s33, v36
	s_or_saveexec_b64 s[6:7], s[6:7]
	v_mov_b64_e32 v[26:27], 0x9600000
	s_xor_b64 exec, exec, s[6:7]
	v_and_or_b32 v24, v190, s34, v37
	v_mov_b64_e32 v[26:27], 0x5600000
	s_or_b64 exec, exec, s[6:7]
	v_mul_f32_e32 v20, v20, v122
	v_mul_f32_e32 v21, v21, v123
	v_mul_f32_e32 v22, v22, v120
	v_mul_f32_e32 v23, v23, v121
	v_ashrrev_i32_e32 v25, 31, v24
	v_mul_f32_e32 v28, v16, v126
	v_mul_f32_e32 v29, v17, v127
	v_cvt_pk_bf16_f32 v16, v20, v21
	v_cvt_pk_bf16_f32 v17, v22, v23
	v_lshl_add_u64 v[20:21], s[48:49], 0, v[26:27]
	v_lshlrev_b64 v[22:23], 7, v[24:25]
	v_mul_f32_e32 v30, v18, v124
	v_mul_f32_e32 v31, v19, v125
	v_lshl_add_u64 v[20:21], v[20:21], 0, v[22:23]
	v_cvt_pk_bf16_f32 v18, v28, v29
	v_cvt_pk_bf16_f32 v19, v30, v31
	v_lshl_add_u64 v[20:21], v[20:21], 0, v[152:153]
	s_movk_i32 s6, 0x34f
	global_store_dwordx4 v[20:21], v[16:19], off
	v_cmp_lt_i32_e32 vcc, s6, v167
	v_or_b32_e32 v20, v68, v181
	s_and_saveexec_b64 s[6:7], vcc
	s_xor_b64 s[6:7], exec, s[6:7]
	v_and_or_b32 v16, v166, s30, v20
	s_or_saveexec_b64 s[6:7], s[6:7]
	v_or_b32_e32 v21, 48, v69
	v_mov_b64_e32 v[18:19], 0x9600000
	s_xor_b64 exec, exec, s[6:7]
	v_and_or_b32 v16, v188, s31, v21
	v_mov_b64_e32 v[18:19], 0x5600000
	s_or_b64 exec, exec, s[6:7]
	v_mul_f32_e32 v12, v12, v140
	v_mul_f32_e32 v13, v13, v141
	v_mul_f32_e32 v14, v14, v142
	v_mul_f32_e32 v15, v15, v143
	v_ashrrev_i32_e32 v17, 31, v16
	v_mul_f32_e32 v22, v8, v136
	v_mul_f32_e32 v23, v9, v137
	v_cvt_pk_bf16_f32 v8, v12, v13
	v_cvt_pk_bf16_f32 v9, v14, v15
	v_lshl_add_u64 v[12:13], s[48:49], 0, v[18:19]
	v_lshlrev_b64 v[14:15], 7, v[16:17]
	v_mul_f32_e32 v24, v10, v138
	v_mul_f32_e32 v25, v11, v139
	v_lshl_add_u64 v[12:13], v[12:13], 0, v[14:15]
	v_cvt_pk_bf16_f32 v10, v22, v23
	v_cvt_pk_bf16_f32 v11, v24, v25
	v_lshl_add_u64 v[12:13], v[12:13], 0, v[152:153]
	global_store_dwordx4 v[12:13], v[8:11], off
	s_and_saveexec_b64 s[6:7], vcc
	s_xor_b64 s[6:7], exec, s[6:7]
	v_and_or_b32 v8, v189, s33, v20
	s_or_saveexec_b64 s[6:7], s[6:7]
	v_mov_b64_e32 v[10:11], 0x9600000
	s_xor_b64 exec, exec, s[6:7]
	v_and_or_b32 v8, v190, s34, v21
	v_mov_b64_e32 v[10:11], 0x5600000
	s_or_b64 exec, exec, s[6:7]
	v_ashrrev_i32_e32 v9, 31, v8
	v_lshl_add_u64 v[10:11], s[48:49], 0, v[10:11]
	v_lshlrev_b64 v[8:9], 7, v[8:9]
	v_mul_f32_e32 v4, v4, v122
	v_mul_f32_e32 v5, v5, v123
	v_mul_f32_e32 v6, v6, v120
	v_mul_f32_e32 v7, v7, v121
	v_mul_f32_e32 v0, v0, v126
	v_mul_f32_e32 v1, v1, v127
	v_lshl_add_u64 v[8:9], v[10:11], 0, v[8:9]
	v_cvt_pk_bf16_f32 v4, v4, v5
	v_cvt_pk_bf16_f32 v5, v6, v7
	v_cvt_pk_bf16_f32 v6, v0, v1
	v_mul_f32_e32 v0, v2, v124
	v_mul_f32_e32 v1, v3, v125
	v_lshl_add_u64 v[8:9], v[8:9], 0, v[152:153]
	v_cvt_pk_bf16_f32 v7, v0, v1
	s_andn2_b64 vcc, exec, s[8:9]
	s_mov_b64 s[6:7], -1
	global_store_dwordx4 v[8:9], v[4:7], off
	s_cbranch_vccnz .LBB0_716
	s_andn2_b64 vcc, exec, s[0:1]
	s_cbranch_vccnz .LBB0_715
	s_barrier
	s_branch .LBB0_715

.LBB0_860:
	s_andn2_b64 vcc, exec, s[6:7]
	s_cbranch_vccnz .LBB0_862
	v_add_u32_e32 v36, -3, v34
	v_cvt_f32_i32_e32 v39, v36
	v_add_u32_e32 v36, -5, v34
	v_cvt_f32_i32_e32 v41, v36
	v_add_u32_e32 v36, -7, v34
	v_cvt_f32_i32_e32 v43, v36
	v_add_u32_e32 v36, -16, v34
	v_cvt_f32_i32_e32 v46, v36
	v_subrev_u32_e32 v36, 19, v34
	v_subrev_u32_e32 v45, 18, v34
	v_add_u32_e32 v35, -1, v34
	v_add_u32_e32 v38, -2, v34
	v_add_u32_e32 v40, -4, v34
	v_add_u32_e32 v42, -6, v34
	v_subrev_u32_e32 v44, 17, v34
	v_cvt_f32_i32_e32 v48, v45
	v_cvt_f32_i32_e32 v47, v36
	v_subrev_u32_e32 v36, 21, v34
	v_subrev_u32_e32 v45, 20, v34
	v_cvt_f32_i32_e32 v35, v35
	v_cvt_f32_i32_e32 v38, v38
	v_cvt_f32_i32_e32 v40, v40
	v_cvt_f32_i32_e32 v42, v42
	v_cvt_f32_i32_e32 v44, v44
	v_cvt_f32_i32_e32 v50, v45
	v_cvt_f32_i32_e32 v49, v36
	v_subrev_u32_e32 v36, 23, v34
	v_subrev_u32_e32 v45, 22, v34
	v_cvt_f32_i32_e32 v52, v45
	v_cvt_f32_i32_e32 v51, v36
	v_and_b32_e32 v36, 0x7fffffff, v37
	v_and_b32_e32 v37, 0x7fffffff, v35
	v_and_b32_e32 v39, 0x7fffffff, v39
	v_and_b32_e32 v38, 0x7fffffff, v38
	v_and_b32_e32 v41, 0x7fffffff, v41
	v_and_b32_e32 v40, 0x7fffffff, v40
	v_and_b32_e32 v43, 0x7fffffff, v43
	v_and_b32_e32 v42, 0x7fffffff, v42
	v_and_b32_e32 v45, 0x7fffffff, v44
	v_and_b32_e32 v44, 0x7fffffff, v46
	v_and_b32_e32 v47, 0x7fffffff, v47
	v_and_b32_e32 v46, 0x7fffffff, v48
	v_and_b32_e32 v49, 0x7fffffff, v49
	v_and_b32_e32 v48, 0x7fffffff, v50
	v_and_b32_e32 v51, 0x7fffffff, v51
	v_and_b32_e32 v50, 0x7fffffff, v52
	v_fma_f32 v28, -s76, v48, v28
	v_fma_f32 v29, -s76, v49, v29
	v_fma_f32 v26, -s76, v46, v26
	v_fma_f32 v27, -s76, v47, v27
	v_fma_f32 v24, -s76, v44, v24
	v_fma_f32 v25, -s76, v45, v25
	v_fma_f32 v22, -s76, v42, v22
	v_fma_f32 v23, -s76, v43, v23
	v_fma_f32 v20, -s76, v40, v20
	v_fma_f32 v21, -s76, v41, v21
	v_fma_f32 v18, -s76, v38, v18
	v_fma_f32 v19, -s76, v39, v19
	v_fma_f32 v16, -s76, v36, v16
	v_fma_f32 v17, -s76, v37, v17
	v_subrev_u32_e32 v35, 33, v34
	v_subrev_u32_e32 v36, 32, v34
	v_subrev_u32_e32 v37, 35, v34
	v_subrev_u32_e32 v38, 34, v34
	v_subrev_u32_e32 v39, 37, v34
	v_subrev_u32_e32 v40, 36, v34
	v_subrev_u32_e32 v41, 39, v34
	v_subrev_u32_e32 v42, 38, v34
	v_subrev_u32_e32 v43, 49, v34
	v_subrev_u32_e32 v44, 48, v34
	v_subrev_u32_e32 v45, 51, v34
	v_subrev_u32_e32 v46, 50, v34
	v_subrev_u32_e32 v47, 53, v34
	v_subrev_u32_e32 v48, 52, v34
	v_subrev_u32_e32 v49, 55, v34
	v_subrev_u32_e32 v34, 54, v34
	v_fma_f32 v30, -s76, v50, v30
	v_fma_f32 v31, -s76, v51, v31
	v_cvt_f32_i32_e32 v50, v34
	v_cvt_f32_i32_e32 v49, v49
	v_cvt_f32_i32_e32 v48, v48
	v_cvt_f32_i32_e32 v47, v47
	v_cvt_f32_i32_e32 v46, v46
	v_cvt_f32_i32_e32 v45, v45
	v_cvt_f32_i32_e32 v44, v44
	v_cvt_f32_i32_e32 v43, v43
	v_cvt_f32_i32_e32 v42, v42
	v_cvt_f32_i32_e32 v41, v41
	v_cvt_f32_i32_e32 v40, v40
	v_cvt_f32_i32_e32 v39, v39
	v_cvt_f32_i32_e32 v34, v35
	v_cvt_f32_i32_e32 v36, v36
	v_cvt_f32_i32_e32 v37, v37
	v_cvt_f32_i32_e32 v38, v38
	v_and_b32_e32 v35, 0x7fffffff, v34
	v_and_b32_e32 v34, 0x7fffffff, v36
	v_and_b32_e32 v37, 0x7fffffff, v37
	v_and_b32_e32 v36, 0x7fffffff, v38
	v_and_b32_e32 v39, 0x7fffffff, v39
	v_and_b32_e32 v38, 0x7fffffff, v40
	v_and_b32_e32 v41, 0x7fffffff, v41
	v_and_b32_e32 v40, 0x7fffffff, v42
	v_and_b32_e32 v43, 0x7fffffff, v43
	v_and_b32_e32 v42, 0x7fffffff, v44
	v_and_b32_e32 v45, 0x7fffffff, v45
	v_and_b32_e32 v44, 0x7fffffff, v46
	v_and_b32_e32 v47, 0x7fffffff, v47
	v_and_b32_e32 v46, 0x7fffffff, v48
	v_and_b32_e32 v49, 0x7fffffff, v49
	v_and_b32_e32 v48, 0x7fffffff, v50
	v_fma_f32 v14, -s76, v48, v14
	v_fma_f32 v15, -s76, v49, v15
	v_fma_f32 v12, -s76, v46, v12
	v_fma_f32 v13, -s76, v47, v13
	v_fma_f32 v10, -s76, v44, v10
	v_fma_f32 v11, -s76, v45, v11
	v_fma_f32 v8, -s76, v42, v8
	v_fma_f32 v9, -s76, v43, v9
	v_fma_f32 v6, -s76, v40, v6
	v_fma_f32 v7, -s76, v41, v7
	v_fma_f32 v4, -s76, v38, v4
	v_fma_f32 v5, -s76, v39, v5
	v_fma_f32 v2, -s76, v36, v2
	v_fma_f32 v3, -s76, v37, v3
	v_fma_f32 v0, -s76, v34, v0
	v_fma_f32 v1, -s76, v35, v1
	v_mov_b32_e32 v35, 0
	v_mov_b32_e32 v36, 0
.LBB0_862:
	v_max_f32_e32 v34, v17, v17
	v_max_f32_e32 v37, v16, v16
	v_max_f32_e32 v34, v37, v34
	v_max_f32_e32 v37, v1, v1
	v_max_f32_e32 v38, v0, v0
	v_max_f32_e32 v37, v38, v37
	v_max3_f32 v34, v34, v18, v19
	v_max3_f32 v37, v37, v2, v3
	v_max3_f32 v34, v34, v20, v21
	v_max3_f32 v37, v37, v4, v5
	v_max3_f32 v34, v34, v22, v23
	v_max3_f32 v37, v37, v6, v7
	v_max3_f32 v34, v34, v24, v25
	v_max3_f32 v37, v37, v8, v9
	v_max3_f32 v34, v34, v26, v27
	v_max3_f32 v37, v37, v10, v11
	v_max3_f32 v34, v34, v28, v29
	v_max3_f32 v37, v37, v12, v13
	v_max3_f32 v34, v34, v30, v31
	v_max3_f32 v37, v37, v14, v15
	v_add_f32_e32 v34, v35, v34
	v_add_f32_e32 v37, v36, v37
	v_max_f32_e32 v34, v34, v37
	v_mov_b32_e32 v37, v34
	s_nop 1
	v_permlane32_swap_b32_e32 v34, v37
	v_max_f32_e32 v37, v37, v37
	v_max_f32_e32 v34, v34, v34
	v_max_f32_e32 v34, v34, v37
	v_add_f32_e32 v37, 0x7f800000, v34
	v_cmp_gt_f32_e32 vcc, s18, v37
	s_cmp_lg_u64 vcc, exec
	s_cselect_b64 s[82:83], -1, 0
	s_cmp_eq_u64 vcc, exec
	s_cbranch_scc1 .LBB0_864
	v_max_f32_e32 v34, v34, v34
	v_max_f32_e32 v112, 0xff800000, v34
	v_sub_f32_e32 v51, v112, v35
	v_sub_f32_e32 v52, v112, v36
	v_sub_f32_e32 v16, v16, v51
	v_sub_f32_e32 v0, v0, v52
	v_exp_f32_e32 v34, v16
	v_exp_f32_e32 v35, v0
	v_sub_f32_e32 v0, v17, v51
	v_sub_f32_e32 v1, v1, v52
	v_exp_f32_e32 v0, v0
	v_exp_f32_e32 v1, v1
	v_sub_f32_e32 v16, v18, v51
	v_sub_f32_e32 v2, v2, v52
	v_exp_f32_e32 v36, v16
	v_exp_f32_e32 v37, v2
	v_sub_f32_e32 v2, v19, v51
	v_sub_f32_e32 v3, v3, v52
	v_exp_f32_e32 v2, v2
	v_exp_f32_e32 v3, v3
	v_sub_f32_e32 v18, v20, v51
	v_sub_f32_e32 v4, v4, v52
	v_add_f32_e32 v16, 0, v34
	v_add_f32_e32 v17, 0, v35
	v_exp_f32_e32 v38, v18
	v_exp_f32_e32 v39, v4
	v_sub_f32_e32 v4, v21, v51
	v_sub_f32_e32 v5, v5, v52
	v_add_f32_e32 v16, v0, v16
	v_add_f32_e32 v17, v1, v17
	v_exp_f32_e32 v4, v4
	v_exp_f32_e32 v5, v5
	v_sub_f32_e32 v18, v22, v51
	v_sub_f32_e32 v6, v6, v52
	v_add_f32_e32 v16, v36, v16
	v_add_f32_e32 v17, v37, v17
	v_exp_f32_e32 v40, v18
	v_exp_f32_e32 v41, v6
	v_sub_f32_e32 v6, v23, v51
	v_sub_f32_e32 v7, v7, v52
	v_add_f32_e32 v16, v2, v16
	v_add_f32_e32 v17, v3, v17
	v_exp_f32_e32 v6, v6
	v_exp_f32_e32 v7, v7
	v_sub_f32_e32 v18, v24, v51
	v_sub_f32_e32 v8, v8, v52
	v_exp_f32_e32 v42, v18
	v_exp_f32_e32 v43, v8
	v_sub_f32_e32 v8, v25, v51
	v_sub_f32_e32 v9, v9, v52
	v_add_f32_e32 v16, v38, v16
	v_add_f32_e32 v17, v39, v17
	v_exp_f32_e32 v8, v8
	v_exp_f32_e32 v9, v9
	v_sub_f32_e32 v18, v26, v51
	v_sub_f32_e32 v10, v10, v52
	v_add_f32_e32 v16, v4, v16
	v_add_f32_e32 v17, v5, v17
	v_exp_f32_e32 v44, v18
	v_exp_f32_e32 v45, v10
	v_sub_f32_e32 v10, v27, v51
	v_sub_f32_e32 v11, v11, v52
	v_add_f32_e32 v16, v40, v16
	v_add_f32_e32 v17, v41, v17
	v_exp_f32_e32 v10, v10
	v_exp_f32_e32 v11, v11
	v_sub_f32_e32 v18, v28, v51
	v_sub_f32_e32 v12, v12, v52
	v_add_f32_e32 v16, v6, v16
	v_add_f32_e32 v17, v7, v17
	v_sub_f32_e32 v50, 0xff800000, v112
	v_exp_f32_e32 v46, v18
	v_exp_f32_e32 v47, v12
	v_sub_f32_e32 v12, v29, v51
	v_sub_f32_e32 v13, v13, v52
	v_sub_f32_e32 v18, v30, v51
	v_add_f32_e32 v16, v42, v16
	v_add_f32_e32 v17, v43, v17
	v_exp_f32_e32 v12, v12
	v_exp_f32_e32 v13, v13
	v_exp_f32_e32 v48, v18
	v_sub_f32_e32 v14, v14, v52
	v_add_f32_e32 v16, v8, v16
	v_add_f32_e32 v17, v9, v17
	v_exp_f32_e32 v18, v50
	v_exp_f32_e32 v49, v14
	v_sub_f32_e32 v14, v31, v51
	v_sub_f32_e32 v15, v15, v52
	v_add_f32_e32 v16, v44, v16
	v_add_f32_e32 v17, v45, v17
	v_exp_f32_e32 v14, v14
	v_exp_f32_e32 v15, v15
	v_add_f32_e32 v16, v10, v16
	v_add_f32_e32 v17, v11, v17
	v_cmp_neq_f32_e32 vcc, 1.0, v18
	v_add_f32_e32 v16, v46, v16
	v_add_f32_e32 v17, v47, v17
	s_cmp_lg_u64 vcc, 0
	v_add_f32_e32 v16, v12, v16
	v_add_f32_e32 v17, v13, v17
	v_mul_f32_e32 v19, 0, v18
	v_add_f32_e32 v16, v48, v16
	v_add_f32_e32 v17, v49, v17
	s_cselect_b64 vcc, -1, 0
	v_add_f32_e32 v16, v14, v16
	v_add_f32_e32 v17, v15, v17
	v_cvt_pk_bf16_f32 v144, v34, v0
	v_add_f32_e32 v193, v16, v17
	v_cndmask_b32_e32 v16, 0, v19, vcc
	v_fmac_f32_e32 v193, 0, v18
	v_mov_b32_e32 v17, v16
	v_mov_b32_e32 v18, v16
	v_mov_b32_e32 v19, v16
	v_mov_b32_e32 v20, v16
	v_mov_b32_e32 v21, v16
	v_mov_b32_e32 v22, v16
	v_mov_b32_e32 v23, v16
	v_mov_b32_e32 v24, v16
	v_mov_b32_e32 v25, v16
	v_mov_b32_e32 v26, v16
	v_mov_b32_e32 v27, v16
	v_mov_b32_e32 v28, v16
	v_mov_b32_e32 v29, v16
	v_mov_b32_e32 v30, v16
	v_mov_b32_e32 v31, v16
	v_cvt_pk_bf16_f32 v145, v36, v2
	v_cvt_pk_bf16_f32 v146, v38, v4
	v_cvt_pk_bf16_f32 v147, v40, v6
	v_cvt_pk_bf16_f32 v148, v42, v8
	v_cvt_pk_bf16_f32 v149, v44, v10
	v_cvt_pk_bf16_f32 v150, v46, v12
	v_cvt_pk_bf16_f32 v151, v48, v14
	v_cvt_pk_bf16_f32 v152, v35, v1
	v_cvt_pk_bf16_f32 v153, v37, v3
	v_cvt_pk_bf16_f32 v154, v39, v5
	v_cvt_pk_bf16_f32 v155, v41, v7
	v_cvt_pk_bf16_f32 v156, v43, v9
	v_cvt_pk_bf16_f32 v157, v45, v11
	v_cvt_pk_bf16_f32 v158, v47, v13
	v_cvt_pk_bf16_f32 v159, v49, v15
	s_branch .LBB0_865

.LBB0_874:
	s_andn2_b64 vcc, exec, s[6:7]
	s_cbranch_vccnz .LBB0_876
	v_add_u32_e32 v98, -3, v96
	v_cvt_f32_i32_e32 v101, v98
	v_add_u32_e32 v98, -5, v96
	v_cvt_f32_i32_e32 v103, v98
	v_add_u32_e32 v98, -7, v96
	v_cvt_f32_i32_e32 v105, v98
	v_add_u32_e32 v98, -16, v96
	v_cvt_f32_i32_e32 v108, v98
	v_subrev_u32_e32 v98, 19, v96
	v_subrev_u32_e32 v107, 18, v96
	v_add_u32_e32 v97, -1, v96
	v_add_u32_e32 v100, -2, v96
	v_add_u32_e32 v102, -4, v96
	v_add_u32_e32 v104, -6, v96
	v_subrev_u32_e32 v106, 17, v96
	v_cvt_f32_i32_e32 v110, v107
	v_cvt_f32_i32_e32 v109, v98
	v_subrev_u32_e32 v98, 21, v96
	v_subrev_u32_e32 v107, 20, v96
	v_cvt_f32_i32_e32 v97, v97
	v_cvt_f32_i32_e32 v100, v100
	v_cvt_f32_i32_e32 v102, v102
	v_cvt_f32_i32_e32 v104, v104
	v_cvt_f32_i32_e32 v106, v106
	v_cvt_f32_i32_e32 v113, v107
	v_cvt_f32_i32_e32 v111, v98
	v_subrev_u32_e32 v98, 23, v96
	v_subrev_u32_e32 v107, 22, v96
	v_cvt_f32_i32_e32 v114, v107
	v_cvt_f32_i32_e32 v115, v98
	v_and_b32_e32 v98, 0x7fffffff, v99
	v_and_b32_e32 v99, 0x7fffffff, v97
	v_and_b32_e32 v101, 0x7fffffff, v101
	v_and_b32_e32 v100, 0x7fffffff, v100
	v_and_b32_e32 v103, 0x7fffffff, v103
	v_and_b32_e32 v102, 0x7fffffff, v102
	v_and_b32_e32 v105, 0x7fffffff, v105
	v_and_b32_e32 v104, 0x7fffffff, v104
	v_and_b32_e32 v107, 0x7fffffff, v106
	v_and_b32_e32 v106, 0x7fffffff, v108
	v_and_b32_e32 v109, 0x7fffffff, v109
	v_and_b32_e32 v108, 0x7fffffff, v110
	v_and_b32_e32 v111, 0x7fffffff, v111
	v_and_b32_e32 v110, 0x7fffffff, v113
	v_fma_f32 v92, -s76, v110, v92
	v_fma_f32 v93, -s76, v111, v93
	v_fma_f32 v90, -s76, v108, v90
	v_fma_f32 v91, -s76, v109, v91
	v_fma_f32 v88, -s76, v106, v88
	v_fma_f32 v89, -s76, v107, v89
	v_fma_f32 v86, -s76, v104, v86
	v_fma_f32 v87, -s76, v105, v87
	v_fma_f32 v84, -s76, v102, v84
	v_fma_f32 v85, -s76, v103, v85
	v_fma_f32 v82, -s76, v100, v82
	v_fma_f32 v83, -s76, v101, v83
	v_fma_f32 v80, -s76, v98, v80
	v_fma_f32 v81, -s76, v99, v81
	v_subrev_u32_e32 v97, 33, v96
	v_subrev_u32_e32 v98, 32, v96
	v_subrev_u32_e32 v99, 35, v96
	v_subrev_u32_e32 v100, 34, v96
	v_subrev_u32_e32 v101, 37, v96
	v_subrev_u32_e32 v102, 36, v96
	v_subrev_u32_e32 v103, 39, v96
	v_subrev_u32_e32 v104, 38, v96
	v_subrev_u32_e32 v105, 49, v96
	v_subrev_u32_e32 v106, 48, v96
	v_subrev_u32_e32 v107, 51, v96
	v_subrev_u32_e32 v108, 50, v96
	v_subrev_u32_e32 v109, 53, v96
	v_subrev_u32_e32 v110, 52, v96
	v_subrev_u32_e32 v111, 55, v96
	v_subrev_u32_e32 v96, 54, v96
	v_cvt_f32_i32_e32 v113, v96
	v_cvt_f32_i32_e32 v111, v111
	v_cvt_f32_i32_e32 v110, v110
	v_cvt_f32_i32_e32 v109, v109
	v_cvt_f32_i32_e32 v108, v108
	v_cvt_f32_i32_e32 v107, v107
	v_cvt_f32_i32_e32 v106, v106
	v_cvt_f32_i32_e32 v105, v105
	v_cvt_f32_i32_e32 v104, v104
	v_cvt_f32_i32_e32 v103, v103
	v_cvt_f32_i32_e32 v102, v102
	v_cvt_f32_i32_e32 v101, v101
	v_cvt_f32_i32_e32 v96, v97
	v_cvt_f32_i32_e32 v98, v98
	v_cvt_f32_i32_e32 v99, v99
	v_cvt_f32_i32_e32 v100, v100
	v_and_b32_e32 v115, 0x7fffffff, v115
	v_and_b32_e32 v114, 0x7fffffff, v114
	v_and_b32_e32 v97, 0x7fffffff, v96
	v_and_b32_e32 v96, 0x7fffffff, v98
	v_and_b32_e32 v99, 0x7fffffff, v99
	v_and_b32_e32 v98, 0x7fffffff, v100
	v_and_b32_e32 v101, 0x7fffffff, v101
	v_and_b32_e32 v100, 0x7fffffff, v102
	v_and_b32_e32 v103, 0x7fffffff, v103
	v_and_b32_e32 v102, 0x7fffffff, v104
	v_and_b32_e32 v105, 0x7fffffff, v105
	v_and_b32_e32 v104, 0x7fffffff, v106
	v_and_b32_e32 v107, 0x7fffffff, v107
	v_and_b32_e32 v106, 0x7fffffff, v108
	v_and_b32_e32 v109, 0x7fffffff, v109
	v_and_b32_e32 v108, 0x7fffffff, v110
	v_and_b32_e32 v111, 0x7fffffff, v111
	v_and_b32_e32 v110, 0x7fffffff, v113
	v_fma_f32 v94, -s76, v114, v94
	v_fma_f32 v95, -s76, v115, v95
	v_fma_f32 v78, -s76, v110, v78
	v_fma_f32 v79, -s76, v111, v79
	v_fma_f32 v76, -s76, v108, v76
	v_fma_f32 v77, -s76, v109, v77
	v_fma_f32 v74, -s76, v106, v74
	v_fma_f32 v75, -s76, v107, v75
	v_fma_f32 v72, -s76, v104, v72
	v_fma_f32 v73, -s76, v105, v73
	v_fma_f32 v70, -s76, v102, v70
	v_fma_f32 v71, -s76, v103, v71
	v_fma_f32 v68, -s76, v100, v68
	v_fma_f32 v69, -s76, v101, v69
	v_fma_f32 v66, -s76, v98, v66
	v_fma_f32 v67, -s76, v99, v67
	v_fma_f32 v64, -s76, v96, v64
	v_fma_f32 v65, -s76, v97, v65
	v_mov_b32_e32 v97, 0
	v_mov_b32_e32 v98, 0
.LBB0_876:
	v_max_f32_e32 v96, v81, v81
	v_max_f32_e32 v99, v80, v80
	v_max_f32_e32 v96, v99, v96
	v_max_f32_e32 v99, v65, v65
	v_max_f32_e32 v100, v64, v64
	v_max_f32_e32 v99, v100, v99
	v_max3_f32 v96, v96, v82, v83
	v_max3_f32 v99, v99, v66, v67
	v_max3_f32 v96, v96, v84, v85
	v_max3_f32 v99, v99, v68, v69
	v_max3_f32 v96, v96, v86, v87
	v_max3_f32 v99, v99, v70, v71
	v_max3_f32 v96, v96, v88, v89
	v_max3_f32 v99, v99, v72, v73
	v_max3_f32 v96, v96, v90, v91
	v_max3_f32 v99, v99, v74, v75
	v_max3_f32 v96, v96, v92, v93
	v_max3_f32 v99, v99, v76, v77
	v_max3_f32 v96, v96, v94, v95
	v_max3_f32 v99, v99, v78, v79
	v_add_f32_e32 v96, v97, v96
	v_add_f32_e32 v99, v98, v99
	v_max_f32_e32 v96, v96, v99
	v_mov_b32_e32 v99, v96
	s_nop 1
	v_permlane32_swap_b32_e32 v96, v99
	v_max_f32_e32 v99, v99, v99
	v_max_f32_e32 v96, v96, v96
	v_max_f32_e32 v96, v96, v99
	v_sub_f32_e32 v99, v96, v112
	v_cmp_gt_f32_e32 vcc, s18, v99
	s_cmp_lg_u64 vcc, exec
	s_cselect_b64 s[78:79], -1, 0
	s_cmp_eq_u64 vcc, exec
	s_cbranch_scc1 .LBB0_880
	v_max_f32_e32 v96, v96, v96
	v_max_f32_e32 v99, v112, v112
	v_max_f32_e32 v203, v99, v96
	v_sub_f32_e32 v96, v112, v203
	v_exp_f32_e32 v96, v96
	s_nop 0
	v_cmp_neq_f32_e32 vcc, 1.0, v96
	s_cbranch_vccz .LBB0_879
	v_mul_f32_e32 v30, v30, v96
	v_mul_f32_e32 v31, v31, v96
	v_mul_f32_e32 v28, v28, v96
	v_mul_f32_e32 v29, v29, v96
	v_mul_f32_e32 v26, v26, v96
	v_mul_f32_e32 v27, v27, v96
	v_mul_f32_e32 v24, v24, v96
	v_mul_f32_e32 v25, v25, v96
	v_mul_f32_e32 v22, v22, v96
	v_mul_f32_e32 v23, v23, v96
	v_mul_f32_e32 v20, v20, v96
	v_mul_f32_e32 v21, v21, v96
	v_mul_f32_e32 v18, v18, v96
	v_mul_f32_e32 v19, v19, v96
	v_mul_f32_e32 v16, v16, v96
	v_mul_f32_e32 v17, v17, v96
	v_mul_f32_e32 v62, v62, v96
	v_mul_f32_e32 v63, v63, v96
	v_mul_f32_e32 v60, v60, v96
	v_mul_f32_e32 v61, v61, v96
	v_mul_f32_e32 v58, v58, v96
	v_mul_f32_e32 v59, v59, v96
	v_mul_f32_e32 v56, v56, v96
	v_mul_f32_e32 v57, v57, v96
	v_mul_f32_e32 v54, v54, v96
	v_mul_f32_e32 v55, v55, v96
	v_mul_f32_e32 v52, v52, v96
	v_mul_f32_e32 v53, v53, v96
	v_mul_f32_e32 v50, v50, v96
	v_mul_f32_e32 v51, v51, v96
	v_mul_f32_e32 v48, v48, v96
	v_mul_f32_e32 v49, v49, v96
	v_mul_f32_e32 v46, v46, v96
	v_mul_f32_e32 v47, v47, v96
	v_mul_f32_e32 v44, v44, v96
	v_mul_f32_e32 v45, v45, v96
	v_mul_f32_e32 v42, v42, v96
	v_mul_f32_e32 v43, v43, v96
	v_mul_f32_e32 v40, v40, v96
	v_mul_f32_e32 v41, v41, v96
	v_mul_f32_e32 v38, v38, v96
	v_mul_f32_e32 v39, v39, v96
	v_mul_f32_e32 v36, v36, v96
	v_mul_f32_e32 v37, v37, v96
	v_mul_f32_e32 v34, v34, v96
	v_mul_f32_e32 v35, v35, v96
	v_mul_f32_e32 v32, v32, v96
	v_mul_f32_e32 v33, v33, v96
	v_mul_f32_e32 v14, v14, v96
	v_mul_f32_e32 v15, v15, v96
	v_mul_f32_e32 v12, v12, v96
	v_mul_f32_e32 v13, v13, v96
	v_mul_f32_e32 v10, v10, v96
	v_mul_f32_e32 v11, v11, v96
	v_mul_f32_e32 v8, v8, v96
	v_mul_f32_e32 v9, v9, v96
	v_mul_f32_e32 v6, v6, v96
	v_mul_f32_e32 v7, v7, v96
	v_mul_f32_e32 v4, v4, v96
	v_mul_f32_e32 v5, v5, v96
	v_mul_f32_e32 v2, v2, v96
	v_mul_f32_e32 v3, v3, v96
	v_mul_f32_e32 v0, v0, v96
	v_mul_f32_e32 v1, v1, v96

.LBB0_895:
	s_andn2_b64 vcc, exec, s[6:7]
	s_cbranch_vccnz .LBB0_897
	v_add_f32_e32 v179, -1.0, v174
	v_add_f32_e32 v204, s10, v174
	v_add_f32_e32 v205, s11, v174
	v_add_f32_e32 v206, s12, v174
	v_add_f32_e32 v207, s13, v174
	v_add_f32_e32 v208, s14, v174
	v_add_f32_e32 v209, s15, v174
	v_add_f32_e32 v210, s36, v174
	v_add_f32_e32 v211, s37, v174
	v_add_f32_e32 v212, s44, v174
	v_add_f32_e32 v213, s45, v174
	v_add_f32_e32 v214, s46, v174
	v_add_f32_e32 v215, s47, v174
	v_add_f32_e32 v216, s52, v174
	v_add_f32_e32 v217, s53, v174
	v_and_b32_e32 v205, 0x7fffffff, v205
	v_and_b32_e32 v204, 0x7fffffff, v204
	v_and_b32_e32 v207, 0x7fffffff, v207
	v_and_b32_e32 v206, 0x7fffffff, v206
	v_and_b32_e32 v209, 0x7fffffff, v209
	v_and_b32_e32 v208, 0x7fffffff, v208
	v_and_b32_e32 v211, 0x7fffffff, v211
	v_and_b32_e32 v210, 0x7fffffff, v210
	v_and_b32_e32 v213, 0x7fffffff, v213
	v_and_b32_e32 v212, 0x7fffffff, v212
	v_and_b32_e32 v215, 0x7fffffff, v215
	v_and_b32_e32 v214, 0x7fffffff, v214
	v_and_b32_e32 v217, 0x7fffffff, v217
	v_and_b32_e32 v216, 0x7fffffff, v216
	v_and_b32_e32 v218, 0x7fffffff, v174
	v_and_b32_e32 v219, 0x7fffffff, v179
	s_xor_b32 s83, s24, 0x80000000
	s_xor_b32 s82, s97, 0x80000000
	s_xor_b32 s85, s43, 0x80000000
	s_xor_b32 s84, s3, 0x80000000
	s_xor_b32 s87, s8, 0x80000000
	s_xor_b32 s86, s51, 0x80000000
	s_xor_b32 s89, s50, 0x80000000
	s_xor_b32 s88, s49, 0x80000000
	s_xor_b32 s91, s48, 0x80000000
	s_xor_b32 s90, s41, 0x80000000
	s_xor_b32 s93, s40, 0x80000000
	s_xor_b32 s92, s39, 0x80000000
	s_xor_b32 s95, s38, 0x80000000
	s_xor_b32 s94, s22, 0x80000000
	v_fma_f32 v126, s82, v216, v126
	v_fma_f32 v127, s83, v217, v127
	v_fma_f32 v124, s84, v214, v124
	v_fma_f32 v125, s85, v215, v125
	v_fma_f32 v122, s86, v212, v122
	v_fma_f32 v123, s87, v213, v123
	v_fma_f32 v120, s88, v210, v120
	v_fma_f32 v121, s89, v211, v121
	v_fma_f32 v118, s90, v208, v118
	v_fma_f32 v119, s91, v209, v119
	v_fma_f32 v116, s92, v206, v116
	v_fma_f32 v117, s93, v207, v117
	v_fma_f32 v114, s94, v204, v114
	v_fma_f32 v115, s95, v205, v115
	v_fma_f32 v112, -s76, v218, v112
	v_fma_f32 v113, -s77, v219, v113
	v_add_f32_e32 v204, s54, v174
	v_add_f32_e32 v205, s55, v174
	v_add_f32_e32 v206, s56, v174
	v_add_f32_e32 v207, s57, v174
	v_add_f32_e32 v208, s58, v174
	v_add_f32_e32 v209, s59, v174
	v_add_f32_e32 v210, s60, v174
	v_add_f32_e32 v211, s61, v174
	v_add_f32_e32 v212, s62, v174
	v_add_f32_e32 v213, s63, v174
	v_add_f32_e32 v214, s64, v174
	v_add_f32_e32 v215, s65, v174
	v_add_f32_e32 v216, s66, v174
	v_add_f32_e32 v217, s67, v174
	v_add_f32_e32 v218, s74, v174
	v_add_f32_e32 v219, s75, v174
	v_and_b32_e32 v219, 0x7fffffff, v219
	v_and_b32_e32 v218, 0x7fffffff, v218
	v_and_b32_e32 v217, 0x7fffffff, v217
	v_and_b32_e32 v216, 0x7fffffff, v216
	v_and_b32_e32 v215, 0x7fffffff, v215
	v_and_b32_e32 v214, 0x7fffffff, v214
	v_and_b32_e32 v213, 0x7fffffff, v213
	v_and_b32_e32 v212, 0x7fffffff, v212
	v_and_b32_e32 v211, 0x7fffffff, v211
	v_and_b32_e32 v210, 0x7fffffff, v210
	v_and_b32_e32 v209, 0x7fffffff, v209
	v_and_b32_e32 v208, 0x7fffffff, v208
	v_and_b32_e32 v207, 0x7fffffff, v207
	v_and_b32_e32 v206, 0x7fffffff, v206
	v_and_b32_e32 v205, 0x7fffffff, v205
	v_and_b32_e32 v204, 0x7fffffff, v204
	v_fma_f32 v110, s82, v204, v110
	v_fma_f32 v111, s83, v205, v111
	v_fma_f32 v108, s84, v206, v108
	v_fma_f32 v109, s85, v207, v109
	v_fma_f32 v106, s86, v208, v106
	v_fma_f32 v107, s87, v209, v107
	v_fma_f32 v104, s88, v210, v104
	v_fma_f32 v105, s89, v211, v105
	v_fma_f32 v102, s90, v212, v102
	v_fma_f32 v103, s91, v213, v103
	v_fma_f32 v100, s92, v214, v100
	v_fma_f32 v101, s93, v215, v101
	v_fma_f32 v98, s94, v216, v98
	v_fma_f32 v99, s95, v217, v99
	v_fma_f32 v96, -s76, v218, v96
	v_fma_f32 v97, -s77, v219, v97
	v_mov_b32_e32 v204, 0
	v_mov_b32_e32 v205, 0
.LBB0_897:
	v_max_f32_e32 v174, v113, v113
	v_max_f32_e32 v179, v112, v112
	v_max_f32_e32 v174, v179, v174
	v_max_f32_e32 v179, v97, v97
	v_max_f32_e32 v206, v96, v96
	v_max_f32_e32 v179, v206, v179
	v_max3_f32 v174, v174, v114, v115
	v_max3_f32 v179, v179, v98, v99
	v_max3_f32 v174, v174, v116, v117
	v_max3_f32 v179, v179, v100, v101
	v_max3_f32 v174, v174, v118, v119
	v_max3_f32 v179, v179, v102, v103
	v_max3_f32 v174, v174, v120, v121
	v_max3_f32 v179, v179, v104, v105
	v_max3_f32 v174, v174, v122, v123
	v_max3_f32 v179, v179, v106, v107
	v_max3_f32 v174, v174, v124, v125
	v_max3_f32 v179, v179, v108, v109
	v_max3_f32 v174, v174, v126, v127
	v_max3_f32 v179, v179, v110, v111
	v_add_f32_e32 v174, v204, v174
	v_add_f32_e32 v179, v205, v179
	v_max_f32_e32 v174, v174, v179
	v_mov_b32_e32 v179, v174
	s_nop 1
	v_permlane32_swap_b32_e32 v174, v179
	v_max_f32_e32 v179, v179, v179
	v_max_f32_e32 v174, v174, v174
	v_max_f32_e32 v174, v174, v179
	v_sub_f32_e32 v179, v174, v203
	v_cmp_gt_f32_e32 vcc, s18, v179
	s_cmp_lg_u64 vcc, exec
	s_cselect_b64 s[82:83], -1, 0
	s_cmp_eq_u64 vcc, exec
	s_cbranch_scc1 .LBB0_901
	v_max_f32_e32 v144, v174, v174
	v_max_f32_e32 v145, v203, v203
	v_max_f32_e32 v174, v145, v144
	v_sub_f32_e32 v144, v203, v174
	v_exp_f32_e32 v144, v144
	s_nop 0
	v_cmp_neq_f32_e32 vcc, 1.0, v144
	s_cbranch_vccz .LBB0_900
	v_mul_f32_e32 v30, v30, v144
	v_mul_f32_e32 v31, v31, v144
	v_mul_f32_e32 v28, v28, v144
	v_mul_f32_e32 v29, v29, v144
	v_mul_f32_e32 v26, v26, v144
	v_mul_f32_e32 v27, v27, v144
	v_mul_f32_e32 v24, v24, v144
	v_mul_f32_e32 v25, v25, v144
	v_mul_f32_e32 v22, v22, v144
	v_mul_f32_e32 v23, v23, v144
	v_mul_f32_e32 v20, v20, v144
	v_mul_f32_e32 v21, v21, v144
	v_mul_f32_e32 v18, v18, v144
	v_mul_f32_e32 v19, v19, v144
	v_mul_f32_e32 v16, v16, v144
	v_mul_f32_e32 v17, v17, v144
	v_mul_f32_e32 v62, v62, v144
	v_mul_f32_e32 v63, v63, v144
	v_mul_f32_e32 v60, v60, v144
	v_mul_f32_e32 v61, v61, v144
	v_mul_f32_e32 v58, v58, v144
	v_mul_f32_e32 v59, v59, v144
	v_mul_f32_e32 v56, v56, v144
	v_mul_f32_e32 v57, v57, v144
	v_mul_f32_e32 v54, v54, v144
	v_mul_f32_e32 v55, v55, v144
	v_mul_f32_e32 v52, v52, v144
	v_mul_f32_e32 v53, v53, v144
	v_mul_f32_e32 v50, v50, v144
	v_mul_f32_e32 v51, v51, v144
	v_mul_f32_e32 v48, v48, v144
	v_mul_f32_e32 v49, v49, v144
	v_mul_f32_e32 v46, v46, v144
	v_mul_f32_e32 v47, v47, v144
	v_mul_f32_e32 v44, v44, v144
	v_mul_f32_e32 v45, v45, v144
	v_mul_f32_e32 v42, v42, v144
	v_mul_f32_e32 v43, v43, v144
	v_mul_f32_e32 v40, v40, v144
	v_mul_f32_e32 v41, v41, v144
	v_mul_f32_e32 v38, v38, v144
	v_mul_f32_e32 v39, v39, v144
	v_mul_f32_e32 v36, v36, v144
	v_mul_f32_e32 v37, v37, v144
	v_mul_f32_e32 v34, v34, v144
	v_mul_f32_e32 v35, v35, v144
	v_mul_f32_e32 v32, v32, v144
	v_mul_f32_e32 v33, v33, v144
	v_mul_f32_e32 v14, v14, v144
	v_mul_f32_e32 v15, v15, v144
	v_mul_f32_e32 v12, v12, v144
	v_mul_f32_e32 v13, v13, v144
	v_mul_f32_e32 v10, v10, v144
	v_mul_f32_e32 v11, v11, v144
	v_mul_f32_e32 v8, v8, v144
	v_mul_f32_e32 v9, v9, v144
	v_mul_f32_e32 v6, v6, v144
	v_mul_f32_e32 v7, v7, v144
	v_mul_f32_e32 v4, v4, v144
	v_mul_f32_e32 v5, v5, v144
	v_mul_f32_e32 v2, v2, v144
	v_mul_f32_e32 v3, v3, v144
	v_mul_f32_e32 v0, v0, v144
	v_mul_f32_e32 v1, v1, v144

.LBB0_909:
	s_andn2_b64 vcc, exec, s[6:7]
	s_cbranch_vccnz .LBB0_911
	v_add_f32_e32 v97, -1.0, v96
	v_add_f32_e32 v98, s10, v96
	v_add_f32_e32 v99, s11, v96
	v_add_f32_e32 v100, s12, v96
	v_add_f32_e32 v101, s13, v96
	v_add_f32_e32 v102, s14, v96
	v_add_f32_e32 v103, s15, v96
	v_add_f32_e32 v104, s36, v96
	v_add_f32_e32 v105, s37, v96
	v_add_f32_e32 v106, s44, v96
	v_add_f32_e32 v107, s45, v96
	v_add_f32_e32 v108, s46, v96
	v_add_f32_e32 v109, s47, v96
	v_add_f32_e32 v110, s52, v96
	v_add_f32_e32 v111, s53, v96
	v_and_b32_e32 v99, 0x7fffffff, v99
	v_and_b32_e32 v98, 0x7fffffff, v98
	v_and_b32_e32 v101, 0x7fffffff, v101
	v_and_b32_e32 v100, 0x7fffffff, v100
	v_and_b32_e32 v103, 0x7fffffff, v103
	v_and_b32_e32 v102, 0x7fffffff, v102
	v_and_b32_e32 v105, 0x7fffffff, v105
	v_and_b32_e32 v104, 0x7fffffff, v104
	v_and_b32_e32 v107, 0x7fffffff, v107
	v_and_b32_e32 v106, 0x7fffffff, v106
	v_and_b32_e32 v109, 0x7fffffff, v109
	v_and_b32_e32 v108, 0x7fffffff, v108
	v_and_b32_e32 v111, 0x7fffffff, v111
	v_and_b32_e32 v110, 0x7fffffff, v110
	s_xor_b32 s79, s24, 0x80000000
	s_xor_b32 s78, s97, 0x80000000
	s_xor_b32 s81, s43, 0x80000000
	s_xor_b32 s80, s3, 0x80000000
	s_xor_b32 s83, s8, 0x80000000
	s_xor_b32 s82, s51, 0x80000000
	s_xor_b32 s85, s50, 0x80000000
	s_xor_b32 s84, s49, 0x80000000
	s_xor_b32 s87, s48, 0x80000000
	s_xor_b32 s86, s41, 0x80000000
	s_xor_b32 s89, s40, 0x80000000
	s_xor_b32 s88, s39, 0x80000000
	s_xor_b32 s91, s38, 0x80000000
	s_xor_b32 s90, s22, 0x80000000
	v_and_b32_e32 v112, 0x7fffffff, v96
	v_and_b32_e32 v113, 0x7fffffff, v97
	v_fma_f32 v94, s78, v110, v94
	v_fma_f32 v95, s79, v111, v95
	v_fma_f32 v92, s80, v108, v92
	v_fma_f32 v93, s81, v109, v93
	v_fma_f32 v90, s82, v106, v90
	v_fma_f32 v91, s83, v107, v91
	v_fma_f32 v88, s84, v104, v88
	v_fma_f32 v89, s85, v105, v89
	v_fma_f32 v86, s86, v102, v86
	v_fma_f32 v87, s87, v103, v87
	v_fma_f32 v84, s88, v100, v84
	v_fma_f32 v85, s89, v101, v85
	v_fma_f32 v82, s90, v98, v82
	v_fma_f32 v83, s91, v99, v83
	v_add_f32_e32 v98, s54, v96
	v_add_f32_e32 v99, s55, v96
	v_add_f32_e32 v100, s56, v96
	v_add_f32_e32 v101, s57, v96
	v_add_f32_e32 v102, s58, v96
	v_add_f32_e32 v103, s59, v96
	v_add_f32_e32 v104, s60, v96
	v_add_f32_e32 v105, s61, v96
	v_add_f32_e32 v106, s62, v96
	v_add_f32_e32 v107, s63, v96
	v_add_f32_e32 v108, s64, v96
	v_add_f32_e32 v109, s65, v96
	v_add_f32_e32 v110, s66, v96
	v_add_f32_e32 v111, s67, v96
	v_add_f32_e32 v97, s75, v96
	v_add_f32_e32 v96, s74, v96
	v_and_b32_e32 v97, 0x7fffffff, v97
	v_and_b32_e32 v96, 0x7fffffff, v96
	v_and_b32_e32 v111, 0x7fffffff, v111
	v_and_b32_e32 v110, 0x7fffffff, v110
	v_and_b32_e32 v109, 0x7fffffff, v109
	v_and_b32_e32 v108, 0x7fffffff, v108
	v_and_b32_e32 v107, 0x7fffffff, v107
	v_and_b32_e32 v106, 0x7fffffff, v106
	v_and_b32_e32 v105, 0x7fffffff, v105
	v_and_b32_e32 v104, 0x7fffffff, v104
	v_and_b32_e32 v103, 0x7fffffff, v103
	v_and_b32_e32 v102, 0x7fffffff, v102
	v_and_b32_e32 v101, 0x7fffffff, v101
	v_and_b32_e32 v100, 0x7fffffff, v100
	v_and_b32_e32 v99, 0x7fffffff, v99
	v_and_b32_e32 v98, 0x7fffffff, v98
	v_fma_f32 v80, -s76, v112, v80
	v_fma_f32 v81, -s77, v113, v81
	v_fma_f32 v78, s78, v98, v78
	v_fma_f32 v79, s79, v99, v79
	v_fma_f32 v76, s80, v100, v76
	v_fma_f32 v77, s81, v101, v77
	v_fma_f32 v74, s82, v102, v74
	v_fma_f32 v75, s83, v103, v75
	v_fma_f32 v72, s84, v104, v72
	v_fma_f32 v73, s85, v105, v73
	v_fma_f32 v70, s86, v106, v70
	v_fma_f32 v71, s87, v107, v71
	v_fma_f32 v68, s88, v108, v68
	v_fma_f32 v69, s89, v109, v69
	v_fma_f32 v66, s90, v110, v66
	v_fma_f32 v67, s91, v111, v67
	v_fma_f32 v64, -s76, v96, v64
	v_fma_f32 v65, -s77, v97, v65
	v_mov_b32_e32 v97, 0
	v_mov_b32_e32 v98, 0
.LBB0_911:
	v_max_f32_e32 v96, v81, v81
	v_max_f32_e32 v99, v80, v80
	v_max_f32_e32 v96, v99, v96
	v_max_f32_e32 v99, v65, v65
	v_max_f32_e32 v100, v64, v64
	v_max_f32_e32 v99, v100, v99
	v_max3_f32 v96, v96, v82, v83
	v_max3_f32 v99, v99, v66, v67
	v_max3_f32 v96, v96, v84, v85
	v_max3_f32 v99, v99, v68, v69
	v_max3_f32 v96, v96, v86, v87
	v_max3_f32 v99, v99, v70, v71
	v_max3_f32 v96, v96, v88, v89
	v_max3_f32 v99, v99, v72, v73
	v_max3_f32 v96, v96, v90, v91
	v_max3_f32 v99, v99, v74, v75
	v_max3_f32 v96, v96, v92, v93
	v_max3_f32 v99, v99, v76, v77
	v_max3_f32 v96, v96, v94, v95
	v_max3_f32 v99, v99, v78, v79
	v_add_f32_e32 v96, v97, v96
	v_add_f32_e32 v99, v98, v99
	v_max_f32_e32 v96, v96, v99
	v_mov_b32_e32 v99, v96
	s_nop 1
	v_permlane32_swap_b32_e32 v96, v99
	v_max_f32_e32 v99, v99, v99
	v_max_f32_e32 v96, v96, v96
	v_max_f32_e32 v96, v96, v99
	v_sub_f32_e32 v99, v96, v174
	v_cmp_gt_f32_e32 vcc, s18, v99
	s_cmp_lg_u64 vcc, exec
	s_cselect_b64 s[78:79], -1, 0
	s_cmp_eq_u64 vcc, exec
	s_cbranch_scc1 .LBB0_915
	v_max_f32_e32 v96, v96, v96
	v_max_f32_e32 v99, v174, v174
	v_max_f32_e32 v203, v99, v96
	v_sub_f32_e32 v96, v174, v203
	v_exp_f32_e32 v96, v96
	s_nop 0
	v_cmp_neq_f32_e32 vcc, 1.0, v96
	s_cbranch_vccz .LBB0_914
	v_mul_f32_e32 v30, v30, v96
	v_mul_f32_e32 v31, v31, v96
	v_mul_f32_e32 v28, v28, v96
	v_mul_f32_e32 v29, v29, v96
	v_mul_f32_e32 v26, v26, v96
	v_mul_f32_e32 v27, v27, v96
	v_mul_f32_e32 v24, v24, v96
	v_mul_f32_e32 v25, v25, v96
	v_mul_f32_e32 v22, v22, v96
	v_mul_f32_e32 v23, v23, v96
	v_mul_f32_e32 v20, v20, v96
	v_mul_f32_e32 v21, v21, v96
	v_mul_f32_e32 v18, v18, v96
	v_mul_f32_e32 v19, v19, v96
	v_mul_f32_e32 v16, v16, v96
	v_mul_f32_e32 v17, v17, v96
	v_mul_f32_e32 v62, v62, v96
	v_mul_f32_e32 v63, v63, v96
	v_mul_f32_e32 v60, v60, v96
	v_mul_f32_e32 v61, v61, v96
	v_mul_f32_e32 v58, v58, v96
	v_mul_f32_e32 v59, v59, v96
	v_mul_f32_e32 v56, v56, v96
	v_mul_f32_e32 v57, v57, v96
	v_mul_f32_e32 v54, v54, v96
	v_mul_f32_e32 v55, v55, v96
	v_mul_f32_e32 v52, v52, v96
	v_mul_f32_e32 v53, v53, v96
	v_mul_f32_e32 v50, v50, v96
	v_mul_f32_e32 v51, v51, v96
	v_mul_f32_e32 v48, v48, v96
	v_mul_f32_e32 v49, v49, v96
	v_mul_f32_e32 v46, v46, v96
	v_mul_f32_e32 v47, v47, v96
	v_mul_f32_e32 v44, v44, v96
	v_mul_f32_e32 v45, v45, v96
	v_mul_f32_e32 v42, v42, v96
	v_mul_f32_e32 v43, v43, v96
	v_mul_f32_e32 v40, v40, v96
	v_mul_f32_e32 v41, v41, v96
	v_mul_f32_e32 v38, v38, v96
	v_mul_f32_e32 v39, v39, v96
	v_mul_f32_e32 v36, v36, v96
	v_mul_f32_e32 v37, v37, v96
	v_mul_f32_e32 v34, v34, v96
	v_mul_f32_e32 v35, v35, v96
	v_mul_f32_e32 v32, v32, v96
	v_mul_f32_e32 v33, v33, v96
	v_mul_f32_e32 v14, v14, v96
	v_mul_f32_e32 v15, v15, v96
	v_mul_f32_e32 v12, v12, v96
	v_mul_f32_e32 v13, v13, v96
	v_mul_f32_e32 v10, v10, v96
	v_mul_f32_e32 v11, v11, v96
	v_mul_f32_e32 v8, v8, v96
	v_mul_f32_e32 v9, v9, v96
	v_mul_f32_e32 v6, v6, v96
	v_mul_f32_e32 v7, v7, v96
	v_mul_f32_e32 v4, v4, v96
	v_mul_f32_e32 v5, v5, v96
	v_mul_f32_e32 v2, v2, v96
	v_mul_f32_e32 v3, v3, v96
	v_mul_f32_e32 v0, v0, v96
	v_mul_f32_e32 v1, v1, v96

.LBB0_928:
	s_andn2_b64 vcc, exec, s[6:7]
	s_cbranch_vccnz .LBB0_930
	v_add_u32_e32 v129, -1, v129
	v_cvt_f32_i32_e32 v129, v129
	s_xor_b32 s83, s24, 0x80000000
	s_xor_b32 s82, s97, 0x80000000
	s_xor_b32 s85, s43, 0x80000000
	v_add_f32_e32 v130, s10, v128
	v_add_f32_e32 v131, s11, v128
	v_add_f32_e32 v132, s12, v128
	v_add_f32_e32 v133, s13, v128
	v_add_f32_e32 v134, s14, v128
	v_add_f32_e32 v135, s15, v128
	v_add_f32_e32 v136, s36, v128
	v_add_f32_e32 v137, s37, v128
	v_add_f32_e32 v138, s44, v128
	v_add_f32_e32 v139, s45, v128
	v_add_f32_e32 v140, s46, v128
	v_add_f32_e32 v141, s47, v128
	v_add_f32_e32 v142, s52, v128
	v_add_f32_e32 v143, s53, v128
	v_and_b32_e32 v131, 0x7fffffff, v131
	v_and_b32_e32 v130, 0x7fffffff, v130
	v_and_b32_e32 v133, 0x7fffffff, v133
	v_and_b32_e32 v132, 0x7fffffff, v132
	v_and_b32_e32 v135, 0x7fffffff, v135
	v_and_b32_e32 v134, 0x7fffffff, v134
	v_and_b32_e32 v137, 0x7fffffff, v137
	v_and_b32_e32 v136, 0x7fffffff, v136
	v_and_b32_e32 v139, 0x7fffffff, v139
	v_and_b32_e32 v138, 0x7fffffff, v138
	v_and_b32_e32 v141, 0x7fffffff, v141
	v_and_b32_e32 v140, 0x7fffffff, v140
	v_and_b32_e32 v143, 0x7fffffff, v143
	v_and_b32_e32 v142, 0x7fffffff, v142
	s_xor_b32 s84, s3, 0x80000000
	s_xor_b32 s87, s8, 0x80000000
	s_xor_b32 s86, s51, 0x80000000
	s_xor_b32 s89, s50, 0x80000000
	s_xor_b32 s88, s49, 0x80000000
	s_xor_b32 s91, s48, 0x80000000
	s_xor_b32 s90, s41, 0x80000000
	s_xor_b32 s93, s40, 0x80000000
	s_xor_b32 s92, s39, 0x80000000
	s_xor_b32 s95, s38, 0x80000000
	s_xor_b32 s94, s22, 0x80000000
	v_and_b32_e32 v168, 0x7fffffff, v128
	v_and_b32_e32 v169, 0x7fffffff, v129
	v_fma_f32 v126, s82, v142, v126
	v_fma_f32 v127, s83, v143, v127
	v_fma_f32 v124, s84, v140, v124
	v_fma_f32 v125, s85, v141, v125
	v_fma_f32 v122, s86, v138, v122
	v_fma_f32 v123, s87, v139, v123
	v_fma_f32 v120, s88, v136, v120
	v_fma_f32 v121, s89, v137, v121
	v_fma_f32 v118, s90, v134, v118
	v_fma_f32 v119, s91, v135, v119
	v_fma_f32 v116, s92, v132, v116
	v_fma_f32 v117, s93, v133, v117
	v_fma_f32 v114, s94, v130, v114
	v_fma_f32 v115, s95, v131, v115
	v_add_f32_e32 v130, s54, v128
	v_add_f32_e32 v131, s55, v128
	v_add_f32_e32 v132, s56, v128
	v_add_f32_e32 v133, s57, v128
	v_add_f32_e32 v134, s58, v128
	v_add_f32_e32 v135, s59, v128
	v_add_f32_e32 v136, s60, v128
	v_add_f32_e32 v137, s61, v128
	v_add_f32_e32 v138, s62, v128
	v_add_f32_e32 v139, s63, v128
	v_add_f32_e32 v140, s64, v128
	v_add_f32_e32 v141, s65, v128
	v_add_f32_e32 v142, s66, v128
	v_add_f32_e32 v143, s67, v128
	v_add_f32_e32 v129, s75, v128
	v_add_f32_e32 v128, s74, v128
	v_and_b32_e32 v129, 0x7fffffff, v129
	v_and_b32_e32 v128, 0x7fffffff, v128
	v_and_b32_e32 v143, 0x7fffffff, v143
	v_and_b32_e32 v142, 0x7fffffff, v142
	v_and_b32_e32 v141, 0x7fffffff, v141
	v_and_b32_e32 v140, 0x7fffffff, v140
	v_and_b32_e32 v139, 0x7fffffff, v139
	v_and_b32_e32 v138, 0x7fffffff, v138
	v_and_b32_e32 v137, 0x7fffffff, v137
	v_and_b32_e32 v136, 0x7fffffff, v136
	v_and_b32_e32 v135, 0x7fffffff, v135
	v_and_b32_e32 v134, 0x7fffffff, v134
	v_and_b32_e32 v133, 0x7fffffff, v133
	v_and_b32_e32 v132, 0x7fffffff, v132
	v_and_b32_e32 v131, 0x7fffffff, v131
	v_and_b32_e32 v130, 0x7fffffff, v130
	v_fma_f32 v112, -s76, v168, v112
	v_fma_f32 v113, -s77, v169, v113
	v_fma_f32 v110, s82, v130, v110
	v_fma_f32 v111, s83, v131, v111
	v_fma_f32 v108, s84, v132, v108
	v_fma_f32 v109, s85, v133, v109
	v_fma_f32 v106, s86, v134, v106
	v_fma_f32 v107, s87, v135, v107
	v_fma_f32 v104, s88, v136, v104
	v_fma_f32 v105, s89, v137, v105
	v_fma_f32 v102, s90, v138, v102
	v_fma_f32 v103, s91, v139, v103
	v_fma_f32 v100, s92, v140, v100
	v_fma_f32 v101, s93, v141, v101
	v_fma_f32 v98, s94, v142, v98
	v_fma_f32 v99, s95, v143, v99
	v_fma_f32 v96, -s76, v128, v96
	v_fma_f32 v97, -s77, v129, v97
	v_mov_b32_e32 v130, 0
	v_mov_b32_e32 v131, 0
.LBB0_930:
	v_max_f32_e32 v128, v113, v113
	v_max_f32_e32 v129, v112, v112
	v_max_f32_e32 v128, v129, v128
	v_max_f32_e32 v129, v97, v97
	v_max_f32_e32 v132, v96, v96
	v_max_f32_e32 v129, v132, v129
	v_max3_f32 v128, v128, v114, v115
	v_max3_f32 v129, v129, v98, v99
	v_max3_f32 v128, v128, v116, v117
	v_max3_f32 v129, v129, v100, v101
	v_max3_f32 v128, v128, v118, v119
	v_max3_f32 v129, v129, v102, v103
	v_max3_f32 v128, v128, v120, v121
	v_max3_f32 v129, v129, v104, v105
	v_max3_f32 v128, v128, v122, v123
	v_max3_f32 v129, v129, v106, v107
	v_max3_f32 v128, v128, v124, v125
	v_max3_f32 v129, v129, v108, v109
	v_max3_f32 v128, v128, v126, v127
	v_max3_f32 v129, v129, v110, v111
	v_add_f32_e32 v128, v130, v128
	v_add_f32_e32 v129, v131, v129
	v_max_f32_e32 v128, v128, v129
	v_mov_b32_e32 v129, v128
	s_nop 1
	v_permlane32_swap_b32_e32 v128, v129
	v_max_f32_e32 v129, v129, v129
	v_max_f32_e32 v128, v128, v128
	v_max_f32_e32 v128, v128, v129
	v_sub_f32_e32 v129, v128, v203
	v_cmp_gt_f32_e32 vcc, s18, v129
	s_cmp_lg_u64 vcc, exec
	s_cselect_b64 s[82:83], -1, 0
	s_cmp_eq_u64 vcc, exec
	s_cbranch_scc1 .LBB0_934
	v_max_f32_e32 v128, v128, v128
	v_max_f32_e32 v129, v203, v203
	v_max_f32_e32 v129, v129, v128
	v_sub_f32_e32 v128, v203, v129
	v_exp_f32_e32 v128, v128
	s_nop 0
	v_cmp_neq_f32_e32 vcc, 1.0, v128
	s_cbranch_vccz .LBB0_933
	v_mul_f32_e32 v30, v30, v128
	v_mul_f32_e32 v31, v31, v128
	v_mul_f32_e32 v28, v28, v128
	v_mul_f32_e32 v29, v29, v128
	v_mul_f32_e32 v26, v26, v128
	v_mul_f32_e32 v27, v27, v128
	v_mul_f32_e32 v24, v24, v128
	v_mul_f32_e32 v25, v25, v128
	v_mul_f32_e32 v22, v22, v128
	v_mul_f32_e32 v23, v23, v128
	v_mul_f32_e32 v20, v20, v128
	v_mul_f32_e32 v21, v21, v128
	v_mul_f32_e32 v18, v18, v128
	v_mul_f32_e32 v19, v19, v128
	v_mul_f32_e32 v16, v16, v128
	v_mul_f32_e32 v17, v17, v128
	v_mul_f32_e32 v62, v62, v128
	v_mul_f32_e32 v63, v63, v128
	v_mul_f32_e32 v60, v60, v128
	v_mul_f32_e32 v61, v61, v128
	v_mul_f32_e32 v58, v58, v128
	v_mul_f32_e32 v59, v59, v128
	v_mul_f32_e32 v56, v56, v128
	v_mul_f32_e32 v57, v57, v128
	v_mul_f32_e32 v54, v54, v128
	v_mul_f32_e32 v55, v55, v128
	v_mul_f32_e32 v52, v52, v128
	v_mul_f32_e32 v53, v53, v128
	v_mul_f32_e32 v50, v50, v128
	v_mul_f32_e32 v51, v51, v128
	v_mul_f32_e32 v48, v48, v128
	v_mul_f32_e32 v49, v49, v128
	v_mul_f32_e32 v46, v46, v128
	v_mul_f32_e32 v47, v47, v128
	v_mul_f32_e32 v44, v44, v128
	v_mul_f32_e32 v45, v45, v128
	v_mul_f32_e32 v42, v42, v128
	v_mul_f32_e32 v43, v43, v128
	v_mul_f32_e32 v40, v40, v128
	v_mul_f32_e32 v41, v41, v128
	v_mul_f32_e32 v38, v38, v128
	v_mul_f32_e32 v39, v39, v128
	v_mul_f32_e32 v36, v36, v128
	v_mul_f32_e32 v37, v37, v128
	v_mul_f32_e32 v34, v34, v128
	v_mul_f32_e32 v35, v35, v128
	v_mul_f32_e32 v32, v32, v128
	v_mul_f32_e32 v33, v33, v128
	v_mul_f32_e32 v14, v14, v128
	v_mul_f32_e32 v15, v15, v128
	v_mul_f32_e32 v12, v12, v128
	v_mul_f32_e32 v13, v13, v128
	v_mul_f32_e32 v10, v10, v128
	v_mul_f32_e32 v11, v11, v128
	v_mul_f32_e32 v8, v8, v128
	v_mul_f32_e32 v9, v9, v128
	v_mul_f32_e32 v6, v6, v128
	v_mul_f32_e32 v7, v7, v128
	v_mul_f32_e32 v4, v4, v128
	v_mul_f32_e32 v5, v5, v128
	v_mul_f32_e32 v2, v2, v128
	v_mul_f32_e32 v3, v3, v128
	v_mul_f32_e32 v0, v0, v128
	v_mul_f32_e32 v1, v1, v128

.LBB0_942:
	s_andn2_b64 vcc, exec, s[6:7]
	s_cbranch_vccnz .LBB0_944
	v_add_u32_e32 v97, -1, v99
	v_cvt_f32_i32_e32 v97, v97
	s_xor_b32 s79, s24, 0x80000000
	s_xor_b32 s78, s97, 0x80000000
	s_xor_b32 s81, s43, 0x80000000
	v_add_f32_e32 v98, s10, v96
	v_add_f32_e32 v99, s11, v96
	v_add_f32_e32 v100, s12, v96
	v_add_f32_e32 v101, s13, v96
	v_add_f32_e32 v102, s14, v96
	v_add_f32_e32 v103, s15, v96
	v_add_f32_e32 v104, s36, v96
	v_add_f32_e32 v105, s37, v96
	v_add_f32_e32 v106, s44, v96
	v_add_f32_e32 v107, s45, v96
	v_add_f32_e32 v108, s46, v96
	v_add_f32_e32 v109, s47, v96
	v_add_f32_e32 v110, s52, v96
	v_add_f32_e32 v111, s53, v96
	v_and_b32_e32 v99, 0x7fffffff, v99
	v_and_b32_e32 v98, 0x7fffffff, v98
	v_and_b32_e32 v101, 0x7fffffff, v101
	v_and_b32_e32 v100, 0x7fffffff, v100
	v_and_b32_e32 v103, 0x7fffffff, v103
	v_and_b32_e32 v102, 0x7fffffff, v102
	v_and_b32_e32 v105, 0x7fffffff, v105
	v_and_b32_e32 v104, 0x7fffffff, v104
	v_and_b32_e32 v107, 0x7fffffff, v107
	v_and_b32_e32 v106, 0x7fffffff, v106
	v_and_b32_e32 v109, 0x7fffffff, v109
	v_and_b32_e32 v108, 0x7fffffff, v108
	v_and_b32_e32 v111, 0x7fffffff, v111
	v_and_b32_e32 v110, 0x7fffffff, v110
	s_xor_b32 s80, s3, 0x80000000
	s_xor_b32 s83, s8, 0x80000000
	s_xor_b32 s82, s51, 0x80000000
	s_xor_b32 s85, s50, 0x80000000
	s_xor_b32 s84, s49, 0x80000000
	s_xor_b32 s87, s48, 0x80000000
	s_xor_b32 s86, s41, 0x80000000
	s_xor_b32 s89, s40, 0x80000000
	s_xor_b32 s88, s39, 0x80000000
	s_xor_b32 s91, s38, 0x80000000
	s_xor_b32 s90, s22, 0x80000000
	v_and_b32_e32 v112, 0x7fffffff, v96
	v_and_b32_e32 v113, 0x7fffffff, v97
	v_fma_f32 v94, s78, v110, v94
	v_fma_f32 v95, s79, v111, v95
	v_fma_f32 v92, s80, v108, v92
	v_fma_f32 v93, s81, v109, v93
	v_fma_f32 v90, s82, v106, v90
	v_fma_f32 v91, s83, v107, v91
	v_fma_f32 v88, s84, v104, v88
	v_fma_f32 v89, s85, v105, v89
	v_fma_f32 v86, s86, v102, v86
	v_fma_f32 v87, s87, v103, v87
	v_fma_f32 v84, s88, v100, v84
	v_fma_f32 v85, s89, v101, v85
	v_fma_f32 v82, s90, v98, v82
	v_fma_f32 v83, s91, v99, v83
	v_add_f32_e32 v98, s54, v96
	v_add_f32_e32 v99, s55, v96
	v_add_f32_e32 v100, s56, v96
	v_add_f32_e32 v101, s57, v96
	v_add_f32_e32 v102, s58, v96
	v_add_f32_e32 v103, s59, v96
	v_add_f32_e32 v104, s60, v96
	v_add_f32_e32 v105, s61, v96
	v_add_f32_e32 v106, s62, v96
	v_add_f32_e32 v107, s63, v96
	v_add_f32_e32 v108, s64, v96
	v_add_f32_e32 v109, s65, v96
	v_add_f32_e32 v110, s66, v96
	v_add_f32_e32 v111, s67, v96
	v_add_f32_e32 v97, s75, v96
	v_add_f32_e32 v96, s74, v96
	v_and_b32_e32 v97, 0x7fffffff, v97
	v_and_b32_e32 v96, 0x7fffffff, v96
	v_and_b32_e32 v111, 0x7fffffff, v111
	v_and_b32_e32 v110, 0x7fffffff, v110
	v_and_b32_e32 v109, 0x7fffffff, v109
	v_and_b32_e32 v108, 0x7fffffff, v108
	v_and_b32_e32 v107, 0x7fffffff, v107
	v_and_b32_e32 v106, 0x7fffffff, v106
	v_and_b32_e32 v105, 0x7fffffff, v105
	v_and_b32_e32 v104, 0x7fffffff, v104
	v_and_b32_e32 v103, 0x7fffffff, v103
	v_and_b32_e32 v102, 0x7fffffff, v102
	v_and_b32_e32 v101, 0x7fffffff, v101
	v_and_b32_e32 v100, 0x7fffffff, v100
	v_and_b32_e32 v99, 0x7fffffff, v99
	v_and_b32_e32 v98, 0x7fffffff, v98
	v_fma_f32 v80, -s76, v112, v80
	v_fma_f32 v81, -s77, v113, v81
	v_fma_f32 v78, s78, v98, v78
	v_fma_f32 v79, s79, v99, v79
	v_fma_f32 v76, s80, v100, v76
	v_fma_f32 v77, s81, v101, v77
	v_fma_f32 v74, s82, v102, v74
	v_fma_f32 v75, s83, v103, v75
	v_fma_f32 v72, s84, v104, v72
	v_fma_f32 v73, s85, v105, v73
	v_fma_f32 v70, s86, v106, v70
	v_fma_f32 v71, s87, v107, v71
	v_fma_f32 v68, s88, v108, v68
	v_fma_f32 v69, s89, v109, v69
	v_fma_f32 v66, s90, v110, v66
	v_fma_f32 v67, s91, v111, v67
	v_fma_f32 v64, -s76, v96, v64
	v_fma_f32 v65, -s77, v97, v65
	v_mov_b32_e32 v97, 0
	v_mov_b32_e32 v98, 0
.LBB0_944:
	v_max_f32_e32 v96, v81, v81
	v_max_f32_e32 v99, v80, v80
	v_max_f32_e32 v96, v99, v96
	v_max_f32_e32 v99, v65, v65
	v_max_f32_e32 v100, v64, v64
	v_max_f32_e32 v99, v100, v99
	v_max3_f32 v96, v96, v82, v83
	v_max3_f32 v99, v99, v66, v67
	v_max3_f32 v96, v96, v84, v85
	v_max3_f32 v99, v99, v68, v69
	v_max3_f32 v96, v96, v86, v87
	v_max3_f32 v99, v99, v70, v71
	v_max3_f32 v96, v96, v88, v89
	v_max3_f32 v99, v99, v72, v73
	v_max3_f32 v96, v96, v90, v91
	v_max3_f32 v99, v99, v74, v75
	v_max3_f32 v96, v96, v92, v93
	v_max3_f32 v99, v99, v76, v77
	v_max3_f32 v96, v96, v94, v95
	v_max3_f32 v99, v99, v78, v79
	v_add_f32_e32 v96, v97, v96
	v_add_f32_e32 v99, v98, v99
	v_max_f32_e32 v96, v96, v99
	v_mov_b32_e32 v99, v96
	s_nop 1
	v_permlane32_swap_b32_e32 v96, v99
	v_max_f32_e32 v99, v99, v99
	v_max_f32_e32 v96, v96, v96
	v_max_f32_e32 v96, v96, v99
	v_sub_f32_e32 v99, v96, v129
	v_cmp_gt_f32_e32 vcc, s18, v99
	v_readlane_b32 s48, v255, 6
	s_cmp_lg_u64 vcc, exec
	v_readlane_b32 s49, v255, 7
	v_readlane_b32 s50, v255, 8
	v_readlane_b32 s51, v255, 9
	s_cselect_b64 s[76:77], -1, 0
	s_cmp_eq_u64 vcc, exec
	s_cbranch_scc1 .LBB0_948
	v_max_f32_e32 v96, v96, v96
	v_max_f32_e32 v99, v129, v129
	v_max_f32_e32 v99, v99, v96
	v_sub_f32_e32 v96, v129, v99
	v_exp_f32_e32 v96, v96
	s_nop 0
	v_cmp_neq_f32_e32 vcc, 1.0, v96
	s_cbranch_vccz .LBB0_947
	v_mul_f32_e32 v30, v30, v96
	v_mul_f32_e32 v31, v31, v96
	v_mul_f32_e32 v28, v28, v96
	v_mul_f32_e32 v29, v29, v96
	v_mul_f32_e32 v26, v26, v96
	v_mul_f32_e32 v27, v27, v96
	v_mul_f32_e32 v24, v24, v96
	v_mul_f32_e32 v25, v25, v96
	v_mul_f32_e32 v22, v22, v96
	v_mul_f32_e32 v23, v23, v96
	v_mul_f32_e32 v20, v20, v96
	v_mul_f32_e32 v21, v21, v96
	v_mul_f32_e32 v18, v18, v96
	v_mul_f32_e32 v19, v19, v96
	v_mul_f32_e32 v16, v16, v96
	v_mul_f32_e32 v17, v17, v96
	v_mul_f32_e32 v62, v62, v96
	v_mul_f32_e32 v63, v63, v96
	v_mul_f32_e32 v60, v60, v96
	v_mul_f32_e32 v61, v61, v96
	v_mul_f32_e32 v58, v58, v96
	v_mul_f32_e32 v59, v59, v96
	v_mul_f32_e32 v56, v56, v96
	v_mul_f32_e32 v57, v57, v96
	v_mul_f32_e32 v54, v54, v96
	v_mul_f32_e32 v55, v55, v96
	v_mul_f32_e32 v52, v52, v96
	v_mul_f32_e32 v53, v53, v96
	v_mul_f32_e32 v50, v50, v96
	v_mul_f32_e32 v51, v51, v96
	v_mul_f32_e32 v48, v48, v96
	v_mul_f32_e32 v49, v49, v96
	v_mul_f32_e32 v46, v46, v96
	v_mul_f32_e32 v47, v47, v96
	v_mul_f32_e32 v44, v44, v96
	v_mul_f32_e32 v45, v45, v96
	v_mul_f32_e32 v42, v42, v96
	v_mul_f32_e32 v43, v43, v96
	v_mul_f32_e32 v40, v40, v96
	v_mul_f32_e32 v41, v41, v96
	v_mul_f32_e32 v38, v38, v96
	v_mul_f32_e32 v39, v39, v96
	v_mul_f32_e32 v36, v36, v96
	v_mul_f32_e32 v37, v37, v96
	v_mul_f32_e32 v34, v34, v96
	v_mul_f32_e32 v35, v35, v96
	v_mul_f32_e32 v32, v32, v96
	v_mul_f32_e32 v33, v33, v96
	v_mul_f32_e32 v14, v14, v96
	v_mul_f32_e32 v15, v15, v96
	v_mul_f32_e32 v12, v12, v96
	v_mul_f32_e32 v13, v13, v96
	v_mul_f32_e32 v10, v10, v96
	v_mul_f32_e32 v11, v11, v96
	v_mul_f32_e32 v8, v8, v96
	v_mul_f32_e32 v9, v9, v96
	v_mul_f32_e32 v6, v6, v96
	v_mul_f32_e32 v7, v7, v96
	v_mul_f32_e32 v4, v4, v96
	v_mul_f32_e32 v5, v5, v96
	v_mul_f32_e32 v2, v2, v96
	v_mul_f32_e32 v3, v3, v96
	v_mul_f32_e32 v0, v0, v96
	v_mul_f32_e32 v1, v1, v96

; __device__ __forceinline__ float xhalf_sum(float m) { auto rr = __builtin_amdgcn_permlane32_swap(__float_as_uint(m), __float_as_uint(m), false, false); return __uint_as_float(rr[0]) + __uint_as_float(rr[1]); }
; template <bool SWA>
; __device__ __forceinline__ void unit(LAS unsigned char* lds, const bf16_t* PROJ, const bf16_t* KT, const bf16_t* VT, bf16_t* OB, int opitch, int ocol, int b, int head, int qb, float slope2, float m_init, float lam, const float* subg) {
;     ...
;         if (c == 0) {
;             float ssq = 0.f;
; #pragma unroll
;             for (int db = 0; db < NDB; ++db)
; #pragma unroll
;                 for (int i = 0; i < 16; ++i) { const float v = o[db][i] * inv - lam * xb[(db * 16 + i) * 64]; o[db][i] = v; ssq += v * v; }
;             ssq = xhalf_sum(ssq);
;             const float rs = __builtin_amdgcn_rsqf(ssq * (1.0f / 128.0f) + RMS_EPS) * 0.8f;
.LBB0_952:
	s_cmpk_gt_u32 s9, 0xff
	s_waitcnt lgkmcnt(0)
	s_barrier
	s_cbranch_scc1 .LBB0_844
	ds_read2st64_b32 v[66:67], v64 offset1:1
	ds_read2st64_b32 v[72:73], v64 offset0:2 offset1:3
	ds_read2st64_b32 v[84:85], v64 offset0:4 offset1:5
	ds_read2st64_b32 v[82:83], v64 offset0:6 offset1:7
	ds_read2st64_b32 v[92:93], v64 offset0:8 offset1:9
	ds_read2st64_b32 v[88:89], v64 offset0:10 offset1:11
	ds_read2st64_b32 v[102:103], v64 offset0:12 offset1:13
	ds_read2st64_b32 v[104:105], v64 offset0:14 offset1:15
	ds_read2st64_b32 v[108:109], v64 offset0:16 offset1:17
	ds_read2st64_b32 v[112:113], v64 offset0:18 offset1:19
	ds_read2st64_b32 v[116:117], v64 offset0:20 offset1:21
	ds_read2st64_b32 v[120:121], v64 offset0:22 offset1:23
	ds_read2st64_b32 v[124:125], v64 offset0:24 offset1:25
	ds_read2st64_b32 v[130:131], v64 offset0:26 offset1:27
	ds_read2st64_b32 v[128:129], v64 offset0:28 offset1:29
	ds_read2st64_b32 v[132:133], v64 offset0:30 offset1:31
	ds_read2st64_b32 v[122:123], v64 offset0:32 offset1:33
	ds_read2st64_b32 v[126:127], v64 offset0:34 offset1:35
	ds_read2st64_b32 v[114:115], v64 offset0:36 offset1:37
	ds_read2st64_b32 v[118:119], v64 offset0:38 offset1:39
	ds_read2st64_b32 v[106:107], v64 offset0:40 offset1:41
	ds_read2st64_b32 v[110:111], v64 offset0:42 offset1:43
	ds_read2st64_b32 v[94:95], v64 offset0:44 offset1:45
	ds_read2st64_b32 v[98:99], v64 offset0:46 offset1:47
	ds_read2st64_b32 v[78:79], v64 offset0:56 offset1:57
	ds_read2st64_b32 v[80:81], v64 offset0:58 offset1:59
	ds_read2st64_b32 v[74:75], v64 offset0:60 offset1:61
	ds_read2st64_b32 v[70:71], v64 offset0:62 offset1:63
	ds_read2st64_b32 v[96:97], v64 offset0:48 offset1:49
	ds_read2st64_b32 v[100:101], v64 offset0:50 offset1:51
	ds_read2st64_b32 v[86:87], v64 offset0:52 offset1:53
	ds_read2st64_b32 v[90:91], v64 offset0:54 offset1:55
	s_waitcnt lgkmcnt(4)
	v_mul_f32_e32 v64, v162, v70
	v_mul_f32_e32 v65, v163, v71
	v_readlane_b32 s0, v255, 10
	v_fma_f32 v70, v14, v68, -v64
	v_fma_f32 v71, v15, v68, -v65
	v_mul_f32_e32 v82, v162, v82
	v_mul_f32_e32 v83, v163, v83
	v_or_b32_e32 v14, s0, v185
	v_mul_u32_u24_e32 v64, 0x110, v14
	v_mul_f32_e32 v14, v162, v72
	v_mul_f32_e32 v15, v163, v73
	s_add_i32 s0, 0, 0x10000
	v_fma_f32 v72, v18, v68, -v14
	v_fma_f32 v73, v19, v68, -v15
	v_mul_f32_e32 v14, v162, v66
	v_mul_f32_e32 v15, v163, v67
	v_mul_f32_e32 v102, v162, v102
	v_mul_f32_e32 v103, v163, v103
	v_fma_f32 v76, v16, v68, -v14
	v_fma_f32 v77, v17, v68, -v15
	v_add3_u32 v69, s0, v64, v187
	v_mul_f32_e32 v14, v77, v77
	v_fma_f32 v15, v77, v77, v14
	v_fma_f32 v14, v76, v76, v14
	v_mul_f32_e32 v16, v73, v73
	v_fma_f32 v14, v72, v72, v14
	v_fma_f32 v15, v73, v73, v15
	v_fma_f32 v82, v22, v68, -v82
	v_fma_f32 v83, v23, v68, -v83
	v_mul_f32_e32 v22, v162, v84
	v_mul_f32_e32 v23, v163, v85
	v_add_f32_e32 v18, v14, v16
	v_add_f32_e32 v19, v15, v16
	v_fma_f32 v84, v20, v68, -v22
	v_fma_f32 v85, v21, v68, -v23
	v_fma_f32 v102, v28, v68, -v102
	v_fma_f32 v103, v29, v68, -v103
	v_fma_f32 v18, v84, v84, v18
	v_fma_f32 v19, v85, v85, v19
	v_mul_f32_e32 v20, v85, v85
	v_add_f32_e32 v18, v18, v20
	v_add_f32_e32 v19, v19, v20
	v_mul_f32_e32 v20, v83, v83
	v_fma_f32 v18, v82, v82, v18
	v_fma_f32 v19, v83, v83, v19
	v_mul_f32_e32 v104, v162, v104
	v_mul_f32_e32 v105, v163, v105
	v_add_f32_e32 v18, v18, v20
	v_add_f32_e32 v19, v19, v20
	v_mul_f32_e32 v20, v162, v88
	v_mul_f32_e32 v21, v163, v89
	v_mul_f32_e32 v28, v103, v103
	v_fma_f32 v88, v26, v68, -v20
	v_fma_f32 v89, v27, v68, -v21
	v_mul_f32_e32 v20, v162, v92
	v_mul_f32_e32 v21, v163, v93
	v_fma_f32 v30, v30, v68, -v104
	v_fma_f32 v31, v31, v68, -v105
	v_fma_f32 v92, v24, v68, -v20
	v_fma_f32 v93, v25, v68, -v21
	v_mul_f32_e32 v128, v162, v128
	v_mul_f32_e32 v129, v163, v129
	v_fma_f32 v18, v92, v92, v18
	v_fma_f32 v19, v93, v93, v19
	v_mul_f32_e32 v20, v93, v93
	v_add_f32_e32 v18, v18, v20
	v_add_f32_e32 v19, v19, v20
	v_mul_f32_e32 v20, v89, v89
	v_fma_f32 v18, v88, v88, v18
	v_fma_f32 v19, v89, v89, v19
	v_fma_f32 v60, v60, v68, -v128
	v_fma_f32 v61, v61, v68, -v129
	v_add_f32_e32 v26, v18, v20
	v_add_f32_e32 v27, v19, v20
	v_mul_f32_e32 v132, v162, v132
	v_mul_f32_e32 v133, v163, v133
	v_fma_f32 v26, v102, v102, v26
	v_fma_f32 v27, v103, v103, v27
	v_fma_f32 v62, v62, v68, -v132
	v_fma_f32 v63, v63, v68, -v133
	v_add_f32_e32 v26, v26, v28
	v_add_f32_e32 v27, v27, v28
	v_mul_f32_e32 v28, v31, v31
	v_fma_f32 v26, v30, v30, v26
	v_fma_f32 v27, v31, v31, v27
	v_mul_f32_e32 v126, v162, v126
	v_mul_f32_e32 v127, v163, v127
	v_add_f32_e32 v26, v26, v28
	v_add_f32_e32 v27, v27, v28
	v_mul_f32_e32 v28, v162, v112
	v_mul_f32_e32 v29, v163, v113
	v_mul_f32_e32 v112, v162, v120
	v_mul_f32_e32 v113, v163, v121
	v_fma_f32 v104, v50, v68, -v28
	v_fma_f32 v105, v51, v68, -v29
	v_mul_f32_e32 v28, v162, v108
	v_mul_f32_e32 v29, v163, v109
	v_fma_f32 v112, v54, v68, -v112
	v_fma_f32 v113, v55, v68, -v113
	v_fma_f32 v108, v48, v68, -v28
	v_fma_f32 v109, v49, v68, -v29
	v_mul_f32_e32 v54, v162, v116
	v_mul_f32_e32 v55, v163, v117
	v_fma_f32 v26, v108, v108, v26
	v_fma_f32 v27, v109, v109, v27
	v_mul_f32_e32 v28, v109, v109
	v_add_f32_e32 v26, v26, v28
	v_add_f32_e32 v27, v27, v28
	v_mul_f32_e32 v28, v105, v105
	v_fma_f32 v26, v104, v104, v26
	v_fma_f32 v27, v105, v105, v27
	v_fma_f32 v116, v52, v68, -v54
	v_fma_f32 v117, v53, v68, -v55
	v_add_f32_e32 v134, v26, v28
	v_add_f32_e32 v135, v27, v28
	v_mul_f32_e32 v54, v117, v117
	v_fma_f32 v52, v116, v116, v134
	v_fma_f32 v53, v117, v117, v135
	v_mul_f32_e32 v118, v162, v118
	v_mul_f32_e32 v119, v163, v119
	v_add_f32_e32 v52, v52, v54
	v_add_f32_e32 v53, v53, v54
	v_mul_f32_e32 v54, v113, v113
; __device__ __forceinline__ float xhalf_sum(float m) { auto rr = __builtin_amdgcn_permlane32_swap(__float_as_uint(m), __float_as_uint(m), false, false); return __uint_as_float(rr[0]) + __uint_as_float(rr[1]); }
; template <bool SWA>
; __device__ __forceinline__ void unit(LAS unsigned char* lds, const bf16_t* PROJ, const bf16_t* KT, const bf16_t* VT, bf16_t* OB, int opitch, int ocol, int b, int head, int qb, float slope2, float m_init, float lam, const float* subg) {
;     ...
;         if (c == 0) {
;             float ssq = 0.f;
; #pragma unroll
;             for (int db = 0; db < NDB; ++db)
; #pragma unroll
;                 for (int i = 0; i < 16; ++i) { const float v = o[db][i] * inv - lam * xb[(db * 16 + i) * 64]; o[db][i] = v; ssq += v * v; }
;             ssq = xhalf_sum(ssq);
;             const float rs = __builtin_amdgcn_rsqf(ssq * (1.0f / 128.0f) + RMS_EPS) * 0.8f;
; #pragma unroll
;             for (int db = 0; db < NDB; ++db)
; #pragma unroll
;                 for (int g4 = 0; g4 < 4; ++g4) {
;                     const f32x4 gg = *(const f32x4*)(subg + 32 * db + 8 * g4 + 4 * h);
	v_fma_f32 v52, v112, v112, v52
	v_fma_f32 v53, v113, v113, v53
	v_fma_f32 v118, v38, v68, -v118
	v_fma_f32 v119, v39, v68, -v119
	v_add_f32_e32 v52, v52, v54
	v_add_f32_e32 v53, v53, v54
	v_mul_f32_e32 v54, v162, v130
	v_mul_f32_e32 v55, v163, v131
	v_mul_f32_e32 v38, v162, v114
	v_mul_f32_e32 v39, v163, v115
	v_fma_f32 v120, v58, v68, -v54
	v_fma_f32 v121, v59, v68, -v55
	v_mul_f32_e32 v54, v162, v124
	v_mul_f32_e32 v55, v163, v125
	v_fma_f32 v114, v36, v68, -v38
	v_fma_f32 v115, v37, v68, -v39
	v_fma_f32 v124, v56, v68, -v54
	v_fma_f32 v125, v57, v68, -v55
	v_mul_f32_e32 v38, v115, v115
	v_fma_f32 v52, v124, v124, v52
	v_fma_f32 v53, v125, v125, v53
	v_mul_f32_e32 v54, v125, v125
	v_add_f32_e32 v52, v52, v54
	v_add_f32_e32 v53, v53, v54
	v_mul_f32_e32 v54, v121, v121
	v_fma_f32 v52, v120, v120, v52
	v_fma_f32 v53, v121, v121, v53
	v_readlane_b32 s76, v254, 9
	v_add_f32_e32 v130, v52, v54
	v_add_f32_e32 v131, v53, v54
	v_readlane_b32 s78, v254, 11
	v_fma_f32 v128, v60, v60, v130
	v_fma_f32 v129, v61, v61, v131
	v_mul_f32_e32 v130, v61, v61
	v_add_f32_e32 v128, v128, v130
	v_add_f32_e32 v129, v129, v130
	v_mul_f32_e32 v130, v63, v63
	v_fma_f32 v128, v62, v62, v128
	v_fma_f32 v129, v63, v63, v129
	v_readlane_b32 s79, v254, 12
	v_add_f32_e32 v128, v128, v130
	v_add_f32_e32 v129, v129, v130
	v_fma_f32 v130, v34, v68, -v126
	v_fma_f32 v131, v35, v68, -v127
	v_mul_f32_e32 v34, v162, v122
	v_mul_f32_e32 v35, v163, v123
	s_nop 1
	global_load_dwordx4 v[64:67], v166, s[78:79]
	global_load_dwordx4 v[14:17], v166, s[78:79] offset:32
	v_fma_f32 v122, v32, v68, -v34
	v_fma_f32 v123, v33, v68, -v35
	v_mul_f32_e32 v98, v162, v98
	v_mul_f32_e32 v99, v163, v99
	v_fma_f32 v32, v122, v122, v128
	v_fma_f32 v33, v123, v123, v129
	v_mul_f32_e32 v34, v123, v123
	v_add_f32_e32 v32, v32, v34
	v_add_f32_e32 v33, v33, v34
	v_mul_f32_e32 v34, v131, v131
	v_fma_f32 v32, v130, v130, v32
	v_fma_f32 v33, v131, v131, v33
	v_fma_f32 v98, v46, v68, -v98
	v_fma_f32 v99, v47, v68, -v99
	v_add_f32_e32 v132, v32, v34
	v_add_f32_e32 v133, v33, v34
	v_mul_f32_e32 v46, v162, v94
	v_mul_f32_e32 v47, v163, v95
	v_fma_f32 v36, v114, v114, v132
	v_fma_f32 v37, v115, v115, v133
	v_fma_f32 v94, v44, v68, -v46
	v_fma_f32 v95, v45, v68, -v47
	v_add_f32_e32 v36, v36, v38
	v_add_f32_e32 v37, v37, v38
	v_mul_f32_e32 v38, v119, v119
	v_fma_f32 v36, v118, v118, v36
	v_fma_f32 v37, v119, v119, v37
	v_mul_f32_e32 v46, v95, v95
	v_add_f32_e32 v36, v36, v38
	v_add_f32_e32 v37, v37, v38
	v_mul_f32_e32 v38, v162, v110
	v_mul_f32_e32 v39, v163, v111
	global_load_dwordx4 v[22:25], v166, s[78:79] offset:64
	global_load_dwordx4 v[18:21], v166, s[78:79] offset:96
	v_fma_f32 v110, v42, v68, -v38
	v_fma_f32 v111, v43, v68, -v39
	v_mul_f32_e32 v38, v162, v106
	v_mul_f32_e32 v39, v163, v107
	global_load_dwordx4 v[48:51], v166, s[78:79] offset:128
	global_load_dwordx4 v[26:29], v166, s[78:79] offset:160
	v_fma_f32 v106, v40, v68, -v38
	v_fma_f32 v107, v41, v68, -v39
	global_load_dwordx4 v[56:59], v166, s[78:79] offset:192
	global_load_dwordx4 v[52:55], v166, s[78:79] offset:224
	v_fma_f32 v36, v106, v106, v36
	v_fma_f32 v37, v107, v107, v37
	v_mul_f32_e32 v38, v107, v107
	v_add_f32_e32 v36, v36, v38
	v_add_f32_e32 v37, v37, v38
	v_mul_f32_e32 v38, v111, v111
	v_fma_f32 v36, v110, v110, v36
	v_fma_f32 v37, v111, v111, v37
	global_load_dwordx4 v[32:35], v166, s[78:79] offset:256
	global_load_dwordx4 v[126:129], v166, s[78:79] offset:288
	v_add_f32_e32 v132, v36, v38
	v_add_f32_e32 v133, v37, v38
	global_load_dwordx4 v[36:39], v166, s[78:79] offset:320
	global_load_dwordx4 v[40:43], v166, s[78:79] offset:352
	v_fma_f32 v44, v94, v94, v132
	v_fma_f32 v45, v95, v95, v133
	v_readlane_b32 s77, v254, 10
	v_add_f32_e32 v44, v44, v46
	v_add_f32_e32 v45, v45, v46
	v_mul_f32_e32 v46, v99, v99
	v_fma_f32 v44, v98, v98, v44
	v_fma_f32 v45, v99, v99, v45
	v_readlane_b32 s80, v254, 13
	v_add_f32_e32 v44, v44, v46
	v_add_f32_e32 v45, v45, v46
	s_waitcnt lgkmcnt(2)
	v_mul_f32_e32 v46, v162, v100
	v_mul_f32_e32 v47, v163, v101
	v_readlane_b32 s81, v254, 14
	v_fma_f32 v100, v2, v68, -v46
	v_fma_f32 v101, v3, v68, -v47
	v_mul_f32_e32 v2, v162, v96
	v_mul_f32_e32 v3, v163, v97
	v_readlane_b32 s82, v254, 15
	v_fma_f32 v96, v0, v68, -v2
	v_fma_f32 v97, v1, v68, -v3
	v_readlane_b32 s83, v254, 16
	v_fma_f32 v0, v96, v96, v44
	v_fma_f32 v1, v97, v97, v45
	v_mul_f32_e32 v2, v97, v97
	v_add_f32_e32 v0, v0, v2
	v_add_f32_e32 v1, v1, v2
	v_mul_f32_e32 v2, v101, v101
	v_fma_f32 v0, v100, v100, v0
	v_fma_f32 v1, v101, v101, v1
	v_readlane_b32 s84, v254, 17
	v_add_f32_e32 v0, v0, v2
	v_add_f32_e32 v1, v1, v2
	s_waitcnt lgkmcnt(0)
; #define LAS __attribute__((address_space(3)))
; __device__ __forceinline__ unsigned cvt_pk_bf16(float lo, float hi) { f32x2_t v = {lo, hi}; bf16x2_t b = __builtin_convertvector(v, bf16x2_t); return __builtin_bit_cast(unsigned, b); }
; __device__ __forceinline__ float xhalf_sum(float m) { auto rr = __builtin_amdgcn_permlane32_swap(__float_as_uint(m), __float_as_uint(m), false, false); return __uint_as_float(rr[0]) + __uint_as_float(rr[1]); }
; template <bool SWA>
; __device__ __forceinline__ void unit(LAS unsigned char* lds, const bf16_t* PROJ, const bf16_t* KT, const bf16_t* VT, bf16_t* OB, int opitch, int ocol, int b, int head, int qb, float slope2, float m_init, float lam, const float* subg) {
;     ...
;                 for (int i = 0; i < 16; ++i) { const float v = o[db][i] * inv - lam * xb[(db * 16 + i) * 64]; o[db][i] = v; ssq += v * v; }
;             ssq = xhalf_sum(ssq);
;             const float rs = __builtin_amdgcn_rsqf(ssq * (1.0f / 128.0f) + RMS_EPS) * 0.8f;
; #pragma unroll
;             for (int db = 0; db < NDB; ++db)
; #pragma unroll
;                 for (int g4 = 0; g4 < 4; ++g4) {
;                     const f32x4 gg = *(const f32x4*)(subg + 32 * db + 8 * g4 + 4 * h);
;                     u32x2 w; w.x = cvt_pk_bf16(o[db][4 * g4] * rs * gg[0], o[db][4 * g4 + 1] * rs * gg[1]); w.y = cvt_pk_bf16(o[db][4 * g4 + 2] * rs * gg[2], o[db][4 * g4 + 3] * rs * gg[3]);
;                     *(LAS u32x2*)(stg + (32 * (wid & 3) + r) * 272 + (32 * db + 8 * g4 + 4 * h) * 2) = w;
	v_mul_f32_e32 v2, v162, v90
	v_mul_f32_e32 v3, v163, v91
	v_readlane_b32 s85, v254, 18
	v_fma_f32 v90, v6, v68, -v2
	v_fma_f32 v91, v7, v68, -v3
	v_mul_f32_e32 v2, v162, v86
	v_mul_f32_e32 v3, v163, v87
	v_readlane_b32 s86, v254, 19
	v_fma_f32 v86, v4, v68, -v2
	v_fma_f32 v87, v5, v68, -v3
	v_readlane_b32 s87, v254, 20
	v_fma_f32 v0, v86, v86, v0
	v_fma_f32 v1, v87, v87, v1
	v_mul_f32_e32 v2, v87, v87
	v_add_f32_e32 v0, v0, v2
	v_add_f32_e32 v1, v1, v2
	v_mul_f32_e32 v2, v91, v91
	v_fma_f32 v0, v90, v90, v0
	v_fma_f32 v1, v91, v91, v1
	v_readlane_b32 s88, v254, 21
	v_add_f32_e32 v0, v0, v2
	v_add_f32_e32 v1, v1, v2
	v_mul_f32_e32 v2, v162, v80
	v_mul_f32_e32 v3, v163, v81
	v_readlane_b32 s89, v254, 22
	v_fma_f32 v80, v10, v68, -v2
	v_fma_f32 v81, v11, v68, -v3
	v_mul_f32_e32 v2, v162, v78
	v_mul_f32_e32 v3, v163, v79
	v_readlane_b32 s90, v254, 23
	v_fma_f32 v78, v8, v68, -v2
	v_fma_f32 v79, v9, v68, -v3
	v_readlane_b32 s91, v254, 24
	v_fma_f32 v0, v78, v78, v0
	v_fma_f32 v1, v79, v79, v1
	v_mul_f32_e32 v2, v79, v79
	v_add_f32_e32 v0, v0, v2
	v_add_f32_e32 v1, v1, v2
	v_mul_f32_e32 v2, v81, v81
	v_fma_f32 v0, v80, v80, v0
	v_fma_f32 v1, v81, v81, v1
	s_nop 0
	v_add_f32_e32 v0, v0, v2
	v_add_f32_e32 v1, v1, v2
	v_mul_f32_e32 v2, v162, v74
	v_mul_f32_e32 v3, v163, v75
	s_nop 0
	v_fma_f32 v12, v12, v68, -v2
	v_fma_f32 v13, v13, v68, -v3
	s_nop 0
	v_fma_f32 v0, v12, v12, v0
	v_fma_f32 v1, v13, v13, v1
	v_mul_f32_e32 v2, v13, v13
	v_add_f32_e32 v0, v0, v2
	v_add_f32_e32 v1, v1, v2
	v_mul_f32_e32 v2, v71, v71
	v_fma_f32 v0, v70, v70, v0
	v_fma_f32 v1, v71, v71, v1
	s_nop 0
	v_add_f32_e32 v0, v0, v2
	v_add_f32_e32 v1, v1, v2
	s_nop 0
	v_mov_b32_e32 v1, v0
	s_nop 1
	v_permlane32_swap_b32_e32 v0, v1
	v_add_f32_e32 v0, v0, v1
	v_fmamk_f32 v0, v0, 0x3c000000, v178
	v_rsq_f32_e32 v68, v0
	global_load_dwordx4 v[0:3], v166, s[78:79] offset:384
	global_load_dwordx4 v[4:7], v166, s[78:79] offset:416
	global_load_dwordx4 v[8:11], v166, s[78:79] offset:448
	global_load_dwordx4 v[44:47], v166, s[78:79] offset:480
	v_mul_f32_e32 v68, 0x3f4ccccd, v68
	v_mul_f32_e32 v74, v76, v68
	v_mul_f32_e32 v75, v77, v68
	v_mul_f32_e32 v72, v72, v68
	v_mul_f32_e32 v73, v73, v68
	s_waitcnt vmcnt(15)
	v_mul_f32_e32 v64, v64, v74
	v_mul_f32_e32 v65, v65, v75
	v_mul_f32_e32 v66, v66, v72
	v_mul_f32_e32 v67, v67, v73
	v_cvt_pk_bf16_f32 v64, v64, v65
	v_cvt_pk_bf16_f32 v65, v66, v67
	v_mul_f32_e32 v66, v84, v68
	v_mul_f32_e32 v67, v85, v68
	s_waitcnt vmcnt(14)
	v_mul_f32_e32 v14, v14, v66
	v_mul_f32_e32 v15, v15, v67
	v_mul_f32_e32 v66, v82, v68
	v_mul_f32_e32 v67, v83, v68
	v_cvt_pk_bf16_f32 v14, v14, v15
	v_mul_f32_e32 v16, v16, v66
	v_mul_f32_e32 v17, v17, v67
	s_nop 0
	v_cvt_pk_bf16_f32 v15, v16, v17
	ds_write2_b64 v69, v[64:65], v[14:15] offset1:2
	v_mul_f32_e32 v14, v92, v68
	v_mul_f32_e32 v15, v93, v68
	v_mul_f32_e32 v16, v88, v68
	v_mul_f32_e32 v17, v89, v68
	s_waitcnt vmcnt(13)
	v_mul_f32_e32 v14, v22, v14
	v_mul_f32_e32 v15, v23, v15
	v_mul_f32_e32 v16, v24, v16
	v_mul_f32_e32 v17, v25, v17
	v_cvt_pk_bf16_f32 v14, v14, v15
	v_cvt_pk_bf16_f32 v15, v16, v17
	v_mul_f32_e32 v16, v102, v68
	v_mul_f32_e32 v17, v103, v68
	s_waitcnt vmcnt(12)
	v_mul_f32_e32 v16, v18, v16
	v_mul_f32_e32 v17, v19, v17
	v_mul_f32_e32 v18, v30, v68
	v_mul_f32_e32 v19, v31, v68
	v_cvt_pk_bf16_f32 v16, v16, v17
	v_mul_f32_e32 v18, v20, v18
	v_mul_f32_e32 v19, v21, v19
	s_nop 0
	v_cvt_pk_bf16_f32 v17, v18, v19
	ds_write2_b64 v69, v[14:15], v[16:17] offset0:4 offset1:6
	v_mul_f32_e32 v14, v108, v68
	v_mul_f32_e32 v15, v109, v68
	v_mul_f32_e32 v16, v104, v68
	v_mul_f32_e32 v17, v105, v68
	s_waitcnt vmcnt(11)
	v_mul_f32_e32 v14, v14, v48
	v_mul_f32_e32 v15, v15, v49
	v_mul_f32_e32 v16, v16, v50
	v_mul_f32_e32 v17, v17, v51
	v_cvt_pk_bf16_f32 v14, v14, v15
	v_cvt_pk_bf16_f32 v15, v16, v17
	v_mul_f32_e32 v16, v116, v68
	v_mul_f32_e32 v17, v117, v68
	v_mul_f32_e32 v18, v112, v68
	v_mul_f32_e32 v19, v113, v68
	s_waitcnt vmcnt(10)
; #define LAS __attribute__((address_space(3)))
; __device__ __forceinline__ unsigned cvt_pk_bf16(float lo, float hi) { f32x2_t v = {lo, hi}; bf16x2_t b = __builtin_convertvector(v, bf16x2_t); return __builtin_bit_cast(unsigned, b); }
; template <bool SWA>
; __device__ __forceinline__ void unit(LAS unsigned char* lds, const bf16_t* PROJ, const bf16_t* KT, const bf16_t* VT, bf16_t* OB, int opitch, int ocol, int b, int head, int qb, float slope2, float m_init, float lam, const float* subg) {
;     ...
; #pragma unroll
;             for (int db = 0; db < NDB; ++db)
; #pragma unroll
;                 for (int g4 = 0; g4 < 4; ++g4) {
;                     const f32x4 gg = *(const f32x4*)(subg + 32 * db + 8 * g4 + 4 * h);
;                     u32x2 w; w.x = cvt_pk_bf16(o[db][4 * g4] * rs * gg[0], o[db][4 * g4 + 1] * rs * gg[1]); w.y = cvt_pk_bf16(o[db][4 * g4 + 2] * rs * gg[2], o[db][4 * g4 + 3] * rs * gg[3]);
;                     *(LAS u32x2*)(stg + (32 * (wid & 3) + r) * 272 + (32 * db + 8 * g4 + 4 * h) * 2) = w;
;                 }
	v_mul_f32_e32 v16, v16, v26
	v_mul_f32_e32 v17, v17, v27
	v_mul_f32_e32 v18, v18, v28
	v_mul_f32_e32 v19, v19, v29
	v_cvt_pk_bf16_f32 v16, v16, v17
	v_cvt_pk_bf16_f32 v17, v18, v19
	ds_write2_b64 v69, v[14:15], v[16:17] offset0:8 offset1:10
	v_mul_f32_e32 v14, v124, v68
	v_mul_f32_e32 v15, v125, v68
	v_mul_f32_e32 v16, v120, v68
	v_mul_f32_e32 v17, v121, v68
	s_waitcnt vmcnt(9)
	v_mul_f32_e32 v14, v14, v56
	v_mul_f32_e32 v15, v15, v57
	v_mul_f32_e32 v16, v16, v58
	v_mul_f32_e32 v17, v17, v59
	v_cvt_pk_bf16_f32 v14, v14, v15
	v_cvt_pk_bf16_f32 v15, v16, v17
	v_mul_f32_e32 v16, v60, v68
	v_mul_f32_e32 v17, v61, v68
	v_mul_f32_e32 v18, v62, v68
	v_mul_f32_e32 v19, v63, v68
	s_waitcnt vmcnt(8)
	v_mul_f32_e32 v16, v16, v52
	v_mul_f32_e32 v17, v17, v53
	v_mul_f32_e32 v18, v18, v54
	v_mul_f32_e32 v19, v19, v55
	v_cvt_pk_bf16_f32 v16, v16, v17
	v_cvt_pk_bf16_f32 v17, v18, v19
	ds_write2_b64 v69, v[14:15], v[16:17] offset0:12 offset1:14
	v_mul_f32_e32 v14, v122, v68
	v_mul_f32_e32 v15, v123, v68
	v_mul_f32_e32 v16, v130, v68
	v_mul_f32_e32 v17, v131, v68
	s_waitcnt vmcnt(7)
	v_mul_f32_e32 v14, v14, v32
	v_mul_f32_e32 v15, v15, v33
	v_mul_f32_e32 v16, v16, v34
	v_mul_f32_e32 v17, v17, v35
	v_cvt_pk_bf16_f32 v14, v14, v15
	v_cvt_pk_bf16_f32 v15, v16, v17
	v_mul_f32_e32 v16, v114, v68
	v_mul_f32_e32 v17, v115, v68
	v_mul_f32_e32 v18, v118, v68
	v_mul_f32_e32 v19, v119, v68
	s_waitcnt vmcnt(6)
	v_mul_f32_e32 v16, v16, v126
	v_mul_f32_e32 v17, v17, v127
	v_mul_f32_e32 v18, v18, v128
	v_mul_f32_e32 v19, v19, v129
	v_cvt_pk_bf16_f32 v16, v16, v17
	v_cvt_pk_bf16_f32 v17, v18, v19
	ds_write2_b64 v69, v[14:15], v[16:17] offset0:16 offset1:18
	v_mul_f32_e32 v14, v106, v68
	v_mul_f32_e32 v15, v107, v68
	v_mul_f32_e32 v16, v110, v68
	v_mul_f32_e32 v17, v111, v68
	s_waitcnt vmcnt(5)
	v_mul_f32_e32 v14, v14, v36
	v_mul_f32_e32 v15, v15, v37
	v_mul_f32_e32 v16, v16, v38
	v_mul_f32_e32 v17, v17, v39
	v_cvt_pk_bf16_f32 v14, v14, v15
	v_cvt_pk_bf16_f32 v15, v16, v17
	v_mul_f32_e32 v16, v94, v68
	v_mul_f32_e32 v17, v95, v68
	v_mul_f32_e32 v18, v98, v68
	v_mul_f32_e32 v19, v99, v68
	s_waitcnt vmcnt(4)
	v_mul_f32_e32 v16, v16, v40
	v_mul_f32_e32 v17, v17, v41
	v_mul_f32_e32 v18, v18, v42
	v_mul_f32_e32 v19, v19, v43
	v_cvt_pk_bf16_f32 v16, v16, v17
	v_cvt_pk_bf16_f32 v17, v18, v19
	ds_write2_b64 v69, v[14:15], v[16:17] offset0:20 offset1:22
	v_mul_f32_e32 v14, v96, v68
	v_mul_f32_e32 v15, v97, v68
	s_waitcnt vmcnt(3)
	v_mul_f32_e32 v0, v14, v0
	v_mul_f32_e32 v1, v15, v1
	v_mul_f32_e32 v14, v100, v68
	v_mul_f32_e32 v15, v101, v68
	v_cvt_pk_bf16_f32 v0, v0, v1
	v_mul_f32_e32 v2, v14, v2
	v_mul_f32_e32 v3, v15, v3
	s_nop 0
	v_cvt_pk_bf16_f32 v1, v2, v3
	v_mul_f32_e32 v2, v86, v68
	v_mul_f32_e32 v3, v87, v68
	s_waitcnt vmcnt(2)
	v_mul_f32_e32 v2, v2, v4
	v_mul_f32_e32 v3, v3, v5
	v_mul_f32_e32 v4, v90, v68
	v_mul_f32_e32 v5, v91, v68
	v_cvt_pk_bf16_f32 v2, v2, v3
	v_mul_f32_e32 v4, v4, v6
	v_mul_f32_e32 v5, v5, v7
	s_nop 0
	v_cvt_pk_bf16_f32 v3, v4, v5
	ds_write2_b64 v69, v[0:1], v[2:3] offset0:24 offset1:26
	v_mul_f32_e32 v0, v78, v68
	v_mul_f32_e32 v1, v79, v68
	v_mul_f32_e32 v2, v80, v68
	v_mul_f32_e32 v3, v81, v68
	s_waitcnt vmcnt(1)
	v_mul_f32_e32 v0, v0, v8
	v_mul_f32_e32 v1, v1, v9
	v_mul_f32_e32 v2, v2, v10
	v_mul_f32_e32 v3, v3, v11
	v_cvt_pk_bf16_f32 v0, v0, v1
	v_cvt_pk_bf16_f32 v1, v2, v3
	v_mul_f32_e32 v2, v12, v68
	v_mul_f32_e32 v3, v13, v68
	v_mul_f32_e32 v4, v70, v68
	v_mul_f32_e32 v5, v71, v68
	s_waitcnt vmcnt(0)
	v_mul_f32_e32 v2, v2, v44
	v_mul_f32_e32 v3, v3, v45
	v_mul_f32_e32 v4, v4, v46
	v_mul_f32_e32 v5, v5, v47
	v_cvt_pk_bf16_f32 v2, v2, v3
	v_cvt_pk_bf16_f32 v3, v4, v5
	ds_write2_b64 v69, v[0:1], v[2:3] offset0:28 offset1:30
	s_branch .LBB0_844

; #define LAS __attribute__((address_space(3)))
; __device__ __forceinline__ unsigned cvt_pk_bf16(float lo, float hi) { f32x2_t v = {lo, hi}; bf16x2_t b = __builtin_convertvector(v, bf16x2_t); return __builtin_bit_cast(unsigned, b); }
; __device__ __forceinline__ float xhalf_sum(float m) { auto rr = __builtin_amdgcn_permlane32_swap(__float_as_uint(m), __float_as_uint(m), false, false); return __uint_as_float(rr[0]) + __uint_as_float(rr[1]); }
; template <bool SWA>
; __device__ __forceinline__ void unit(LAS unsigned char* lds, const bf16_t* PROJ, const bf16_t* KT, const bf16_t* VT, bf16_t* OB, int opitch, int ocol, int b, int head, int qb, float slope2, float m_init, float lam, const float* subg) {
;     ...
;     const float lt = xhalf_sum(lrun);
;     const float inv = 1.0f / lt;
;     if (SWA) {
;         LAS unsigned char* stg = lds + (wid < 4 ? 32768 : 98304) + (wid & 3) * 4608;
; #pragma unroll
;         for (int db = 0; db < NDB; ++db)
; #pragma unroll
;             for (int g4 = 0; g4 < 4; ++g4) {
;                 u32x2 w; w.x = cvt_pk_bf16(o[db][4 * g4] * inv, o[db][4 * g4 + 1] * inv); w.y = cvt_pk_bf16(o[db][4 * g4 + 2] * inv, o[db][4 * g4 + 3] * inv);
;                 *(LAS u32x2*)(stg + r * 144 + (32 * db + 8 * g4 + 4 * h) * 2) = w;
;             }
;         asm volatile("s_waitcnt lgkmcnt(0)" ::: "memory");
; #pragma unroll
;         for (int i = 0; i < 4; ++i) { const int row = i * 8 + (lane >> 3), ch = lane & 7; const u32x4 v = *(const LAS u32x4*)(stg + row * 144 + ch * 16);
;             *(u32x4*)(OB + (size_t)(b * SEQ + qw + row) * opitch + ocol + ch * 8) = v; }
;         asm volatile("s_waitcnt lgkmcnt(0)" ::: "memory");
.LBB0_956:
	v_mov_b32_e32 v0, v147
	s_lshl_b32 s0, s23, 8
	s_lshl_b32 s1, s24, 6
	v_permlane32_swap_b32_e32 v147, v0
	s_add_i32 s0, s1, s0
	v_add_f32_e32 v0, v147, v0
	s_add_i32 s8, s0, 0x400
	v_div_scale_f32 v34, s[0:1], v0, v0, 1.0
	v_rcp_f32_e32 v35, v34
	s_cmp_lt_i32 s22, 4
	s_mov_b32 s0, 0x8000
	s_cselect_b32 s0, s0, 0x18000
	v_fma_f32 v36, -v34, v35, 1.0
	v_fmac_f32_e32 v35, v36, v35
	v_div_scale_f32 v36, vcc, 1.0, v0, 1.0
	v_mul_f32_e32 v37, v36, v35
	v_fma_f32 v38, -v34, v37, v36
	v_fmac_f32_e32 v37, v38, v35
	v_fma_f32 v34, -v34, v37, v36
	v_div_fmas_f32 v34, v34, v35, v37
	v_div_fixup_f32 v0, v34, v0, 1.0
	s_bfe_u32 s1, s19, 0x20006
	s_add_i32 s0, s0, 0
	s_mulk_i32 s1, 0x1200
	v_mul_f32_e32 v2, v2, v0
	v_mul_f32_e32 v3, v3, v0
	v_mul_f32_e32 v4, v4, v0
	v_mul_f32_e32 v5, v5, v0
	s_add_i32 s0, s0, s1
	v_mul_u32_u24_e32 v34, 0x90, v144
	v_cvt_pk_bf16_f32 v2, v2, v3
	v_cvt_pk_bf16_f32 v3, v4, v5
	v_mul_f32_e32 v4, v6, v0
	v_mul_f32_e32 v5, v7, v0
	v_mul_f32_e32 v6, v8, v0
	v_mul_f32_e32 v7, v9, v0
	v_add3_u32 v34, s0, v34, v146
	v_cvt_pk_bf16_f32 v4, v4, v5
	v_cvt_pk_bf16_f32 v5, v6, v7
	s_waitcnt lgkmcnt(0)
	s_barrier
	ds_write2_b64 v34, v[2:3], v[4:5] offset1:2
	v_mul_f32_e32 v2, v10, v0
	v_mul_f32_e32 v3, v11, v0
	v_mul_f32_e32 v4, v12, v0
	v_mul_f32_e32 v5, v13, v0
	v_cvt_pk_bf16_f32 v2, v2, v3
	v_cvt_pk_bf16_f32 v3, v4, v5
	v_mul_f32_e32 v4, v14, v0
	v_mul_f32_e32 v5, v15, v0
	v_mul_f32_e32 v6, v16, v0
	v_mul_f32_e32 v7, v17, v0
	v_cvt_pk_bf16_f32 v4, v4, v5
	v_cvt_pk_bf16_f32 v5, v6, v7
	ds_write2_b64 v34, v[2:3], v[4:5] offset0:4 offset1:6
	v_mul_f32_e32 v2, v18, v0
	v_mul_f32_e32 v3, v19, v0
	v_mul_f32_e32 v4, v20, v0
	v_mul_f32_e32 v5, v21, v0
	v_cvt_pk_bf16_f32 v2, v2, v3
	v_cvt_pk_bf16_f32 v3, v4, v5
	v_mul_f32_e32 v4, v22, v0
	v_mul_f32_e32 v5, v23, v0
	v_mul_f32_e32 v6, v24, v0
	v_mul_f32_e32 v7, v25, v0
	v_cvt_pk_bf16_f32 v4, v4, v5
	v_cvt_pk_bf16_f32 v5, v6, v7
	ds_write2_b64 v34, v[2:3], v[4:5] offset0:8 offset1:10
	v_mul_f32_e32 v2, v26, v0
	v_mul_f32_e32 v3, v27, v0
	v_mul_f32_e32 v4, v28, v0
	v_mul_f32_e32 v5, v29, v0
	v_cvt_pk_bf16_f32 v2, v2, v3
	v_cvt_pk_bf16_f32 v3, v4, v5
	v_mul_f32_e32 v4, v30, v0
	v_mul_f32_e32 v5, v31, v0
	v_mul_f32_e32 v6, v32, v0
	v_mul_f32_e32 v7, v33, v0
	v_cvt_pk_bf16_f32 v4, v4, v5
	v_cvt_pk_bf16_f32 v5, v6, v7
	v_lshlrev_b32_e32 v0, 4, v143
	ds_write2_b64 v34, v[2:3], v[4:5] offset0:12 offset1:14
	v_and_b32_e32 v0, 0x70, v0
	v_mul_u32_u24_e32 v2, 0x90, v145
	s_waitcnt lgkmcnt(0)
	v_lshl_add_u64 v[10:11], s[20:21], 0, v[0:1]
	v_add3_u32 v0, s0, v0, v2
	ds_read_b128 v[2:5], v0
	v_or_b32_e32 v12, s18, v145
	v_ashrrev_i32_e32 v13, 31, v12
	s_ashr_i32 s9, s8, 31
	v_lshlrev_b64 v[6:7], 13, v[12:13]
	v_lshl_add_u64 v[6:7], v[10:11], 0, v[6:7]
	s_lshl_b64 s[0:1], s[8:9], 1
	v_lshl_add_u64 v[14:15], v[6:7], 0, s[0:1]
	ds_read_b128 v[6:9], v0 offset:1152
	s_waitcnt lgkmcnt(1)
	global_store_dwordx4 v[14:15], v[2:5], off
	s_add_i32 s17, s17, 1
	s_add_i32 s16, s16, s50
	v_or_b32_e32 v2, 8, v12
	v_ashrrev_i32_e32 v3, 31, v2
	v_lshlrev_b64 v[2:3], 13, v[2:3]
	v_lshl_add_u64 v[2:3], v[10:11], 0, v[2:3]
	v_lshl_add_u64 v[2:3], v[2:3], 0, s[0:1]
	s_waitcnt lgkmcnt(0)
	global_store_dwordx4 v[2:3], v[6:9], off
	ds_read_b128 v[2:5], v0 offset:2304
	s_cmp_eq_u32 s17, 8
	v_or_b32_e32 v6, 16, v12
	v_ashrrev_i32_e32 v7, 31, v6
	v_lshlrev_b64 v[6:7], 13, v[6:7]
	v_lshl_add_u64 v[6:7], v[10:11], 0, v[6:7]
	v_lshl_add_u64 v[14:15], v[6:7], 0, s[0:1]
	ds_read_b128 v[6:9], v0 offset:3456
	s_waitcnt lgkmcnt(1)
	global_store_dwordx4 v[14:15], v[2:5], off
	s_cselect_b64 s[6:7], -1, 0
	s_nop 0
	v_or_b32_e32 v2, 24, v12
	v_ashrrev_i32_e32 v3, 31, v2
	v_lshlrev_b64 v[2:3], 13, v[2:3]
	v_lshl_add_u64 v[2:3], v[10:11], 0, v[2:3]
	v_lshl_add_u64 v[2:3], v[2:3], 0, s[0:1]
	s_waitcnt lgkmcnt(0)
	global_store_dwordx4 v[2:3], v[6:9], off
	s_waitcnt lgkmcnt(0)
	v_readlane_b32 s1, v254, 38

.LBB0_986:
	s_andn2_b64 vcc, exec, s[6:7]
	s_cbranch_vccnz .LBB0_988
	v_add_f32_e32 v222, s74, v0
	v_add_f32_e32 v223, s75, v0
	v_and_b32_e32 v227, 0x7fffffff, v223
	v_and_b32_e32 v226, 0x7fffffff, v222
	s_xor_b32 s93, s34, 0x80000000
	s_xor_b32 s92, s1, 0x80000000
	v_add_f32_e32 v214, s64, v0
	v_add_f32_e32 v215, s65, v0
	v_fma_f32 v80, s92, v226, v80
	v_fma_f32 v81, s93, v227, v81
	v_cmp_le_f32_e64 vcc, |v223|, s5
	v_and_b32_e32 v219, 0x7fffffff, v215
	v_and_b32_e32 v218, 0x7fffffff, v214
	s_xor_b32 s91, s0, 0x80000000
	s_xor_b32 s90, s13, 0x80000000
	v_cndmask_b32_e32 v81, v142, v81, vcc
	v_cmp_le_f32_e64 vcc, |v222|, s5
	v_add_f32_e32 v206, s60, v0
	v_add_f32_e32 v207, s61, v0
	v_fma_f32 v78, s90, v218, v78
	v_fma_f32 v79, s91, v219, v79
	v_cndmask_b32_e32 v80, v142, v80, vcc
	v_cmp_le_f32_e64 vcc, |v215|, s5
	v_and_b32_e32 v211, 0x7fffffff, v207
	v_and_b32_e32 v210, 0x7fffffff, v206
	s_xor_b32 s89, s3, 0x80000000
	s_xor_b32 s88, s2, 0x80000000
	v_cndmask_b32_e32 v79, v142, v79, vcc
	v_cmp_le_f32_e64 vcc, |v214|, s5
	v_add_f32_e32 v198, s56, v0
	v_add_f32_e32 v199, s57, v0
	v_fma_f32 v76, s88, v210, v76
	v_fma_f32 v77, s89, v211, v77
	v_cndmask_b32_e32 v78, v142, v78, vcc
	v_cmp_le_f32_e64 vcc, |v207|, s5
	v_and_b32_e32 v203, 0x7fffffff, v199
	v_and_b32_e32 v202, 0x7fffffff, v198
	s_xor_b32 s87, s97, 0x80000000
	s_xor_b32 s86, s96, 0x80000000
	v_cndmask_b32_e32 v77, v142, v77, vcc
	v_cmp_le_f32_e64 vcc, |v206|, s5
	v_add_f32_e32 v190, s52, v0
	v_add_f32_e32 v191, s53, v0
	v_fma_f32 v74, s86, v202, v74
	v_fma_f32 v75, s87, v203, v75
	v_cndmask_b32_e32 v76, v142, v76, vcc
	v_cmp_le_f32_e64 vcc, |v199|, s5
	v_and_b32_e32 v195, 0x7fffffff, v191
	v_and_b32_e32 v194, 0x7fffffff, v190
	s_xor_b32 s85, s95, 0x80000000
	s_xor_b32 s84, s94, 0x80000000
	v_cndmask_b32_e32 v75, v142, v75, vcc
	v_cmp_le_f32_e64 vcc, |v198|, s5
	v_add_f32_e32 v184, s44, v0
	v_add_f32_e32 v185, s45, v0
	v_fma_f32 v72, s84, v194, v72
	v_fma_f32 v73, s85, v195, v73
	v_cndmask_b32_e32 v74, v142, v74, vcc
	v_cmp_le_f32_e64 vcc, |v191|, s5
	v_and_b32_e32 v187, 0x7fffffff, v185
	v_and_b32_e32 v186, 0x7fffffff, v184
	s_xor_b32 s83, s73, 0x80000000
	s_xor_b32 s82, s72, 0x80000000
	v_cndmask_b32_e32 v73, v142, v73, vcc
	v_cmp_le_f32_e64 vcc, |v190|, s5
	v_add_f32_e32 v168, s38, v0
	v_add_f32_e32 v169, s39, v0
	v_fma_f32 v70, s82, v186, v70
	v_fma_f32 v71, s83, v187, v71
	v_cndmask_b32_e32 v72, v142, v72, vcc
	v_cmp_le_f32_e64 vcc, |v185|, s5
	v_and_b32_e32 v171, 0x7fffffff, v169
	v_and_b32_e32 v170, 0x7fffffff, v168
	s_xor_b32 s11, s51, 0x80000000
	s_xor_b32 s10, s50, 0x80000000
	v_cndmask_b32_e32 v71, v142, v71, vcc
	v_cmp_le_f32_e64 vcc, |v184|, s5
	v_add_f32_e32 v163, -1.0, v0
	v_fma_f32 v68, s10, v170, v68
	v_fma_f32 v69, s11, v171, v69
	v_cndmask_b32_e32 v70, v142, v70, vcc
	v_cmp_le_f32_e64 vcc, |v169|, s5
	v_and_b32_e32 v164, 0x7fffffff, v0
	v_and_b32_e32 v165, 0x7fffffff, v163
	v_cndmask_b32_e32 v69, v142, v69, vcc
	v_cmp_le_f32_e64 vcc, |v168|, s5
	v_add_f32_e32 v224, s76, v0
	v_add_f32_e32 v225, s77, v0
	v_fma_f32 v66, -s78, v164, v66
	v_fma_f32 v67, -s79, v165, v67
	v_cndmask_b32_e32 v68, v142, v68, vcc
	v_cmp_le_f32_e64 vcc, |v163|, s5
	v_and_b32_e32 v229, 0x7fffffff, v225
	v_and_b32_e32 v228, 0x7fffffff, v224
	v_cndmask_b32_e32 v67, v142, v67, vcc
	v_cmp_le_f32_e64 vcc, |v0|, s5
	v_add_f32_e32 v216, s66, v0
	v_add_f32_e32 v217, s67, v0
	v_fma_f32 v48, s92, v228, v48
	v_fma_f32 v49, s93, v229, v49
	v_cndmask_b32_e32 v66, v142, v66, vcc
	v_cmp_le_f32_e64 vcc, |v225|, s5
	v_and_b32_e32 v221, 0x7fffffff, v217
	v_and_b32_e32 v220, 0x7fffffff, v216
	v_cndmask_b32_e32 v49, v142, v49, vcc
	v_cmp_le_f32_e64 vcc, |v224|, s5
	v_add_f32_e32 v208, s62, v0
	v_add_f32_e32 v209, s63, v0
	v_fma_f32 v46, s90, v220, v46
	v_fma_f32 v47, s91, v221, v47
	v_cndmask_b32_e32 v48, v142, v48, vcc
	v_cmp_le_f32_e64 vcc, |v217|, s5
	v_and_b32_e32 v213, 0x7fffffff, v209
	v_and_b32_e32 v212, 0x7fffffff, v208
	v_cndmask_b32_e32 v47, v142, v47, vcc
	v_cmp_le_f32_e64 vcc, |v216|, s5
	v_add_f32_e32 v200, s58, v0
	v_add_f32_e32 v201, s59, v0
	v_fma_f32 v44, s88, v212, v44
	v_fma_f32 v45, s89, v213, v45
	v_cndmask_b32_e32 v46, v142, v46, vcc
	v_cmp_le_f32_e64 vcc, |v209|, s5
	v_and_b32_e32 v205, 0x7fffffff, v201
	v_and_b32_e32 v204, 0x7fffffff, v200
	v_cndmask_b32_e32 v45, v142, v45, vcc
	v_cmp_le_f32_e64 vcc, |v208|, s5
	v_add_f32_e32 v192, s54, v0
	v_add_f32_e32 v193, s55, v0
	v_fma_f32 v42, s86, v204, v42
	v_fma_f32 v43, s87, v205, v43
	v_cndmask_b32_e32 v44, v142, v44, vcc
	v_cmp_le_f32_e64 vcc, |v201|, s5
	v_and_b32_e32 v197, 0x7fffffff, v193
	v_and_b32_e32 v196, 0x7fffffff, v192
	v_cndmask_b32_e32 v43, v142, v43, vcc
	v_cmp_le_f32_e64 vcc, |v200|, s5
	v_add_f32_e32 v138, s46, v0
	v_add_f32_e32 v139, s47, v0
	v_fma_f32 v40, s84, v196, v40
	v_fma_f32 v41, s85, v197, v41
	v_cndmask_b32_e32 v42, v142, v42, vcc
	v_cmp_le_f32_e64 vcc, |v193|, s5
	v_and_b32_e32 v189, 0x7fffffff, v139
	v_and_b32_e32 v188, 0x7fffffff, v138
	v_cndmask_b32_e32 v41, v142, v41, vcc
	v_cmp_le_f32_e64 vcc, |v192|, s5
	v_add_f32_e32 v136, s42, v0
	v_add_f32_e32 v137, s43, v0
	v_fma_f32 v38, s82, v188, v38
	v_fma_f32 v39, s83, v189, v39
	v_cndmask_b32_e32 v40, v142, v40, vcc
	v_cmp_le_f32_e64 vcc, |v139|, s5
	v_and_b32_e32 v173, 0x7fffffff, v137
	v_and_b32_e32 v172, 0x7fffffff, v136
	v_cndmask_b32_e32 v39, v142, v39, vcc
	v_cmp_le_f32_e64 vcc, |v138|, s5
	v_add_f32_e32 v134, s36, v0
	v_add_f32_e32 v135, s37, v0
	v_fma_f32 v36, s10, v172, v36
	v_fma_f32 v37, s11, v173, v37
	v_cndmask_b32_e32 v38, v142, v38, vcc
	v_cmp_le_f32_e64 vcc, |v137|, s5
	v_and_b32_e32 v167, 0x7fffffff, v135
	v_and_b32_e32 v166, 0x7fffffff, v134
	v_cndmask_b32_e32 v37, v142, v37, vcc
	v_cmp_le_f32_e64 vcc, |v136|, s5
	v_fma_f32 v34, -s78, v166, v34
	v_fma_f32 v35, -s79, v167, v35
	s_nop 0
	v_cndmask_b32_e32 v36, v142, v36, vcc
	v_cmp_le_f32_e64 vcc, |v135|, s5
	v_mov_b32_e32 v135, 0
	s_nop 0
	v_cndmask_b32_e32 v35, v142, v35, vcc
	v_cmp_le_f32_e64 vcc, |v134|, s5
	v_mov_b32_e32 v134, 0
	s_nop 0
	v_cndmask_b32_e32 v34, v142, v34, vcc
.LBB0_988:
	v_max_f32_e32 v0, v67, v67
	v_max_f32_e32 v136, v66, v66
	v_max_f32_e32 v0, v136, v0
	v_max_f32_e32 v136, v35, v35
	v_max_f32_e32 v137, v34, v34
	v_max_f32_e32 v136, v137, v136
	v_max3_f32 v0, v0, v68, v69
	v_max3_f32 v136, v136, v36, v37
	v_max3_f32 v0, v0, v70, v71
	v_max3_f32 v136, v136, v38, v39
	v_max3_f32 v0, v0, v72, v73
	v_max3_f32 v136, v136, v40, v41
	v_max3_f32 v0, v0, v74, v75
	v_max3_f32 v136, v136, v42, v43
	v_max3_f32 v0, v0, v76, v77
	v_max3_f32 v136, v136, v44, v45
	v_max3_f32 v0, v0, v78, v79
	v_max3_f32 v136, v136, v46, v47
	v_max3_f32 v0, v0, v80, v81
	v_max3_f32 v136, v136, v48, v49
	v_add_f32_e32 v0, v134, v0
	v_add_f32_e32 v136, v135, v136
	v_max_f32_e32 v0, v0, v136
	v_mov_b32_e32 v136, v0
	s_nop 1
	v_permlane32_swap_b32_e32 v0, v136
	v_max_f32_e32 v136, v136, v136
	v_max_f32_e32 v0, v0, v0
	v_max_f32_e32 v0, v0, v136
	v_sub_f32_e32 v136, v0, v162
	v_cmp_gt_f32_e32 vcc, s4, v136
	s_cmp_lg_u64 vcc, exec
	s_cselect_b64 s[10:11], -1, 0
	s_cmp_eq_u64 vcc, exec
	s_cbranch_scc1 .LBB0_993
	v_max_f32_e32 v0, v0, v0
	v_max_f32_e32 v114, v162, v162
	v_max_f32_e32 v163, v114, v0
	v_sub_f32_e32 v0, v162, v163
	v_exp_f32_e32 v0, v0
	s_nop 0
	v_cmp_neq_f32_e32 vcc, 1.0, v0
	s_cbranch_vccz .LBB0_991
	v_mul_f32_e32 v32, v32, v0
	v_mul_f32_e32 v33, v33, v0
	v_mul_f32_e32 v30, v30, v0
	v_mul_f32_e32 v31, v31, v0
	v_mul_f32_e32 v28, v28, v0
	v_mul_f32_e32 v29, v29, v0
	v_mul_f32_e32 v26, v26, v0
	v_mul_f32_e32 v27, v27, v0
	v_mul_f32_e32 v24, v24, v0
	v_mul_f32_e32 v25, v25, v0
	v_mul_f32_e32 v22, v22, v0
	v_mul_f32_e32 v23, v23, v0
	v_mul_f32_e32 v20, v20, v0
	v_mul_f32_e32 v21, v21, v0
	v_mul_f32_e32 v18, v18, v0
	v_mul_f32_e32 v19, v19, v0
	v_mul_f32_e32 v16, v16, v0
	v_mul_f32_e32 v17, v17, v0
	v_mul_f32_e32 v14, v14, v0
	v_mul_f32_e32 v15, v15, v0
	v_mul_f32_e32 v12, v12, v0
	v_mul_f32_e32 v13, v13, v0
	v_mul_f32_e32 v10, v10, v0
	v_mul_f32_e32 v11, v11, v0
	v_mul_f32_e32 v8, v8, v0
	v_mul_f32_e32 v9, v9, v0
	v_mul_f32_e32 v6, v6, v0
	v_mul_f32_e32 v7, v7, v0
	v_mul_f32_e32 v4, v4, v0
	v_mul_f32_e32 v5, v5, v0
	v_mul_f32_e32 v2, v2, v0
	v_mul_f32_e32 v3, v3, v0

.LBB0_1002:
	s_andn2_b64 vcc, exec, s[6:7]
	s_cbranch_vccnz .LBB0_1004
	v_add_f32_e32 v222, s74, v0
	v_add_f32_e32 v223, s75, v0
	v_and_b32_e32 v227, 0x7fffffff, v223
	v_and_b32_e32 v226, 0x7fffffff, v222
	s_xor_b32 s91, s34, 0x80000000
	s_xor_b32 s90, s1, 0x80000000
	v_add_f32_e32 v214, s64, v0
	v_add_f32_e32 v215, s65, v0
	v_fma_f32 v96, s90, v226, v96
	v_fma_f32 v97, s91, v227, v97
	v_cmp_le_f32_e64 vcc, |v223|, s5
	v_and_b32_e32 v219, 0x7fffffff, v215
	v_and_b32_e32 v218, 0x7fffffff, v214
	s_xor_b32 s89, s0, 0x80000000
	s_xor_b32 s88, s13, 0x80000000
	v_cndmask_b32_e32 v97, v142, v97, vcc
	v_cmp_le_f32_e64 vcc, |v222|, s5
	v_add_f32_e32 v206, s60, v0
	v_add_f32_e32 v207, s61, v0
	v_fma_f32 v94, s88, v218, v94
	v_fma_f32 v95, s89, v219, v95
	v_cndmask_b32_e32 v96, v142, v96, vcc
	v_cmp_le_f32_e64 vcc, |v215|, s5
	v_and_b32_e32 v211, 0x7fffffff, v207
	v_and_b32_e32 v210, 0x7fffffff, v206
	s_xor_b32 s87, s3, 0x80000000
	s_xor_b32 s86, s2, 0x80000000
	v_cndmask_b32_e32 v95, v142, v95, vcc
	v_cmp_le_f32_e64 vcc, |v214|, s5
	v_add_f32_e32 v198, s56, v0
	v_add_f32_e32 v199, s57, v0
	v_fma_f32 v92, s86, v210, v92
	v_fma_f32 v93, s87, v211, v93
	v_cndmask_b32_e32 v94, v142, v94, vcc
	v_cmp_le_f32_e64 vcc, |v207|, s5
	v_and_b32_e32 v203, 0x7fffffff, v199
	v_and_b32_e32 v202, 0x7fffffff, v198
	s_xor_b32 s85, s97, 0x80000000
	s_xor_b32 s84, s96, 0x80000000
	v_cndmask_b32_e32 v93, v142, v93, vcc
	v_cmp_le_f32_e64 vcc, |v206|, s5
	v_add_f32_e32 v190, s52, v0
	v_add_f32_e32 v191, s53, v0
	v_fma_f32 v90, s84, v202, v90
	v_fma_f32 v91, s85, v203, v91
	v_cndmask_b32_e32 v92, v142, v92, vcc
	v_cmp_le_f32_e64 vcc, |v199|, s5
	v_and_b32_e32 v195, 0x7fffffff, v191
	v_and_b32_e32 v194, 0x7fffffff, v190
	s_xor_b32 s83, s95, 0x80000000
	s_xor_b32 s82, s94, 0x80000000
	v_cndmask_b32_e32 v91, v142, v91, vcc
	v_cmp_le_f32_e64 vcc, |v198|, s5
	v_add_f32_e32 v184, s44, v0
	v_add_f32_e32 v185, s45, v0
	v_fma_f32 v88, s82, v194, v88
	v_fma_f32 v89, s83, v195, v89
	v_cndmask_b32_e32 v90, v142, v90, vcc
	v_cmp_le_f32_e64 vcc, |v191|, s5
	v_and_b32_e32 v187, 0x7fffffff, v185
	v_and_b32_e32 v186, 0x7fffffff, v184
	s_xor_b32 s11, s73, 0x80000000
	s_xor_b32 s10, s72, 0x80000000
	v_cndmask_b32_e32 v89, v142, v89, vcc
	v_cmp_le_f32_e64 vcc, |v190|, s5
	v_add_f32_e32 v168, s38, v0
	v_add_f32_e32 v169, s39, v0
	v_fma_f32 v86, s10, v186, v86
	v_fma_f32 v87, s11, v187, v87
	v_cndmask_b32_e32 v88, v142, v88, vcc
	v_cmp_le_f32_e64 vcc, |v185|, s5
	v_and_b32_e32 v171, 0x7fffffff, v169
	v_and_b32_e32 v170, 0x7fffffff, v168
	s_xor_b32 s9, s51, 0x80000000
	s_xor_b32 s8, s50, 0x80000000
	v_cndmask_b32_e32 v87, v142, v87, vcc
	v_cmp_le_f32_e64 vcc, |v184|, s5
	v_add_f32_e32 v162, -1.0, v0
	v_fma_f32 v84, s8, v170, v84
	v_fma_f32 v85, s9, v171, v85
	v_cndmask_b32_e32 v86, v142, v86, vcc
	v_cmp_le_f32_e64 vcc, |v169|, s5
	v_and_b32_e32 v164, 0x7fffffff, v0
	v_and_b32_e32 v165, 0x7fffffff, v162
	v_cndmask_b32_e32 v85, v142, v85, vcc
	v_cmp_le_f32_e64 vcc, |v168|, s5
	v_add_f32_e32 v224, s76, v0
	v_add_f32_e32 v225, s77, v0
	v_fma_f32 v82, -s78, v164, v82
	v_fma_f32 v83, -s79, v165, v83
	v_cndmask_b32_e32 v84, v142, v84, vcc
	v_cmp_le_f32_e64 vcc, |v162|, s5
	v_and_b32_e32 v229, 0x7fffffff, v225
	v_and_b32_e32 v228, 0x7fffffff, v224
	v_cndmask_b32_e32 v83, v142, v83, vcc
	v_cmp_le_f32_e64 vcc, |v0|, s5
	v_add_f32_e32 v216, s66, v0
	v_add_f32_e32 v217, s67, v0
	v_fma_f32 v64, s90, v228, v64
	v_fma_f32 v65, s91, v229, v65
	v_cndmask_b32_e32 v82, v142, v82, vcc
	v_cmp_le_f32_e64 vcc, |v225|, s5
	v_and_b32_e32 v221, 0x7fffffff, v217
	v_and_b32_e32 v220, 0x7fffffff, v216
	v_cndmask_b32_e32 v65, v142, v65, vcc
	v_cmp_le_f32_e64 vcc, |v224|, s5
	v_add_f32_e32 v208, s62, v0
	v_add_f32_e32 v209, s63, v0
	v_fma_f32 v62, s88, v220, v62
	v_fma_f32 v63, s89, v221, v63
	v_cndmask_b32_e32 v64, v142, v64, vcc
	v_cmp_le_f32_e64 vcc, |v217|, s5
	v_and_b32_e32 v213, 0x7fffffff, v209
	v_and_b32_e32 v212, 0x7fffffff, v208
	v_cndmask_b32_e32 v63, v142, v63, vcc
	v_cmp_le_f32_e64 vcc, |v216|, s5
	v_add_f32_e32 v200, s58, v0
	v_add_f32_e32 v201, s59, v0
	v_fma_f32 v60, s86, v212, v60
	v_fma_f32 v61, s87, v213, v61
	v_cndmask_b32_e32 v62, v142, v62, vcc
	v_cmp_le_f32_e64 vcc, |v209|, s5
	v_and_b32_e32 v205, 0x7fffffff, v201
	v_and_b32_e32 v204, 0x7fffffff, v200
	v_cndmask_b32_e32 v61, v142, v61, vcc
	v_cmp_le_f32_e64 vcc, |v208|, s5
	v_add_f32_e32 v192, s54, v0
	v_add_f32_e32 v193, s55, v0
	v_fma_f32 v58, s84, v204, v58
	v_fma_f32 v59, s85, v205, v59
	v_cndmask_b32_e32 v60, v142, v60, vcc
	v_cmp_le_f32_e64 vcc, |v201|, s5
	v_and_b32_e32 v197, 0x7fffffff, v193
	v_and_b32_e32 v196, 0x7fffffff, v192
	v_cndmask_b32_e32 v59, v142, v59, vcc
	v_cmp_le_f32_e64 vcc, |v200|, s5
	v_add_f32_e32 v138, s46, v0
	v_add_f32_e32 v139, s47, v0
	v_fma_f32 v56, s82, v196, v56
	v_fma_f32 v57, s83, v197, v57
	v_cndmask_b32_e32 v58, v142, v58, vcc
	v_cmp_le_f32_e64 vcc, |v193|, s5
	v_and_b32_e32 v189, 0x7fffffff, v139
	v_and_b32_e32 v188, 0x7fffffff, v138
	v_cndmask_b32_e32 v57, v142, v57, vcc
	v_cmp_le_f32_e64 vcc, |v192|, s5
	v_add_f32_e32 v136, s42, v0
	v_add_f32_e32 v137, s43, v0
	v_fma_f32 v54, s10, v188, v54
	v_fma_f32 v55, s11, v189, v55
	v_cndmask_b32_e32 v56, v142, v56, vcc
	v_cmp_le_f32_e64 vcc, |v139|, s5
	v_and_b32_e32 v173, 0x7fffffff, v137
	v_and_b32_e32 v172, 0x7fffffff, v136
	v_cndmask_b32_e32 v55, v142, v55, vcc
	v_cmp_le_f32_e64 vcc, |v138|, s5
	v_add_f32_e32 v134, s36, v0
	v_add_f32_e32 v135, s37, v0
	v_fma_f32 v52, s8, v172, v52
	v_fma_f32 v53, s9, v173, v53
	v_cndmask_b32_e32 v54, v142, v54, vcc
	v_cmp_le_f32_e64 vcc, |v137|, s5
	v_and_b32_e32 v167, 0x7fffffff, v135
	v_and_b32_e32 v166, 0x7fffffff, v134
	v_cndmask_b32_e32 v53, v142, v53, vcc
	v_cmp_le_f32_e64 vcc, |v136|, s5
	v_fma_f32 v50, -s78, v166, v50
	v_fma_f32 v51, -s79, v167, v51
	s_nop 0
	v_cndmask_b32_e32 v52, v142, v52, vcc
	v_cmp_le_f32_e64 vcc, |v135|, s5
	v_mov_b32_e32 v135, 0
	s_nop 0
	v_cndmask_b32_e32 v51, v142, v51, vcc
	v_cmp_le_f32_e64 vcc, |v134|, s5
	v_mov_b32_e32 v134, 0
	s_nop 0
	v_cndmask_b32_e32 v50, v142, v50, vcc
.LBB0_1004:
	v_max_f32_e32 v0, v83, v83
	v_max_f32_e32 v136, v82, v82
	v_max_f32_e32 v0, v136, v0
	v_max_f32_e32 v136, v51, v51
	v_max_f32_e32 v137, v50, v50
	v_max_f32_e32 v136, v137, v136
	v_max3_f32 v0, v0, v84, v85
	v_max3_f32 v136, v136, v52, v53
	v_max3_f32 v0, v0, v86, v87
	v_max3_f32 v136, v136, v54, v55
	v_max3_f32 v0, v0, v88, v89
	v_max3_f32 v136, v136, v56, v57
	v_max3_f32 v0, v0, v90, v91
	v_max3_f32 v136, v136, v58, v59
	v_max3_f32 v0, v0, v92, v93
	v_max3_f32 v136, v136, v60, v61
	v_max3_f32 v0, v0, v94, v95
	v_max3_f32 v136, v136, v62, v63
	v_max3_f32 v0, v0, v96, v97
	v_max3_f32 v136, v136, v64, v65
	v_add_f32_e32 v0, v134, v0
	v_add_f32_e32 v136, v135, v136
	v_max_f32_e32 v0, v0, v136
	v_mov_b32_e32 v136, v0
	s_nop 1
	v_permlane32_swap_b32_e32 v0, v136
	v_max_f32_e32 v136, v136, v136
	v_max_f32_e32 v0, v0, v0
	v_max_f32_e32 v0, v0, v136
	v_sub_f32_e32 v136, v0, v163
	v_cmp_gt_f32_e32 vcc, s4, v136
	s_cmp_lg_u64 vcc, exec
	s_cselect_b64 s[8:9], -1, 0
	s_cmp_eq_u64 vcc, exec
	s_cbranch_scc1 .LBB0_1009
	v_max_f32_e32 v0, v0, v0
	v_max_f32_e32 v114, v163, v163
	v_max_f32_e32 v162, v114, v0
	v_sub_f32_e32 v0, v163, v162
	v_exp_f32_e32 v0, v0
	s_nop 0
	v_cmp_neq_f32_e32 vcc, 1.0, v0
	s_cbranch_vccz .LBB0_1007
	v_mul_f32_e32 v32, v32, v0
	v_mul_f32_e32 v33, v33, v0
	v_mul_f32_e32 v30, v30, v0
	v_mul_f32_e32 v31, v31, v0
	v_mul_f32_e32 v28, v28, v0
	v_mul_f32_e32 v29, v29, v0
	v_mul_f32_e32 v26, v26, v0
	v_mul_f32_e32 v27, v27, v0
	v_mul_f32_e32 v24, v24, v0
	v_mul_f32_e32 v25, v25, v0
	v_mul_f32_e32 v22, v22, v0
	v_mul_f32_e32 v23, v23, v0
	v_mul_f32_e32 v20, v20, v0
	v_mul_f32_e32 v21, v21, v0
	v_mul_f32_e32 v18, v18, v0
	v_mul_f32_e32 v19, v19, v0
	v_mul_f32_e32 v16, v16, v0
	v_mul_f32_e32 v17, v17, v0
	v_mul_f32_e32 v14, v14, v0
	v_mul_f32_e32 v15, v15, v0
	v_mul_f32_e32 v12, v12, v0
	v_mul_f32_e32 v13, v13, v0
	v_mul_f32_e32 v10, v10, v0
	v_mul_f32_e32 v11, v11, v0
	v_mul_f32_e32 v8, v8, v0
	v_mul_f32_e32 v9, v9, v0
	v_mul_f32_e32 v6, v6, v0
	v_mul_f32_e32 v7, v7, v0
	v_mul_f32_e32 v4, v4, v0
	v_mul_f32_e32 v5, v5, v0
	v_mul_f32_e32 v2, v2, v0
	v_mul_f32_e32 v3, v3, v0

; __device__ __forceinline__ float bf_lo(unsigned w) { return __uint_as_float(w << 16); }
; __device__ __forceinline__ float bf_hi(unsigned w) { return __uint_as_float(w & 0xffff0000u); }
;     __device__ __forceinline__ void mid(Acc& acc, const Unit& u, int wr, int wc, int fr, int fq) const {
;     ...
;                 const int row = row0 + ai * HALF + m * 16;
; #pragma unroll
;                 for (int bj = 0; bj < 2; ++bj) {
;                     const int col = col0 + bj * HALF;
;                     const u32x4 ga = *(const u32x4*)(P + (size_t)row * PP + C_GA + col), gb = *(const u32x4*)(P + (size_t)row * PP + C_GB + col);
;                     const float ra[8] = {bf_lo(ga.x), bf_hi(ga.x), bf_lo(ga.y), bf_hi(ga.y), bf_lo(ga.z), bf_hi(ga.z), bf_lo(ga.w), bf_hi(ga.w)};
;                     const float rb[8] = {bf_lo(gb.x), bf_hi(gb.x), bf_lo(gb.y), bf_hi(gb.y), bf_lo(gb.z), bf_hi(gb.z), bf_lo(gb.w), bf_hi(gb.w)};
; #pragma unroll
;                     for (int n = 0; n < 2; ++n)
; #pragma unroll
;                         for (int e = 0; e < 4; ++e) acc[ai][bj][m][n][e] *= ra[4 * n + e] * __builtin_amdgcn_rcpf(rb[4 * n + e]);
.LBB0_1084:
	s_cmpk_lg_i32 s54, 0x800
	s_cbranch_scc1 .LBB0_1083
	v_mov_b32_e32 v128, v152
	s_mov_b64 s[0:1], 0x1000
	v_ashrrev_i32_e32 v129, 31, v128
	v_lshlrev_b64 v[128:129], 13, v[128:129]
	v_lshl_add_u64 v[134:135], s[20:21], 0, v[128:129]
	v_lshl_add_u64 v[184:185], v[134:135], 0, s[0:1]
	v_lshlrev_b64 v[164:165], 1, v[156:157]
	v_lshl_add_u64 v[186:187], v[134:135], 0, s[14:15]
	v_lshl_add_u64 v[128:129], v[184:185], 0, v[164:165]
	v_lshl_add_u64 v[132:133], v[186:187], 0, v[164:165]
	global_load_dwordx4 v[128:131], v[128:129], off
	s_mov_b64 s[0:1], 0x21000
	global_load_dwordx4 v[166:169], v[132:133], off
	s_mov_b64 s[56:57], 0x21800
	s_waitcnt vmcnt(0)
	v_lshlrev_b32_e32 v132, 16, v166
	v_and_b32_e32 v133, 0xffff0000, v166
	v_rcp_f32_e32 v132, v132
	v_rcp_f32_e32 v133, v133
	v_lshlrev_b32_e32 v153, 16, v167
	v_and_b32_e32 v174, 0xffff0000, v167
	v_lshlrev_b32_e32 v166, 16, v128
	v_and_b32_e32 v167, 0xffff0000, v128
	v_mul_f32_e32 v132, v132, v166
	v_mul_f32_e32 v133, v133, v167
	v_lshlrev_b32_e32 v128, 16, v129
	v_mul_f32_e32 v124, v124, v132
	v_mul_f32_e32 v125, v125, v133
	v_rcp_f32_e32 v132, v153
	v_rcp_f32_e32 v133, v174
	v_and_b32_e32 v129, 0xffff0000, v129
	v_lshlrev_b32_e32 v178, 16, v168
	v_and_b32_e32 v168, 0xffff0000, v168
	v_mul_f32_e32 v128, v132, v128
	v_mul_f32_e32 v129, v133, v129
	v_lshlrev_b32_e32 v132, 16, v130
	v_mul_f32_e32 v126, v126, v128
	v_mul_f32_e32 v127, v127, v129
	v_rcp_f32_e32 v128, v178
	v_rcp_f32_e32 v129, v168
	v_and_b32_e32 v133, 0xffff0000, v130
	v_lshlrev_b32_e32 v179, 16, v169
	v_and_b32_e32 v169, 0xffff0000, v169
	v_mul_f32_e32 v128, v128, v132
	v_mul_f32_e32 v129, v129, v133
	v_lshlrev_b32_e32 v130, 16, v131
	v_mul_f32_e32 v120, v120, v128
	v_mul_f32_e32 v121, v121, v129
	v_rcp_f32_e32 v128, v179
	v_rcp_f32_e32 v129, v169
	v_and_b32_e32 v131, 0xffff0000, v131
	v_lshlrev_b64 v[132:133], 1, v[154:155]
	v_lshl_add_u64 v[166:167], v[186:187], 0, v[132:133]
	v_mul_f32_e32 v128, v128, v130
	v_mul_f32_e32 v129, v129, v131
	global_load_dwordx4 v[166:169], v[166:167], off
	v_mul_f32_e32 v122, v122, v128
	v_mul_f32_e32 v123, v123, v129
	v_lshl_add_u64 v[128:129], v[184:185], 0, v[132:133]
	global_load_dwordx4 v[128:131], v[128:129], off
	v_lshl_add_u64 v[186:187], v[134:135], 0, s[56:57]
	s_mov_b64 s[56:57], 0x41800
	s_waitcnt vmcnt(0)
	v_lshlrev_b32_e32 v153, 16, v166
	v_and_b32_e32 v174, 0xffff0000, v166
	v_lshlrev_b32_e32 v178, 16, v167
	v_and_b32_e32 v179, 0xffff0000, v167
	v_rcp_f32_e32 v166, v153
	v_rcp_f32_e32 v167, v174
	v_lshlrev_b32_e32 v180, 16, v168
	v_and_b32_e32 v183, 0xffff0000, v168
	v_lshlrev_b32_e32 v184, 16, v169
	v_and_b32_e32 v185, 0xffff0000, v169
	v_lshlrev_b32_e32 v168, 16, v128
	v_and_b32_e32 v169, 0xffff0000, v128
	v_mul_f32_e32 v166, v166, v168
	v_mul_f32_e32 v167, v167, v169
	v_lshlrev_b32_e32 v128, 16, v129
	v_mul_f32_e32 v116, v116, v166
	v_mul_f32_e32 v117, v117, v167
	v_rcp_f32_e32 v166, v178
	v_rcp_f32_e32 v167, v179
	v_and_b32_e32 v129, 0xffff0000, v129
	v_mul_f32_e32 v128, v166, v128
	v_mul_f32_e32 v129, v167, v129
	s_nop 0
	v_mul_f32_e32 v118, v118, v128
	v_mul_f32_e32 v119, v119, v129
	v_rcp_f32_e32 v128, v180
	v_rcp_f32_e32 v129, v183
	v_lshlrev_b32_e32 v166, 16, v130
	v_and_b32_e32 v167, 0xffff0000, v130
	v_lshlrev_b32_e32 v130, 16, v131
	v_mul_f32_e32 v128, v128, v166
	v_mul_f32_e32 v129, v129, v167
	v_and_b32_e32 v131, 0xffff0000, v131
	v_mul_f32_e32 v112, v112, v128
	v_mul_f32_e32 v113, v113, v129
	v_rcp_f32_e32 v128, v184
	v_rcp_f32_e32 v129, v185
	v_lshl_add_u64 v[184:185], v[134:135], 0, s[0:1]
	v_lshl_add_u64 v[166:167], v[186:187], 0, v[164:165]
	global_load_dwordx4 v[166:169], v[166:167], off
	v_mul_f32_e32 v128, v128, v130
	v_mul_f32_e32 v129, v129, v131
	s_mov_b64 s[0:1], 0x41000
	v_mul_f32_e32 v114, v114, v128
	v_mul_f32_e32 v115, v115, v129
	v_lshl_add_u64 v[128:129], v[184:185], 0, v[164:165]
	global_load_dwordx4 v[128:131], v[128:129], off
	s_waitcnt vmcnt(0)
	v_lshlrev_b32_e32 v153, 16, v166
	v_and_b32_e32 v174, 0xffff0000, v166
	v_lshlrev_b32_e32 v178, 16, v167
	v_and_b32_e32 v179, 0xffff0000, v167
	v_rcp_f32_e32 v166, v153
	v_rcp_f32_e32 v167, v174
	v_lshlrev_b32_e32 v180, 16, v168
	v_and_b32_e32 v183, 0xffff0000, v168
	v_lshlrev_b32_e32 v188, 16, v169
	v_and_b32_e32 v189, 0xffff0000, v169
	v_lshlrev_b32_e32 v168, 16, v128
	v_and_b32_e32 v169, 0xffff0000, v128
	v_mul_f32_e32 v166, v166, v168
	v_mul_f32_e32 v167, v167, v169
	v_lshlrev_b32_e32 v128, 16, v129
	v_mul_f32_e32 v108, v108, v166
	v_mul_f32_e32 v109, v109, v167
	v_rcp_f32_e32 v166, v178
	v_rcp_f32_e32 v167, v179
	v_and_b32_e32 v129, 0xffff0000, v129
	v_mul_f32_e32 v128, v166, v128
	v_mul_f32_e32 v129, v167, v129
	s_nop 0
	v_mul_f32_e32 v110, v110, v128
	v_mul_f32_e32 v111, v111, v129
	v_rcp_f32_e32 v128, v180
	v_rcp_f32_e32 v129, v183
	v_lshlrev_b32_e32 v166, 16, v130
	v_and_b32_e32 v167, 0xffff0000, v130
	v_lshlrev_b32_e32 v130, 16, v131
	v_mul_f32_e32 v128, v128, v166
	v_mul_f32_e32 v129, v129, v167
	v_and_b32_e32 v131, 0xffff0000, v131
	v_mul_f32_e32 v104, v104, v128
	v_mul_f32_e32 v105, v105, v129
	v_rcp_f32_e32 v128, v188
	v_rcp_f32_e32 v129, v189
	v_lshl_add_u64 v[166:167], v[186:187], 0, v[132:133]
	global_load_dwordx4 v[166:169], v[166:167], off
	v_mul_f32_e32 v128, v128, v130
	v_mul_f32_e32 v129, v129, v131
	s_nop 0
	v_mul_f32_e32 v106, v106, v128
	v_mul_f32_e32 v107, v107, v129
	v_lshl_add_u64 v[128:129], v[184:185], 0, v[132:133]
	global_load_dwordx4 v[128:131], v[128:129], off
	s_waitcnt vmcnt(0)
; __device__ __forceinline__ float bf_lo(unsigned w) { return __uint_as_float(w << 16); }
; __device__ __forceinline__ float bf_hi(unsigned w) { return __uint_as_float(w & 0xffff0000u); }
;     __device__ __forceinline__ void mid(Acc& acc, const Unit& u, int wr, int wc, int fr, int fq) const {
;     ...
;                 const int row = row0 + ai * HALF + m * 16;
; #pragma unroll
;                 for (int bj = 0; bj < 2; ++bj) {
;                     const int col = col0 + bj * HALF;
;                     const u32x4 ga = *(const u32x4*)(P + (size_t)row * PP + C_GA + col), gb = *(const u32x4*)(P + (size_t)row * PP + C_GB + col);
;                     const float ra[8] = {bf_lo(ga.x), bf_hi(ga.x), bf_lo(ga.y), bf_hi(ga.y), bf_lo(ga.z), bf_hi(ga.z), bf_lo(ga.w), bf_hi(ga.w)};
;                     const float rb[8] = {bf_lo(gb.x), bf_hi(gb.x), bf_lo(gb.y), bf_hi(gb.y), bf_lo(gb.z), bf_hi(gb.z), bf_lo(gb.w), bf_hi(gb.w)};
; #pragma unroll
;                     for (int n = 0; n < 2; ++n)
; #pragma unroll
;                         for (int e = 0; e < 4; ++e) acc[ai][bj][m][n][e] *= ra[4 * n + e] * __builtin_amdgcn_rcpf(rb[4 * n + e]);
	v_lshlrev_b32_e32 v153, 16, v166
	v_and_b32_e32 v174, 0xffff0000, v166
	v_lshlrev_b32_e32 v178, 16, v167
	v_and_b32_e32 v179, 0xffff0000, v167
	v_rcp_f32_e32 v166, v153
	v_rcp_f32_e32 v167, v174
	v_lshlrev_b32_e32 v180, 16, v168
	v_and_b32_e32 v183, 0xffff0000, v168
	v_lshlrev_b32_e32 v184, 16, v169
	v_and_b32_e32 v185, 0xffff0000, v169
	v_lshlrev_b32_e32 v168, 16, v128
	v_and_b32_e32 v169, 0xffff0000, v128
	v_mul_f32_e32 v166, v166, v168
	v_mul_f32_e32 v167, v167, v169
	v_lshlrev_b32_e32 v128, 16, v129
	v_mul_f32_e32 v100, v100, v166
	v_mul_f32_e32 v101, v101, v167
	v_rcp_f32_e32 v166, v178
	v_rcp_f32_e32 v167, v179
	v_and_b32_e32 v129, 0xffff0000, v129
	v_lshl_add_u64 v[168:169], v[134:135], 0, s[0:1]
	s_mov_b64 s[0:1], 0x61000
	v_mul_f32_e32 v128, v166, v128
	v_mul_f32_e32 v129, v167, v129
	v_lshlrev_b32_e32 v166, 16, v130
	v_mul_f32_e32 v102, v102, v128
	v_mul_f32_e32 v103, v103, v129
	v_rcp_f32_e32 v128, v180
	v_rcp_f32_e32 v129, v183
	v_and_b32_e32 v167, 0xffff0000, v130
	v_lshlrev_b32_e32 v130, 16, v131
	v_and_b32_e32 v131, 0xffff0000, v131
	v_mul_f32_e32 v128, v128, v166
	v_mul_f32_e32 v129, v129, v167
	v_lshl_add_u64 v[166:167], v[134:135], 0, s[56:57]
	v_mul_f32_e32 v96, v96, v128
	v_mul_f32_e32 v97, v97, v129
	v_rcp_f32_e32 v128, v184
	v_rcp_f32_e32 v129, v185
	v_lshl_add_u64 v[184:185], v[166:167], 0, v[164:165]
	global_load_dwordx4 v[184:187], v[184:185], off
	v_lshl_add_u64 v[166:167], v[166:167], 0, v[132:133]
	v_mul_f32_e32 v128, v128, v130
	v_mul_f32_e32 v129, v129, v131
	s_waitcnt vmcnt(0)
	v_lshlrev_b32_e32 v153, 16, v184
	v_mul_f32_e32 v98, v98, v128
	v_mul_f32_e32 v99, v99, v129
	v_lshl_add_u64 v[128:129], v[168:169], 0, v[164:165]
	global_load_dwordx4 v[128:131], v[128:129], off
	v_and_b32_e32 v174, 0xffff0000, v184
	v_lshlrev_b32_e32 v178, 16, v185
	v_and_b32_e32 v179, 0xffff0000, v185
	v_rcp_f32_e32 v184, v153
	v_rcp_f32_e32 v185, v174
	v_lshlrev_b32_e32 v180, 16, v186
	v_and_b32_e32 v183, 0xffff0000, v186
	v_lshlrev_b32_e32 v188, 16, v187
	v_and_b32_e32 v189, 0xffff0000, v187
	s_waitcnt vmcnt(0)
	v_lshlrev_b32_e32 v186, 16, v128
	v_and_b32_e32 v187, 0xffff0000, v128
	v_mul_f32_e32 v184, v184, v186
	v_mul_f32_e32 v185, v185, v187
	v_lshlrev_b32_e32 v128, 16, v129
	v_mul_f32_e32 v92, v92, v184
	v_mul_f32_e32 v93, v93, v185
	v_rcp_f32_e32 v184, v178
	v_rcp_f32_e32 v185, v179
	v_and_b32_e32 v129, 0xffff0000, v129
	v_mul_f32_e32 v128, v184, v128
	v_mul_f32_e32 v129, v185, v129
	s_nop 0
	v_mul_f32_e32 v94, v94, v128
	v_mul_f32_e32 v95, v95, v129
	v_rcp_f32_e32 v128, v180
	v_rcp_f32_e32 v129, v183
	v_lshlrev_b32_e32 v184, 16, v130
	v_and_b32_e32 v185, 0xffff0000, v130
	v_lshlrev_b32_e32 v130, 16, v131
	v_mul_f32_e32 v128, v128, v184
	v_mul_f32_e32 v129, v129, v185
	v_and_b32_e32 v131, 0xffff0000, v131
	v_mul_f32_e32 v88, v88, v128
	v_mul_f32_e32 v89, v89, v129
	v_rcp_f32_e32 v128, v188
	v_rcp_f32_e32 v129, v189
	s_nop 0
	v_mul_f32_e32 v128, v128, v130
	v_mul_f32_e32 v129, v129, v131
	s_nop 0
	v_mul_f32_e32 v90, v90, v128
	v_mul_f32_e32 v91, v91, v129
	v_lshl_add_u64 v[128:129], v[168:169], 0, v[132:133]
	global_load_dwordx4 v[128:131], v[128:129], off
	s_nop 0
	global_load_dwordx4 v[166:169], v[166:167], off
	s_waitcnt vmcnt(0)
	v_lshlrev_b32_e32 v153, 16, v166
	v_and_b32_e32 v174, 0xffff0000, v166
	v_lshlrev_b32_e32 v178, 16, v167
	v_and_b32_e32 v179, 0xffff0000, v167
	v_rcp_f32_e32 v166, v153
	v_rcp_f32_e32 v167, v174
	v_lshlrev_b32_e32 v180, 16, v168
	v_and_b32_e32 v183, 0xffff0000, v168
	v_lshlrev_b32_e32 v184, 16, v169
	v_and_b32_e32 v185, 0xffff0000, v169
	v_lshlrev_b32_e32 v168, 16, v128
	v_and_b32_e32 v169, 0xffff0000, v128
	v_mul_f32_e32 v166, v166, v168
	v_mul_f32_e32 v167, v167, v169
	v_lshlrev_b32_e32 v128, 16, v129
	v_mul_f32_e32 v84, v84, v166
	v_mul_f32_e32 v85, v85, v167
	v_rcp_f32_e32 v166, v178
	v_rcp_f32_e32 v167, v179
	v_and_b32_e32 v129, 0xffff0000, v129
	v_mul_f32_e32 v128, v166, v128
	v_mul_f32_e32 v129, v167, v129
	s_nop 0
	v_mul_f32_e32 v86, v86, v128
	v_mul_f32_e32 v87, v87, v129
	v_rcp_f32_e32 v128, v180
	v_rcp_f32_e32 v129, v183
	v_lshlrev_b32_e32 v166, 16, v130
	v_and_b32_e32 v167, 0xffff0000, v130
	v_lshlrev_b32_e32 v130, 16, v131
	v_mul_f32_e32 v128, v128, v166
	v_mul_f32_e32 v129, v129, v167
	v_and_b32_e32 v131, 0xffff0000, v131
	v_mul_f32_e32 v80, v80, v128
	v_mul_f32_e32 v81, v81, v129
	v_rcp_f32_e32 v128, v184
	v_rcp_f32_e32 v129, v185
	s_nop 0
	v_mul_f32_e32 v128, v128, v130
	v_mul_f32_e32 v129, v129, v131
	v_lshl_add_u64 v[130:131], v[134:135], 0, s[0:1]
	v_mul_f32_e32 v82, v82, v128
	v_mul_f32_e32 v83, v83, v129
	v_lshl_add_u64 v[128:129], v[130:131], 0, v[164:165]
	s_mov_b64 s[0:1], 0x61800
	global_load_dwordx4 v[166:169], v[128:129], off
	v_lshl_add_u64 v[128:129], v[134:135], 0, s[0:1]
	v_lshl_add_u64 v[184:185], v[128:129], 0, v[164:165]
	global_load_dwordx4 v[184:187], v[184:185], off
	v_lshl_add_u64 v[130:131], v[130:131], 0, v[132:133]
	v_lshl_add_u64 v[128:129], v[128:129], 0, v[132:133]
	s_mov_b64 s[0:1], 0x101000
	s_waitcnt vmcnt(0)
; __device__ __forceinline__ float bf_lo(unsigned w) { return __uint_as_float(w << 16); }
; __device__ __forceinline__ float bf_hi(unsigned w) { return __uint_as_float(w & 0xffff0000u); }
;     __device__ __forceinline__ void mid(Acc& acc, const Unit& u, int wr, int wc, int fr, int fq) const {
;     ...
;                 const int row = row0 + ai * HALF + m * 16;
; #pragma unroll
;                 for (int bj = 0; bj < 2; ++bj) {
;                     const int col = col0 + bj * HALF;
;                     const u32x4 ga = *(const u32x4*)(P + (size_t)row * PP + C_GA + col), gb = *(const u32x4*)(P + (size_t)row * PP + C_GB + col);
;                     const float ra[8] = {bf_lo(ga.x), bf_hi(ga.x), bf_lo(ga.y), bf_hi(ga.y), bf_lo(ga.z), bf_hi(ga.z), bf_lo(ga.w), bf_hi(ga.w)};
;                     const float rb[8] = {bf_lo(gb.x), bf_hi(gb.x), bf_lo(gb.y), bf_hi(gb.y), bf_lo(gb.z), bf_hi(gb.z), bf_lo(gb.w), bf_hi(gb.w)};
; #pragma unroll
;                     for (int n = 0; n < 2; ++n)
; #pragma unroll
;                         for (int e = 0; e < 4; ++e) acc[ai][bj][m][n][e] *= ra[4 * n + e] * __builtin_amdgcn_rcpf(rb[4 * n + e]);
	v_lshlrev_b32_e32 v153, 16, v184
	v_and_b32_e32 v174, 0xffff0000, v184
	v_lshlrev_b32_e32 v178, 16, v185
	v_and_b32_e32 v179, 0xffff0000, v185
	v_rcp_f32_e32 v184, v153
	v_rcp_f32_e32 v185, v174
	v_lshlrev_b32_e32 v180, 16, v186
	v_and_b32_e32 v183, 0xffff0000, v186
	v_lshlrev_b32_e32 v188, 16, v187
	v_and_b32_e32 v189, 0xffff0000, v187
	v_lshlrev_b32_e32 v186, 16, v166
	v_and_b32_e32 v187, 0xffff0000, v166
	v_mul_f32_e32 v184, v184, v186
	v_mul_f32_e32 v185, v185, v187
	v_lshlrev_b32_e32 v166, 16, v167
	v_mul_f32_e32 v76, v76, v184
	v_mul_f32_e32 v77, v77, v185
	v_rcp_f32_e32 v184, v178
	v_rcp_f32_e32 v185, v179
	v_and_b32_e32 v167, 0xffff0000, v167
	v_mul_f32_e32 v166, v184, v166
	v_mul_f32_e32 v167, v185, v167
	s_nop 0
	v_mul_f32_e32 v78, v78, v166
	v_mul_f32_e32 v79, v79, v167
	v_rcp_f32_e32 v166, v180
	v_rcp_f32_e32 v167, v183
	v_lshlrev_b32_e32 v184, 16, v168
	v_and_b32_e32 v185, 0xffff0000, v168
	v_lshlrev_b32_e32 v168, 16, v169
	v_mul_f32_e32 v166, v166, v184
	v_mul_f32_e32 v167, v167, v185
	v_and_b32_e32 v169, 0xffff0000, v169
	v_mul_f32_e32 v72, v72, v166
	v_mul_f32_e32 v73, v73, v167
	v_rcp_f32_e32 v166, v188
	v_rcp_f32_e32 v167, v189
	s_nop 0
	v_mul_f32_e32 v166, v166, v168
	v_mul_f32_e32 v167, v167, v169
	s_nop 0
	v_mul_f32_e32 v74, v74, v166
	v_mul_f32_e32 v75, v75, v167
	global_load_dwordx4 v[166:169], v[130:131], off
	s_nop 0
	global_load_dwordx4 v[128:131], v[128:129], off
	s_waitcnt vmcnt(0)
	v_lshlrev_b32_e32 v153, 16, v128
	v_and_b32_e32 v174, 0xffff0000, v128
	v_lshlrev_b32_e32 v178, 16, v129
	v_and_b32_e32 v179, 0xffff0000, v129
	v_rcp_f32_e32 v128, v153
	v_rcp_f32_e32 v129, v174
	v_lshlrev_b32_e32 v180, 16, v130
	v_and_b32_e32 v183, 0xffff0000, v130
	v_lshlrev_b32_e32 v184, 16, v131
	v_and_b32_e32 v185, 0xffff0000, v131
	v_lshlrev_b32_e32 v130, 16, v166
	v_and_b32_e32 v131, 0xffff0000, v166
	v_mul_f32_e32 v128, v128, v130
	v_mul_f32_e32 v129, v129, v131
	v_lshlrev_b32_e32 v130, 16, v167
	v_mul_f32_e32 v68, v68, v128
	v_mul_f32_e32 v69, v69, v129
	v_rcp_f32_e32 v128, v178
	v_rcp_f32_e32 v129, v179
	v_and_b32_e32 v131, 0xffff0000, v167
	v_mul_f32_e32 v128, v128, v130
	v_mul_f32_e32 v129, v129, v131
	s_nop 0
	v_mul_f32_e32 v70, v70, v128
	v_mul_f32_e32 v71, v71, v129
	v_rcp_f32_e32 v128, v180
	v_rcp_f32_e32 v129, v183
	v_lshlrev_b32_e32 v130, 16, v168
	v_and_b32_e32 v131, 0xffff0000, v168
	v_mul_f32_e32 v128, v128, v130
	v_mul_f32_e32 v129, v129, v131
	s_nop 0
	v_mul_f32_e32 v64, v64, v128
	v_mul_f32_e32 v65, v65, v129
	v_rcp_f32_e32 v128, v184
	v_rcp_f32_e32 v129, v185
	v_lshlrev_b32_e32 v130, 16, v169
	v_and_b32_e32 v131, 0xffff0000, v169
	v_mul_f32_e32 v128, v128, v130
	v_mul_f32_e32 v129, v129, v131
	v_lshl_add_u64 v[130:131], v[134:135], 0, s[0:1]
	v_mul_f32_e32 v66, v66, v128
	v_mul_f32_e32 v67, v67, v129
	v_lshl_add_u64 v[128:129], v[130:131], 0, v[164:165]
	s_mov_b64 s[0:1], 0x101800
	global_load_dwordx4 v[166:169], v[128:129], off
	v_lshl_add_u64 v[128:129], v[134:135], 0, s[0:1]
	v_lshl_add_u64 v[184:185], v[128:129], 0, v[164:165]
	global_load_dwordx4 v[184:187], v[184:185], off
	v_lshl_add_u64 v[130:131], v[130:131], 0, v[132:133]
	v_lshl_add_u64 v[128:129], v[128:129], 0, v[132:133]
	s_mov_b64 s[0:1], 0x121000
	s_waitcnt vmcnt(0)
	v_lshlrev_b32_e32 v153, 16, v184
	v_and_b32_e32 v174, 0xffff0000, v184
	v_lshlrev_b32_e32 v178, 16, v185
	v_and_b32_e32 v179, 0xffff0000, v185
	v_rcp_f32_e32 v184, v153
	v_rcp_f32_e32 v185, v174
	v_lshlrev_b32_e32 v180, 16, v186
	v_and_b32_e32 v183, 0xffff0000, v186
	v_lshlrev_b32_e32 v188, 16, v187
	v_and_b32_e32 v189, 0xffff0000, v187
	v_lshlrev_b32_e32 v186, 16, v166
	v_and_b32_e32 v187, 0xffff0000, v166
	v_mul_f32_e32 v184, v184, v186
	v_mul_f32_e32 v185, v185, v187
	v_lshlrev_b32_e32 v166, 16, v167
	v_mul_f32_e32 v60, v60, v184
	v_mul_f32_e32 v61, v61, v185
	v_rcp_f32_e32 v184, v178
	v_rcp_f32_e32 v185, v179
	v_and_b32_e32 v167, 0xffff0000, v167
	v_mul_f32_e32 v166, v184, v166
	v_mul_f32_e32 v167, v185, v167
	s_nop 0
	v_mul_f32_e32 v62, v62, v166
	v_mul_f32_e32 v63, v63, v167
	v_rcp_f32_e32 v166, v180
	v_rcp_f32_e32 v167, v183
	v_lshlrev_b32_e32 v184, 16, v168
	v_and_b32_e32 v185, 0xffff0000, v168
	v_lshlrev_b32_e32 v168, 16, v169
	v_mul_f32_e32 v166, v166, v184
	v_mul_f32_e32 v167, v167, v185
	v_and_b32_e32 v169, 0xffff0000, v169
	v_mul_f32_e32 v56, v56, v166
	v_mul_f32_e32 v57, v57, v167
	v_rcp_f32_e32 v166, v188
	v_rcp_f32_e32 v167, v189
	s_nop 0
	v_mul_f32_e32 v166, v166, v168
	v_mul_f32_e32 v167, v167, v169
	s_nop 0
	v_mul_f32_e32 v58, v58, v166
	v_mul_f32_e32 v59, v59, v167
	global_load_dwordx4 v[166:169], v[130:131], off
	s_nop 0
	global_load_dwordx4 v[128:131], v[128:129], off
	s_waitcnt vmcnt(0)
	v_lshlrev_b32_e32 v153, 16, v128
	v_and_b32_e32 v174, 0xffff0000, v128
	v_lshlrev_b32_e32 v178, 16, v129
	v_and_b32_e32 v179, 0xffff0000, v129
	v_rcp_f32_e32 v128, v153
	v_rcp_f32_e32 v129, v174
	v_lshlrev_b32_e32 v180, 16, v130
	v_and_b32_e32 v183, 0xffff0000, v130
	v_lshlrev_b32_e32 v184, 16, v131
	v_and_b32_e32 v185, 0xffff0000, v131
	v_lshlrev_b32_e32 v130, 16, v166
	v_and_b32_e32 v131, 0xffff0000, v166
	v_mul_f32_e32 v128, v128, v130
	v_mul_f32_e32 v129, v129, v131
	v_lshlrev_b32_e32 v130, 16, v167
	v_mul_f32_e32 v52, v52, v128
	v_mul_f32_e32 v53, v53, v129
	v_rcp_f32_e32 v128, v178
	v_rcp_f32_e32 v129, v179
	v_and_b32_e32 v131, 0xffff0000, v167
	v_mul_f32_e32 v128, v128, v130
	v_mul_f32_e32 v129, v129, v131
	s_nop 0
	v_mul_f32_e32 v54, v54, v128
	v_mul_f32_e32 v55, v55, v129
	v_rcp_f32_e32 v128, v180
	v_rcp_f32_e32 v129, v183
	v_lshlrev_b32_e32 v130, 16, v168
	v_and_b32_e32 v131, 0xffff0000, v168
	v_mul_f32_e32 v128, v128, v130
	v_mul_f32_e32 v129, v129, v131
	s_nop 0
	v_mul_f32_e32 v48, v48, v128
	v_mul_f32_e32 v49, v49, v129
	v_rcp_f32_e32 v128, v184
	v_rcp_f32_e32 v129, v185
	v_lshlrev_b32_e32 v130, 16, v169
	v_and_b32_e32 v131, 0xffff0000, v169
	v_mul_f32_e32 v128, v128, v130
	v_mul_f32_e32 v129, v129, v131
	v_lshl_add_u64 v[130:131], v[134:135], 0, s[0:1]
	v_mul_f32_e32 v50, v50, v128
	v_mul_f32_e32 v51, v51, v129
	v_lshl_add_u64 v[128:129], v[130:131], 0, v[164:165]
	s_mov_b64 s[0:1], 0x121800
	global_load_dwordx4 v[166:169], v[128:129], off
	v_lshl_add_u64 v[128:129], v[134:135], 0, s[0:1]
	v_lshl_add_u64 v[184:185], v[128:129], 0, v[164:165]
	global_load_dwordx4 v[184:187], v[184:185], off
	v_lshl_add_u64 v[130:131], v[130:131], 0, v[132:133]
	v_lshl_add_u64 v[128:129], v[128:129], 0, v[132:133]
	s_mov_b64 s[0:1], 0x141000
	s_waitcnt vmcnt(0)
; __device__ __forceinline__ float bf_lo(unsigned w) { return __uint_as_float(w << 16); }
; __device__ __forceinline__ float bf_hi(unsigned w) { return __uint_as_float(w & 0xffff0000u); }
;     __device__ __forceinline__ void mid(Acc& acc, const Unit& u, int wr, int wc, int fr, int fq) const {
;     ...
;                 const int row = row0 + ai * HALF + m * 16;
; #pragma unroll
;                 for (int bj = 0; bj < 2; ++bj) {
;                     const int col = col0 + bj * HALF;
;                     const u32x4 ga = *(const u32x4*)(P + (size_t)row * PP + C_GA + col), gb = *(const u32x4*)(P + (size_t)row * PP + C_GB + col);
;                     const float ra[8] = {bf_lo(ga.x), bf_hi(ga.x), bf_lo(ga.y), bf_hi(ga.y), bf_lo(ga.z), bf_hi(ga.z), bf_lo(ga.w), bf_hi(ga.w)};
;                     const float rb[8] = {bf_lo(gb.x), bf_hi(gb.x), bf_lo(gb.y), bf_hi(gb.y), bf_lo(gb.z), bf_hi(gb.z), bf_lo(gb.w), bf_hi(gb.w)};
; #pragma unroll
;                     for (int n = 0; n < 2; ++n)
; #pragma unroll
;                         for (int e = 0; e < 4; ++e) acc[ai][bj][m][n][e] *= ra[4 * n + e] * __builtin_amdgcn_rcpf(rb[4 * n + e]);
	v_lshlrev_b32_e32 v153, 16, v184
	v_and_b32_e32 v174, 0xffff0000, v184
	v_lshlrev_b32_e32 v178, 16, v185
	v_and_b32_e32 v179, 0xffff0000, v185
	v_rcp_f32_e32 v184, v153
	v_rcp_f32_e32 v185, v174
	v_lshlrev_b32_e32 v180, 16, v186
	v_and_b32_e32 v183, 0xffff0000, v186
	v_lshlrev_b32_e32 v188, 16, v187
	v_and_b32_e32 v189, 0xffff0000, v187
	v_lshlrev_b32_e32 v186, 16, v166
	v_and_b32_e32 v187, 0xffff0000, v166
	v_mul_f32_e32 v184, v184, v186
	v_mul_f32_e32 v185, v185, v187
	v_lshlrev_b32_e32 v166, 16, v167
	v_mul_f32_e32 v44, v44, v184
	v_mul_f32_e32 v45, v45, v185
	v_rcp_f32_e32 v184, v178
	v_rcp_f32_e32 v185, v179
	v_and_b32_e32 v167, 0xffff0000, v167
	v_mul_f32_e32 v166, v184, v166
	v_mul_f32_e32 v167, v185, v167
	s_nop 0
	v_mul_f32_e32 v46, v46, v166
	v_mul_f32_e32 v47, v47, v167
	v_rcp_f32_e32 v166, v180
	v_rcp_f32_e32 v167, v183
	v_lshlrev_b32_e32 v184, 16, v168
	v_and_b32_e32 v185, 0xffff0000, v168
	v_lshlrev_b32_e32 v168, 16, v169
	v_mul_f32_e32 v166, v166, v184
	v_mul_f32_e32 v167, v167, v185
	v_and_b32_e32 v169, 0xffff0000, v169
	v_mul_f32_e32 v40, v40, v166
	v_mul_f32_e32 v41, v41, v167
	v_rcp_f32_e32 v166, v188
	v_rcp_f32_e32 v167, v189
	s_nop 0
	v_mul_f32_e32 v166, v166, v168
	v_mul_f32_e32 v167, v167, v169
	s_nop 0
	v_mul_f32_e32 v42, v42, v166
	v_mul_f32_e32 v43, v43, v167
	global_load_dwordx4 v[166:169], v[130:131], off
	s_nop 0
	global_load_dwordx4 v[128:131], v[128:129], off
	s_waitcnt vmcnt(0)
	v_lshlrev_b32_e32 v153, 16, v128
	v_and_b32_e32 v174, 0xffff0000, v128
	v_lshlrev_b32_e32 v178, 16, v129
	v_and_b32_e32 v179, 0xffff0000, v129
	v_rcp_f32_e32 v128, v153
	v_rcp_f32_e32 v129, v174
	v_lshlrev_b32_e32 v180, 16, v130
	v_and_b32_e32 v183, 0xffff0000, v130
	v_lshlrev_b32_e32 v184, 16, v131
	v_and_b32_e32 v185, 0xffff0000, v131
	v_lshlrev_b32_e32 v130, 16, v166
	v_and_b32_e32 v131, 0xffff0000, v166
	v_mul_f32_e32 v128, v128, v130
	v_mul_f32_e32 v129, v129, v131
	v_lshlrev_b32_e32 v130, 16, v167
	v_mul_f32_e32 v36, v36, v128
	v_mul_f32_e32 v37, v37, v129
	v_rcp_f32_e32 v128, v178
	v_rcp_f32_e32 v129, v179
	v_and_b32_e32 v131, 0xffff0000, v167
	v_mul_f32_e32 v128, v128, v130
	v_mul_f32_e32 v129, v129, v131
	s_nop 0
	v_mul_f32_e32 v38, v38, v128
	v_mul_f32_e32 v39, v39, v129
	v_rcp_f32_e32 v128, v180
	v_rcp_f32_e32 v129, v183
	v_lshlrev_b32_e32 v130, 16, v168
	v_and_b32_e32 v131, 0xffff0000, v168
	v_mul_f32_e32 v128, v128, v130
	v_mul_f32_e32 v129, v129, v131
	s_nop 0
	v_mul_f32_e32 v32, v32, v128
	v_mul_f32_e32 v33, v33, v129
	v_rcp_f32_e32 v128, v184
	v_rcp_f32_e32 v129, v185
	v_lshlrev_b32_e32 v130, 16, v169
	v_and_b32_e32 v131, 0xffff0000, v169
	v_mul_f32_e32 v128, v128, v130
	v_mul_f32_e32 v129, v129, v131
	v_lshl_add_u64 v[130:131], v[134:135], 0, s[0:1]
	v_mul_f32_e32 v34, v34, v128
	v_mul_f32_e32 v35, v35, v129
	v_lshl_add_u64 v[128:129], v[130:131], 0, v[164:165]
	s_mov_b64 s[0:1], 0x141800
	global_load_dwordx4 v[166:169], v[128:129], off
	v_lshl_add_u64 v[128:129], v[134:135], 0, s[0:1]
	v_lshl_add_u64 v[184:185], v[128:129], 0, v[164:165]
	global_load_dwordx4 v[184:187], v[184:185], off
	v_lshl_add_u64 v[130:131], v[130:131], 0, v[132:133]
	v_lshl_add_u64 v[128:129], v[128:129], 0, v[132:133]
	s_waitcnt vmcnt(0)
	v_lshlrev_b32_e32 v153, 16, v184
	v_and_b32_e32 v174, 0xffff0000, v184
	v_lshlrev_b32_e32 v178, 16, v185
	v_and_b32_e32 v179, 0xffff0000, v185
	v_rcp_f32_e32 v184, v153
	v_rcp_f32_e32 v185, v174
	v_lshlrev_b32_e32 v180, 16, v186
	v_and_b32_e32 v183, 0xffff0000, v186
	v_lshlrev_b32_e32 v188, 16, v187
	v_and_b32_e32 v189, 0xffff0000, v187
	v_lshlrev_b32_e32 v186, 16, v166
	v_and_b32_e32 v187, 0xffff0000, v166
	v_mul_f32_e32 v184, v184, v186
	v_mul_f32_e32 v185, v185, v187
	v_lshlrev_b32_e32 v166, 16, v167
	v_mul_f32_e32 v28, v28, v184
	v_mul_f32_e32 v29, v29, v185
	v_rcp_f32_e32 v184, v178
	v_rcp_f32_e32 v185, v179
	v_and_b32_e32 v167, 0xffff0000, v167
	v_mul_f32_e32 v166, v184, v166
	v_mul_f32_e32 v167, v185, v167
	s_nop 0
	v_mul_f32_e32 v30, v30, v166
	v_mul_f32_e32 v31, v31, v167
	v_rcp_f32_e32 v166, v180
	v_rcp_f32_e32 v167, v183
	v_lshlrev_b32_e32 v184, 16, v168
	v_and_b32_e32 v185, 0xffff0000, v168
	v_lshlrev_b32_e32 v168, 16, v169
	v_mul_f32_e32 v166, v166, v184
	v_mul_f32_e32 v167, v167, v185
	v_and_b32_e32 v169, 0xffff0000, v169
	v_mul_f32_e32 v24, v24, v166
	v_mul_f32_e32 v25, v25, v167
	v_rcp_f32_e32 v166, v188
	v_rcp_f32_e32 v167, v189
	s_nop 0
	v_mul_f32_e32 v166, v166, v168
	v_mul_f32_e32 v167, v167, v169
	s_nop 0
	v_mul_f32_e32 v26, v26, v166
	v_mul_f32_e32 v27, v27, v167
	global_load_dwordx4 v[166:169], v[130:131], off
	s_nop 0
	global_load_dwordx4 v[128:131], v[128:129], off
	s_waitcnt vmcnt(0)
; __device__ __forceinline__ float bf_lo(unsigned w) { return __uint_as_float(w << 16); }
; __device__ __forceinline__ float bf_hi(unsigned w) { return __uint_as_float(w & 0xffff0000u); }
;     __device__ __forceinline__ void mid(Acc& acc, const Unit& u, int wr, int wc, int fr, int fq) const {
;     ...
;                 const int row = row0 + ai * HALF + m * 16;
; #pragma unroll
;                 for (int bj = 0; bj < 2; ++bj) {
;                     const int col = col0 + bj * HALF;
;                     const u32x4 ga = *(const u32x4*)(P + (size_t)row * PP + C_GA + col), gb = *(const u32x4*)(P + (size_t)row * PP + C_GB + col);
;                     const float ra[8] = {bf_lo(ga.x), bf_hi(ga.x), bf_lo(ga.y), bf_hi(ga.y), bf_lo(ga.z), bf_hi(ga.z), bf_lo(ga.w), bf_hi(ga.w)};
;                     const float rb[8] = {bf_lo(gb.x), bf_hi(gb.x), bf_lo(gb.y), bf_hi(gb.y), bf_lo(gb.z), bf_hi(gb.z), bf_lo(gb.w), bf_hi(gb.w)};
; #pragma unroll
;                     for (int n = 0; n < 2; ++n)
; #pragma unroll
;                         for (int e = 0; e < 4; ++e) acc[ai][bj][m][n][e] *= ra[4 * n + e] * __builtin_amdgcn_rcpf(rb[4 * n + e]);
	v_lshlrev_b32_e32 v153, 16, v128
	v_and_b32_e32 v174, 0xffff0000, v128
	v_lshlrev_b32_e32 v178, 16, v129
	v_and_b32_e32 v179, 0xffff0000, v129
	v_rcp_f32_e32 v128, v153
	v_rcp_f32_e32 v129, v174
	v_lshlrev_b32_e32 v180, 16, v130
	v_and_b32_e32 v183, 0xffff0000, v130
	v_lshlrev_b32_e32 v184, 16, v131
	v_and_b32_e32 v185, 0xffff0000, v131
	v_lshlrev_b32_e32 v130, 16, v166
	v_and_b32_e32 v131, 0xffff0000, v166
	v_mul_f32_e32 v128, v128, v130
	v_mul_f32_e32 v129, v129, v131
	v_lshlrev_b32_e32 v130, 16, v167
	v_mul_f32_e32 v20, v20, v128
	v_mul_f32_e32 v21, v21, v129
	v_rcp_f32_e32 v128, v178
	v_rcp_f32_e32 v129, v179
	v_and_b32_e32 v131, 0xffff0000, v167
	v_mul_f32_e32 v128, v128, v130
	v_mul_f32_e32 v129, v129, v131
	s_nop 0
	v_mul_f32_e32 v22, v22, v128
	v_mul_f32_e32 v23, v23, v129
	v_rcp_f32_e32 v128, v180
	v_rcp_f32_e32 v129, v183
	v_lshlrev_b32_e32 v130, 16, v168
	v_and_b32_e32 v131, 0xffff0000, v168
	v_mul_f32_e32 v128, v128, v130
	v_mul_f32_e32 v129, v129, v131
	s_nop 0
	v_mul_f32_e32 v16, v16, v128
	v_mul_f32_e32 v17, v17, v129
	v_rcp_f32_e32 v128, v184
	v_rcp_f32_e32 v129, v185
	v_lshlrev_b32_e32 v130, 16, v169
	v_and_b32_e32 v131, 0xffff0000, v169
	v_lshl_add_u64 v[168:169], v[134:135], 0, s[36:37]
	v_mul_f32_e32 v128, v128, v130
	v_mul_f32_e32 v129, v129, v131
	v_lshl_add_u64 v[134:135], v[134:135], 0, s[38:39]
	v_mul_f32_e32 v18, v18, v128
	v_mul_f32_e32 v19, v19, v129
	v_lshl_add_u64 v[128:129], v[168:169], 0, v[164:165]
	v_lshl_add_u64 v[164:165], v[134:135], 0, v[164:165]
	global_load_dwordx4 v[128:131], v[128:129], off
	s_nop 0
	global_load_dwordx4 v[164:167], v[164:165], off
	s_waitcnt vmcnt(0)
	v_lshlrev_b32_e32 v153, 16, v164
	v_and_b32_e32 v174, 0xffff0000, v164
	v_lshlrev_b32_e32 v178, 16, v165
	v_and_b32_e32 v179, 0xffff0000, v165
	v_rcp_f32_e32 v164, v153
	v_rcp_f32_e32 v165, v174
	v_lshlrev_b32_e32 v180, 16, v166
	v_and_b32_e32 v183, 0xffff0000, v166
	v_lshlrev_b32_e32 v184, 16, v167
	v_and_b32_e32 v185, 0xffff0000, v167
	v_lshlrev_b32_e32 v166, 16, v128
	v_and_b32_e32 v167, 0xffff0000, v128
	v_mul_f32_e32 v164, v164, v166
	v_mul_f32_e32 v165, v165, v167
	v_lshlrev_b32_e32 v128, 16, v129
	v_mul_f32_e32 v12, v12, v164
	v_mul_f32_e32 v13, v13, v165
	v_rcp_f32_e32 v164, v178
	v_rcp_f32_e32 v165, v179
	v_and_b32_e32 v129, 0xffff0000, v129
	v_mul_f32_e32 v128, v164, v128
	v_mul_f32_e32 v129, v165, v129
	s_nop 0
	v_mul_f32_e32 v14, v14, v128
	v_mul_f32_e32 v15, v15, v129
	v_rcp_f32_e32 v128, v180
	v_rcp_f32_e32 v129, v183
	v_lshlrev_b32_e32 v164, 16, v130
	v_and_b32_e32 v165, 0xffff0000, v130
	v_lshlrev_b32_e32 v130, 16, v131
	v_mul_f32_e32 v128, v128, v164
	v_mul_f32_e32 v129, v129, v165
	v_and_b32_e32 v131, 0xffff0000, v131
	v_mul_f32_e32 v8, v8, v128
	v_mul_f32_e32 v9, v9, v129
	v_rcp_f32_e32 v128, v184
	v_rcp_f32_e32 v129, v185
	s_nop 0
	v_mul_f32_e32 v128, v128, v130
	v_mul_f32_e32 v129, v129, v131
	s_nop 0
	v_mul_f32_e32 v10, v10, v128
	v_mul_f32_e32 v11, v11, v129
	v_lshl_add_u64 v[128:129], v[168:169], 0, v[132:133]
	v_lshl_add_u64 v[132:133], v[134:135], 0, v[132:133]
	global_load_dwordx4 v[128:131], v[128:129], off
	s_nop 0
	global_load_dwordx4 v[132:135], v[132:133], off
	s_waitcnt vmcnt(0)
	v_lshlrev_b32_e32 v153, 16, v132
	v_and_b32_e32 v164, 0xffff0000, v132
	v_lshlrev_b32_e32 v165, 16, v133
	v_and_b32_e32 v166, 0xffff0000, v133
	v_rcp_f32_e32 v132, v153
	v_rcp_f32_e32 v133, v164
	v_lshlrev_b32_e32 v167, 16, v134
	v_and_b32_e32 v168, 0xffff0000, v134
	v_lshlrev_b32_e32 v169, 16, v135
	v_and_b32_e32 v174, 0xffff0000, v135
	v_lshlrev_b32_e32 v134, 16, v128
	v_and_b32_e32 v135, 0xffff0000, v128
	v_mul_f32_e32 v132, v132, v134
	v_mul_f32_e32 v133, v133, v135
	v_lshlrev_b32_e32 v128, 16, v129
	v_mul_f32_e32 v4, v4, v132
	v_mul_f32_e32 v5, v5, v133
	v_rcp_f32_e32 v132, v165
	v_rcp_f32_e32 v133, v166
	v_and_b32_e32 v129, 0xffff0000, v129
	v_mul_f32_e32 v128, v132, v128
	v_mul_f32_e32 v129, v133, v129
	s_nop 0
	v_mul_f32_e32 v6, v6, v128
	v_mul_f32_e32 v7, v7, v129
	v_rcp_f32_e32 v128, v167
	v_rcp_f32_e32 v129, v168
	v_lshlrev_b32_e32 v132, 16, v130
	v_and_b32_e32 v133, 0xffff0000, v130
	v_lshlrev_b32_e32 v130, 16, v131
	v_mul_f32_e32 v128, v128, v132
	v_mul_f32_e32 v129, v129, v133
	v_and_b32_e32 v131, 0xffff0000, v131
	v_mul_f32_e32 v0, v0, v128
	v_mul_f32_e32 v1, v1, v129
	v_rcp_f32_e32 v128, v169
	v_rcp_f32_e32 v129, v174
	s_nop 0
	v_mul_f32_e32 v128, v128, v130
	v_mul_f32_e32 v129, v129, v131
	s_nop 0
	v_mul_f32_e32 v2, v2, v128
	v_mul_f32_e32 v3, v3, v129
	s_branch .LBB0_1083

; __device__ __forceinline__ unsigned cvt_pk_bf16(float lo, float hi) { f32x2_t v = {lo, hi}; bf16x2_t b = __builtin_convertvector(v, bf16x2_t); return __builtin_bit_cast(unsigned, b); }
; __device__ __forceinline__ float bf_lo(unsigned w) { return __uint_as_float(w << 16); }
; __device__ __forceinline__ float bf_hi(unsigned w) { return __uint_as_float(w & 0xffff0000u); }
;     __device__ __forceinline__ void operator()(const Acc& acc, const Unit& u, int wr, int wc, int fr, int fq) const {
;     ...
;                 const int row = row0 + ai * HALF + m * 16;
; #pragma unroll
;                 for (int bj = 0; bj < 2; ++bj) {
;                     const int col = col0 + bj * HALF;
;                     const u32x4 gb = *(const u32x4*)(P + (size_t)row * PP + C_GB + col);
;                     const float rb[8] = {bf_lo(gb.x), bf_hi(gb.x), bf_lo(gb.y), bf_hi(gb.y), bf_lo(gb.z), bf_hi(gb.z), bf_lo(gb.w), bf_hi(gb.w)};
;                     float o[8];
; #pragma unroll
;                     for (int n = 0; n < 2; ++n)
; #pragma unroll
;                         for (int e = 0; e < 4; ++e) o[4 * n + e] = acc[ai][bj][m][n][e] * rb[4 * n + e];
;                     u32x4 w; w.x = cvt_pk_bf16(o[0], o[1]); w.y = cvt_pk_bf16(o[2], o[3]); w.z = cvt_pk_bf16(o[4], o[5]); w.w = cvt_pk_bf16(o[6], o[7]);
;                     *(u32x4*)(OUT + (size_t)row * DM + col) = w;
.LBB0_1088:
	v_ashrrev_i32_e32 v153, 31, v152
	v_lshlrev_b64 v[128:129], 13, v[152:153]
	v_lshl_add_u64 v[128:129], s[20:21], 0, v[128:129]
	v_lshl_add_u64 v[158:159], v[128:129], 0, s[14:15]
	v_lshlrev_b64 v[128:129], 1, v[156:157]
	v_lshl_add_u64 v[130:131], v[158:159], 0, v[128:129]
	global_load_dwordx4 v[132:135], v[130:131], off
	v_lshlrev_b64 v[130:131], 1, v[154:155]
	v_lshl_add_u64 v[154:155], v[158:159], 0, v[130:131]
	global_load_dwordx4 v[154:157], v[154:155], off
	v_or_b32_e32 v158, 16, v152
	v_ashrrev_i32_e32 v159, 31, v158
	v_lshlrev_b64 v[162:163], 11, v[152:153]
	v_lshlrev_b64 v[164:165], 13, v[158:159]
	v_lshl_add_u64 v[162:163], s[70:71], 0, v[162:163]
	v_lshl_add_u64 v[164:165], s[20:21], 0, v[164:165]
	v_lshl_add_u64 v[162:163], v[162:163], 0, v[128:129]
	v_lshl_add_u64 v[164:165], v[164:165], 0, s[14:15]
	v_lshl_add_u64 v[166:167], v[164:165], 0, v[128:129]
	v_lshl_add_u64 v[164:165], v[164:165], 0, v[130:131]
	s_andn2_b64 vcc, exec, s[8:9]
	s_mov_b64 s[6:7], -1
	s_waitcnt vmcnt(0)
	v_lshlrev_b32_e32 v168, 16, v132
	v_and_b32_e32 v169, 0xffff0000, v132
	v_lshlrev_b32_e32 v132, 16, v133
	v_and_b32_e32 v133, 0xffff0000, v133
	v_lshlrev_b32_e32 v184, 16, v134
	v_and_b32_e32 v185, 0xffff0000, v134
	v_lshlrev_b32_e32 v134, 16, v135
	v_and_b32_e32 v135, 0xffff0000, v135
	v_lshlrev_b32_e32 v186, 16, v154
	v_and_b32_e32 v187, 0xffff0000, v154
	v_lshlrev_b32_e32 v154, 16, v155
	v_and_b32_e32 v155, 0xffff0000, v155
	v_lshlrev_b32_e32 v188, 16, v156
	v_and_b32_e32 v189, 0xffff0000, v156
	v_lshlrev_b32_e32 v156, 16, v157
	v_and_b32_e32 v157, 0xffff0000, v157
	v_mul_f32_e32 v124, v124, v168
	v_mul_f32_e32 v125, v125, v169
	v_mul_f32_e32 v126, v126, v132
	v_mul_f32_e32 v127, v127, v133
	v_mul_f32_e32 v120, v120, v184
	v_mul_f32_e32 v121, v121, v185
	v_mul_f32_e32 v122, v122, v134
	v_mul_f32_e32 v123, v123, v135
	v_mul_f32_e32 v132, v116, v186
	v_mul_f32_e32 v133, v117, v187
	v_mul_f32_e32 v134, v118, v154
	v_mul_f32_e32 v135, v119, v155
	v_cvt_pk_bf16_f32 v116, v124, v125
	v_cvt_pk_bf16_f32 v117, v126, v127
	v_cvt_pk_bf16_f32 v118, v120, v121
	v_cvt_pk_bf16_f32 v119, v122, v123
	v_mul_f32_e32 v120, v112, v188
	v_mul_f32_e32 v121, v113, v189
	v_mul_f32_e32 v122, v114, v156
	v_mul_f32_e32 v123, v115, v157
	global_store_dwordx4 v[162:163], v[116:119], off
	v_cvt_pk_bf16_f32 v112, v132, v133
	v_cvt_pk_bf16_f32 v113, v134, v135
	v_cvt_pk_bf16_f32 v114, v120, v121
	v_cvt_pk_bf16_f32 v115, v122, v123
	global_load_dwordx4 v[116:119], v[166:167], off
	v_or_b32_e32 v120, 32, v152
	global_store_dwordx4 v[162:163], v[112:115], off offset:256
	global_load_dwordx4 v[112:115], v[164:165], off
	v_ashrrev_i32_e32 v121, 31, v120
	v_lshlrev_b64 v[122:123], 11, v[158:159]
	v_lshlrev_b64 v[124:125], 13, v[120:121]
	v_lshl_add_u64 v[122:123], s[70:71], 0, v[122:123]
	v_lshl_add_u64 v[124:125], s[20:21], 0, v[124:125]
	v_lshl_add_u64 v[122:123], v[122:123], 0, v[128:129]
	v_lshl_add_u64 v[124:125], v[124:125], 0, s[14:15]
	v_lshl_add_u64 v[126:127], v[124:125], 0, v[128:129]
	v_lshl_add_u64 v[124:125], v[124:125], 0, v[130:131]
	s_waitcnt vmcnt(2)
	v_lshlrev_b32_e32 v132, 16, v116
	v_and_b32_e32 v133, 0xffff0000, v116
	v_lshlrev_b32_e32 v116, 16, v117
	v_and_b32_e32 v117, 0xffff0000, v117
	v_lshlrev_b32_e32 v134, 16, v118
	v_and_b32_e32 v135, 0xffff0000, v118
	v_lshlrev_b32_e32 v118, 16, v119
	v_and_b32_e32 v119, 0xffff0000, v119
	s_waitcnt vmcnt(0)
	v_lshlrev_b32_e32 v154, 16, v112
	v_and_b32_e32 v155, 0xffff0000, v112
	v_lshlrev_b32_e32 v112, 16, v113
	v_and_b32_e32 v113, 0xffff0000, v113
	v_lshlrev_b32_e32 v156, 16, v114
	v_and_b32_e32 v157, 0xffff0000, v114
	v_lshlrev_b32_e32 v114, 16, v115
	v_and_b32_e32 v115, 0xffff0000, v115
	v_mul_f32_e32 v108, v108, v132
	v_mul_f32_e32 v109, v109, v133
	v_mul_f32_e32 v110, v110, v116
	v_mul_f32_e32 v111, v111, v117
	v_mul_f32_e32 v104, v104, v134
	v_mul_f32_e32 v105, v105, v135
	v_mul_f32_e32 v106, v106, v118
	v_mul_f32_e32 v107, v107, v119
	v_mul_f32_e32 v116, v100, v154
	v_mul_f32_e32 v117, v101, v155
	v_mul_f32_e32 v112, v102, v112
	v_mul_f32_e32 v113, v103, v113
	v_cvt_pk_bf16_f32 v100, v108, v109
	v_cvt_pk_bf16_f32 v101, v110, v111
	v_cvt_pk_bf16_f32 v102, v104, v105
	v_cvt_pk_bf16_f32 v103, v106, v107
	v_mul_f32_e32 v104, v96, v156
	v_mul_f32_e32 v105, v97, v157
	v_mul_f32_e32 v106, v98, v114
	v_mul_f32_e32 v107, v99, v115
	global_store_dwordx4 v[122:123], v[100:103], off
	v_cvt_pk_bf16_f32 v96, v116, v117
	v_cvt_pk_bf16_f32 v97, v112, v113
	v_cvt_pk_bf16_f32 v98, v104, v105
	v_cvt_pk_bf16_f32 v99, v106, v107
	global_load_dwordx4 v[100:103], v[126:127], off
	v_or_b32_e32 v104, 48, v152
	global_store_dwordx4 v[122:123], v[96:99], off offset:256
	global_load_dwordx4 v[96:99], v[124:125], off
	v_ashrrev_i32_e32 v105, 31, v104
	v_lshlrev_b64 v[106:107], 11, v[120:121]
	v_lshlrev_b64 v[108:109], 13, v[104:105]
	v_lshl_add_u64 v[106:107], s[70:71], 0, v[106:107]
	v_lshl_add_u64 v[108:109], s[20:21], 0, v[108:109]
	v_lshl_add_u64 v[106:107], v[106:107], 0, v[128:129]
	v_lshl_add_u64 v[108:109], v[108:109], 0, s[14:15]
	v_lshl_add_u64 v[110:111], v[108:109], 0, v[128:129]
	v_lshl_add_u64 v[108:109], v[108:109], 0, v[130:131]
	s_waitcnt vmcnt(2)
	v_lshlrev_b32_e32 v112, 16, v100
	v_and_b32_e32 v113, 0xffff0000, v100
	v_lshlrev_b32_e32 v100, 16, v101
	v_and_b32_e32 v101, 0xffff0000, v101
	v_lshlrev_b32_e32 v114, 16, v102
	v_and_b32_e32 v115, 0xffff0000, v102
	v_lshlrev_b32_e32 v102, 16, v103
	v_and_b32_e32 v103, 0xffff0000, v103
	s_waitcnt vmcnt(0)
; __device__ __forceinline__ unsigned cvt_pk_bf16(float lo, float hi) { f32x2_t v = {lo, hi}; bf16x2_t b = __builtin_convertvector(v, bf16x2_t); return __builtin_bit_cast(unsigned, b); }
; __device__ __forceinline__ float bf_lo(unsigned w) { return __uint_as_float(w << 16); }
; __device__ __forceinline__ float bf_hi(unsigned w) { return __uint_as_float(w & 0xffff0000u); }
;     __device__ __forceinline__ void operator()(const Acc& acc, const Unit& u, int wr, int wc, int fr, int fq) const {
;     ...
;                 const int row = row0 + ai * HALF + m * 16;
; #pragma unroll
;                 for (int bj = 0; bj < 2; ++bj) {
;                     const int col = col0 + bj * HALF;
;                     const u32x4 gb = *(const u32x4*)(P + (size_t)row * PP + C_GB + col);
;                     const float rb[8] = {bf_lo(gb.x), bf_hi(gb.x), bf_lo(gb.y), bf_hi(gb.y), bf_lo(gb.z), bf_hi(gb.z), bf_lo(gb.w), bf_hi(gb.w)};
;                     float o[8];
; #pragma unroll
;                     for (int n = 0; n < 2; ++n)
; #pragma unroll
;                         for (int e = 0; e < 4; ++e) o[4 * n + e] = acc[ai][bj][m][n][e] * rb[4 * n + e];
;                     u32x4 w; w.x = cvt_pk_bf16(o[0], o[1]); w.y = cvt_pk_bf16(o[2], o[3]); w.z = cvt_pk_bf16(o[4], o[5]); w.w = cvt_pk_bf16(o[6], o[7]);
;                     *(u32x4*)(OUT + (size_t)row * DM + col) = w;
	v_lshlrev_b32_e32 v116, 16, v96
	v_and_b32_e32 v117, 0xffff0000, v96
	v_lshlrev_b32_e32 v96, 16, v97
	v_and_b32_e32 v97, 0xffff0000, v97
	v_lshlrev_b32_e32 v118, 16, v98
	v_and_b32_e32 v119, 0xffff0000, v98
	v_lshlrev_b32_e32 v98, 16, v99
	v_and_b32_e32 v99, 0xffff0000, v99
	v_mul_f32_e32 v92, v92, v112
	v_mul_f32_e32 v93, v93, v113
	v_mul_f32_e32 v94, v94, v100
	v_mul_f32_e32 v95, v95, v101
	v_mul_f32_e32 v88, v88, v114
	v_mul_f32_e32 v89, v89, v115
	v_mul_f32_e32 v90, v90, v102
	v_mul_f32_e32 v91, v91, v103
	v_mul_f32_e32 v100, v84, v116
	v_mul_f32_e32 v101, v85, v117
	v_mul_f32_e32 v96, v86, v96
	v_mul_f32_e32 v97, v87, v97
	v_cvt_pk_bf16_f32 v84, v92, v93
	v_cvt_pk_bf16_f32 v85, v94, v95
	v_cvt_pk_bf16_f32 v86, v88, v89
	v_cvt_pk_bf16_f32 v87, v90, v91
	v_mul_f32_e32 v88, v80, v118
	v_mul_f32_e32 v89, v81, v119
	v_mul_f32_e32 v90, v82, v98
	v_mul_f32_e32 v91, v83, v99
	global_store_dwordx4 v[106:107], v[84:87], off
	v_cvt_pk_bf16_f32 v80, v100, v101
	v_cvt_pk_bf16_f32 v81, v96, v97
	v_cvt_pk_bf16_f32 v82, v88, v89
	v_cvt_pk_bf16_f32 v83, v90, v91
	global_load_dwordx4 v[84:87], v[110:111], off
	v_add_u32_e32 v88, 0x80, v152
	global_store_dwordx4 v[106:107], v[80:83], off offset:256
	global_load_dwordx4 v[80:83], v[108:109], off
	v_ashrrev_i32_e32 v89, 31, v88
	v_lshlrev_b64 v[90:91], 11, v[104:105]
	v_lshlrev_b64 v[92:93], 13, v[88:89]
	v_lshl_add_u64 v[90:91], s[70:71], 0, v[90:91]
	v_lshl_add_u64 v[92:93], s[20:21], 0, v[92:93]
	v_lshl_add_u64 v[90:91], v[90:91], 0, v[128:129]
	v_lshl_add_u64 v[92:93], v[92:93], 0, s[14:15]
	v_lshl_add_u64 v[94:95], v[92:93], 0, v[128:129]
	v_lshl_add_u64 v[92:93], v[92:93], 0, v[130:131]
	s_waitcnt vmcnt(2)
	v_lshlrev_b32_e32 v96, 16, v84
	v_and_b32_e32 v97, 0xffff0000, v84
	v_lshlrev_b32_e32 v84, 16, v85
	v_and_b32_e32 v85, 0xffff0000, v85
	v_lshlrev_b32_e32 v98, 16, v86
	v_and_b32_e32 v99, 0xffff0000, v86
	v_lshlrev_b32_e32 v86, 16, v87
	v_and_b32_e32 v87, 0xffff0000, v87
	s_waitcnt vmcnt(0)
	v_lshlrev_b32_e32 v100, 16, v80
	v_and_b32_e32 v101, 0xffff0000, v80
	v_lshlrev_b32_e32 v80, 16, v81
	v_and_b32_e32 v81, 0xffff0000, v81
	v_lshlrev_b32_e32 v102, 16, v82
	v_and_b32_e32 v103, 0xffff0000, v82
	v_lshlrev_b32_e32 v82, 16, v83
	v_and_b32_e32 v83, 0xffff0000, v83
	v_mul_f32_e32 v76, v76, v96
	v_mul_f32_e32 v77, v77, v97
	v_mul_f32_e32 v78, v78, v84
	v_mul_f32_e32 v79, v79, v85
	v_mul_f32_e32 v72, v72, v98
	v_mul_f32_e32 v73, v73, v99
	v_mul_f32_e32 v74, v74, v86
	v_mul_f32_e32 v75, v75, v87
	v_mul_f32_e32 v84, v68, v100
	v_mul_f32_e32 v85, v69, v101
	v_mul_f32_e32 v80, v70, v80
	v_mul_f32_e32 v81, v71, v81
	v_cvt_pk_bf16_f32 v68, v76, v77
	v_cvt_pk_bf16_f32 v69, v78, v79
	v_cvt_pk_bf16_f32 v70, v72, v73
	v_cvt_pk_bf16_f32 v71, v74, v75
	v_mul_f32_e32 v72, v64, v102
	v_mul_f32_e32 v73, v65, v103
	v_mul_f32_e32 v74, v66, v82
	v_mul_f32_e32 v75, v67, v83
	global_store_dwordx4 v[90:91], v[68:71], off
	v_cvt_pk_bf16_f32 v64, v84, v85
	v_cvt_pk_bf16_f32 v65, v80, v81
	v_cvt_pk_bf16_f32 v66, v72, v73
	v_cvt_pk_bf16_f32 v67, v74, v75
	global_load_dwordx4 v[68:71], v[94:95], off
	v_add_u32_e32 v72, 0x90, v152
	global_store_dwordx4 v[90:91], v[64:67], off offset:256
	global_load_dwordx4 v[64:67], v[92:93], off
	v_ashrrev_i32_e32 v73, 31, v72
	v_lshlrev_b64 v[74:75], 11, v[88:89]
	v_lshlrev_b64 v[76:77], 13, v[72:73]
	v_lshl_add_u64 v[74:75], s[70:71], 0, v[74:75]
	v_lshl_add_u64 v[76:77], s[20:21], 0, v[76:77]
	v_lshl_add_u64 v[74:75], v[74:75], 0, v[128:129]
	v_lshl_add_u64 v[76:77], v[76:77], 0, s[14:15]
	v_lshl_add_u64 v[78:79], v[76:77], 0, v[128:129]
	v_lshl_add_u64 v[76:77], v[76:77], 0, v[130:131]
	s_waitcnt vmcnt(2)
	v_lshlrev_b32_e32 v80, 16, v68
	v_and_b32_e32 v81, 0xffff0000, v68
	v_lshlrev_b32_e32 v68, 16, v69
	v_and_b32_e32 v69, 0xffff0000, v69
	v_lshlrev_b32_e32 v82, 16, v70
	v_and_b32_e32 v83, 0xffff0000, v70
	v_lshlrev_b32_e32 v70, 16, v71
	v_and_b32_e32 v71, 0xffff0000, v71
	s_waitcnt vmcnt(0)
	v_lshlrev_b32_e32 v84, 16, v64
	v_and_b32_e32 v85, 0xffff0000, v64
	v_lshlrev_b32_e32 v64, 16, v65
	v_and_b32_e32 v65, 0xffff0000, v65
	v_lshlrev_b32_e32 v86, 16, v66
	v_and_b32_e32 v87, 0xffff0000, v66
	v_lshlrev_b32_e32 v66, 16, v67
	v_and_b32_e32 v67, 0xffff0000, v67
	v_mul_f32_e32 v60, v60, v80
	v_mul_f32_e32 v61, v61, v81
	v_mul_f32_e32 v62, v62, v68
	v_mul_f32_e32 v63, v63, v69
	v_mul_f32_e32 v56, v56, v82
	v_mul_f32_e32 v57, v57, v83
	v_mul_f32_e32 v58, v58, v70
	v_mul_f32_e32 v59, v59, v71
	v_mul_f32_e32 v68, v52, v84
	v_mul_f32_e32 v69, v53, v85
	v_mul_f32_e32 v64, v54, v64
	v_mul_f32_e32 v65, v55, v65
	v_cvt_pk_bf16_f32 v52, v60, v61
	v_cvt_pk_bf16_f32 v53, v62, v63
	v_cvt_pk_bf16_f32 v54, v56, v57
	v_cvt_pk_bf16_f32 v55, v58, v59
	v_mul_f32_e32 v56, v48, v86
	v_mul_f32_e32 v57, v49, v87
	v_mul_f32_e32 v58, v50, v66
	v_mul_f32_e32 v59, v51, v67
	global_store_dwordx4 v[74:75], v[52:55], off
	v_cvt_pk_bf16_f32 v48, v68, v69
	v_cvt_pk_bf16_f32 v49, v64, v65
	v_cvt_pk_bf16_f32 v50, v56, v57
	v_cvt_pk_bf16_f32 v51, v58, v59
	global_load_dwordx4 v[52:55], v[78:79], off
	v_add_u32_e32 v56, 0xa0, v152
	global_store_dwordx4 v[74:75], v[48:51], off offset:256
	global_load_dwordx4 v[48:51], v[76:77], off
	v_ashrrev_i32_e32 v57, 31, v56
	v_lshlrev_b64 v[58:59], 11, v[72:73]
	v_lshlrev_b64 v[60:61], 13, v[56:57]
	v_lshl_add_u64 v[58:59], s[70:71], 0, v[58:59]
	v_lshl_add_u64 v[60:61], s[20:21], 0, v[60:61]
	v_lshl_add_u64 v[58:59], v[58:59], 0, v[128:129]
	v_lshl_add_u64 v[60:61], v[60:61], 0, s[14:15]
	v_lshl_add_u64 v[62:63], v[60:61], 0, v[128:129]
	v_lshl_add_u64 v[60:61], v[60:61], 0, v[130:131]
	s_waitcnt vmcnt(2)
; __device__ __forceinline__ unsigned cvt_pk_bf16(float lo, float hi) { f32x2_t v = {lo, hi}; bf16x2_t b = __builtin_convertvector(v, bf16x2_t); return __builtin_bit_cast(unsigned, b); }
; __device__ __forceinline__ float bf_lo(unsigned w) { return __uint_as_float(w << 16); }
; __device__ __forceinline__ float bf_hi(unsigned w) { return __uint_as_float(w & 0xffff0000u); }
;     __device__ __forceinline__ void operator()(const Acc& acc, const Unit& u, int wr, int wc, int fr, int fq) const {
;     ...
;                 const int row = row0 + ai * HALF + m * 16;
; #pragma unroll
;                 for (int bj = 0; bj < 2; ++bj) {
;                     const int col = col0 + bj * HALF;
;                     const u32x4 gb = *(const u32x4*)(P + (size_t)row * PP + C_GB + col);
;                     const float rb[8] = {bf_lo(gb.x), bf_hi(gb.x), bf_lo(gb.y), bf_hi(gb.y), bf_lo(gb.z), bf_hi(gb.z), bf_lo(gb.w), bf_hi(gb.w)};
;                     float o[8];
; #pragma unroll
;                     for (int n = 0; n < 2; ++n)
; #pragma unroll
;                         for (int e = 0; e < 4; ++e) o[4 * n + e] = acc[ai][bj][m][n][e] * rb[4 * n + e];
;                     u32x4 w; w.x = cvt_pk_bf16(o[0], o[1]); w.y = cvt_pk_bf16(o[2], o[3]); w.z = cvt_pk_bf16(o[4], o[5]); w.w = cvt_pk_bf16(o[6], o[7]);
;                     *(u32x4*)(OUT + (size_t)row * DM + col) = w;
	v_lshlrev_b32_e32 v64, 16, v52
	v_and_b32_e32 v65, 0xffff0000, v52
	v_lshlrev_b32_e32 v52, 16, v53
	v_and_b32_e32 v53, 0xffff0000, v53
	v_lshlrev_b32_e32 v66, 16, v54
	v_and_b32_e32 v67, 0xffff0000, v54
	v_lshlrev_b32_e32 v54, 16, v55
	v_and_b32_e32 v55, 0xffff0000, v55
	s_waitcnt vmcnt(0)
	v_lshlrev_b32_e32 v68, 16, v48
	v_and_b32_e32 v69, 0xffff0000, v48
	v_lshlrev_b32_e32 v48, 16, v49
	v_and_b32_e32 v49, 0xffff0000, v49
	v_lshlrev_b32_e32 v70, 16, v50
	v_and_b32_e32 v71, 0xffff0000, v50
	v_lshlrev_b32_e32 v50, 16, v51
	v_and_b32_e32 v51, 0xffff0000, v51
	v_mul_f32_e32 v44, v44, v64
	v_mul_f32_e32 v45, v45, v65
	v_mul_f32_e32 v46, v46, v52
	v_mul_f32_e32 v47, v47, v53
	v_mul_f32_e32 v40, v40, v66
	v_mul_f32_e32 v41, v41, v67
	v_mul_f32_e32 v42, v42, v54
	v_mul_f32_e32 v43, v43, v55
	v_mul_f32_e32 v52, v36, v68
	v_mul_f32_e32 v53, v37, v69
	v_mul_f32_e32 v48, v38, v48
	v_mul_f32_e32 v49, v39, v49
	v_cvt_pk_bf16_f32 v36, v44, v45
	v_cvt_pk_bf16_f32 v37, v46, v47
	v_cvt_pk_bf16_f32 v38, v40, v41
	v_cvt_pk_bf16_f32 v39, v42, v43
	v_mul_f32_e32 v40, v32, v70
	v_mul_f32_e32 v41, v33, v71
	v_mul_f32_e32 v42, v34, v50
	v_mul_f32_e32 v43, v35, v51
	global_store_dwordx4 v[58:59], v[36:39], off
	v_cvt_pk_bf16_f32 v32, v52, v53
	v_cvt_pk_bf16_f32 v33, v48, v49
	v_cvt_pk_bf16_f32 v34, v40, v41
	v_cvt_pk_bf16_f32 v35, v42, v43
	global_load_dwordx4 v[36:39], v[62:63], off
	v_add_u32_e32 v40, 0xb0, v152
	global_store_dwordx4 v[58:59], v[32:35], off offset:256
	global_load_dwordx4 v[32:35], v[60:61], off
	v_ashrrev_i32_e32 v41, 31, v40
	v_lshlrev_b64 v[42:43], 11, v[56:57]
	v_lshlrev_b64 v[44:45], 13, v[40:41]
	v_lshl_add_u64 v[42:43], s[70:71], 0, v[42:43]
	v_lshl_add_u64 v[44:45], s[20:21], 0, v[44:45]
	v_lshl_add_u64 v[42:43], v[42:43], 0, v[128:129]
	v_lshl_add_u64 v[44:45], v[44:45], 0, s[14:15]
	v_lshl_add_u64 v[46:47], v[44:45], 0, v[128:129]
	v_lshl_add_u64 v[44:45], v[44:45], 0, v[130:131]
	s_waitcnt vmcnt(2)
	v_lshlrev_b32_e32 v48, 16, v36
	v_and_b32_e32 v49, 0xffff0000, v36
	v_lshlrev_b32_e32 v36, 16, v37
	v_and_b32_e32 v37, 0xffff0000, v37
	v_lshlrev_b32_e32 v50, 16, v38
	v_and_b32_e32 v51, 0xffff0000, v38
	v_lshlrev_b32_e32 v38, 16, v39
	v_and_b32_e32 v39, 0xffff0000, v39
	s_waitcnt vmcnt(0)
	v_lshlrev_b32_e32 v52, 16, v32
	v_and_b32_e32 v53, 0xffff0000, v32
	v_lshlrev_b32_e32 v32, 16, v33
	v_and_b32_e32 v33, 0xffff0000, v33
	v_lshlrev_b32_e32 v54, 16, v34
	v_and_b32_e32 v55, 0xffff0000, v34
	v_lshlrev_b32_e32 v34, 16, v35
	v_and_b32_e32 v35, 0xffff0000, v35
	v_mul_f32_e32 v28, v28, v48
	v_mul_f32_e32 v29, v29, v49
	v_mul_f32_e32 v30, v30, v36
	v_mul_f32_e32 v31, v31, v37
	v_mul_f32_e32 v24, v24, v50
	v_mul_f32_e32 v25, v25, v51
	v_mul_f32_e32 v26, v26, v38
	v_mul_f32_e32 v27, v27, v39
	v_mul_f32_e32 v36, v20, v52
	v_mul_f32_e32 v37, v21, v53
	v_mul_f32_e32 v32, v22, v32
	v_mul_f32_e32 v33, v23, v33
	v_cvt_pk_bf16_f32 v20, v28, v29
	v_cvt_pk_bf16_f32 v21, v30, v31
	v_cvt_pk_bf16_f32 v22, v24, v25
	v_cvt_pk_bf16_f32 v23, v26, v27
	v_mul_f32_e32 v24, v16, v54
	v_mul_f32_e32 v25, v17, v55
	v_mul_f32_e32 v26, v18, v34
	v_mul_f32_e32 v27, v19, v35
	global_store_dwordx4 v[42:43], v[20:23], off
	v_cvt_pk_bf16_f32 v16, v36, v37
	v_cvt_pk_bf16_f32 v17, v32, v33
	v_cvt_pk_bf16_f32 v18, v24, v25
	v_cvt_pk_bf16_f32 v19, v26, v27
	global_load_dwordx4 v[20:23], v[46:47], off
	v_lshlrev_b64 v[24:25], 11, v[40:41]
	global_store_dwordx4 v[42:43], v[16:19], off offset:256
	global_load_dwordx4 v[16:19], v[44:45], off
	v_lshl_add_u64 v[24:25], s[70:71], 0, v[24:25]
	v_lshl_add_u64 v[24:25], v[24:25], 0, v[128:129]
	s_waitcnt vmcnt(2)
	v_lshlrev_b32_e32 v26, 16, v20
	v_and_b32_e32 v27, 0xffff0000, v20
	v_lshlrev_b32_e32 v20, 16, v21
	v_and_b32_e32 v21, 0xffff0000, v21
	v_lshlrev_b32_e32 v28, 16, v22
	v_and_b32_e32 v29, 0xffff0000, v22
	v_lshlrev_b32_e32 v22, 16, v23
	v_and_b32_e32 v23, 0xffff0000, v23
	s_waitcnt vmcnt(0)
	v_lshlrev_b32_e32 v30, 16, v16
	v_and_b32_e32 v31, 0xffff0000, v16
	v_lshlrev_b32_e32 v16, 16, v17
	v_and_b32_e32 v17, 0xffff0000, v17
	v_lshlrev_b32_e32 v32, 16, v18
	v_and_b32_e32 v33, 0xffff0000, v18
	v_lshlrev_b32_e32 v18, 16, v19
	v_and_b32_e32 v19, 0xffff0000, v19
	v_mul_f32_e32 v12, v12, v26
	v_mul_f32_e32 v13, v13, v27
	v_mul_f32_e32 v14, v14, v20
	v_mul_f32_e32 v15, v15, v21
	v_mul_f32_e32 v8, v8, v28
	v_mul_f32_e32 v9, v9, v29
	v_mul_f32_e32 v10, v10, v22
	v_mul_f32_e32 v11, v11, v23
	v_mul_f32_e32 v4, v4, v30
	v_mul_f32_e32 v5, v5, v31
	v_mul_f32_e32 v6, v6, v16
	v_mul_f32_e32 v7, v7, v17
	v_mul_f32_e32 v16, v0, v32
	v_mul_f32_e32 v17, v1, v33
	v_mul_f32_e32 v18, v2, v18
	v_mul_f32_e32 v19, v3, v19
	v_cvt_pk_bf16_f32 v0, v12, v13
	v_cvt_pk_bf16_f32 v1, v14, v15
	v_cvt_pk_bf16_f32 v2, v8, v9
	v_cvt_pk_bf16_f32 v3, v10, v11
	v_cvt_pk_bf16_f32 v4, v4, v5
	v_cvt_pk_bf16_f32 v5, v6, v7
	v_cvt_pk_bf16_f32 v6, v16, v17
	v_cvt_pk_bf16_f32 v7, v18, v19
	global_store_dwordx4 v[24:25], v[0:3], off
	global_store_dwordx4 v[24:25], v[4:7], off offset:256
	s_cbranch_vccnz .LBB0_1075
	s_andn2_b64 vcc, exec, s[2:3]
	s_cbranch_vccnz .LBB0_1074
	s_barrier
	s_branch .LBB0_1074

; __device__ __forceinline__ unsigned cvt_pk_bf16(float lo, float hi) { f32x2_t v = {lo, hi}; bf16x2_t b = __builtin_convertvector(v, bf16x2_t); return __builtin_bit_cast(unsigned, b); }
;     __device__ __forceinline__ void operator()(const Acc& acc, const Unit& u, int wr, int wc, int fr, int fq) const {
;     ...
;                 const int row = row0 + ai * HALF + m * 16; float sq = 0.f;
; #pragma unroll
;                 for (int bj = 0; bj < 2; ++bj) {
;                     const size_t off = (size_t)row * DM + col0 + bj * HALF;
;                     const f32x4 b0 = *(const f32x4*)(base + off), b1 = *(const f32x4*)(base + off + 4);
;                     const f32x4 x0 = b0 + acc[ai][bj][m][0] * alpha, x1 = b1 + acc[ai][bj][m][1] * alpha;
;                     __builtin_nontemporal_store(x0, (f32x4*)(out + off)); __builtin_nontemporal_store(x1, (f32x4*)(out + off + 4));
;                     sq += (x0[0] * x0[0] + x0[1] * x0[1]) + (x0[2] * x0[2] + x0[3] * x0[3]) + (x1[0] * x1[0] + x1[1] * x1[1]) + (x1[2] * x1[2] + x1[3] * x1[3]);
;                     if (xb) { u32x4 w; w.x = cvt_pk_bf16(x0[0], x0[1]); w.y = cvt_pk_bf16(x0[2], x0[3]); w.z = cvt_pk_bf16(x1[0], x1[1]); w.w = cvt_pk_bf16(x1[2], x1[3]); *(u32x4*)(xb + off) = w; }
;                 }
.LBB0_1237:
	v_lshl_add_u32 v146, s12, 8, v152
	v_lshl_or_b32 v144, s46, 8, v154
	v_ashrrev_i32_e32 v147, 31, v146
	v_ashrrev_i32_e32 v145, 31, v144
	v_lshlrev_b64 v[148:149], 10, v[146:147]
	v_lshl_add_u64 v[148:149], v[148:149], 0, v[144:145]
	v_lshl_add_u64 v[150:151], v[148:149], 2, s[82:83]
	global_load_dwordx4 v[162:165], v[150:151], off
	global_load_dwordx4 v[166:169], v[150:151], off offset:16
	v_cndmask_b32_e64 v158, 0, 1, s[36:37]
	v_cmp_ne_u32_e64 s[12:13], 1, v158
	s_andn2_b64 vcc, exec, s[36:37]
	s_waitcnt vmcnt(0)
	v_add_f32_e32 v126, v126, v164
	v_add_f32_e32 v127, v127, v165
	v_add_f32_e32 v124, v124, v162
	v_add_f32_e32 v125, v125, v163
	v_add_f32_e32 v122, v122, v168
	v_add_f32_e32 v123, v123, v169
	v_add_f32_e32 v120, v120, v166
	v_add_f32_e32 v121, v121, v167
	global_store_dwordx4 v[150:151], v[124:127], off nt
	global_store_dwordx4 v[150:151], v[120:123], off offset:16 nt
	s_cbranch_vccnz .LBB0_1239
	v_cvt_pk_bf16_f32 v162, v124, v125
	v_cvt_pk_bf16_f32 v163, v126, v127
	v_cvt_pk_bf16_f32 v164, v120, v121
	v_cvt_pk_bf16_f32 v165, v122, v123
	v_lshl_add_u64 v[158:159], v[148:149], 1, s[72:73]
	global_store_dwordx4 v[158:159], v[162:165], off
.LBB0_1239:
	global_load_dwordx4 v[162:165], v[150:151], off offset:512
	s_nop 0
	global_load_dwordx4 v[166:169], v[150:151], off offset:528
	s_and_b64 vcc, exec, s[12:13]
	s_waitcnt vmcnt(1)
	v_add_f32_e32 v118, v118, v164
	v_add_f32_e32 v119, v119, v165
	v_add_f32_e32 v116, v116, v162
	v_add_f32_e32 v117, v117, v163
	s_waitcnt vmcnt(0)
	v_add_f32_e32 v114, v114, v168
	v_add_f32_e32 v115, v115, v169
	v_add_f32_e32 v112, v112, v166
	v_add_f32_e32 v113, v113, v167
	global_store_dwordx4 v[150:151], v[116:119], off offset:512 nt
	global_store_dwordx4 v[150:151], v[112:115], off offset:528 nt
	s_cbranch_vccnz .LBB0_1241
	v_lshlrev_b64 v[158:159], 1, v[148:149]
	v_or_b32_e32 v158, 0x100, v158
	v_cvt_pk_bf16_f32 v148, v116, v117
	v_cvt_pk_bf16_f32 v149, v118, v119
	v_cvt_pk_bf16_f32 v150, v112, v113
	v_cvt_pk_bf16_f32 v151, v114, v115
	v_lshl_add_u64 v[158:159], s[72:73], 0, v[158:159]
	global_store_dwordx4 v[158:159], v[148:151], off

; __device__ __forceinline__ unsigned cvt_pk_bf16(float lo, float hi) { f32x2_t v = {lo, hi}; bf16x2_t b = __builtin_convertvector(v, bf16x2_t); return __builtin_bit_cast(unsigned, b); }
;     __device__ __forceinline__ void operator()(const Acc& acc, const Unit& u, int wr, int wc, int fr, int fq) const {
;     ...
;                 const int row = row0 + ai * HALF + m * 16; float sq = 0.f;
; #pragma unroll
;                 for (int bj = 0; bj < 2; ++bj) {
;                     const size_t off = (size_t)row * DM + col0 + bj * HALF;
;                     const f32x4 b0 = *(const f32x4*)(base + off), b1 = *(const f32x4*)(base + off + 4);
;                     const f32x4 x0 = b0 + acc[ai][bj][m][0] * alpha, x1 = b1 + acc[ai][bj][m][1] * alpha;
;                     __builtin_nontemporal_store(x0, (f32x4*)(out + off)); __builtin_nontemporal_store(x1, (f32x4*)(out + off + 4));
;                     sq += (x0[0] * x0[0] + x0[1] * x0[1]) + (x0[2] * x0[2] + x0[3] * x0[3]) + (x1[0] * x1[0] + x1[1] * x1[1]) + (x1[2] * x1[2] + x1[3] * x1[3]);
;                     if (xb) { u32x4 w; w.x = cvt_pk_bf16(x0[0], x0[1]); w.y = cvt_pk_bf16(x0[2], x0[3]); w.z = cvt_pk_bf16(x1[0], x1[1]); w.w = cvt_pk_bf16(x1[2], x1[3]); *(u32x4*)(xb + off) = w; }
;                 }
.LBB0_1243:
	s_or_b64 exec, exec, s[6:7]
	v_or_b32_e32 v112, 16, v146
	s_waitcnt lgkmcnt(0)
	v_ashrrev_i32_e32 v113, 31, v112
	v_lshlrev_b64 v[114:115], 10, v[112:113]
	v_lshl_add_u64 v[114:115], v[114:115], 0, v[144:145]
	v_lshl_add_u64 v[116:117], v[114:115], 2, s[82:83]
	global_load_dwordx4 v[118:121], v[116:117], off
	global_load_dwordx4 v[122:125], v[116:117], off offset:16
	s_and_b64 vcc, exec, s[12:13]
	s_waitcnt vmcnt(1)
	v_add_f32_e32 v110, v110, v120
	v_add_f32_e32 v111, v111, v121
	v_add_f32_e32 v108, v108, v118
	v_add_f32_e32 v109, v109, v119
	s_waitcnt vmcnt(0)
	v_add_f32_e32 v106, v106, v124
	v_add_f32_e32 v107, v107, v125
	v_add_f32_e32 v104, v104, v122
	v_add_f32_e32 v105, v105, v123
	global_store_dwordx4 v[116:117], v[108:111], off nt
	global_store_dwordx4 v[116:117], v[104:107], off offset:16 nt
	s_cbranch_vccnz .LBB0_1245
	v_cvt_pk_bf16_f32 v118, v108, v109
	v_cvt_pk_bf16_f32 v119, v110, v111
	v_cvt_pk_bf16_f32 v120, v104, v105
	v_cvt_pk_bf16_f32 v121, v106, v107
	v_lshl_add_u64 v[122:123], v[114:115], 1, s[72:73]
	global_store_dwordx4 v[122:123], v[118:121], off
.LBB0_1245:
	global_load_dwordx4 v[118:121], v[116:117], off offset:512
	s_nop 0
	global_load_dwordx4 v[122:125], v[116:117], off offset:528
	s_and_b64 vcc, exec, s[12:13]
	s_waitcnt vmcnt(1)
	v_add_f32_e32 v102, v102, v120
	v_add_f32_e32 v103, v103, v121
	v_add_f32_e32 v100, v100, v118
	v_add_f32_e32 v101, v101, v119
	s_waitcnt vmcnt(0)
	v_add_f32_e32 v98, v98, v124
	v_add_f32_e32 v99, v99, v125
	v_add_f32_e32 v96, v96, v122
	v_add_f32_e32 v97, v97, v123
	global_store_dwordx4 v[116:117], v[100:103], off offset:512 nt
	global_store_dwordx4 v[116:117], v[96:99], off offset:528 nt
	s_cbranch_vccnz .LBB0_1247
	v_lshlrev_b64 v[118:119], 1, v[114:115]
	v_or_b32_e32 v118, 0x100, v118
	v_cvt_pk_bf16_f32 v114, v100, v101
	v_cvt_pk_bf16_f32 v115, v102, v103
	v_cvt_pk_bf16_f32 v116, v96, v97
	v_cvt_pk_bf16_f32 v117, v98, v99
	v_lshl_add_u64 v[118:119], s[72:73], 0, v[118:119]
	global_store_dwordx4 v[118:119], v[114:117], off

; __device__ __forceinline__ unsigned cvt_pk_bf16(float lo, float hi) { f32x2_t v = {lo, hi}; bf16x2_t b = __builtin_convertvector(v, bf16x2_t); return __builtin_bit_cast(unsigned, b); }
;     __device__ __forceinline__ void operator()(const Acc& acc, const Unit& u, int wr, int wc, int fr, int fq) const {
;     ...
;                 const int row = row0 + ai * HALF + m * 16; float sq = 0.f;
; #pragma unroll
;                 for (int bj = 0; bj < 2; ++bj) {
;                     const size_t off = (size_t)row * DM + col0 + bj * HALF;
;                     const f32x4 b0 = *(const f32x4*)(base + off), b1 = *(const f32x4*)(base + off + 4);
;                     const f32x4 x0 = b0 + acc[ai][bj][m][0] * alpha, x1 = b1 + acc[ai][bj][m][1] * alpha;
;                     __builtin_nontemporal_store(x0, (f32x4*)(out + off)); __builtin_nontemporal_store(x1, (f32x4*)(out + off + 4));
;                     sq += (x0[0] * x0[0] + x0[1] * x0[1]) + (x0[2] * x0[2] + x0[3] * x0[3]) + (x1[0] * x1[0] + x1[1] * x1[1]) + (x1[2] * x1[2] + x1[3] * x1[3]);
;                     if (xb) { u32x4 w; w.x = cvt_pk_bf16(x0[0], x0[1]); w.y = cvt_pk_bf16(x0[2], x0[3]); w.z = cvt_pk_bf16(x1[0], x1[1]); w.w = cvt_pk_bf16(x1[2], x1[3]); *(u32x4*)(xb + off) = w; }
;                 }
.LBB0_1249:
	s_or_b64 exec, exec, s[6:7]
	v_or_b32_e32 v96, 32, v146
	s_waitcnt lgkmcnt(0)
	v_ashrrev_i32_e32 v97, 31, v96
	v_lshlrev_b64 v[98:99], 10, v[96:97]
	v_lshl_add_u64 v[98:99], v[98:99], 0, v[144:145]
	v_lshl_add_u64 v[100:101], v[98:99], 2, s[82:83]
	global_load_dwordx4 v[102:105], v[100:101], off
	global_load_dwordx4 v[106:109], v[100:101], off offset:16
	s_and_b64 vcc, exec, s[12:13]
	s_waitcnt vmcnt(1)
	v_add_f32_e32 v94, v94, v104
	v_add_f32_e32 v95, v95, v105
	v_add_f32_e32 v92, v92, v102
	v_add_f32_e32 v93, v93, v103
	s_waitcnt vmcnt(0)
	v_add_f32_e32 v90, v90, v108
	v_add_f32_e32 v91, v91, v109
	v_add_f32_e32 v88, v88, v106
	v_add_f32_e32 v89, v89, v107
	global_store_dwordx4 v[100:101], v[92:95], off nt
	global_store_dwordx4 v[100:101], v[88:91], off offset:16 nt
	s_cbranch_vccnz .LBB0_1251
	v_cvt_pk_bf16_f32 v102, v92, v93
	v_cvt_pk_bf16_f32 v103, v94, v95
	v_cvt_pk_bf16_f32 v104, v88, v89
	v_cvt_pk_bf16_f32 v105, v90, v91
	v_lshl_add_u64 v[106:107], v[98:99], 1, s[72:73]
	global_store_dwordx4 v[106:107], v[102:105], off
.LBB0_1251:
	global_load_dwordx4 v[102:105], v[100:101], off offset:512
	s_nop 0
	global_load_dwordx4 v[106:109], v[100:101], off offset:528
	s_and_b64 vcc, exec, s[12:13]
	s_waitcnt vmcnt(1)
	v_add_f32_e32 v86, v86, v104
	v_add_f32_e32 v87, v87, v105
	v_add_f32_e32 v84, v84, v102
	v_add_f32_e32 v85, v85, v103
	s_waitcnt vmcnt(0)
	v_add_f32_e32 v82, v82, v108
	v_add_f32_e32 v83, v83, v109
	v_add_f32_e32 v80, v80, v106
	v_add_f32_e32 v81, v81, v107
	global_store_dwordx4 v[100:101], v[84:87], off offset:512 nt
	global_store_dwordx4 v[100:101], v[80:83], off offset:528 nt
	s_cbranch_vccnz .LBB0_1253
	v_lshlrev_b64 v[102:103], 1, v[98:99]
	v_or_b32_e32 v102, 0x100, v102
	v_cvt_pk_bf16_f32 v98, v84, v85
	v_cvt_pk_bf16_f32 v99, v86, v87
	v_cvt_pk_bf16_f32 v100, v80, v81
	v_cvt_pk_bf16_f32 v101, v82, v83
	v_lshl_add_u64 v[102:103], s[72:73], 0, v[102:103]
	global_store_dwordx4 v[102:103], v[98:101], off

; __device__ __forceinline__ unsigned cvt_pk_bf16(float lo, float hi) { f32x2_t v = {lo, hi}; bf16x2_t b = __builtin_convertvector(v, bf16x2_t); return __builtin_bit_cast(unsigned, b); }
;     __device__ __forceinline__ void operator()(const Acc& acc, const Unit& u, int wr, int wc, int fr, int fq) const {
;     ...
;                 const int row = row0 + ai * HALF + m * 16; float sq = 0.f;
; #pragma unroll
;                 for (int bj = 0; bj < 2; ++bj) {
;                     const size_t off = (size_t)row * DM + col0 + bj * HALF;
;                     const f32x4 b0 = *(const f32x4*)(base + off), b1 = *(const f32x4*)(base + off + 4);
;                     const f32x4 x0 = b0 + acc[ai][bj][m][0] * alpha, x1 = b1 + acc[ai][bj][m][1] * alpha;
;                     __builtin_nontemporal_store(x0, (f32x4*)(out + off)); __builtin_nontemporal_store(x1, (f32x4*)(out + off + 4));
;                     sq += (x0[0] * x0[0] + x0[1] * x0[1]) + (x0[2] * x0[2] + x0[3] * x0[3]) + (x1[0] * x1[0] + x1[1] * x1[1]) + (x1[2] * x1[2] + x1[3] * x1[3]);
;                     if (xb) { u32x4 w; w.x = cvt_pk_bf16(x0[0], x0[1]); w.y = cvt_pk_bf16(x0[2], x0[3]); w.z = cvt_pk_bf16(x1[0], x1[1]); w.w = cvt_pk_bf16(x1[2], x1[3]); *(u32x4*)(xb + off) = w; }
;                 }
.LBB0_1255:
	s_or_b64 exec, exec, s[6:7]
	v_or_b32_e32 v80, 48, v146
	s_waitcnt lgkmcnt(0)
	v_ashrrev_i32_e32 v81, 31, v80
	v_lshlrev_b64 v[82:83], 10, v[80:81]
	v_lshl_add_u64 v[82:83], v[82:83], 0, v[144:145]
	v_lshl_add_u64 v[84:85], v[82:83], 2, s[82:83]
	global_load_dwordx4 v[86:89], v[84:85], off
	global_load_dwordx4 v[90:93], v[84:85], off offset:16
	s_and_b64 vcc, exec, s[12:13]
	s_waitcnt vmcnt(1)
	v_add_f32_e32 v78, v78, v88
	v_add_f32_e32 v79, v79, v89
	v_add_f32_e32 v76, v76, v86
	v_add_f32_e32 v77, v77, v87
	s_waitcnt vmcnt(0)
	v_add_f32_e32 v74, v74, v92
	v_add_f32_e32 v75, v75, v93
	v_add_f32_e32 v72, v72, v90
	v_add_f32_e32 v73, v73, v91
	global_store_dwordx4 v[84:85], v[76:79], off nt
	global_store_dwordx4 v[84:85], v[72:75], off offset:16 nt
	s_cbranch_vccnz .LBB0_1257
	v_cvt_pk_bf16_f32 v86, v76, v77
	v_cvt_pk_bf16_f32 v87, v78, v79
	v_cvt_pk_bf16_f32 v88, v72, v73
	v_cvt_pk_bf16_f32 v89, v74, v75
	v_lshl_add_u64 v[90:91], v[82:83], 1, s[72:73]
	global_store_dwordx4 v[90:91], v[86:89], off
.LBB0_1257:
	global_load_dwordx4 v[86:89], v[84:85], off offset:512
	s_nop 0
	global_load_dwordx4 v[90:93], v[84:85], off offset:528
	s_and_b64 vcc, exec, s[12:13]
	s_waitcnt vmcnt(1)
	v_add_f32_e32 v70, v70, v88
	v_add_f32_e32 v71, v71, v89
	v_add_f32_e32 v68, v68, v86
	v_add_f32_e32 v69, v69, v87
	s_waitcnt vmcnt(0)
	v_add_f32_e32 v66, v66, v92
	v_add_f32_e32 v67, v67, v93
	v_add_f32_e32 v64, v64, v90
	v_add_f32_e32 v65, v65, v91
	global_store_dwordx4 v[84:85], v[68:71], off offset:512 nt
	global_store_dwordx4 v[84:85], v[64:67], off offset:528 nt
	s_cbranch_vccnz .LBB0_1259
	v_lshlrev_b64 v[86:87], 1, v[82:83]
	v_or_b32_e32 v86, 0x100, v86
	v_cvt_pk_bf16_f32 v82, v68, v69
	v_cvt_pk_bf16_f32 v83, v70, v71
	v_cvt_pk_bf16_f32 v84, v64, v65
	v_cvt_pk_bf16_f32 v85, v66, v67
	v_lshl_add_u64 v[86:87], s[72:73], 0, v[86:87]
	global_store_dwordx4 v[86:87], v[82:85], off

; __device__ __forceinline__ unsigned cvt_pk_bf16(float lo, float hi) { f32x2_t v = {lo, hi}; bf16x2_t b = __builtin_convertvector(v, bf16x2_t); return __builtin_bit_cast(unsigned, b); }
;     __device__ __forceinline__ void operator()(const Acc& acc, const Unit& u, int wr, int wc, int fr, int fq) const {
;     ...
;                 const int row = row0 + ai * HALF + m * 16; float sq = 0.f;
; #pragma unroll
;                 for (int bj = 0; bj < 2; ++bj) {
;                     const size_t off = (size_t)row * DM + col0 + bj * HALF;
;                     const f32x4 b0 = *(const f32x4*)(base + off), b1 = *(const f32x4*)(base + off + 4);
;                     const f32x4 x0 = b0 + acc[ai][bj][m][0] * alpha, x1 = b1 + acc[ai][bj][m][1] * alpha;
;                     __builtin_nontemporal_store(x0, (f32x4*)(out + off)); __builtin_nontemporal_store(x1, (f32x4*)(out + off + 4));
;                     sq += (x0[0] * x0[0] + x0[1] * x0[1]) + (x0[2] * x0[2] + x0[3] * x0[3]) + (x1[0] * x1[0] + x1[1] * x1[1]) + (x1[2] * x1[2] + x1[3] * x1[3]);
;                     if (xb) { u32x4 w; w.x = cvt_pk_bf16(x0[0], x0[1]); w.y = cvt_pk_bf16(x0[2], x0[3]); w.z = cvt_pk_bf16(x1[0], x1[1]); w.w = cvt_pk_bf16(x1[2], x1[3]); *(u32x4*)(xb + off) = w; }
;                 }
.LBB0_1261:
	s_or_b64 exec, exec, s[6:7]
	v_add_u32_e32 v64, 0x80, v146
	s_waitcnt lgkmcnt(0)
	v_ashrrev_i32_e32 v65, 31, v64
	v_lshlrev_b64 v[66:67], 10, v[64:65]
	v_lshl_add_u64 v[66:67], v[66:67], 0, v[144:145]
	v_lshl_add_u64 v[68:69], v[66:67], 2, s[82:83]
	global_load_dwordx4 v[70:73], v[68:69], off
	global_load_dwordx4 v[74:77], v[68:69], off offset:16
	s_and_b64 vcc, exec, s[12:13]
	s_waitcnt vmcnt(1)
	v_add_f32_e32 v62, v62, v72
	v_add_f32_e32 v63, v63, v73
	v_add_f32_e32 v60, v60, v70
	v_add_f32_e32 v61, v61, v71
	s_waitcnt vmcnt(0)
	v_add_f32_e32 v58, v58, v76
	v_add_f32_e32 v59, v59, v77
	v_add_f32_e32 v56, v56, v74
	v_add_f32_e32 v57, v57, v75
	global_store_dwordx4 v[68:69], v[60:63], off nt
	global_store_dwordx4 v[68:69], v[56:59], off offset:16 nt
	s_cbranch_vccnz .LBB0_1263
	v_cvt_pk_bf16_f32 v70, v60, v61
	v_cvt_pk_bf16_f32 v71, v62, v63
	v_cvt_pk_bf16_f32 v72, v56, v57
	v_cvt_pk_bf16_f32 v73, v58, v59
	v_lshl_add_u64 v[74:75], v[66:67], 1, s[72:73]
	global_store_dwordx4 v[74:75], v[70:73], off
.LBB0_1263:
	global_load_dwordx4 v[70:73], v[68:69], off offset:512
	s_nop 0
	global_load_dwordx4 v[74:77], v[68:69], off offset:528
	s_and_b64 vcc, exec, s[12:13]
	s_waitcnt vmcnt(1)
	v_add_f32_e32 v54, v54, v72
	v_add_f32_e32 v55, v55, v73
	v_add_f32_e32 v52, v52, v70
	v_add_f32_e32 v53, v53, v71
	s_waitcnt vmcnt(0)
	v_add_f32_e32 v50, v50, v76
	v_add_f32_e32 v51, v51, v77
	v_add_f32_e32 v48, v48, v74
	v_add_f32_e32 v49, v49, v75
	global_store_dwordx4 v[68:69], v[52:55], off offset:512 nt
	global_store_dwordx4 v[68:69], v[48:51], off offset:528 nt
	s_cbranch_vccnz .LBB0_1265
	v_lshlrev_b64 v[70:71], 1, v[66:67]
	v_or_b32_e32 v70, 0x100, v70
	v_cvt_pk_bf16_f32 v66, v52, v53
	v_cvt_pk_bf16_f32 v67, v54, v55
	v_cvt_pk_bf16_f32 v68, v48, v49
	v_cvt_pk_bf16_f32 v69, v50, v51
	v_lshl_add_u64 v[70:71], s[72:73], 0, v[70:71]
	global_store_dwordx4 v[70:71], v[66:69], off

; __device__ __forceinline__ unsigned cvt_pk_bf16(float lo, float hi) { f32x2_t v = {lo, hi}; bf16x2_t b = __builtin_convertvector(v, bf16x2_t); return __builtin_bit_cast(unsigned, b); }
;     __device__ __forceinline__ void operator()(const Acc& acc, const Unit& u, int wr, int wc, int fr, int fq) const {
;     ...
;                 const int row = row0 + ai * HALF + m * 16; float sq = 0.f;
; #pragma unroll
;                 for (int bj = 0; bj < 2; ++bj) {
;                     const size_t off = (size_t)row * DM + col0 + bj * HALF;
;                     const f32x4 b0 = *(const f32x4*)(base + off), b1 = *(const f32x4*)(base + off + 4);
;                     const f32x4 x0 = b0 + acc[ai][bj][m][0] * alpha, x1 = b1 + acc[ai][bj][m][1] * alpha;
;                     __builtin_nontemporal_store(x0, (f32x4*)(out + off)); __builtin_nontemporal_store(x1, (f32x4*)(out + off + 4));
;                     sq += (x0[0] * x0[0] + x0[1] * x0[1]) + (x0[2] * x0[2] + x0[3] * x0[3]) + (x1[0] * x1[0] + x1[1] * x1[1]) + (x1[2] * x1[2] + x1[3] * x1[3]);
;                     if (xb) { u32x4 w; w.x = cvt_pk_bf16(x0[0], x0[1]); w.y = cvt_pk_bf16(x0[2], x0[3]); w.z = cvt_pk_bf16(x1[0], x1[1]); w.w = cvt_pk_bf16(x1[2], x1[3]); *(u32x4*)(xb + off) = w; }
;                 }
.LBB0_1267:
	s_or_b64 exec, exec, s[6:7]
	v_add_u32_e32 v48, 0x90, v146
	s_waitcnt lgkmcnt(0)
	v_ashrrev_i32_e32 v49, 31, v48
	v_lshlrev_b64 v[50:51], 10, v[48:49]
	v_lshl_add_u64 v[50:51], v[50:51], 0, v[144:145]
	v_lshl_add_u64 v[52:53], v[50:51], 2, s[82:83]
	global_load_dwordx4 v[54:57], v[52:53], off
	global_load_dwordx4 v[58:61], v[52:53], off offset:16
	s_and_b64 vcc, exec, s[12:13]
	s_waitcnt vmcnt(1)
	v_add_f32_e32 v46, v46, v56
	v_add_f32_e32 v47, v47, v57
	v_add_f32_e32 v44, v44, v54
	v_add_f32_e32 v45, v45, v55
	s_waitcnt vmcnt(0)
	v_add_f32_e32 v42, v42, v60
	v_add_f32_e32 v43, v43, v61
	v_add_f32_e32 v40, v40, v58
	v_add_f32_e32 v41, v41, v59
	global_store_dwordx4 v[52:53], v[44:47], off nt
	global_store_dwordx4 v[52:53], v[40:43], off offset:16 nt
	s_cbranch_vccnz .LBB0_1269
	v_cvt_pk_bf16_f32 v54, v44, v45
	v_cvt_pk_bf16_f32 v55, v46, v47
	v_cvt_pk_bf16_f32 v56, v40, v41
	v_cvt_pk_bf16_f32 v57, v42, v43
	v_lshl_add_u64 v[58:59], v[50:51], 1, s[72:73]
	global_store_dwordx4 v[58:59], v[54:57], off
.LBB0_1269:
	global_load_dwordx4 v[54:57], v[52:53], off offset:512
	s_nop 0
	global_load_dwordx4 v[58:61], v[52:53], off offset:528
	s_and_b64 vcc, exec, s[12:13]
	s_waitcnt vmcnt(1)
	v_add_f32_e32 v38, v38, v56
	v_add_f32_e32 v39, v39, v57
	v_add_f32_e32 v36, v36, v54
	v_add_f32_e32 v37, v37, v55
	s_waitcnt vmcnt(0)
	v_add_f32_e32 v34, v34, v60
	v_add_f32_e32 v35, v35, v61
	v_add_f32_e32 v32, v32, v58
	v_add_f32_e32 v33, v33, v59
	global_store_dwordx4 v[52:53], v[36:39], off offset:512 nt
	global_store_dwordx4 v[52:53], v[32:35], off offset:528 nt
	s_cbranch_vccnz .LBB0_1271
	v_lshlrev_b64 v[54:55], 1, v[50:51]
	v_or_b32_e32 v54, 0x100, v54
	v_cvt_pk_bf16_f32 v50, v36, v37
	v_cvt_pk_bf16_f32 v51, v38, v39
	v_cvt_pk_bf16_f32 v52, v32, v33
	v_cvt_pk_bf16_f32 v53, v34, v35
	v_lshl_add_u64 v[54:55], s[72:73], 0, v[54:55]
	global_store_dwordx4 v[54:55], v[50:53], off

; __device__ __forceinline__ unsigned cvt_pk_bf16(float lo, float hi) { f32x2_t v = {lo, hi}; bf16x2_t b = __builtin_convertvector(v, bf16x2_t); return __builtin_bit_cast(unsigned, b); }
;     __device__ __forceinline__ void operator()(const Acc& acc, const Unit& u, int wr, int wc, int fr, int fq) const {
;     ...
;                 const int row = row0 + ai * HALF + m * 16; float sq = 0.f;
; #pragma unroll
;                 for (int bj = 0; bj < 2; ++bj) {
;                     const size_t off = (size_t)row * DM + col0 + bj * HALF;
;                     const f32x4 b0 = *(const f32x4*)(base + off), b1 = *(const f32x4*)(base + off + 4);
;                     const f32x4 x0 = b0 + acc[ai][bj][m][0] * alpha, x1 = b1 + acc[ai][bj][m][1] * alpha;
;                     __builtin_nontemporal_store(x0, (f32x4*)(out + off)); __builtin_nontemporal_store(x1, (f32x4*)(out + off + 4));
;                     sq += (x0[0] * x0[0] + x0[1] * x0[1]) + (x0[2] * x0[2] + x0[3] * x0[3]) + (x1[0] * x1[0] + x1[1] * x1[1]) + (x1[2] * x1[2] + x1[3] * x1[3]);
;                     if (xb) { u32x4 w; w.x = cvt_pk_bf16(x0[0], x0[1]); w.y = cvt_pk_bf16(x0[2], x0[3]); w.z = cvt_pk_bf16(x1[0], x1[1]); w.w = cvt_pk_bf16(x1[2], x1[3]); *(u32x4*)(xb + off) = w; }
;                 }
.LBB0_1273:
	s_or_b64 exec, exec, s[6:7]
	v_add_u32_e32 v32, 0xa0, v146
	s_waitcnt lgkmcnt(0)
	v_ashrrev_i32_e32 v33, 31, v32
	v_lshlrev_b64 v[34:35], 10, v[32:33]
	v_lshl_add_u64 v[34:35], v[34:35], 0, v[144:145]
	v_lshl_add_u64 v[36:37], v[34:35], 2, s[82:83]
	global_load_dwordx4 v[38:41], v[36:37], off
	global_load_dwordx4 v[42:45], v[36:37], off offset:16
	s_and_b64 vcc, exec, s[12:13]
	s_waitcnt vmcnt(1)
	v_add_f32_e32 v30, v30, v40
	v_add_f32_e32 v31, v31, v41
	v_add_f32_e32 v28, v28, v38
	v_add_f32_e32 v29, v29, v39
	s_waitcnt vmcnt(0)
	v_add_f32_e32 v26, v26, v44
	v_add_f32_e32 v27, v27, v45
	v_add_f32_e32 v24, v24, v42
	v_add_f32_e32 v25, v25, v43
	global_store_dwordx4 v[36:37], v[28:31], off nt
	global_store_dwordx4 v[36:37], v[24:27], off offset:16 nt
	s_cbranch_vccnz .LBB0_1275
	v_cvt_pk_bf16_f32 v38, v28, v29
	v_cvt_pk_bf16_f32 v39, v30, v31
	v_cvt_pk_bf16_f32 v40, v24, v25
	v_cvt_pk_bf16_f32 v41, v26, v27
	v_lshl_add_u64 v[42:43], v[34:35], 1, s[72:73]
	global_store_dwordx4 v[42:43], v[38:41], off
.LBB0_1275:
	global_load_dwordx4 v[38:41], v[36:37], off offset:512
	s_nop 0
	global_load_dwordx4 v[42:45], v[36:37], off offset:528
	s_and_b64 vcc, exec, s[12:13]
	s_waitcnt vmcnt(1)
	v_add_f32_e32 v22, v22, v40
	v_add_f32_e32 v23, v23, v41
	v_add_f32_e32 v20, v20, v38
	v_add_f32_e32 v21, v21, v39
	s_waitcnt vmcnt(0)
	v_add_f32_e32 v18, v18, v44
	v_add_f32_e32 v19, v19, v45
	v_add_f32_e32 v16, v16, v42
	v_add_f32_e32 v17, v17, v43
	global_store_dwordx4 v[36:37], v[20:23], off offset:512 nt
	global_store_dwordx4 v[36:37], v[16:19], off offset:528 nt
	s_cbranch_vccnz .LBB0_1277
	v_lshlrev_b64 v[38:39], 1, v[34:35]
	v_or_b32_e32 v38, 0x100, v38
	v_cvt_pk_bf16_f32 v34, v20, v21
	v_cvt_pk_bf16_f32 v35, v22, v23
	v_cvt_pk_bf16_f32 v36, v16, v17
	v_cvt_pk_bf16_f32 v37, v18, v19
	v_lshl_add_u64 v[38:39], s[72:73], 0, v[38:39]
	global_store_dwordx4 v[38:39], v[34:37], off

; __device__ __forceinline__ unsigned cvt_pk_bf16(float lo, float hi) { f32x2_t v = {lo, hi}; bf16x2_t b = __builtin_convertvector(v, bf16x2_t); return __builtin_bit_cast(unsigned, b); }
;     __device__ __forceinline__ void operator()(const Acc& acc, const Unit& u, int wr, int wc, int fr, int fq) const {
;     ...
;                 const int row = row0 + ai * HALF + m * 16; float sq = 0.f;
; #pragma unroll
;                 for (int bj = 0; bj < 2; ++bj) {
;                     const size_t off = (size_t)row * DM + col0 + bj * HALF;
;                     const f32x4 b0 = *(const f32x4*)(base + off), b1 = *(const f32x4*)(base + off + 4);
;                     const f32x4 x0 = b0 + acc[ai][bj][m][0] * alpha, x1 = b1 + acc[ai][bj][m][1] * alpha;
;                     __builtin_nontemporal_store(x0, (f32x4*)(out + off)); __builtin_nontemporal_store(x1, (f32x4*)(out + off + 4));
;                     sq += (x0[0] * x0[0] + x0[1] * x0[1]) + (x0[2] * x0[2] + x0[3] * x0[3]) + (x1[0] * x1[0] + x1[1] * x1[1]) + (x1[2] * x1[2] + x1[3] * x1[3]);
;                     if (xb) { u32x4 w; w.x = cvt_pk_bf16(x0[0], x0[1]); w.y = cvt_pk_bf16(x0[2], x0[3]); w.z = cvt_pk_bf16(x1[0], x1[1]); w.w = cvt_pk_bf16(x1[2], x1[3]); *(u32x4*)(xb + off) = w; }
;                 }
.LBB0_1279:
	s_or_b64 exec, exec, s[6:7]
	v_add_u32_e32 v16, 0xb0, v146
	s_waitcnt lgkmcnt(0)
	v_ashrrev_i32_e32 v17, 31, v16
	v_lshlrev_b64 v[18:19], 10, v[16:17]
	v_lshl_add_u64 v[18:19], v[18:19], 0, v[144:145]
	v_lshl_add_u64 v[20:21], v[18:19], 2, s[82:83]
	global_load_dwordx4 v[22:25], v[20:21], off
	global_load_dwordx4 v[26:29], v[20:21], off offset:16
	s_and_b64 vcc, exec, s[12:13]
	s_waitcnt vmcnt(1)
	v_add_f32_e32 v14, v14, v24
	v_add_f32_e32 v15, v15, v25
	v_add_f32_e32 v12, v12, v22
	v_add_f32_e32 v13, v13, v23
	s_waitcnt vmcnt(0)
	v_add_f32_e32 v10, v10, v28
	v_add_f32_e32 v11, v11, v29
	v_add_f32_e32 v8, v8, v26
	v_add_f32_e32 v9, v9, v27
	global_store_dwordx4 v[20:21], v[12:15], off nt
	global_store_dwordx4 v[20:21], v[8:11], off offset:16 nt
	s_cbranch_vccnz .LBB0_1281
	v_cvt_pk_bf16_f32 v22, v12, v13
	v_cvt_pk_bf16_f32 v23, v14, v15
	v_cvt_pk_bf16_f32 v24, v8, v9
	v_cvt_pk_bf16_f32 v25, v10, v11
	v_lshl_add_u64 v[26:27], v[18:19], 1, s[72:73]
	global_store_dwordx4 v[26:27], v[22:25], off
.LBB0_1281:
	global_load_dwordx4 v[22:25], v[20:21], off offset:512
	s_nop 0
	global_load_dwordx4 v[26:29], v[20:21], off offset:528
	s_and_b64 vcc, exec, s[12:13]
	s_waitcnt vmcnt(1)
	v_add_f32_e32 v6, v6, v24
	v_add_f32_e32 v7, v7, v25
	v_add_f32_e32 v4, v4, v22
	v_add_f32_e32 v5, v5, v23
	s_waitcnt vmcnt(0)
	v_add_f32_e32 v2, v2, v28
	v_add_f32_e32 v3, v3, v29
	v_add_f32_e32 v0, v0, v26
	v_add_f32_e32 v1, v1, v27
	global_store_dwordx4 v[20:21], v[4:7], off offset:512 nt
	global_store_dwordx4 v[20:21], v[0:3], off offset:528 nt
	s_cbranch_vccnz .LBB0_1283
	v_lshlrev_b64 v[22:23], 1, v[18:19]
	v_or_b32_e32 v22, 0x100, v22
	v_cvt_pk_bf16_f32 v18, v4, v5
	v_cvt_pk_bf16_f32 v19, v6, v7
	v_cvt_pk_bf16_f32 v20, v0, v1
	v_cvt_pk_bf16_f32 v21, v2, v3
	v_lshl_add_u64 v[22:23], s[72:73], 0, v[22:23]
	global_store_dwordx4 v[22:23], v[18:21], off

; __device__ __forceinline__ unsigned cvt_pk_bf16(float lo, float hi) { f32x2_t v = {lo, hi}; bf16x2_t b = __builtin_convertvector(v, bf16x2_t); return __builtin_bit_cast(unsigned, b); }
; __device__ __forceinline__ float rstd_of(const float* ss, int row) { return __builtin_amdgcn_rsqf(ss[row] * (1.0f / 1024.0f) + RMS_EPS); }
; __device__ __forceinline__ float sigmoidf_(float v) { return __builtin_amdgcn_rcpf(1.0f + __builtin_amdgcn_exp2f(-v * LOG2E)); }
;     __device__ __forceinline__ void operator()(const Acc& acc, const Unit& u, int wr, int wc, int fr, int fq) const {
;     ...
;             for (int m = 0; m < 4; ++m) {
;                 const int row = row0 + ai * HALF + m * 16; const float rs = rstd_of(ss, row);
;                 float o[8];
; #pragma unroll
;                 for (int n = 0; n < 2; ++n)
; #pragma unroll
;                     for (int e = 0; e < 4; ++e) { const float gv = acc[ai][0][m][n][e] * rs, uv = acc[ai][1][m][n][e] * rs; o[4 * n + e] = gv * sigmoidf_(gv) * uv; }
;                 u32x4 w; w.x = cvt_pk_bf16(o[0], o[1]); w.y = cvt_pk_bf16(o[2], o[3]); w.z = cvt_pk_bf16(o[4], o[5]); w.w = cvt_pk_bf16(o[6], o[7]);
;                 *(u32x4*)(H + (size_t)row * FF + col0) = w;
.LBB0_1353:
	v_lshl_add_u32 v144, s36, 8, v152
	v_ashrrev_i32_e32 v145, 31, v144
	v_lshl_add_u64 v[150:151], v[144:145], 2, s[2:3]
	global_load_dword v145, v[150:151], off
	v_or_b32_e32 v164, 16, v144
	v_ashrrev_i32_e32 v165, 31, v164
	v_lshl_add_u64 v[166:167], v[164:165], 2, s[2:3]
	v_lshl_or_b32 v148, s37, 7, v154
	v_mov_b64_e32 v[146:147], s[20:21]
	v_ashrrev_i32_e32 v149, 31, v148
	v_mad_i64_i32 v[162:163], s[36:37], v144, s33, v[146:147]
	v_lshlrev_b64 v[148:149], 1, v[148:149]
	v_lshl_add_u64 v[162:163], v[162:163], 0, v[148:149]
	v_readlane_b32 s48, v255, 6
	s_andn2_b64 vcc, exec, s[6:7]
	s_mov_b64 s[6:7], -1
	v_readlane_b32 s49, v255, 7
	v_readlane_b32 s50, v255, 8
	v_readlane_b32 s51, v255, 9
	s_waitcnt vmcnt(0)
	v_fmamk_f32 v145, v145, 0x3a800000, v158
	v_rsq_f32_e32 v160, v145
	s_nop 0
	v_mul_f32_e32 v124, v124, v160
	v_mul_f32_e32 v125, v125, v160
	v_mul_f32_e32 v126, v126, v160
	v_mul_f32_e32 v127, v127, v160
	v_mul_f32_e32 v120, v120, v160
	v_mul_f32_e32 v121, v121, v160
	v_mul_f32_e32 v122, v122, v160
	v_mul_f32_e32 v123, v123, v160
	v_mul_f32_e32 v116, v116, v160
	v_mul_f32_e32 v117, v117, v160
	v_mul_f32_e32 v118, v118, v160
	v_mul_f32_e32 v119, v119, v160
	v_mul_f32_e32 v112, v112, v160
	v_mul_f32_e32 v113, v113, v160
	v_mul_f32_e32 v114, v114, v160
	v_mul_f32_e32 v115, v115, v160
	v_mul_f32_e32 v145, 0xbfb8aa3b, v124
	v_mul_f32_e32 v159, 0xbfb8aa3b, v125
	v_mul_f32_e32 v160, 0xbfb8aa3b, v126
	v_mul_f32_e32 v165, 0xbfb8aa3b, v127
	v_mul_f32_e32 v168, 0xbfb8aa3b, v120
	v_mul_f32_e32 v169, 0xbfb8aa3b, v121
	v_mul_f32_e32 v170, 0xbfb8aa3b, v122
	v_mul_f32_e32 v171, 0xbfb8aa3b, v123
	v_exp_f32_e32 v145, v145
	v_exp_f32_e32 v159, v159
	v_exp_f32_e32 v160, v160
	v_exp_f32_e32 v165, v165
	v_exp_f32_e32 v168, v168
	v_exp_f32_e32 v169, v169
	v_exp_f32_e32 v170, v170
	v_exp_f32_e32 v171, v171
	v_add_f32_e32 v145, 1.0, v145
	v_add_f32_e32 v159, 1.0, v159
	v_add_f32_e32 v160, 1.0, v160
	v_add_f32_e32 v165, 1.0, v165
	v_add_f32_e32 v172, 1.0, v168
	v_add_f32_e32 v173, 1.0, v169
	v_add_f32_e32 v174, 1.0, v170
	v_add_f32_e32 v175, 1.0, v171
	v_rcp_f32_e32 v168, v145
	v_rcp_f32_e32 v169, v159
	v_rcp_f32_e32 v170, v160
	v_rcp_f32_e32 v171, v165
	v_rcp_f32_e32 v172, v172
	v_rcp_f32_e32 v173, v173
	v_rcp_f32_e32 v174, v174
	v_rcp_f32_e32 v175, v175
	v_mul_f32_e32 v124, v124, v168
	v_mul_f32_e32 v125, v125, v169
	v_mul_f32_e32 v126, v126, v170
	v_mul_f32_e32 v127, v127, v171
	v_mul_f32_e32 v120, v120, v172
	v_mul_f32_e32 v121, v121, v173
	v_mul_f32_e32 v122, v122, v174
	v_mul_f32_e32 v123, v123, v175
	v_mul_f32_e32 v116, v116, v124
	v_mul_f32_e32 v117, v117, v125
	v_mul_f32_e32 v118, v118, v126
	v_mul_f32_e32 v119, v119, v127
	v_mul_f32_e32 v120, v112, v120
	v_mul_f32_e32 v121, v113, v121
	v_mul_f32_e32 v122, v114, v122
	v_mul_f32_e32 v123, v115, v123
	v_cvt_pk_bf16_f32 v112, v116, v117
	v_cvt_pk_bf16_f32 v113, v118, v119
	v_cvt_pk_bf16_f32 v114, v120, v121
	v_cvt_pk_bf16_f32 v115, v122, v123
	global_store_dwordx4 v[162:163], v[112:115], off
	global_load_dword v113, v[166:167], off
	s_nop 0
	v_or_b32_e32 v112, 32, v144
	v_mad_i64_i32 v[114:115], s[36:37], v164, s33, v[146:147]
	v_lshl_add_u64 v[114:115], v[114:115], 0, v[148:149]
	s_waitcnt vmcnt(0)
	v_fmamk_f32 v113, v113, 0x3a800000, v158
	v_rsq_f32_e32 v116, v113
	v_ashrrev_i32_e32 v113, 31, v112
	v_lshl_add_u64 v[118:119], v[112:113], 2, s[2:3]
	v_mul_f32_e32 v108, v108, v116
	v_mul_f32_e32 v109, v109, v116
	v_mul_f32_e32 v110, v110, v116
	v_mul_f32_e32 v111, v111, v116
	v_mul_f32_e32 v104, v104, v116
	v_mul_f32_e32 v105, v105, v116
	v_mul_f32_e32 v106, v106, v116
	v_mul_f32_e32 v107, v107, v116
	v_mul_f32_e32 v100, v100, v116
	v_mul_f32_e32 v101, v101, v116
	v_mul_f32_e32 v102, v102, v116
	v_mul_f32_e32 v103, v103, v116
	v_mul_f32_e32 v96, v96, v116
	v_mul_f32_e32 v97, v97, v116
	v_mul_f32_e32 v98, v98, v116
	v_mul_f32_e32 v99, v99, v116
	v_mul_f32_e32 v113, 0xbfb8aa3b, v108
	v_mul_f32_e32 v116, 0xbfb8aa3b, v109
	v_mul_f32_e32 v117, 0xbfb8aa3b, v110
	v_mul_f32_e32 v120, 0xbfb8aa3b, v111
	v_mul_f32_e32 v121, 0xbfb8aa3b, v104
	v_mul_f32_e32 v122, 0xbfb8aa3b, v105
	v_mul_f32_e32 v123, 0xbfb8aa3b, v106
	v_mul_f32_e32 v124, 0xbfb8aa3b, v107
	v_exp_f32_e32 v113, v113
	v_exp_f32_e32 v116, v116
	v_exp_f32_e32 v117, v117
	v_exp_f32_e32 v120, v120
	v_exp_f32_e32 v121, v121
	v_exp_f32_e32 v122, v122
	v_exp_f32_e32 v123, v123
	v_exp_f32_e32 v124, v124
	v_add_f32_e32 v113, 1.0, v113
	v_add_f32_e32 v125, 1.0, v116
	v_add_f32_e32 v126, 1.0, v117
	v_add_f32_e32 v127, 1.0, v120
	v_add_f32_e32 v145, 1.0, v121
	v_add_f32_e32 v159, 1.0, v122
	v_add_f32_e32 v160, 1.0, v123
	v_add_f32_e32 v162, 1.0, v124
	v_rcp_f32_e32 v116, v113
	v_rcp_f32_e32 v117, v125
	v_rcp_f32_e32 v120, v126
	v_rcp_f32_e32 v121, v127
	v_rcp_f32_e32 v122, v145
	v_rcp_f32_e32 v123, v159
	v_rcp_f32_e32 v124, v160
	v_rcp_f32_e32 v125, v162
	v_mul_f32_e32 v108, v108, v116
	v_mul_f32_e32 v109, v109, v117
	v_mul_f32_e32 v110, v110, v120
	v_mul_f32_e32 v111, v111, v121
	v_mul_f32_e32 v104, v104, v122
	v_mul_f32_e32 v105, v105, v123
	v_mul_f32_e32 v106, v106, v124
	v_mul_f32_e32 v107, v107, v125
	v_mul_f32_e32 v100, v100, v108
	v_mul_f32_e32 v101, v101, v109
	v_mul_f32_e32 v102, v102, v110
	v_mul_f32_e32 v103, v103, v111
	v_mul_f32_e32 v104, v96, v104
	v_mul_f32_e32 v105, v97, v105
	v_mul_f32_e32 v106, v98, v106
	v_mul_f32_e32 v107, v99, v107
	v_cvt_pk_bf16_f32 v96, v100, v101
	v_cvt_pk_bf16_f32 v97, v102, v103
	v_cvt_pk_bf16_f32 v98, v104, v105
	v_cvt_pk_bf16_f32 v99, v106, v107
	global_store_dwordx4 v[114:115], v[96:99], off
	global_load_dword v97, v[118:119], off
	s_nop 0
	v_or_b32_e32 v96, 48, v144
	v_mad_i64_i32 v[98:99], s[36:37], v112, s33, v[146:147]
	v_lshl_add_u64 v[98:99], v[98:99], 0, v[148:149]
	s_waitcnt vmcnt(0)
; __device__ __forceinline__ unsigned cvt_pk_bf16(float lo, float hi) { f32x2_t v = {lo, hi}; bf16x2_t b = __builtin_convertvector(v, bf16x2_t); return __builtin_bit_cast(unsigned, b); }
; __device__ __forceinline__ float rstd_of(const float* ss, int row) { return __builtin_amdgcn_rsqf(ss[row] * (1.0f / 1024.0f) + RMS_EPS); }
; __device__ __forceinline__ float sigmoidf_(float v) { return __builtin_amdgcn_rcpf(1.0f + __builtin_amdgcn_exp2f(-v * LOG2E)); }
;     __device__ __forceinline__ void operator()(const Acc& acc, const Unit& u, int wr, int wc, int fr, int fq) const {
;     ...
;             for (int m = 0; m < 4; ++m) {
;                 const int row = row0 + ai * HALF + m * 16; const float rs = rstd_of(ss, row);
;                 float o[8];
; #pragma unroll
;                 for (int n = 0; n < 2; ++n)
; #pragma unroll
;                     for (int e = 0; e < 4; ++e) { const float gv = acc[ai][0][m][n][e] * rs, uv = acc[ai][1][m][n][e] * rs; o[4 * n + e] = gv * sigmoidf_(gv) * uv; }
;                 u32x4 w; w.x = cvt_pk_bf16(o[0], o[1]); w.y = cvt_pk_bf16(o[2], o[3]); w.z = cvt_pk_bf16(o[4], o[5]); w.w = cvt_pk_bf16(o[6], o[7]);
;                 *(u32x4*)(H + (size_t)row * FF + col0) = w;
	v_fmamk_f32 v97, v97, 0x3a800000, v158
	v_rsq_f32_e32 v100, v97
	v_ashrrev_i32_e32 v97, 31, v96
	v_lshl_add_u64 v[102:103], v[96:97], 2, s[2:3]
	v_mul_f32_e32 v92, v92, v100
	v_mul_f32_e32 v93, v93, v100
	v_mul_f32_e32 v94, v94, v100
	v_mul_f32_e32 v95, v95, v100
	v_mul_f32_e32 v88, v88, v100
	v_mul_f32_e32 v89, v89, v100
	v_mul_f32_e32 v90, v90, v100
	v_mul_f32_e32 v91, v91, v100
	v_mul_f32_e32 v84, v84, v100
	v_mul_f32_e32 v85, v85, v100
	v_mul_f32_e32 v86, v86, v100
	v_mul_f32_e32 v87, v87, v100
	v_mul_f32_e32 v80, v80, v100
	v_mul_f32_e32 v81, v81, v100
	v_mul_f32_e32 v82, v82, v100
	v_mul_f32_e32 v83, v83, v100
	v_mul_f32_e32 v97, 0xbfb8aa3b, v92
	v_mul_f32_e32 v100, 0xbfb8aa3b, v93
	v_mul_f32_e32 v101, 0xbfb8aa3b, v94
	v_mul_f32_e32 v104, 0xbfb8aa3b, v95
	v_mul_f32_e32 v105, 0xbfb8aa3b, v88
	v_mul_f32_e32 v106, 0xbfb8aa3b, v89
	v_mul_f32_e32 v107, 0xbfb8aa3b, v90
	v_mul_f32_e32 v108, 0xbfb8aa3b, v91
	v_exp_f32_e32 v97, v97
	v_exp_f32_e32 v100, v100
	v_exp_f32_e32 v101, v101
	v_exp_f32_e32 v104, v104
	v_exp_f32_e32 v105, v105
	v_exp_f32_e32 v106, v106
	v_exp_f32_e32 v107, v107
	v_exp_f32_e32 v108, v108
	v_add_f32_e32 v97, 1.0, v97
	v_add_f32_e32 v109, 1.0, v100
	v_add_f32_e32 v110, 1.0, v101
	v_add_f32_e32 v111, 1.0, v104
	v_add_f32_e32 v112, 1.0, v105
	v_add_f32_e32 v113, 1.0, v106
	v_add_f32_e32 v114, 1.0, v107
	v_add_f32_e32 v115, 1.0, v108
	v_rcp_f32_e32 v100, v97
	v_rcp_f32_e32 v101, v109
	v_rcp_f32_e32 v104, v110
	v_rcp_f32_e32 v105, v111
	v_rcp_f32_e32 v106, v112
	v_rcp_f32_e32 v107, v113
	v_rcp_f32_e32 v108, v114
	v_rcp_f32_e32 v109, v115
	v_mul_f32_e32 v92, v92, v100
	v_mul_f32_e32 v93, v93, v101
	v_mul_f32_e32 v94, v94, v104
	v_mul_f32_e32 v95, v95, v105
	v_mul_f32_e32 v88, v88, v106
	v_mul_f32_e32 v89, v89, v107
	v_mul_f32_e32 v90, v90, v108
	v_mul_f32_e32 v91, v91, v109
	v_mul_f32_e32 v84, v84, v92
	v_mul_f32_e32 v85, v85, v93
	v_mul_f32_e32 v86, v86, v94
	v_mul_f32_e32 v87, v87, v95
	v_mul_f32_e32 v88, v80, v88
	v_mul_f32_e32 v89, v81, v89
	v_mul_f32_e32 v90, v82, v90
	v_mul_f32_e32 v91, v83, v91
	v_cvt_pk_bf16_f32 v80, v84, v85
	v_cvt_pk_bf16_f32 v81, v86, v87
	v_cvt_pk_bf16_f32 v82, v88, v89
	v_cvt_pk_bf16_f32 v83, v90, v91
	global_store_dwordx4 v[98:99], v[80:83], off
	global_load_dword v80, v[102:103], off
	s_nop 0
	v_mad_i64_i32 v[82:83], s[36:37], v96, s33, v[146:147]
	v_lshl_add_u64 v[82:83], v[82:83], 0, v[148:149]
	s_waitcnt vmcnt(0)
	v_fmamk_f32 v80, v80, 0x3a800000, v158
	v_rsq_f32_e32 v80, v80
	s_nop 0
	v_mul_f32_e32 v76, v76, v80
	v_mul_f32_e32 v77, v77, v80
	v_mul_f32_e32 v78, v78, v80
	v_mul_f32_e32 v79, v79, v80
	v_mul_f32_e32 v72, v72, v80
	v_mul_f32_e32 v73, v73, v80
	v_mul_f32_e32 v74, v74, v80
	v_mul_f32_e32 v75, v75, v80
	v_mul_f32_e32 v68, v68, v80
	v_mul_f32_e32 v69, v69, v80
	v_mul_f32_e32 v70, v70, v80
	v_mul_f32_e32 v71, v71, v80
	v_mul_f32_e32 v64, v64, v80
	v_mul_f32_e32 v65, v65, v80
	v_mul_f32_e32 v66, v66, v80
	v_mul_f32_e32 v67, v67, v80
	v_mul_f32_e32 v80, 0xbfb8aa3b, v76
	v_mul_f32_e32 v81, 0xbfb8aa3b, v77
	v_mul_f32_e32 v84, 0xbfb8aa3b, v78
	v_mul_f32_e32 v85, 0xbfb8aa3b, v79
	v_mul_f32_e32 v86, 0xbfb8aa3b, v72
	v_mul_f32_e32 v87, 0xbfb8aa3b, v73
	v_mul_f32_e32 v88, 0xbfb8aa3b, v74
	v_mul_f32_e32 v89, 0xbfb8aa3b, v75
	v_exp_f32_e32 v80, v80
	v_exp_f32_e32 v81, v81
	v_exp_f32_e32 v84, v84
	v_exp_f32_e32 v85, v85
	v_exp_f32_e32 v86, v86
	v_exp_f32_e32 v87, v87
	v_exp_f32_e32 v88, v88
	v_exp_f32_e32 v89, v89
	v_add_f32_e32 v80, 1.0, v80
	v_add_f32_e32 v81, 1.0, v81
	v_add_f32_e32 v84, 1.0, v84
	v_add_f32_e32 v85, 1.0, v85
	v_add_f32_e32 v86, 1.0, v86
	v_add_f32_e32 v87, 1.0, v87
	v_add_f32_e32 v88, 1.0, v88
	v_add_f32_e32 v89, 1.0, v89
	v_rcp_f32_e32 v80, v80
	v_rcp_f32_e32 v81, v81
	v_rcp_f32_e32 v84, v84
	v_rcp_f32_e32 v85, v85
	v_rcp_f32_e32 v86, v86
	v_rcp_f32_e32 v87, v87
	v_rcp_f32_e32 v88, v88
	v_rcp_f32_e32 v89, v89
	v_mul_f32_e32 v76, v76, v80
	v_mul_f32_e32 v77, v77, v81
	v_mul_f32_e32 v78, v78, v84
	v_mul_f32_e32 v79, v79, v85
	v_mul_f32_e32 v72, v72, v86
	v_mul_f32_e32 v73, v73, v87
	v_mul_f32_e32 v74, v74, v88
	v_mul_f32_e32 v75, v75, v89
	v_mul_f32_e32 v68, v68, v76
	v_mul_f32_e32 v69, v69, v77
	v_mul_f32_e32 v70, v70, v78
	v_mul_f32_e32 v71, v71, v79
	v_mul_f32_e32 v72, v64, v72
	v_mul_f32_e32 v73, v65, v73
	v_mul_f32_e32 v74, v66, v74
	v_mul_f32_e32 v75, v67, v75
	v_cvt_pk_bf16_f32 v64, v68, v69
	v_cvt_pk_bf16_f32 v65, v70, v71
	v_cvt_pk_bf16_f32 v66, v72, v73
	v_cvt_pk_bf16_f32 v67, v74, v75
	global_store_dwordx4 v[82:83], v[64:67], off
	global_load_dword v64, v[150:151], off offset:512
	s_nop 0
	v_add_u32_e32 v65, 0x80, v144
	v_mad_i64_i32 v[66:67], s[36:37], v65, s33, v[146:147]
	v_lshl_add_u64 v[66:67], v[66:67], 0, v[148:149]
	s_waitcnt vmcnt(0)
; __device__ __forceinline__ unsigned cvt_pk_bf16(float lo, float hi) { f32x2_t v = {lo, hi}; bf16x2_t b = __builtin_convertvector(v, bf16x2_t); return __builtin_bit_cast(unsigned, b); }
; __device__ __forceinline__ float rstd_of(const float* ss, int row) { return __builtin_amdgcn_rsqf(ss[row] * (1.0f / 1024.0f) + RMS_EPS); }
; __device__ __forceinline__ float sigmoidf_(float v) { return __builtin_amdgcn_rcpf(1.0f + __builtin_amdgcn_exp2f(-v * LOG2E)); }
;     __device__ __forceinline__ void operator()(const Acc& acc, const Unit& u, int wr, int wc, int fr, int fq) const {
;     ...
;             for (int m = 0; m < 4; ++m) {
;                 const int row = row0 + ai * HALF + m * 16; const float rs = rstd_of(ss, row);
;                 float o[8];
; #pragma unroll
;                 for (int n = 0; n < 2; ++n)
; #pragma unroll
;                     for (int e = 0; e < 4; ++e) { const float gv = acc[ai][0][m][n][e] * rs, uv = acc[ai][1][m][n][e] * rs; o[4 * n + e] = gv * sigmoidf_(gv) * uv; }
;                 u32x4 w; w.x = cvt_pk_bf16(o[0], o[1]); w.y = cvt_pk_bf16(o[2], o[3]); w.z = cvt_pk_bf16(o[4], o[5]); w.w = cvt_pk_bf16(o[6], o[7]);
;                 *(u32x4*)(H + (size_t)row * FF + col0) = w;
	v_fmamk_f32 v64, v64, 0x3a800000, v158
	v_rsq_f32_e32 v64, v64
	s_nop 0
	v_mul_f32_e32 v60, v60, v64
	v_mul_f32_e32 v61, v61, v64
	v_mul_f32_e32 v62, v62, v64
	v_mul_f32_e32 v63, v63, v64
	v_mul_f32_e32 v56, v56, v64
	v_mul_f32_e32 v57, v57, v64
	v_mul_f32_e32 v58, v58, v64
	v_mul_f32_e32 v59, v59, v64
	v_mul_f32_e32 v52, v52, v64
	v_mul_f32_e32 v53, v53, v64
	v_mul_f32_e32 v54, v54, v64
	v_mul_f32_e32 v55, v55, v64
	v_mul_f32_e32 v48, v48, v64
	v_mul_f32_e32 v49, v49, v64
	v_mul_f32_e32 v50, v50, v64
	v_mul_f32_e32 v51, v51, v64
	v_mul_f32_e32 v64, 0xbfb8aa3b, v60
	v_mul_f32_e32 v65, 0xbfb8aa3b, v61
	v_mul_f32_e32 v68, 0xbfb8aa3b, v62
	v_mul_f32_e32 v69, 0xbfb8aa3b, v63
	v_mul_f32_e32 v70, 0xbfb8aa3b, v56
	v_mul_f32_e32 v71, 0xbfb8aa3b, v57
	v_mul_f32_e32 v72, 0xbfb8aa3b, v58
	v_mul_f32_e32 v73, 0xbfb8aa3b, v59
	v_exp_f32_e32 v64, v64
	v_exp_f32_e32 v65, v65
	v_exp_f32_e32 v68, v68
	v_exp_f32_e32 v69, v69
	v_exp_f32_e32 v70, v70
	v_exp_f32_e32 v71, v71
	v_exp_f32_e32 v72, v72
	v_exp_f32_e32 v73, v73
	v_add_f32_e32 v64, 1.0, v64
	v_add_f32_e32 v65, 1.0, v65
	v_add_f32_e32 v68, 1.0, v68
	v_add_f32_e32 v69, 1.0, v69
	v_add_f32_e32 v70, 1.0, v70
	v_add_f32_e32 v71, 1.0, v71
	v_add_f32_e32 v72, 1.0, v72
	v_add_f32_e32 v73, 1.0, v73
	v_rcp_f32_e32 v64, v64
	v_rcp_f32_e32 v65, v65
	v_rcp_f32_e32 v68, v68
	v_rcp_f32_e32 v69, v69
	v_rcp_f32_e32 v70, v70
	v_rcp_f32_e32 v71, v71
	v_rcp_f32_e32 v72, v72
	v_rcp_f32_e32 v73, v73
	v_mul_f32_e32 v60, v60, v64
	v_mul_f32_e32 v61, v61, v65
	v_mul_f32_e32 v62, v62, v68
	v_mul_f32_e32 v63, v63, v69
	v_mul_f32_e32 v56, v56, v70
	v_mul_f32_e32 v57, v57, v71
	v_mul_f32_e32 v58, v58, v72
	v_mul_f32_e32 v59, v59, v73
	v_mul_f32_e32 v52, v52, v60
	v_mul_f32_e32 v53, v53, v61
	v_mul_f32_e32 v54, v54, v62
	v_mul_f32_e32 v55, v55, v63
	v_mul_f32_e32 v56, v48, v56
	v_mul_f32_e32 v57, v49, v57
	v_mul_f32_e32 v58, v50, v58
	v_mul_f32_e32 v59, v51, v59
	v_cvt_pk_bf16_f32 v48, v52, v53
	v_cvt_pk_bf16_f32 v49, v54, v55
	v_cvt_pk_bf16_f32 v50, v56, v57
	v_cvt_pk_bf16_f32 v51, v58, v59
	global_store_dwordx4 v[66:67], v[48:51], off
	global_load_dword v48, v[150:151], off offset:576
	s_nop 0
	v_add_u32_e32 v49, 0x90, v144
	v_mad_i64_i32 v[50:51], s[36:37], v49, s33, v[146:147]
	v_lshl_add_u64 v[50:51], v[50:51], 0, v[148:149]
	s_waitcnt vmcnt(0)
	v_fmamk_f32 v48, v48, 0x3a800000, v158
	v_rsq_f32_e32 v48, v48
	s_nop 0
	v_mul_f32_e32 v44, v44, v48
	v_mul_f32_e32 v45, v45, v48
	v_mul_f32_e32 v46, v46, v48
	v_mul_f32_e32 v47, v47, v48
	v_mul_f32_e32 v40, v40, v48
	v_mul_f32_e32 v41, v41, v48
	v_mul_f32_e32 v42, v42, v48
	v_mul_f32_e32 v43, v43, v48
	v_mul_f32_e32 v36, v36, v48
	v_mul_f32_e32 v37, v37, v48
	v_mul_f32_e32 v38, v38, v48
	v_mul_f32_e32 v39, v39, v48
	v_mul_f32_e32 v32, v32, v48
	v_mul_f32_e32 v33, v33, v48
	v_mul_f32_e32 v34, v34, v48
	v_mul_f32_e32 v35, v35, v48
	v_mul_f32_e32 v48, 0xbfb8aa3b, v44
	v_mul_f32_e32 v49, 0xbfb8aa3b, v45
	v_mul_f32_e32 v52, 0xbfb8aa3b, v46
	v_mul_f32_e32 v53, 0xbfb8aa3b, v47
	v_mul_f32_e32 v54, 0xbfb8aa3b, v40
	v_mul_f32_e32 v55, 0xbfb8aa3b, v41
	v_mul_f32_e32 v56, 0xbfb8aa3b, v42
	v_mul_f32_e32 v57, 0xbfb8aa3b, v43
	v_exp_f32_e32 v48, v48
	v_exp_f32_e32 v49, v49
	v_exp_f32_e32 v52, v52
	v_exp_f32_e32 v53, v53
	v_exp_f32_e32 v54, v54
	v_exp_f32_e32 v55, v55
	v_exp_f32_e32 v56, v56
	v_exp_f32_e32 v57, v57
	v_add_f32_e32 v48, 1.0, v48
	v_add_f32_e32 v49, 1.0, v49
	v_add_f32_e32 v52, 1.0, v52
	v_add_f32_e32 v53, 1.0, v53
	v_add_f32_e32 v54, 1.0, v54
	v_add_f32_e32 v55, 1.0, v55
	v_add_f32_e32 v56, 1.0, v56
	v_add_f32_e32 v57, 1.0, v57
	v_rcp_f32_e32 v48, v48
	v_rcp_f32_e32 v49, v49
	v_rcp_f32_e32 v52, v52
	v_rcp_f32_e32 v53, v53
	v_rcp_f32_e32 v54, v54
	v_rcp_f32_e32 v55, v55
	v_rcp_f32_e32 v56, v56
	v_rcp_f32_e32 v57, v57
	v_mul_f32_e32 v44, v44, v48
	v_mul_f32_e32 v45, v45, v49
	v_mul_f32_e32 v46, v46, v52
	v_mul_f32_e32 v47, v47, v53
	v_mul_f32_e32 v40, v40, v54
	v_mul_f32_e32 v41, v41, v55
	v_mul_f32_e32 v42, v42, v56
	v_mul_f32_e32 v43, v43, v57
	v_mul_f32_e32 v36, v36, v44
	v_mul_f32_e32 v37, v37, v45
	v_mul_f32_e32 v38, v38, v46
	v_mul_f32_e32 v39, v39, v47
	v_mul_f32_e32 v40, v32, v40
	v_mul_f32_e32 v41, v33, v41
	v_mul_f32_e32 v42, v34, v42
	v_mul_f32_e32 v43, v35, v43
	v_cvt_pk_bf16_f32 v32, v36, v37
	v_cvt_pk_bf16_f32 v33, v38, v39
	v_cvt_pk_bf16_f32 v34, v40, v41
	v_cvt_pk_bf16_f32 v35, v42, v43
	global_store_dwordx4 v[50:51], v[32:35], off
	global_load_dword v32, v[150:151], off offset:640
	s_nop 0
	v_add_u32_e32 v33, 0xa0, v144
	v_mad_i64_i32 v[34:35], s[36:37], v33, s33, v[146:147]
	v_lshl_add_u64 v[34:35], v[34:35], 0, v[148:149]
	s_waitcnt vmcnt(0)
; __device__ __forceinline__ unsigned cvt_pk_bf16(float lo, float hi) { f32x2_t v = {lo, hi}; bf16x2_t b = __builtin_convertvector(v, bf16x2_t); return __builtin_bit_cast(unsigned, b); }
; __device__ __forceinline__ float rstd_of(const float* ss, int row) { return __builtin_amdgcn_rsqf(ss[row] * (1.0f / 1024.0f) + RMS_EPS); }
; __device__ __forceinline__ float sigmoidf_(float v) { return __builtin_amdgcn_rcpf(1.0f + __builtin_amdgcn_exp2f(-v * LOG2E)); }
;     __device__ __forceinline__ void operator()(const Acc& acc, const Unit& u, int wr, int wc, int fr, int fq) const {
;     ...
;             for (int m = 0; m < 4; ++m) {
;                 const int row = row0 + ai * HALF + m * 16; const float rs = rstd_of(ss, row);
;                 float o[8];
; #pragma unroll
;                 for (int n = 0; n < 2; ++n)
; #pragma unroll
;                     for (int e = 0; e < 4; ++e) { const float gv = acc[ai][0][m][n][e] * rs, uv = acc[ai][1][m][n][e] * rs; o[4 * n + e] = gv * sigmoidf_(gv) * uv; }
;                 u32x4 w; w.x = cvt_pk_bf16(o[0], o[1]); w.y = cvt_pk_bf16(o[2], o[3]); w.z = cvt_pk_bf16(o[4], o[5]); w.w = cvt_pk_bf16(o[6], o[7]);
;                 *(u32x4*)(H + (size_t)row * FF + col0) = w;
	v_fmamk_f32 v32, v32, 0x3a800000, v158
	v_rsq_f32_e32 v32, v32
	s_nop 0
	v_mul_f32_e32 v28, v28, v32
	v_mul_f32_e32 v29, v29, v32
	v_mul_f32_e32 v30, v30, v32
	v_mul_f32_e32 v31, v31, v32
	v_mul_f32_e32 v24, v24, v32
	v_mul_f32_e32 v25, v25, v32
	v_mul_f32_e32 v26, v26, v32
	v_mul_f32_e32 v27, v27, v32
	v_mul_f32_e32 v20, v20, v32
	v_mul_f32_e32 v21, v21, v32
	v_mul_f32_e32 v22, v22, v32
	v_mul_f32_e32 v23, v23, v32
	v_mul_f32_e32 v16, v16, v32
	v_mul_f32_e32 v17, v17, v32
	v_mul_f32_e32 v18, v18, v32
	v_mul_f32_e32 v19, v19, v32
	v_mul_f32_e32 v32, 0xbfb8aa3b, v28
	v_mul_f32_e32 v33, 0xbfb8aa3b, v29
	v_mul_f32_e32 v36, 0xbfb8aa3b, v30
	v_mul_f32_e32 v37, 0xbfb8aa3b, v31
	v_mul_f32_e32 v38, 0xbfb8aa3b, v24
	v_mul_f32_e32 v39, 0xbfb8aa3b, v25
	v_mul_f32_e32 v40, 0xbfb8aa3b, v26
	v_mul_f32_e32 v41, 0xbfb8aa3b, v27
	v_exp_f32_e32 v32, v32
	v_exp_f32_e32 v33, v33
	v_exp_f32_e32 v36, v36
	v_exp_f32_e32 v37, v37
	v_exp_f32_e32 v38, v38
	v_exp_f32_e32 v39, v39
	v_exp_f32_e32 v40, v40
	v_exp_f32_e32 v41, v41
	v_add_f32_e32 v32, 1.0, v32
	v_add_f32_e32 v33, 1.0, v33
	v_add_f32_e32 v36, 1.0, v36
	v_add_f32_e32 v37, 1.0, v37
	v_add_f32_e32 v38, 1.0, v38
	v_add_f32_e32 v39, 1.0, v39
	v_add_f32_e32 v40, 1.0, v40
	v_add_f32_e32 v41, 1.0, v41
	v_rcp_f32_e32 v32, v32
	v_rcp_f32_e32 v33, v33
	v_rcp_f32_e32 v36, v36
	v_rcp_f32_e32 v37, v37
	v_rcp_f32_e32 v38, v38
	v_rcp_f32_e32 v39, v39
	v_rcp_f32_e32 v40, v40
	v_rcp_f32_e32 v41, v41
	v_mul_f32_e32 v28, v28, v32
	v_mul_f32_e32 v29, v29, v33
	v_mul_f32_e32 v30, v30, v36
	v_mul_f32_e32 v31, v31, v37
	v_mul_f32_e32 v24, v24, v38
	v_mul_f32_e32 v25, v25, v39
	v_mul_f32_e32 v26, v26, v40
	v_mul_f32_e32 v27, v27, v41
	v_mul_f32_e32 v20, v20, v28
	v_mul_f32_e32 v21, v21, v29
	v_mul_f32_e32 v22, v22, v30
	v_mul_f32_e32 v23, v23, v31
	v_mul_f32_e32 v24, v16, v24
	v_mul_f32_e32 v25, v17, v25
	v_mul_f32_e32 v26, v18, v26
	v_mul_f32_e32 v27, v19, v27
	v_cvt_pk_bf16_f32 v16, v20, v21
	v_cvt_pk_bf16_f32 v17, v22, v23
	v_cvt_pk_bf16_f32 v18, v24, v25
	v_cvt_pk_bf16_f32 v19, v26, v27
	global_store_dwordx4 v[34:35], v[16:19], off
	global_load_dword v16, v[150:151], off offset:704
	s_nop 0
	v_add_u32_e32 v17, 0xb0, v144
	v_mad_i64_i32 v[18:19], s[36:37], v17, s33, v[146:147]
	v_lshl_add_u64 v[18:19], v[18:19], 0, v[148:149]
	s_waitcnt vmcnt(0)
	v_fmamk_f32 v16, v16, 0x3a800000, v158
	v_rsq_f32_e32 v16, v16
	s_nop 0
	v_mul_f32_e32 v12, v12, v16
	v_mul_f32_e32 v13, v13, v16
	v_mul_f32_e32 v14, v14, v16
	v_mul_f32_e32 v15, v15, v16
	v_mul_f32_e32 v8, v8, v16
	v_mul_f32_e32 v9, v9, v16
	v_mul_f32_e32 v10, v10, v16
	v_mul_f32_e32 v11, v11, v16
	v_mul_f32_e32 v4, v4, v16
	v_mul_f32_e32 v5, v5, v16
	v_mul_f32_e32 v6, v6, v16
	v_mul_f32_e32 v7, v7, v16
	v_mul_f32_e32 v0, v0, v16
	v_mul_f32_e32 v1, v1, v16
	v_mul_f32_e32 v2, v2, v16
	v_mul_f32_e32 v3, v3, v16
	v_mul_f32_e32 v16, 0xbfb8aa3b, v12
	v_mul_f32_e32 v17, 0xbfb8aa3b, v13
	v_mul_f32_e32 v20, 0xbfb8aa3b, v14
	v_mul_f32_e32 v21, 0xbfb8aa3b, v15
	v_mul_f32_e32 v22, 0xbfb8aa3b, v8
	v_mul_f32_e32 v23, 0xbfb8aa3b, v9
	v_mul_f32_e32 v24, 0xbfb8aa3b, v10
	v_mul_f32_e32 v25, 0xbfb8aa3b, v11
	v_exp_f32_e32 v16, v16
	v_exp_f32_e32 v17, v17
	v_exp_f32_e32 v20, v20
	v_exp_f32_e32 v21, v21
	v_exp_f32_e32 v22, v22
	v_exp_f32_e32 v23, v23
	v_exp_f32_e32 v24, v24
	v_exp_f32_e32 v25, v25
	v_add_f32_e32 v16, 1.0, v16
	v_add_f32_e32 v17, 1.0, v17
	v_add_f32_e32 v20, 1.0, v20
	v_add_f32_e32 v21, 1.0, v21
	v_add_f32_e32 v22, 1.0, v22
	v_add_f32_e32 v23, 1.0, v23
	v_add_f32_e32 v24, 1.0, v24
	v_add_f32_e32 v25, 1.0, v25
	v_rcp_f32_e32 v16, v16
	v_rcp_f32_e32 v17, v17
	v_rcp_f32_e32 v20, v20
	v_rcp_f32_e32 v21, v21
	v_rcp_f32_e32 v22, v22
	v_rcp_f32_e32 v23, v23
	v_rcp_f32_e32 v24, v24
	v_rcp_f32_e32 v25, v25
	v_mul_f32_e32 v12, v12, v16
	v_mul_f32_e32 v13, v13, v17
	v_mul_f32_e32 v14, v14, v20
	v_mul_f32_e32 v15, v15, v21
	v_mul_f32_e32 v8, v8, v22
	v_mul_f32_e32 v9, v9, v23
	v_mul_f32_e32 v10, v10, v24
	v_mul_f32_e32 v11, v11, v25
	v_mul_f32_e32 v4, v4, v12
	v_mul_f32_e32 v5, v5, v13
	v_mul_f32_e32 v6, v6, v14
	v_mul_f32_e32 v7, v7, v15
	v_mul_f32_e32 v8, v0, v8
	v_mul_f32_e32 v9, v1, v9
	v_mul_f32_e32 v10, v2, v10
	v_mul_f32_e32 v11, v3, v11
	v_cvt_pk_bf16_f32 v0, v4, v5
	v_cvt_pk_bf16_f32 v1, v6, v7
	v_cvt_pk_bf16_f32 v2, v8, v9
	v_cvt_pk_bf16_f32 v3, v10, v11
	global_store_dwordx4 v[18:19], v[0:3], off
	s_cbranch_vccnz .LBB0_1346
	s_andn2_b64 vcc, exec, s[8:9]
	s_cbranch_vccnz .LBB0_1345
	s_barrier
	s_branch .LBB0_1345

;     __device__ __forceinline__ void operator()(Acc& acc, const Unit& u, int wr, int wc, int fr, int fq) const {
;     ...
;                 const int rt = rt0 + ai * HALF + m * 16; float sq = 0.f;
; #pragma unroll
;                 for (int bj = 0; bj < 2; ++bj) {
;                     const size_t off = (size_t)(u.pm * BM + rt) * DM + col0 + bj * HALF;
;                     const f32x4 b0 = *(const f32x4*)(base + off), b1 = *(const f32x4*)(base + off + 4);
;                     const f32x4 x0 = b0 + acc[ai][bj][m][0] * alpha, x1 = b1 + acc[ai][bj][m][1] * alpha;
;                     acc[ai][bj][m][0] = x0; acc[ai][bj][m][1] = x1;
;                     sq += (x0[0] * x0[0] + x0[1] * x0[1]) + (x0[2] * x0[2] + x0[3] * x0[3]) + (x1[0] * x1[0] + x1[1] * x1[1]) + (x1[2] * x1[2] + x1[3] * x1[3]);
;                 }
;                 sq += __shfl_xor(sq, 16); sq += __shfl_xor(sq, 32);
;                 if (fq == 0) P[rt * 4 + wc] = sq;
.LBB0_1436:
	s_lshl_b32 s25, s49, 8
	v_add_u32_e32 v144, s25, v183
	v_ashrrev_i32_e32 v145, 31, v144
	v_lshl_or_b32 v154, s24, 8, v185
	v_lshlrev_b64 v[144:145], 12, v[144:145]
	v_ashrrev_i32_e32 v155, 31, v154
	v_lshl_add_u64 v[144:145], s[82:83], 0, v[144:145]
	v_lshl_add_u64 v[144:145], v[154:155], 2, v[144:145]
	global_load_dwordx4 v[146:149], v[144:145], off
	global_load_dwordx4 v[150:153], v[144:145], off offset:16
	global_load_dwordx4 v[156:159], v[144:145], off offset:512
	global_load_dwordx4 v[160:163], v[144:145], off offset:528
	s_waitcnt vmcnt(0)
	v_fma_f32 v126, v126, 0.5, v148
	v_fma_f32 v127, v127, 0.5, v149
	v_fma_f32 v124, v124, 0.5, v146
	v_fma_f32 v125, v125, 0.5, v147
	v_fma_f32 v118, v118, 0.5, v158
	v_fma_f32 v119, v119, 0.5, v159
	v_fma_f32 v116, v116, 0.5, v156
	v_fma_f32 v117, v117, 0.5, v157
	v_fma_f32 v120, v120, 0.5, v150
	v_fma_f32 v121, v121, 0.5, v151
	v_fma_f32 v146, v112, 0.5, v160
	v_fma_f32 v147, v113, 0.5, v161
	v_mul_f32_e32 v112, v125, v125
	v_mul_f32_e32 v113, v127, v127
	v_mul_f32_e32 v150, v117, v117
	v_mul_f32_e32 v151, v119, v119
	v_fma_f32 v122, v122, 0.5, v152
	v_fma_f32 v123, v123, 0.5, v153
	v_fma_f32 v114, v114, 0.5, v162
	v_fma_f32 v115, v115, 0.5, v163
	v_mul_f32_e32 v148, v121, v121
	v_mul_f32_e32 v152, v147, v147
	v_fmac_f32_e32 v112, v124, v124
	v_fmac_f32_e32 v113, v126, v126
	v_fmac_f32_e32 v150, v116, v116
	v_fmac_f32_e32 v151, v118, v118
	v_mul_f32_e32 v149, v123, v123
	v_mul_f32_e32 v153, v115, v115
	v_fmac_f32_e32 v148, v120, v120
	v_fmac_f32_e32 v152, v146, v146
	v_add_f32_e32 v112, v112, v113
	v_add_f32_e32 v113, v150, v151
	v_fmac_f32_e32 v149, v122, v122
	v_fmac_f32_e32 v153, v114, v114
	v_add_f32_e32 v112, v148, v112
	v_add_f32_e32 v113, v152, v113
	v_add_f32_e32 v112, v149, v112
	v_add_f32_e32 v113, v153, v113
	v_add_f32_e32 v112, v112, v113
	ds_bpermute_b32 v113, v181, v112
	s_waitcnt lgkmcnt(0)
	v_add_f32_e32 v112, v112, v113
	ds_bpermute_b32 v113, v182, v112
	s_and_saveexec_b64 s[26:27], s[2:3]
	s_cbranch_execz .LBB0_1438
	s_waitcnt lgkmcnt(0)
	v_add_f32_e32 v112, v112, v113
	ds_write_b32 v205, v112
.LBB0_1438:
	s_or_b64 exec, exec, s[26:27]
	v_add_u32_e32 v112, s25, v186
	s_waitcnt lgkmcnt(0)
	v_ashrrev_i32_e32 v113, 31, v112
	v_lshlrev_b64 v[112:113], 12, v[112:113]
	v_lshl_add_u64 v[112:113], s[82:83], 0, v[112:113]
	v_lshl_add_u64 v[112:113], v[154:155], 2, v[112:113]
	global_load_dwordx4 v[148:151], v[112:113], off
	global_load_dwordx4 v[156:159], v[112:113], off offset:16
	global_load_dwordx4 v[160:163], v[112:113], off offset:512
	global_load_dwordx4 v[164:167], v[112:113], off offset:528
	s_waitcnt vmcnt(3)
	v_fma_f32 v110, v110, 0.5, v150
	v_fma_f32 v111, v111, 0.5, v151
	v_fma_f32 v108, v108, 0.5, v148
	v_fma_f32 v109, v109, 0.5, v149
	s_waitcnt vmcnt(1)
	v_fma_f32 v102, v102, 0.5, v162
	v_fma_f32 v103, v103, 0.5, v163
	v_fma_f32 v100, v100, 0.5, v160
	v_fma_f32 v101, v101, 0.5, v161
	v_fma_f32 v104, v104, 0.5, v156
	v_fma_f32 v105, v105, 0.5, v157
	s_waitcnt vmcnt(0)
	v_fma_f32 v96, v96, 0.5, v164
	v_fma_f32 v97, v97, 0.5, v165
	v_mul_f32_e32 v148, v109, v109
	v_mul_f32_e32 v149, v111, v111
	v_mul_f32_e32 v152, v101, v101
	v_mul_f32_e32 v153, v103, v103
	v_fma_f32 v106, v106, 0.5, v158
	v_fma_f32 v107, v107, 0.5, v159
	v_fma_f32 v98, v98, 0.5, v166
	v_fma_f32 v99, v99, 0.5, v167
	v_mul_f32_e32 v150, v105, v105
	v_mul_f32_e32 v156, v97, v97
	v_fmac_f32_e32 v148, v108, v108
	v_fmac_f32_e32 v149, v110, v110
	v_fmac_f32_e32 v152, v100, v100
	v_fmac_f32_e32 v153, v102, v102
	v_mul_f32_e32 v151, v107, v107
	v_mul_f32_e32 v157, v99, v99
	v_fmac_f32_e32 v150, v104, v104
	v_fmac_f32_e32 v156, v96, v96
	v_add_f32_e32 v148, v148, v149
	v_add_f32_e32 v149, v152, v153
	v_fmac_f32_e32 v151, v106, v106
	v_fmac_f32_e32 v157, v98, v98
	v_add_f32_e32 v148, v150, v148
	v_add_f32_e32 v149, v156, v149
	v_add_f32_e32 v148, v151, v148
	v_add_f32_e32 v149, v157, v149
	v_add_f32_e32 v148, v148, v149
	ds_bpermute_b32 v149, v181, v148
	s_waitcnt lgkmcnt(0)
	v_add_f32_e32 v148, v148, v149
	ds_bpermute_b32 v149, v182, v148
	s_mov_b64 s[26:27], exec
	s_and_b64 s[34:35], s[26:27], s[2:3]
	v_mov_b32_e32 v246, v180
	s_mov_b64 exec, s[34:35]
	s_cbranch_execz .LBB0_1440
	s_waitcnt lgkmcnt(0)
	v_add_f32_e32 v148, v148, v149
	ds_write_b32 v206, v148
.LBB0_1440:
	s_or_b64 exec, exec, s[26:27]
	v_add_u32_e32 v148, s25, v187
	s_waitcnt lgkmcnt(0)
	v_ashrrev_i32_e32 v149, 31, v148
	v_lshlrev_b64 v[148:149], 12, v[148:149]
	v_lshl_add_u64 v[148:149], s[82:83], 0, v[148:149]
	v_lshl_add_u64 v[148:149], v[154:155], 2, v[148:149]
	global_load_dwordx4 v[150:153], v[148:149], off
	global_load_dwordx4 v[156:159], v[148:149], off offset:16
	global_load_dwordx4 v[160:163], v[148:149], off offset:512
	global_load_dwordx4 v[164:167], v[148:149], off offset:528
	s_waitcnt vmcnt(3)
	v_fma_f32 v94, v94, 0.5, v152
	v_fma_f32 v95, v95, 0.5, v153
	v_fma_f32 v92, v92, 0.5, v150
	v_fma_f32 v93, v93, 0.5, v151
	s_waitcnt vmcnt(1)
	v_fma_f32 v86, v86, 0.5, v162
	v_fma_f32 v87, v87, 0.5, v163
	v_fma_f32 v84, v84, 0.5, v160
	v_fma_f32 v85, v85, 0.5, v161
	v_fma_f32 v88, v88, 0.5, v156
	v_fma_f32 v89, v89, 0.5, v157
	s_waitcnt vmcnt(0)
	v_fma_f32 v150, v80, 0.5, v164
	v_fma_f32 v151, v81, 0.5, v165
	v_mul_f32_e32 v80, v93, v93
	v_mul_f32_e32 v81, v95, v95
	v_mul_f32_e32 v156, v85, v85
	v_mul_f32_e32 v157, v87, v87
	v_fma_f32 v90, v90, 0.5, v158
	v_fma_f32 v91, v91, 0.5, v159
	v_fma_f32 v82, v82, 0.5, v166
	v_fma_f32 v83, v83, 0.5, v167
	v_mul_f32_e32 v152, v89, v89
	v_mul_f32_e32 v158, v151, v151
	v_fmac_f32_e32 v80, v92, v92
	v_fmac_f32_e32 v81, v94, v94
	v_fmac_f32_e32 v156, v84, v84
	v_fmac_f32_e32 v157, v86, v86
	v_mul_f32_e32 v153, v91, v91
	v_mul_f32_e32 v159, v83, v83
	v_fmac_f32_e32 v152, v88, v88
	v_fmac_f32_e32 v158, v150, v150
	v_add_f32_e32 v80, v80, v81
	v_add_f32_e32 v81, v156, v157
	v_fmac_f32_e32 v153, v90, v90
	v_fmac_f32_e32 v159, v82, v82
	v_add_f32_e32 v80, v152, v80
	v_add_f32_e32 v81, v158, v81
	v_add_f32_e32 v80, v153, v80
	v_add_f32_e32 v81, v159, v81
	v_add_f32_e32 v80, v80, v81
	ds_bpermute_b32 v81, v181, v80
	s_waitcnt lgkmcnt(0)
	v_add_f32_e32 v80, v80, v81
	ds_bpermute_b32 v81, v182, v80
	s_and_saveexec_b64 s[26:27], s[2:3]
	s_cbranch_execz .LBB0_1442
	s_waitcnt lgkmcnt(0)
	v_add_f32_e32 v80, v80, v81
	ds_write_b32 v207, v80
;     __device__ __forceinline__ void operator()(Acc& acc, const Unit& u, int wr, int wc, int fr, int fq) const {
;     ...
;                 const int rt = rt0 + ai * HALF + m * 16; float sq = 0.f;
; #pragma unroll
;                 for (int bj = 0; bj < 2; ++bj) {
;                     const size_t off = (size_t)(u.pm * BM + rt) * DM + col0 + bj * HALF;
;                     const f32x4 b0 = *(const f32x4*)(base + off), b1 = *(const f32x4*)(base + off + 4);
;                     const f32x4 x0 = b0 + acc[ai][bj][m][0] * alpha, x1 = b1 + acc[ai][bj][m][1] * alpha;
;                     acc[ai][bj][m][0] = x0; acc[ai][bj][m][1] = x1;
;                     sq += (x0[0] * x0[0] + x0[1] * x0[1]) + (x0[2] * x0[2] + x0[3] * x0[3]) + (x1[0] * x1[0] + x1[1] * x1[1]) + (x1[2] * x1[2] + x1[3] * x1[3]);
;                 }
;                 sq += __shfl_xor(sq, 16); sq += __shfl_xor(sq, 32);
;                 if (fq == 0) P[rt * 4 + wc] = sq;
.LBB0_1442:
	s_or_b64 exec, exec, s[26:27]
	v_add_u32_e32 v80, s25, v188
	s_waitcnt lgkmcnt(0)
	v_ashrrev_i32_e32 v81, 31, v80
	v_lshlrev_b64 v[80:81], 12, v[80:81]
	v_lshl_add_u64 v[80:81], s[82:83], 0, v[80:81]
	v_lshl_add_u64 v[80:81], v[154:155], 2, v[80:81]
	global_load_dwordx4 v[156:159], v[80:81], off
	global_load_dwordx4 v[160:163], v[80:81], off offset:16
	global_load_dwordx4 v[164:167], v[80:81], off offset:512
	global_load_dwordx4 v[168:171], v[80:81], off offset:528
	s_waitcnt vmcnt(3)
	v_fma_f32 v78, v78, 0.5, v158
	v_fma_f32 v79, v79, 0.5, v159
	v_fma_f32 v152, v76, 0.5, v156
	v_fma_f32 v153, v77, 0.5, v157
	s_waitcnt vmcnt(1)
	v_fma_f32 v70, v70, 0.5, v166
	v_fma_f32 v71, v71, 0.5, v167
	v_fma_f32 v68, v68, 0.5, v164
	v_fma_f32 v69, v69, 0.5, v165
	v_fma_f32 v76, v72, 0.5, v160
	v_fma_f32 v77, v73, 0.5, v161
	s_waitcnt vmcnt(0)
	v_fma_f32 v64, v64, 0.5, v168
	v_fma_f32 v65, v65, 0.5, v169
	v_mul_f32_e32 v72, v153, v153
	v_mul_f32_e32 v73, v79, v79
	v_mul_f32_e32 v158, v69, v69
	v_mul_f32_e32 v159, v71, v71
	v_fma_f32 v74, v74, 0.5, v162
	v_fma_f32 v75, v75, 0.5, v163
	v_fma_f32 v66, v66, 0.5, v170
	v_fma_f32 v67, v67, 0.5, v171
	v_mul_f32_e32 v156, v77, v77
	v_mul_f32_e32 v160, v65, v65
	v_fmac_f32_e32 v72, v152, v152
	v_fmac_f32_e32 v73, v78, v78
	v_fmac_f32_e32 v158, v68, v68
	v_fmac_f32_e32 v159, v70, v70
	v_mul_f32_e32 v157, v75, v75
	v_mul_f32_e32 v161, v67, v67
	v_fmac_f32_e32 v156, v76, v76
	v_fmac_f32_e32 v160, v64, v64
	v_add_f32_e32 v72, v72, v73
	v_add_f32_e32 v73, v158, v159
	v_fmac_f32_e32 v157, v74, v74
	v_fmac_f32_e32 v161, v66, v66
	v_add_f32_e32 v72, v156, v72
	v_add_f32_e32 v73, v160, v73
	v_add_f32_e32 v72, v157, v72
	v_add_f32_e32 v73, v161, v73
	v_add_f32_e32 v72, v72, v73
	ds_bpermute_b32 v73, v181, v72
	s_waitcnt lgkmcnt(0)
	v_add_f32_e32 v72, v72, v73
	ds_bpermute_b32 v73, v182, v72
	s_and_saveexec_b64 s[26:27], s[2:3]
	s_cbranch_execz .LBB0_1444
	s_waitcnt lgkmcnt(0)
	v_add_f32_e32 v72, v72, v73
	ds_write_b32 v208, v72
.LBB0_1444:
	s_or_b64 exec, exec, s[26:27]
	v_add_u32_e32 v72, s25, v189
	s_waitcnt lgkmcnt(0)
	v_ashrrev_i32_e32 v73, 31, v72
	v_lshlrev_b64 v[72:73], 12, v[72:73]
	v_lshl_add_u64 v[72:73], s[82:83], 0, v[72:73]
	v_lshl_add_u64 v[72:73], v[154:155], 2, v[72:73]
	global_load_dwordx4 v[156:159], v[72:73], off
	global_load_dwordx4 v[160:163], v[72:73], off offset:16
	global_load_dwordx4 v[164:167], v[72:73], off offset:512
	global_load_dwordx4 v[168:171], v[72:73], off offset:528
	s_waitcnt vmcnt(3)
	v_fma_f32 v62, v62, 0.5, v158
	v_fma_f32 v63, v63, 0.5, v159
	v_fma_f32 v60, v60, 0.5, v156
	v_fma_f32 v61, v61, 0.5, v157
	s_waitcnt vmcnt(1)
	v_fma_f32 v54, v54, 0.5, v166
	v_fma_f32 v55, v55, 0.5, v167
	v_fma_f32 v52, v52, 0.5, v164
	v_fma_f32 v53, v53, 0.5, v165
	v_fma_f32 v56, v56, 0.5, v160
	v_fma_f32 v57, v57, 0.5, v161
	s_waitcnt vmcnt(0)
	v_fma_f32 v48, v48, 0.5, v168
	v_fma_f32 v49, v49, 0.5, v169
	v_mul_f32_e32 v156, v61, v61
	v_mul_f32_e32 v157, v63, v63
	v_mul_f32_e32 v160, v53, v53
	v_mul_f32_e32 v161, v55, v55
	v_fma_f32 v58, v58, 0.5, v162
	v_fma_f32 v59, v59, 0.5, v163
	v_fma_f32 v50, v50, 0.5, v170
	v_fma_f32 v51, v51, 0.5, v171
	v_mul_f32_e32 v158, v57, v57
	v_mul_f32_e32 v162, v49, v49
	v_fmac_f32_e32 v156, v60, v60
	v_fmac_f32_e32 v157, v62, v62
	v_fmac_f32_e32 v160, v52, v52
	v_fmac_f32_e32 v161, v54, v54
	v_mul_f32_e32 v159, v59, v59
	v_mul_f32_e32 v163, v51, v51
	v_fmac_f32_e32 v158, v56, v56
	v_fmac_f32_e32 v162, v48, v48
	v_add_f32_e32 v156, v156, v157
	v_add_f32_e32 v157, v160, v161
	v_fmac_f32_e32 v159, v58, v58
	v_fmac_f32_e32 v163, v50, v50
	v_add_f32_e32 v156, v158, v156
	v_add_f32_e32 v157, v162, v157
	v_add_f32_e32 v156, v159, v156
	v_add_f32_e32 v157, v163, v157
	v_add_f32_e32 v156, v156, v157
	ds_bpermute_b32 v157, v181, v156
	s_waitcnt lgkmcnt(0)
	v_add_f32_e32 v156, v156, v157
	ds_bpermute_b32 v157, v182, v156
	s_and_saveexec_b64 s[26:27], s[2:3]
	s_cbranch_execz .LBB0_1446
	s_waitcnt lgkmcnt(0)
	v_add_f32_e32 v156, v156, v157
	ds_write_b32 v209, v156
.LBB0_1446:
	s_or_b64 exec, exec, s[26:27]
	v_add_u32_e32 v156, s25, v190
	s_waitcnt lgkmcnt(0)
	v_ashrrev_i32_e32 v157, 31, v156
	v_lshlrev_b64 v[156:157], 12, v[156:157]
	v_lshl_add_u64 v[156:157], s[82:83], 0, v[156:157]
	v_lshl_add_u64 v[156:157], v[154:155], 2, v[156:157]
	global_load_dwordx4 v[158:161], v[156:157], off
	global_load_dwordx4 v[162:165], v[156:157], off offset:16
	global_load_dwordx4 v[166:169], v[156:157], off offset:512
	global_load_dwordx4 v[170:173], v[156:157], off offset:528
	s_waitcnt vmcnt(3)
	v_fma_f32 v46, v46, 0.5, v160
	v_fma_f32 v47, v47, 0.5, v161
	v_fma_f32 v44, v44, 0.5, v158
	v_fma_f32 v45, v45, 0.5, v159
	s_waitcnt vmcnt(1)
	v_fma_f32 v38, v38, 0.5, v168
	v_fma_f32 v39, v39, 0.5, v169
	v_fma_f32 v36, v36, 0.5, v166
	v_fma_f32 v37, v37, 0.5, v167
	v_fma_f32 v40, v40, 0.5, v162
	v_fma_f32 v41, v41, 0.5, v163
	s_waitcnt vmcnt(0)
	v_fma_f32 v32, v32, 0.5, v170
	v_fma_f32 v33, v33, 0.5, v171
	v_mul_f32_e32 v158, v45, v45
	v_mul_f32_e32 v159, v47, v47
	v_mul_f32_e32 v162, v37, v37
	v_mul_f32_e32 v163, v39, v39
	v_fma_f32 v42, v42, 0.5, v164
	v_fma_f32 v43, v43, 0.5, v165
	v_fma_f32 v34, v34, 0.5, v172
	v_fma_f32 v35, v35, 0.5, v173
	v_mul_f32_e32 v160, v41, v41
	v_mul_f32_e32 v164, v33, v33
	v_fmac_f32_e32 v158, v44, v44
	v_fmac_f32_e32 v159, v46, v46
	v_fmac_f32_e32 v162, v36, v36
	v_fmac_f32_e32 v163, v38, v38
	v_mul_f32_e32 v161, v43, v43
	v_mul_f32_e32 v165, v35, v35
	v_fmac_f32_e32 v160, v40, v40
	v_fmac_f32_e32 v164, v32, v32
	v_add_f32_e32 v158, v158, v159
	v_add_f32_e32 v159, v162, v163
	v_fmac_f32_e32 v161, v42, v42
	v_fmac_f32_e32 v165, v34, v34
	v_add_f32_e32 v158, v160, v158
	v_add_f32_e32 v159, v164, v159
	v_add_f32_e32 v158, v161, v158
	v_add_f32_e32 v159, v165, v159
	v_add_f32_e32 v158, v158, v159
	ds_bpermute_b32 v159, v181, v158
	s_waitcnt lgkmcnt(0)
	v_add_f32_e32 v158, v158, v159
	ds_bpermute_b32 v159, v182, v158
	s_and_saveexec_b64 s[26:27], s[2:3]
	s_cbranch_execz .LBB0_1448
	s_waitcnt lgkmcnt(0)
	v_add_f32_e32 v158, v158, v159
	ds_write_b32 v210, v158
; #define LAS __attribute__((address_space(3)))
;     __device__ __forceinline__ void operator()(Acc& acc, const Unit& u, int wr, int wc, int fr, int fq) const {
;     ...
;                 sq += __shfl_xor(sq, 16); sq += __shfl_xor(sq, 32);
;                 if (fq == 0) P[rt * 4 + wc] = sq;
;             }
;         asm volatile("s_waitcnt lgkmcnt(0)" ::: "memory"); __builtin_amdgcn_s_barrier(); asm volatile("" ::: "memory");
;         const int tid = threadIdx.x;
;         if (tid < 256) {
;             const f32x4 p = *(const LAS f32x4*)(P + tid * 4);
;             __hip_atomic_store(xs + (size_t)(u.pm * BM + tid) * 4 + u.pn, (p[0] + p[1]) + (p[2] + p[3]), __ATOMIC_RELAXED, __HIP_MEMORY_SCOPE_AGENT);
;             asm volatile("s_waitcnt vmcnt(0)" ::: "memory");
;             if ((tid & 63) == 0) __hip_atomic_fetch_add(cnt + 64 * u.pm, 1u, __ATOMIC_RELAXED, __HIP_MEMORY_SCOPE_AGENT);
.LBB0_1448:
	s_or_b64 exec, exec, s[26:27]
	v_add_u32_e32 v158, s25, v191
	s_waitcnt lgkmcnt(0)
	v_ashrrev_i32_e32 v159, 31, v158
	v_lshlrev_b64 v[158:159], 12, v[158:159]
	v_lshl_add_u64 v[158:159], s[82:83], 0, v[158:159]
	v_lshl_add_u64 v[158:159], v[154:155], 2, v[158:159]
	global_load_dwordx4 v[160:163], v[158:159], off
	global_load_dwordx4 v[164:167], v[158:159], off offset:16
	global_load_dwordx4 v[168:171], v[158:159], off offset:512
	global_load_dwordx4 v[172:175], v[158:159], off offset:528
	s_waitcnt vmcnt(3)
	v_fma_f32 v30, v30, 0.5, v162
	v_fma_f32 v31, v31, 0.5, v163
	v_fma_f32 v28, v28, 0.5, v160
	v_fma_f32 v29, v29, 0.5, v161
	s_waitcnt vmcnt(1)
	v_fma_f32 v22, v22, 0.5, v170
	v_fma_f32 v23, v23, 0.5, v171
	v_fma_f32 v20, v20, 0.5, v168
	v_fma_f32 v21, v21, 0.5, v169
	v_fma_f32 v24, v24, 0.5, v164
	v_fma_f32 v25, v25, 0.5, v165
	s_waitcnt vmcnt(0)
	v_fma_f32 v16, v16, 0.5, v172
	v_fma_f32 v17, v17, 0.5, v173
	v_mul_f32_e32 v160, v29, v29
	v_mul_f32_e32 v161, v31, v31
	v_mul_f32_e32 v164, v21, v21
	v_mul_f32_e32 v165, v23, v23
	v_fma_f32 v26, v26, 0.5, v166
	v_fma_f32 v27, v27, 0.5, v167
	v_fma_f32 v18, v18, 0.5, v174
	v_fma_f32 v19, v19, 0.5, v175
	v_mul_f32_e32 v162, v25, v25
	v_mul_f32_e32 v166, v17, v17
	v_fmac_f32_e32 v160, v28, v28
	v_fmac_f32_e32 v161, v30, v30
	v_fmac_f32_e32 v164, v20, v20
	v_fmac_f32_e32 v165, v22, v22
	v_mul_f32_e32 v163, v27, v27
	v_mul_f32_e32 v167, v19, v19
	v_fmac_f32_e32 v162, v24, v24
	v_fmac_f32_e32 v166, v16, v16
	v_add_f32_e32 v160, v160, v161
	v_add_f32_e32 v161, v164, v165
	v_fmac_f32_e32 v163, v26, v26
	v_fmac_f32_e32 v167, v18, v18
	v_add_f32_e32 v160, v162, v160
	v_add_f32_e32 v161, v166, v161
	v_add_f32_e32 v160, v163, v160
	v_add_f32_e32 v161, v167, v161
	v_add_f32_e32 v160, v160, v161
	ds_bpermute_b32 v161, v181, v160
	s_waitcnt lgkmcnt(0)
	v_add_f32_e32 v160, v160, v161
	ds_bpermute_b32 v161, v182, v160
	s_and_saveexec_b64 s[26:27], s[2:3]
	s_cbranch_execz .LBB0_1450
	s_waitcnt lgkmcnt(0)
	v_add_f32_e32 v160, v160, v161
	ds_write_b32 v211, v160
.LBB0_1450:
	s_or_b64 exec, exec, s[26:27]
	v_add_u32_e32 v160, s25, v192
	s_waitcnt lgkmcnt(0)
	v_ashrrev_i32_e32 v161, 31, v160
	v_lshlrev_b64 v[160:161], 12, v[160:161]
	v_lshl_add_u64 v[160:161], s[82:83], 0, v[160:161]
	v_lshl_add_u64 v[160:161], v[154:155], 2, v[160:161]
	global_load_dwordx4 v[162:165], v[160:161], off
	global_load_dwordx4 v[166:169], v[160:161], off offset:16
	global_load_dwordx4 v[216:219], v[160:161], off offset:512
	global_load_dwordx4 v[220:223], v[160:161], off offset:528
	s_waitcnt vmcnt(3)
	v_fma_f32 v174, v14, 0.5, v164
	v_fma_f32 v175, v15, 0.5, v165
	v_fma_f32 v176, v12, 0.5, v162
	v_fma_f32 v177, v13, 0.5, v163
	s_waitcnt vmcnt(2)
	v_fma_f32 v170, v10, 0.5, v168
	v_fma_f32 v171, v11, 0.5, v169
	v_fma_f32 v172, v8, 0.5, v166
	v_fma_f32 v173, v9, 0.5, v167
	s_waitcnt vmcnt(1)
	v_fma_f32 v166, v6, 0.5, v218
	v_fma_f32 v167, v7, 0.5, v219
	v_fma_f32 v168, v4, 0.5, v216
	v_fma_f32 v169, v5, 0.5, v217
	s_waitcnt vmcnt(0)
	v_fma_f32 v164, v0, 0.5, v220
	v_fma_f32 v165, v1, 0.5, v221
	v_mul_f32_e32 v0, v177, v177
	v_mul_f32_e32 v1, v175, v175
	v_mul_f32_e32 v4, v169, v169
	v_mul_f32_e32 v5, v167, v167
	v_fma_f32 v162, v2, 0.5, v222
	v_fma_f32 v163, v3, 0.5, v223
	v_mul_f32_e32 v2, v173, v173
	v_mul_f32_e32 v6, v165, v165
	v_fmac_f32_e32 v0, v176, v176
	v_fmac_f32_e32 v1, v174, v174
	v_fmac_f32_e32 v4, v168, v168
	v_fmac_f32_e32 v5, v166, v166
	v_mul_f32_e32 v3, v171, v171
	v_mul_f32_e32 v7, v163, v163
	v_fmac_f32_e32 v2, v172, v172
	v_fmac_f32_e32 v6, v164, v164
	v_add_f32_e32 v0, v0, v1
	v_add_f32_e32 v1, v4, v5
	v_fmac_f32_e32 v3, v170, v170
	v_fmac_f32_e32 v7, v162, v162
	v_add_f32_e32 v0, v2, v0
	v_add_f32_e32 v1, v6, v1
	v_add_f32_e32 v0, v3, v0
	v_add_f32_e32 v1, v7, v1
	v_add_f32_e32 v0, v0, v1
	ds_bpermute_b32 v1, v181, v0
	s_waitcnt lgkmcnt(0)
	v_add_f32_e32 v0, v0, v1
	ds_bpermute_b32 v1, v182, v0
	s_and_saveexec_b64 s[26:27], s[2:3]
	s_cbranch_execz .LBB0_1452
	s_waitcnt lgkmcnt(0)
	v_add_f32_e32 v0, v0, v1
	ds_write_b32 v212, v0
.LBB0_1452:
	s_or_b64 exec, exec, s[26:27]
	s_waitcnt lgkmcnt(0)
	s_barrier
	v_or_b32_e32 v0, s25, v246
	s_waitcnt lgkmcnt(0)
	v_ashrrev_i32_e32 v1, 31, v0
	s_and_saveexec_b64 s[26:27], s[4:5]
	s_cbranch_execz .LBB0_1456
	ds_read_b128 v[2:5], v213
	v_lshl_add_u64 v[6:7], v[0:1], 4, s[12:13]
	s_ashr_i32 s25, s24, 31
	v_lshl_add_u64 v[6:7], s[24:25], 2, v[6:7]
	s_waitcnt lgkmcnt(0)
	v_mov_b32_e32 v8, v3
	v_mov_b32_e32 v9, v4
	v_mov_b32_e32 v3, v5
	v_add_f32_e32 v2, v8, v2
	v_add_f32_e32 v3, v9, v3
	s_nop 0
	v_pk_add_f32 v[2:3], v[2:3], v[2:3] op_sel:[0,1] op_sel_hi:[1,0]
	global_store_dword v[6:7], v2, off sc1
	s_waitcnt vmcnt(0)
	s_and_b64 exec, exec, s[6:7]
	s_cbranch_execz .LBB0_1456
	s_mov_b64 s[24:25], exec
	v_mbcnt_lo_u32_b32 v2, s24, 0
	v_mbcnt_hi_u32_b32 v2, s25, v2
	v_cmp_eq_u32_e32 vcc, 0, v2
	s_and_b64 s[34:35], exec, vcc
	s_mov_b64 exec, s[34:35]
	s_cbranch_execz .LBB0_1456
	s_lshl_b32 s34, s49, 6
	s_ashr_i32 s35, s34, 31
	s_lshl_b64 s[34:35], s[34:35], 2
	s_add_u32 s34, s33, s34
	s_addc_u32 s35, s40, s35
	s_bcnt1_i32_b64 s24, s[24:25]
	v_mov_b32_e32 v2, s24
	global_atomic_add v131, v2, s[34:35]

;     __device__ __forceinline__ void operator()(Acc& acc, const Unit& u, int wr, int wc, int fr, int fq) const {
;     ...
;         if (tid < 256) {
;             const float* sl = xs + (size_t)(u.pm * BM + tid) * 4;
;             const float t = (__hip_atomic_load(sl, __ATOMIC_RELAXED, __HIP_MEMORY_SCOPE_AGENT) + __hip_atomic_load(sl + 1, __ATOMIC_RELAXED, __HIP_MEMORY_SCOPE_AGENT))
;                           + (__hip_atomic_load(sl + 2, __ATOMIC_RELAXED, __HIP_MEMORY_SCOPE_AGENT) + __hip_atomic_load(sl + 3, __ATOMIC_RELAXED, __HIP_MEMORY_SCOPE_AGENT));
;             R[tid] = __builtin_amdgcn_rsqf(t * (1.0f / 1024.0f) + RMS_EPS);
;         }
;         asm volatile("s_waitcnt vmcnt(0) lgkmcnt(0)" ::: "memory"); __builtin_amdgcn_s_barrier(); asm volatile("" ::: "memory");
;         f32x4 gv[2][2];
; #pragma unroll
;         for (int bj = 0; bj < 2; ++bj) { gv[bj][0] = *(const f32x4*)(gfin + col0 + bj * HALF); gv[bj][1] = *(const f32x4*)(gfin + col0 + bj * HALF + 4); }
; #pragma unroll
;         for (int ai = 0; ai < 2; ++ai)
; #pragma unroll
;             for (int m = 0; m < 4; ++m) {
;                 const int rt = rt0 + ai * HALF + m * 16; const float rs = R[rt];
; #pragma unroll
;                 for (int bj = 0; bj < 2; ++bj) {
;                     const size_t off = (size_t)(u.pm * BM + rt) * DM + col0 + bj * HALF;
;                     __builtin_nontemporal_store(acc[ai][bj][m][0] * rs * gv[bj][0], (f32x4*)(out + off)); __builtin_nontemporal_store(acc[ai][bj][m][1] * rs * gv[bj][1], (f32x4*)(out + off + 4));
.LBB0_1466:
	s_or_b64 exec, exec, s[24:25]
	s_waitcnt vmcnt(0) lgkmcnt(0)
	s_barrier
	s_and_saveexec_b64 s[24:25], s[4:5]
	s_cbranch_execz .LBB0_1468
	v_lshl_add_u64 v[0:1], v[0:1], 4, s[12:13]
	global_load_dword v2, v[0:1], off sc1
	global_load_dword v4, v[0:1], off offset:4 sc1
	global_load_dword v3, v[0:1], off offset:8 sc1
	global_load_dword v5, v[0:1], off offset:12 sc1
	s_waitcnt vmcnt(0)
	v_add_f32_e32 v0, v2, v4
	v_add_f32_e32 v1, v3, v5
	s_nop 0
	v_add_f32_e32 v0, v0, v1
	v_fmamk_f32 v0, v0, 0x3a800000, v214
	v_rsq_f32_e32 v0, v0
	ds_write_b32 v193, v0
.LBB0_1468:
	s_or_b64 exec, exec, s[24:25]
	s_waitcnt vmcnt(0) lgkmcnt(0)
	s_barrier
	v_lshl_add_u64 v[0:1], v[154:155], 2, s[80:81]
	global_load_dwordx4 v[12:15], v[0:1], off
	global_load_dwordx4 v[8:11], v[0:1], off offset:16
	global_load_dwordx4 v[4:7], v[0:1], off offset:512
	s_nop 0
	global_load_dwordx4 v[0:3], v[0:1], off offset:528
	ds_read_b32 v154, v194
	ds_read_b32 v178, v195
	ds_read_b32 v216, v196
	ds_read_b32 v180, v197
	ds_read_b32 v220, v198
	ds_read_b32 v222, v199
	ds_read_b32 v224, v200
	ds_read_b32 v226, v201
	s_waitcnt lgkmcnt(7)
	v_mul_f32_e32 v126, v126, v154
	v_mul_f32_e32 v127, v127, v154
	v_mul_f32_e32 v124, v124, v154
	v_mul_f32_e32 v125, v125, v154
	v_mul_f32_e32 v122, v122, v154
	v_mul_f32_e32 v123, v123, v154
	s_waitcnt lgkmcnt(1)
	v_mul_f32_e32 v18, v18, v224
	v_mul_f32_e32 v19, v19, v224
	v_mul_f32_e32 v16, v16, v224
	v_mul_f32_e32 v17, v17, v224
	v_mul_f32_e32 v120, v120, v154
	v_mul_f32_e32 v121, v121, v154
	v_mul_f32_e32 v118, v118, v154
	v_mul_f32_e32 v119, v119, v154
	v_mul_f32_e32 v116, v116, v154
	v_mul_f32_e32 v117, v117, v154
	v_mul_f32_e32 v114, v114, v154
	v_mul_f32_e32 v115, v115, v154
	v_mul_f32_e32 v146, v146, v154
	v_mul_f32_e32 v147, v147, v154
	v_mul_f32_e32 v110, v110, v178
	v_mul_f32_e32 v111, v111, v178
	v_mul_f32_e32 v108, v108, v178
	v_mul_f32_e32 v109, v109, v178
	v_mul_f32_e32 v106, v106, v178
	v_mul_f32_e32 v107, v107, v178
	v_mul_f32_e32 v104, v104, v178
	v_mul_f32_e32 v105, v105, v178
	v_mul_f32_e32 v102, v102, v178
	v_mul_f32_e32 v103, v103, v178
	v_mul_f32_e32 v154, v100, v178
	v_mul_f32_e32 v155, v101, v178
	v_mul_f32_e32 v218, v98, v178
	v_mul_f32_e32 v219, v99, v178
	v_mul_f32_e32 v179, v97, v178
	v_mul_f32_e32 v178, v96, v178
	v_mul_f32_e32 v228, v94, v216
	v_mul_f32_e32 v229, v95, v216
	v_mul_f32_e32 v230, v92, v216
	v_mul_f32_e32 v231, v93, v216
	v_mul_f32_e32 v232, v90, v216
	v_mul_f32_e32 v233, v91, v216
	v_mul_f32_e32 v234, v88, v216
	v_mul_f32_e32 v235, v89, v216
	v_mul_f32_e32 v236, v86, v216
	v_mul_f32_e32 v237, v87, v216
	v_mul_f32_e32 v238, v84, v216
	v_mul_f32_e32 v239, v85, v216
	v_mul_f32_e32 v240, v82, v216
	v_mul_f32_e32 v241, v83, v216
	v_mul_f32_e32 v150, v150, v216
	v_mul_f32_e32 v151, v151, v216
	v_mul_f32_e32 v78, v78, v180
	v_mul_f32_e32 v79, v79, v180
	v_mul_f32_e32 v216, v152, v180
	v_mul_f32_e32 v217, v153, v180
	v_mul_f32_e32 v242, v74, v180
	v_mul_f32_e32 v243, v75, v180
	v_mul_f32_e32 v244, v76, v180
	v_mul_f32_e32 v245, v77, v180
	v_mul_f32_e32 v62, v62, v220
	v_mul_f32_e32 v63, v63, v220
	v_mul_f32_e32 v60, v60, v220
	v_mul_f32_e32 v61, v61, v220
	v_mul_f32_e32 v46, v46, v222
	v_mul_f32_e32 v47, v47, v222
	v_mul_f32_e32 v44, v44, v222
	v_mul_f32_e32 v45, v45, v222
	v_mul_f32_e32 v30, v30, v224
	v_mul_f32_e32 v31, v31, v224
	v_mul_f32_e32 v28, v28, v224
	v_mul_f32_e32 v29, v29, v224
	v_mul_f32_e32 v58, v58, v220
	v_mul_f32_e32 v59, v59, v220
	v_mul_f32_e32 v56, v56, v220
	v_mul_f32_e32 v57, v57, v220
	v_mul_f32_e32 v42, v42, v222
	v_mul_f32_e32 v43, v43, v222
	v_mul_f32_e32 v40, v40, v222
	v_mul_f32_e32 v41, v41, v222
	v_mul_f32_e32 v26, v26, v224
	v_mul_f32_e32 v27, v27, v224
	v_mul_f32_e32 v24, v24, v224
	v_mul_f32_e32 v25, v25, v224
	v_mul_f32_e32 v70, v70, v180
	v_mul_f32_e32 v71, v71, v180
	v_mul_f32_e32 v68, v68, v180
	v_mul_f32_e32 v69, v69, v180
	v_mul_f32_e32 v54, v54, v220
	v_mul_f32_e32 v55, v55, v220
	v_mul_f32_e32 v52, v52, v220
	v_mul_f32_e32 v53, v53, v220
	v_mul_f32_e32 v38, v38, v222
	v_mul_f32_e32 v39, v39, v222
	v_mul_f32_e32 v36, v36, v222
	v_mul_f32_e32 v37, v37, v222
	v_mul_f32_e32 v22, v22, v224
	v_mul_f32_e32 v23, v23, v224
	v_mul_f32_e32 v20, v20, v224
	v_mul_f32_e32 v21, v21, v224
	v_mul_f32_e32 v66, v66, v180
	v_mul_f32_e32 v67, v67, v180
	v_mul_f32_e32 v64, v64, v180
	v_mul_f32_e32 v65, v65, v180
	v_mul_f32_e32 v50, v50, v220
	v_mul_f32_e32 v51, v51, v220
	v_mul_f32_e32 v48, v48, v220
	v_mul_f32_e32 v49, v49, v220
	v_mul_f32_e32 v34, v34, v222
	v_mul_f32_e32 v35, v35, v222
	v_mul_f32_e32 v32, v32, v222
	v_mul_f32_e32 v33, v33, v222
	s_and_b64 vcc, exec, s[8:9]
	s_mov_b64 s[8:9], -1
	s_waitcnt vmcnt(3)
	v_mul_f32_e32 v76, v14, v126
	v_mul_f32_e32 v77, v15, v127
	v_mul_f32_e32 v74, v12, v124
	v_mul_f32_e32 v75, v13, v125
	s_waitcnt vmcnt(2)
	v_mul_f32_e32 v84, v10, v122
	v_mul_f32_e32 v85, v11, v123
	s_waitcnt vmcnt(0)
;     __device__ __forceinline__ void operator()(Acc& acc, const Unit& u, int wr, int wc, int fr, int fq) const {
;     ...
;         for (int bj = 0; bj < 2; ++bj) { gv[bj][0] = *(const f32x4*)(gfin + col0 + bj * HALF); gv[bj][1] = *(const f32x4*)(gfin + col0 + bj * HALF + 4); }
; #pragma unroll
;         for (int ai = 0; ai < 2; ++ai)
; #pragma unroll
;             for (int m = 0; m < 4; ++m) {
;                 const int rt = rt0 + ai * HALF + m * 16; const float rs = R[rt];
; #pragma unroll
;                 for (int bj = 0; bj < 2; ++bj) {
;                     const size_t off = (size_t)(u.pm * BM + rt) * DM + col0 + bj * HALF;
;                     __builtin_nontemporal_store(acc[ai][bj][m][0] * rs * gv[bj][0], (f32x4*)(out + off)); __builtin_nontemporal_store(acc[ai][bj][m][1] * rs * gv[bj][1], (f32x4*)(out + off + 4));
;                 }
;             }
;         asm volatile("s_waitcnt lgkmcnt(0)" ::: "memory"); __builtin_amdgcn_s_barrier(); asm volatile("" ::: "memory");
	v_mul_f32_e32 v18, v2, v18
	v_mul_f32_e32 v19, v3, v19
	v_mul_f32_e32 v16, v0, v16
	v_mul_f32_e32 v17, v1, v17
	v_mul_f32_e32 v82, v8, v120
	v_mul_f32_e32 v83, v9, v121
	v_mul_f32_e32 v88, v6, v118
	v_mul_f32_e32 v89, v7, v119
	v_mul_f32_e32 v86, v4, v116
	v_mul_f32_e32 v87, v5, v117
	v_mul_f32_e32 v92, v2, v114
	v_mul_f32_e32 v93, v3, v115
	v_mul_f32_e32 v90, v0, v146
	v_mul_f32_e32 v91, v1, v147
	v_mul_f32_e32 v96, v14, v110
	v_mul_f32_e32 v97, v15, v111
	v_mul_f32_e32 v94, v12, v108
	v_mul_f32_e32 v95, v13, v109
	v_mul_f32_e32 v100, v10, v106
	v_mul_f32_e32 v101, v11, v107
	v_mul_f32_e32 v98, v8, v104
	v_mul_f32_e32 v99, v9, v105
	v_mul_f32_e32 v104, v6, v102
	v_mul_f32_e32 v105, v7, v103
	v_mul_f32_e32 v102, v4, v154
	v_mul_f32_e32 v103, v5, v155
	v_mul_f32_e32 v108, v2, v218
	v_mul_f32_e32 v109, v3, v219
	v_mul_f32_e32 v106, v0, v178
	v_mul_f32_e32 v107, v1, v179
	v_mul_f32_e32 v116, v14, v228
	v_mul_f32_e32 v117, v15, v229
	v_mul_f32_e32 v114, v12, v230
	v_mul_f32_e32 v115, v13, v231
	v_mul_f32_e32 v120, v10, v232
	v_mul_f32_e32 v121, v11, v233
	v_mul_f32_e32 v118, v8, v234
	v_mul_f32_e32 v119, v9, v235
	v_mul_f32_e32 v124, v6, v236
	v_mul_f32_e32 v125, v7, v237
	v_mul_f32_e32 v122, v4, v238
	v_mul_f32_e32 v123, v5, v239
	v_mul_f32_e32 v152, v2, v240
	v_mul_f32_e32 v153, v3, v241
	v_mul_f32_e32 v150, v0, v150
	v_mul_f32_e32 v151, v1, v151
	v_mul_f32_e32 v218, v14, v78
	v_mul_f32_e32 v219, v15, v79
	v_mul_f32_e32 v216, v12, v216
	v_mul_f32_e32 v217, v13, v217
	global_store_dwordx4 v[144:145], v[74:77], off nt
	global_store_dwordx4 v[144:145], v[82:85], off offset:16 nt
	global_store_dwordx4 v[144:145], v[86:89], off offset:512 nt
	global_store_dwordx4 v[144:145], v[90:93], off offset:528 nt
	global_store_dwordx4 v[112:113], v[94:97], off nt
	global_store_dwordx4 v[112:113], v[98:101], off offset:16 nt
	global_store_dwordx4 v[112:113], v[102:105], off offset:512 nt
	global_store_dwordx4 v[112:113], v[106:109], off offset:528 nt
	global_store_dwordx4 v[148:149], v[114:117], off nt
	global_store_dwordx4 v[148:149], v[118:121], off offset:16 nt
	global_store_dwordx4 v[148:149], v[122:125], off offset:512 nt
	global_store_dwordx4 v[148:149], v[150:153], off offset:528 nt
	global_store_dwordx4 v[80:81], v[216:219], off nt
	global_store_dwordx4 v[158:159], v[16:19], off offset:528 nt
	v_mul_f32_e32 v62, v14, v62
	v_mul_f32_e32 v63, v15, v63
	v_mul_f32_e32 v60, v12, v60
	v_mul_f32_e32 v61, v13, v61
	s_waitcnt lgkmcnt(0)
	v_mul_f32_e32 v16, v174, v226
	v_mul_f32_e32 v17, v175, v226
	v_mul_f32_e32 v18, v176, v226
	v_mul_f32_e32 v19, v177, v226
	v_mul_f32_e32 v46, v14, v46
	v_mul_f32_e32 v47, v15, v47
	v_mul_f32_e32 v44, v12, v44
	v_mul_f32_e32 v45, v13, v45
	v_mul_f32_e32 v30, v14, v30
	v_mul_f32_e32 v31, v15, v31
	v_mul_f32_e32 v28, v12, v28
	v_mul_f32_e32 v29, v13, v29
	v_mul_f32_e32 v14, v14, v16
	v_mul_f32_e32 v15, v15, v17
	v_mul_f32_e32 v12, v12, v18
	v_mul_f32_e32 v13, v13, v19
	global_store_dwordx4 v[160:161], v[12:15], off nt
	v_mul_f32_e32 v76, v10, v242
	v_mul_f32_e32 v77, v11, v243
	v_mul_f32_e32 v74, v8, v244
	v_mul_f32_e32 v75, v9, v245
	v_mul_f32_e32 v12, v170, v226
	v_mul_f32_e32 v13, v171, v226
	v_mul_f32_e32 v14, v172, v226
	v_mul_f32_e32 v15, v173, v226
	v_mul_f32_e32 v58, v10, v58
	v_mul_f32_e32 v59, v11, v59
	v_mul_f32_e32 v56, v8, v56
	v_mul_f32_e32 v57, v9, v57
	v_mul_f32_e32 v42, v10, v42
	v_mul_f32_e32 v43, v11, v43
	v_mul_f32_e32 v40, v8, v40
	v_mul_f32_e32 v41, v9, v41
	v_mul_f32_e32 v26, v10, v26
	v_mul_f32_e32 v27, v11, v27
	v_mul_f32_e32 v24, v8, v24
	v_mul_f32_e32 v25, v9, v25
	v_mul_f32_e32 v10, v10, v12
	v_mul_f32_e32 v11, v11, v13
	v_mul_f32_e32 v8, v8, v14
	v_mul_f32_e32 v9, v9, v15
	global_store_dwordx4 v[80:81], v[74:77], off offset:16 nt
	global_store_dwordx4 v[160:161], v[8:11], off offset:16 nt
	v_mul_f32_e32 v70, v6, v70
	v_mul_f32_e32 v71, v7, v71
	v_mul_f32_e32 v68, v4, v68
	v_mul_f32_e32 v69, v5, v69
	v_mul_f32_e32 v8, v166, v226
	v_mul_f32_e32 v9, v167, v226
	v_mul_f32_e32 v10, v168, v226
	v_mul_f32_e32 v11, v169, v226
	v_mul_f32_e32 v54, v6, v54
	v_mul_f32_e32 v55, v7, v55
	v_mul_f32_e32 v52, v4, v52
	v_mul_f32_e32 v53, v5, v53
	v_mul_f32_e32 v38, v6, v38
	v_mul_f32_e32 v39, v7, v39
	v_mul_f32_e32 v36, v4, v36
	v_mul_f32_e32 v37, v5, v37
	v_mul_f32_e32 v22, v6, v22
	v_mul_f32_e32 v23, v7, v23
	v_mul_f32_e32 v20, v4, v20
	v_mul_f32_e32 v21, v5, v21
	v_mul_f32_e32 v6, v6, v8
	v_mul_f32_e32 v7, v7, v9
	v_mul_f32_e32 v4, v4, v10
	v_mul_f32_e32 v5, v5, v11
	global_store_dwordx4 v[80:81], v[68:71], off offset:512 nt
	global_store_dwordx4 v[160:161], v[4:7], off offset:512 nt
	v_mul_f32_e32 v66, v2, v66
	v_mul_f32_e32 v67, v3, v67
	v_mul_f32_e32 v64, v0, v64
	v_mul_f32_e32 v65, v1, v65
	v_mul_f32_e32 v4, v162, v226
	v_mul_f32_e32 v5, v163, v226
	v_mul_f32_e32 v6, v164, v226
	v_mul_f32_e32 v7, v165, v226
	v_mul_f32_e32 v50, v2, v50
	v_mul_f32_e32 v51, v3, v51
	v_mul_f32_e32 v48, v0, v48
	v_mul_f32_e32 v49, v1, v49
	v_mul_f32_e32 v34, v2, v34
	v_mul_f32_e32 v35, v3, v35
	v_mul_f32_e32 v32, v0, v32
	v_mul_f32_e32 v33, v1, v33
	v_mul_f32_e32 v2, v2, v4
	v_mul_f32_e32 v3, v3, v5
	v_mul_f32_e32 v0, v0, v6
	v_mul_f32_e32 v1, v1, v7
	global_store_dwordx4 v[80:81], v[64:67], off offset:528 nt
	global_store_dwordx4 v[72:73], v[60:63], off nt
	global_store_dwordx4 v[72:73], v[56:59], off offset:16 nt
	global_store_dwordx4 v[72:73], v[52:55], off offset:512 nt
	global_store_dwordx4 v[72:73], v[48:51], off offset:528 nt
	global_store_dwordx4 v[156:157], v[44:47], off nt
	global_store_dwordx4 v[156:157], v[40:43], off offset:16 nt
	global_store_dwordx4 v[156:157], v[36:39], off offset:512 nt
	global_store_dwordx4 v[156:157], v[32:35], off offset:528 nt
	global_store_dwordx4 v[158:159], v[28:31], off nt
	global_store_dwordx4 v[158:159], v[24:27], off offset:16 nt
	global_store_dwordx4 v[158:159], v[20:23], off offset:512 nt
	global_store_dwordx4 v[160:161], v[0:3], off offset:528 nt
	s_waitcnt lgkmcnt(0)
	s_barrier
	s_cbranch_vccnz .LBB0_1421
	s_andn2_b64 vcc, exec, s[10:11]
	s_cbranch_vccnz .LBB0_1420
	s_barrier
	s_branch .LBB0_1420
